# added: batched G2 epilogue loads, branchless rw_prep wave-offset accumulation (batched LDS reads), rw_phaseB wait relaxations + batched ds_reads, DPP-broadcast solver, R1 row prefetch
# speedup vs baseline: 1.0285x; 1.0285x over previous
; __device__ __forceinline__ float siluf_(float x) { return x * __builtin_amdgcn_rcpf(1.0f + __expf(-x)); }
; __global__ void __launch_bounds__(NTHREADS, 2) fwd_megakernel(Args args) {
;     ...
;         for (int r = gw; r < M; r += NGW) {
;             const int b = r / T, t = r - b * T;
;             const bf16_t* pr = PROJ + (size_t)r * NP;
; #pragma unroll
;             for (int it = 0; it < 2; ++it) {
;                 const int c8 = (it * 64 + lane) * 8;
;                 float o[8];
; #pragma unroll
;                 for (int i = 0; i < 8; ++i) o[i] = 0.f;
; #pragma unroll
;                 for (int j = 0; j < 4; ++j) {
;                     if (t - 3 + j >= 0) {
;                         float xv[8]; unpack8(*(const u32x4*)(pr - (size_t)(3 - j) * NP + C_BQ + c8), xv);
;                         const float* wp = mconv + ((size_t)l * 4 + j) * 1024 + c8;
;                         const f32x4 w0v = *(const f32x4*)wp, w1v = *(const f32x4*)(wp + 4);
; #pragma unroll
;                         for (int i = 0; i < 4; ++i) { o[i] += w0v[i] * xv[i]; o[4 + i] += w1v[i] * xv[4 + i]; }
;                     }
;                 }
;                 const float sc = (c8 < 512) ? 0.08838834764831845f : 1.0f;
; #pragma unroll
;                 for (int i = 0; i < 8; ++i) o[i] = siluf_(o[i]) * sc;
;                 *(u32x4*)(BQK + (size_t)r * 1024 + c8) = pack8(o);
;             }
;             if (lane < 8) {
;                 const float raw = IGFG[(size_t)r * 8 + lane];
;                 float o;
;                 if (lane < 4) o = raw + ig_b[l * 4 + lane];
;                 else { const float z = raw + fg_b[l * 4 + (lane - 4)]; o = fminf(z, 0.f) - __logf(1.0f + __expf(-fabsf(z))); }
;                 IL[(size_t)r * 8 + lane] = o;
;             }
; #pragma unroll
;             for (int it = 0; it < 6; ++it) {
;                 const int c8 = (it * 64 + lane) * 8;
;                 float cur[8], prv[8], o[8];
;                 unpack8(*(const u32x4*)(pr + C_CR + c8), cur);
;                 if (t > 0) unpack8(*(const u32x4*)(pr - NP + C_CR + c8), prv);
.LBB0_411:
	v_mul_hi_i32 v0, v60, s14
	v_lshrrev_b32_e32 v1, 31, v0
	v_ashrrev_i32_e32 v0, 12, v0
	v_add_u32_e32 v0, v0, v1
	v_mul_i32_i24_e32 v0, 0x2010, v0
	v_sub_u32_e32 v5, v60, v0
	v_mov_b64_e32 v[0:1], s[78:79]
	v_mov_b32_e32 v62, 0
	v_mad_i64_i32 v[66:67], s[0:1], v60, s58, v[0:1]
	v_and_b32_e32 v210, 63, v226
	v_lshlrev_b32_e32 v210, 4, v210
	v_mov_b32_e32 v211, 0
	v_lshl_add_u64 v[204:205], v[66:67], 0, v[210:211]
	s_mov_b64 s[100:101], 0x4000
	v_lshl_add_u64 v[206:207], v[204:205], 0, s[100:101]
	global_load_dwordx4 v[200:203], v[206:207], off
	global_load_dwordx4 v[200:203], v[206:207], off offset:1024
	global_load_dwordx4 v[200:203], v[206:207], off offset:2048
	global_load_dwordx4 v[200:203], v[206:207], off offset:3072
	s_mov_b64 s[100:101], 0x5000
	v_lshl_add_u64 v[206:207], v[204:205], 0, s[100:101]
	global_load_dwordx4 v[200:203], v[206:207], off
	global_load_dwordx4 v[200:203], v[206:207], off offset:1024
	s_mov_b32 s100, 0xffffae00
	s_mov_b32 s101, -1
	v_lshl_add_u64 v[206:207], v[204:205], 0, s[100:101]
	global_load_dwordx4 v[200:203], v[206:207], off
	global_load_dwordx4 v[200:203], v[206:207], off offset:1024
	global_load_dwordx4 v[200:203], v[206:207], off offset:2048
	global_load_dwordx4 v[200:203], v[206:207], off offset:3072
	s_mov_b32 s100, 0xffffbe00
	s_mov_b32 s101, -1
	v_lshl_add_u64 v[206:207], v[204:205], 0, s[100:101]
	global_load_dwordx4 v[200:203], v[206:207], off
	global_load_dwordx4 v[200:203], v[206:207], off offset:1024
	s_mov_b32 s100, 0xfffe6a00
	s_mov_b32 s101, -1
	v_lshl_add_u64 v[206:207], v[204:205], 0, s[100:101]
	global_load_dwordx4 v[200:203], v[206:207], off
	global_load_dwordx4 v[200:203], v[206:207], off offset:1024
	s_mov_b32 s100, 0xfffefc00
	s_mov_b32 s101, -1
	v_lshl_add_u64 v[206:207], v[204:205], 0, s[100:101]
	global_load_dwordx4 v[200:203], v[206:207], off
	global_load_dwordx4 v[200:203], v[206:207], off offset:1024
	s_mov_b32 s100, 0xffff8e00
	s_mov_b32 s101, -1
	v_lshl_add_u64 v[206:207], v[204:205], 0, s[100:101]
	global_load_dwordx4 v[200:203], v[206:207], off
	global_load_dwordx4 v[200:203], v[206:207], off offset:1024
	s_mov_b64 s[100:101], 0x2000
	v_lshl_add_u64 v[206:207], v[204:205], 0, s[100:101]
	global_load_dwordx4 v[200:203], v[206:207], off
	global_load_dwordx4 v[200:203], v[206:207], off offset:1024
	v_cmp_lt_i32_e64 s[46:47], 2, v5
	v_lshlrev_b32_e32 v54, 1, v6
	v_mov_b32_e32 v63, 0
	v_mov_b32_e32 v56, 0
	v_mov_b32_e32 v57, 0
	v_mov_b32_e32 v2, 0
	v_mov_b32_e32 v3, v62
	v_mov_b32_e32 v0, v62
	v_mov_b32_e32 v1, v62
	v_mov_b32_e32 v58, 0
	v_mov_b32_e32 v59, 0
	s_and_saveexec_b64 s[0:1], s[46:47]
	s_cbranch_execnz .LBB0_552
	s_or_b64 exec, exec, s[0:1]
	v_cmp_lt_i32_e64 s[48:49], 1, v5
	s_and_saveexec_b64 s[0:1], s[48:49]
	s_cbranch_execnz .LBB0_553

; __device__ __forceinline__ float siluf_(float x) { return x * __builtin_amdgcn_rcpf(1.0f + __expf(-x)); }
; __global__ void __launch_bounds__(NTHREADS, 2) fwd_megakernel(Args args) {
;     ...
;         for (int r = gw; r < M; r += NGW) {
;             const int b = r / T, t = r - b * T;
;             const bf16_t* pr = PROJ + (size_t)r * NP;
; #pragma unroll
;             for (int it = 0; it < 2; ++it) {
;                 const int c8 = (it * 64 + lane) * 8;
;                 float o[8];
; #pragma unroll
;                 for (int i = 0; i < 8; ++i) o[i] = 0.f;
; #pragma unroll
;                 for (int j = 0; j < 4; ++j) {
;                     if (t - 3 + j >= 0) {
;                         float xv[8]; unpack8(*(const u32x4*)(pr - (size_t)(3 - j) * NP + C_BQ + c8), xv);
;                         const float* wp = mconv + ((size_t)l * 4 + j) * 1024 + c8;
;                         const f32x4 w0v = *(const f32x4*)wp, w1v = *(const f32x4*)(wp + 4);
; #pragma unroll
;                         for (int i = 0; i < 4; ++i) { o[i] += w0v[i] * xv[i]; o[4 + i] += w1v[i] * xv[4 + i]; }
;                     }
;                 }
;                 const float sc = (c8 < 512) ? 0.08838834764831845f : 1.0f;
; #pragma unroll
;                 for (int i = 0; i < 8; ++i) o[i] = siluf_(o[i]) * sc;
;                 *(u32x4*)(BQK + (size_t)r * 1024 + c8) = pack8(o);
;             }
;             if (lane < 8) {
;                 const float raw = IGFG[(size_t)r * 8 + lane];
;                 float o;
;                 if (lane < 4) o = raw + ig_b[l * 4 + lane];
;                 else { const float z = raw + fg_b[l * 4 + (lane - 4)]; o = fminf(z, 0.f) - __logf(1.0f + __expf(-fabsf(z))); }
;                 IL[(size_t)r * 8 + lane] = o;
;             }
; #pragma unroll
;             for (int it = 0; it < 6; ++it) {
;                 const int c8 = (it * 64 + lane) * 8;
;                 float cur[8], prv[8], o[8];
;                 unpack8(*(const u32x4*)(pr + C_CR + c8), cur);
;                 if (t > 0) unpack8(*(const u32x4*)(pr - NP + C_CR + c8), prv);
.LBB0_481:
	s_or_b64 exec, exec, s[44:45]
	v_add_u32_e32 v66, s74, v60
	s_movk_i32 s0, 0x4020
	v_cmp_gt_i32_e32 vcc, s0, v66
	s_mov_b64 s[0:1], -1
	s_and_saveexec_b64 s[54:55], vcc
	s_cbranch_execz .LBB0_410
	v_mul_hi_i32 v0, v66, s14
	v_lshrrev_b32_e32 v1, 31, v0
	v_ashrrev_i32_e32 v0, 12, v0
	v_add_u32_e32 v0, v0, v1
	v_mul_i32_i24_e32 v0, 0x2010, v0
	v_sub_u32_e32 v5, v66, v0
	v_mov_b64_e32 v[0:1], s[78:79]
	v_mov_b32_e32 v72, 0
	v_mad_i64_i32 v[60:61], s[0:1], v66, s58, v[0:1]
	v_and_b32_e32 v210, 63, v226
	v_lshlrev_b32_e32 v210, 4, v210
	v_mov_b32_e32 v211, 0
	v_lshl_add_u64 v[204:205], v[60:61], 0, v[210:211]
	s_mov_b64 s[100:101], 0x4000
	v_lshl_add_u64 v[206:207], v[204:205], 0, s[100:101]
	global_load_dwordx4 v[200:203], v[206:207], off
	global_load_dwordx4 v[200:203], v[206:207], off offset:1024
	global_load_dwordx4 v[200:203], v[206:207], off offset:2048
	global_load_dwordx4 v[200:203], v[206:207], off offset:3072
	s_mov_b64 s[100:101], 0x5000
	v_lshl_add_u64 v[206:207], v[204:205], 0, s[100:101]
	global_load_dwordx4 v[200:203], v[206:207], off
	global_load_dwordx4 v[200:203], v[206:207], off offset:1024
	s_mov_b32 s100, 0xffffae00
	s_mov_b32 s101, -1
	v_lshl_add_u64 v[206:207], v[204:205], 0, s[100:101]
	global_load_dwordx4 v[200:203], v[206:207], off
	global_load_dwordx4 v[200:203], v[206:207], off offset:1024
	global_load_dwordx4 v[200:203], v[206:207], off offset:2048
	global_load_dwordx4 v[200:203], v[206:207], off offset:3072
	s_mov_b32 s100, 0xffffbe00
	s_mov_b32 s101, -1
	v_lshl_add_u64 v[206:207], v[204:205], 0, s[100:101]
	global_load_dwordx4 v[200:203], v[206:207], off
	global_load_dwordx4 v[200:203], v[206:207], off offset:1024
	s_mov_b32 s100, 0xfffe6a00
	s_mov_b32 s101, -1
	v_lshl_add_u64 v[206:207], v[204:205], 0, s[100:101]
	global_load_dwordx4 v[200:203], v[206:207], off
	global_load_dwordx4 v[200:203], v[206:207], off offset:1024
	s_mov_b32 s100, 0xfffefc00
	s_mov_b32 s101, -1
	v_lshl_add_u64 v[206:207], v[204:205], 0, s[100:101]
	global_load_dwordx4 v[200:203], v[206:207], off
	global_load_dwordx4 v[200:203], v[206:207], off offset:1024
	s_mov_b32 s100, 0xffff8e00
	s_mov_b32 s101, -1
	v_lshl_add_u64 v[206:207], v[204:205], 0, s[100:101]
	global_load_dwordx4 v[200:203], v[206:207], off
	global_load_dwordx4 v[200:203], v[206:207], off offset:1024
	s_mov_b64 s[100:101], 0x2000
	v_lshl_add_u64 v[206:207], v[204:205], 0, s[100:101]
	global_load_dwordx4 v[200:203], v[206:207], off
	global_load_dwordx4 v[200:203], v[206:207], off offset:1024
	v_cmp_lt_i32_e64 s[46:47], 2, v5
	v_mov_b32_e32 v73, 0
	v_mov_b32_e32 v68, 0
	v_mov_b32_e32 v69, v72
	v_mov_b32_e32 v2, v72
	v_mov_b32_e32 v3, v72
	v_mov_b32_e32 v0, v72
	v_mov_b32_e32 v1, v72
	v_mov_b32_e32 v70, v72
	v_mov_b32_e32 v71, v72
	s_and_saveexec_b64 s[0:1], s[46:47]
	s_cbranch_execnz .LBB0_558
	s_or_b64 exec, exec, s[0:1]
	v_cmp_lt_i32_e64 s[48:49], 1, v5
	s_and_saveexec_b64 s[0:1], s[48:49]
	s_cbranch_execnz .LBB0_559

; #define LDS_BAR() do { asm volatile("s_waitcnt lgkmcnt(0)" ::: "memory"); __builtin_amdgcn_s_barrier(); asm volatile("" ::: "memory"); } while (0)
; __device__ __forceinline__ void rw_prep(LAS float* SCR, const RwCtx& X, int b, int h, int t0, int tid, RwTok& K) {
;     ...
;     LDS_BAR();
; #pragma unroll
;     for (int i = 0; i < 8; ++i) { float off = 0.f;
; #pragma unroll
;         for (int w = 0; w < 7; ++w) if (w < wave) off += SCR[w * 64 + dq * 8 + i];
;         K.cw[i] += off; }
.LBB0_723:
	s_or_b64 exec, exec, s[0:1]
	s_waitcnt lgkmcnt(0)
	s_barrier
	v_ashrrev_i32_e32 v14, 6, v117
	v_readlane_b32 s0, v254, 49
	v_cmp_lt_i32_e32 vcc, 0, v14
	v_mov_b32_e32 v31, 0
	v_lshl_add_u32 v32, v32, 2, s0
	v_cmp_lt_i32_e64 s[46:47], 1, v14
	v_cmp_lt_i32_e64 s[48:49], 2, v14
	v_cmp_lt_i32_e64 s[50:51], 3, v14
	v_cmp_lt_i32_e64 s[52:53], 4, v14
	v_cmp_lt_i32_e64 s[54:55], 5, v14
	v_cmp_lt_i32_e64 s[56:57], 6, v14
	v_readlane_b32 s8, v254, 50
	ds_read_b128 v[148:151], v32 offset:0
	ds_read_b128 v[152:155], v32 offset:16
	ds_read_b128 v[156:159], v32 offset:256
	ds_read_b128 v[160:163], v32 offset:272
	ds_read_b128 v[164:167], v32 offset:512
	ds_read_b128 v[168:171], v32 offset:528
	ds_read_b128 v[172:175], v32 offset:768
	ds_read_b128 v[176:179], v32 offset:784
	ds_read_b128 v[180:183], v32 offset:1024
	ds_read_b128 v[184:187], v32 offset:1040
	ds_read_b128 v[188:191], v32 offset:1280
	ds_read_b128 v[192:195], v32 offset:1296
	ds_read_b128 v[196:199], v32 offset:1536
	ds_read_b128 v[200:203], v32 offset:1552
	v_cndmask_b32_e64 v204, 0, 1.0, vcc
	v_cndmask_b32_e64 v205, 0, 1.0, s[46:47]
	v_cndmask_b32_e64 v206, 0, 1.0, s[48:49]
	v_cndmask_b32_e64 v207, 0, 1.0, s[50:51]
	v_cndmask_b32_e64 v208, 0, 1.0, s[52:53]
	v_cndmask_b32_e64 v209, 0, 1.0, s[54:55]
	v_cndmask_b32_e64 v210, 0, 1.0, s[56:57]
	v_mov_b32_e32 v31, 0
	v_mov_b32_e32 v111, 0
	v_mov_b32_e32 v121, 0
	v_mov_b32_e32 v122, 0
	v_mov_b32_e32 v123, 0
	v_mov_b32_e32 v124, 0
	v_mov_b32_e32 v125, 0
	v_mov_b32_e32 v126, 0
	s_waitcnt lgkmcnt(0)
	v_fmac_f32_e32 v31, v204, v148
	v_fmac_f32_e32 v111, v204, v149
	v_fmac_f32_e32 v121, v204, v150
	v_fmac_f32_e32 v122, v204, v151
	v_fmac_f32_e32 v123, v204, v152
	v_fmac_f32_e32 v124, v204, v153
	v_fmac_f32_e32 v125, v204, v154
	v_fmac_f32_e32 v126, v204, v155
	v_fmac_f32_e32 v31, v205, v156
	v_fmac_f32_e32 v111, v205, v157
	v_fmac_f32_e32 v121, v205, v158
	v_fmac_f32_e32 v122, v205, v159
	v_fmac_f32_e32 v123, v205, v160
	v_fmac_f32_e32 v124, v205, v161
	v_fmac_f32_e32 v125, v205, v162
	v_fmac_f32_e32 v126, v205, v163
	v_fmac_f32_e32 v31, v206, v164
	v_fmac_f32_e32 v111, v206, v165
	v_fmac_f32_e32 v121, v206, v166
	v_fmac_f32_e32 v122, v206, v167
	v_fmac_f32_e32 v123, v206, v168
	v_fmac_f32_e32 v124, v206, v169
	v_fmac_f32_e32 v125, v206, v170
	v_fmac_f32_e32 v126, v206, v171
	v_fmac_f32_e32 v31, v207, v172
	v_fmac_f32_e32 v111, v207, v173
	v_fmac_f32_e32 v121, v207, v174
	v_fmac_f32_e32 v122, v207, v175
	v_fmac_f32_e32 v123, v207, v176
	v_fmac_f32_e32 v124, v207, v177
	v_fmac_f32_e32 v125, v207, v178
	v_fmac_f32_e32 v126, v207, v179
	v_fmac_f32_e32 v31, v208, v180
	v_fmac_f32_e32 v111, v208, v181
	v_fmac_f32_e32 v121, v208, v182
	v_fmac_f32_e32 v122, v208, v183
	v_fmac_f32_e32 v123, v208, v184
	v_fmac_f32_e32 v124, v208, v185
	v_fmac_f32_e32 v125, v208, v186
	v_fmac_f32_e32 v126, v208, v187
	v_fmac_f32_e32 v31, v209, v188
	v_fmac_f32_e32 v111, v209, v189
	v_fmac_f32_e32 v121, v209, v190
	v_fmac_f32_e32 v122, v209, v191
	v_fmac_f32_e32 v123, v209, v192
	v_fmac_f32_e32 v124, v209, v193
	v_fmac_f32_e32 v125, v209, v194
	v_fmac_f32_e32 v126, v209, v195
	v_fmac_f32_e32 v31, v210, v196
	v_fmac_f32_e32 v111, v210, v197
	v_fmac_f32_e32 v121, v210, v198
	v_fmac_f32_e32 v122, v210, v199
	v_fmac_f32_e32 v123, v210, v200
	v_fmac_f32_e32 v124, v210, v201
	v_fmac_f32_e32 v125, v210, v202
	v_fmac_f32_e32 v126, v210, v203

; #define LAS __attribute__((address_space(3)))
; __device__ __forceinline__ unsigned cvt_pk_bf16(float lo, float hi) { const bf16x2_t r = __builtin_convertvector((f32x2){lo, hi}, bf16x2_t); return __builtin_bit_cast(unsigned, r); }
; #define LDS_BAR() do { asm volatile("s_waitcnt lgkmcnt(0)" ::: "memory"); __builtin_amdgcn_s_barrier(); asm volatile("" ::: "memory"); } while (0)
; __device__ __forceinline__ void rw_phaseA(LAS unsigned char* lds, const RwCtx& X, int item) {
;     ...
;             for (int j = 0; j < 4; ++j) { const int tt = t0b + fq * 4 + j, sidx = s0 + fr; LAB[tt * 68 + sidx] = (sidx < tt) ? acc[j] : 0.f; }
;             float p[4];
; #pragma unroll
;             for (int j = 0; j < 4; ++j) p[j] = (s0 + fq * 4 + j < t0b + fr) ? acc2[j] : 0.f;
;             u32x2 o; o.x = cvt_pk_bf16(p[0], p[1]); o.y = cvt_pk_bf16(p[2], p[3]);
;             *(LAS u32x2*)(LAK + (t0b + fr) * 72 + s0 + fq * 4) = o; }
;     }
;     LDS_BAR();
;     {
;         bf16x8 fl[2];
; #pragma unroll
;         for (int k = 0; k < 2; ++k) fl[k] = *(const LAS bf16x8*)(LAK + (t0b + fr) * 72 + k * 32 + fq * 8);
; #pragma unroll
;         for (int bi = 0; bi < 2; ++bi) { const int v0 = ((wave & 1) * 2 + bi) * 16; f32x4 acc = (f32x4){0.f, 0.f, 0.f, 0.f};
; #pragma unroll
;             for (int k = 0; k < 2; ++k) { const bf16x8 fv = *(const LAS bf16x8*)(VT + (v0 + fr) * 72 + k * 32 + fq * 8); acc = __builtin_amdgcn_mfma_f32_16x16x32_bf16(fl[k], fv, acc, 0, 0, 0); }
; #pragma unroll
;             for (int j = 0; j < 4; ++j) XS[(t0b + fq * 4 + j) * 129 + 64 + v0 + fr] = acc[j]; }
;     }
;     LDS_BAR();
;     int tid_s = threadIdx.x; asm volatile("" : "+v"(tid_s));
;     if (tid_s < 128) {
;         float x[64];
;         int zv = 0; asm volatile("" : "+v"(zv));
;         const LAS float* LABv = LAB + zv;
; #pragma unroll
;         for (int i = 0; i < 64; ++i) x[i] = XS[i * 129 + tid_s];
; #pragma unroll
;         for (int tt = 1; tt < 64; ++tt) { float a = x[tt];
; #pragma unroll
;             for (int s4 = 0; s4 < (tt + 3) / 4; ++s4) { const f32x4 l4 = *(const LAS f32x4*)(LABv + tt * 68 + s4 * 4);
;                 a += l4[0] * x[s4 * 4]; if (s4 * 4 + 1 < tt) a += l4[1] * x[s4 * 4 + 1]; if (s4 * 4 + 2 < tt) a += l4[2] * x[s4 * 4 + 2]; if (s4 * 4 + 3 < tt) a += l4[3] * x[s4 * 4 + 3]; }
.LBB0_801:
	s_or_b64 exec, exec, s[0:1]
	v_cmp_lt_i32_e32 vcc, v18, v27
	s_waitcnt lgkmcnt(5)
	v_lshlrev_b32_e32 v5, 2, v18
	v_add3_u32 v6, s88, v30, v5
	v_cndmask_b32_e32 v4, 0, v14, vcc
	v_cmp_le_i32_e32 vcc, v18, v27
	ds_write_b32 v6, v4
	v_add3_u32 v6, s88, v19, v5
	v_cndmask_b32_e32 v4, 0, v15, vcc
	v_cmp_lt_i32_e32 vcc, v18, v31
	ds_write_b32 v6, v4
	v_add3_u32 v6, s88, v20, v5
	v_cndmask_b32_e32 v4, 0, v16, vcc
	v_cmp_lt_i32_e32 vcc, v18, v32
	ds_write_b32 v6, v4
	v_add3_u32 v5, s88, v21, v5
	v_cndmask_b32_e32 v4, 0, v17, vcc
	ds_write_b32 v5, v4
	v_or_b32_e32 v4, v34, v29
	v_cmp_lt_i32_e32 vcc, v4, v26
	v_or_b32_e32 v5, 1, v4
	v_mad_u32_u24 v14, v25, s91, v22
	v_cndmask_b32_e32 v0, 0, v0, vcc
	v_cmp_lt_i32_e32 vcc, v5, v26
	v_or_b32_e32 v5, 2, v4
	v_or_b32_e32 v4, 3, v4
	v_cndmask_b32_e32 v1, 0, v1, vcc
	v_cmp_lt_i32_e32 vcc, v5, v26
	v_cvt_pk_bf16_f32 v0, v0, v1
	s_movk_i32 s0, 0x204
	v_cndmask_b32_e32 v2, 0, v2, vcc
	v_cmp_lt_i32_e32 vcc, v4, v26
	v_add_u32_e32 v4, v28, v24
	v_lshlrev_b32_e32 v8, 2, v8
	v_cndmask_b32_e32 v3, 0, v3, vcc
	v_cvt_pk_bf16_f32 v1, v2, v3
	ds_write_b64 v33, v[0:1] offset:32
	s_waitcnt lgkmcnt(0)
	s_barrier
	ds_read_b128 v[0:3], v4
	ds_read_b128 v[4:7], v4 offset:64
	ds_read_b128 v[10:13], v14 offset:46080
	ds_read_b128 v[14:17], v14 offset:46144
	s_waitcnt lgkmcnt(1)
	v_mfma_f32_16x16x32_bf16 v[10:13], v[0:3], v[10:13], 0
	v_mov_b32_e32 v247, v226
	s_waitcnt lgkmcnt(0)
	v_mfma_f32_16x16x32_bf16 v[10:13], v[4:7], v[14:17], v[10:13]
	v_mul_lo_u32 v14, v27, s0
	v_add_u32_e32 v14, 0, v14
	v_lshlrev_b32_e32 v15, 2, v23
	v_add3_u32 v8, v14, v15, v8
	s_nop 3
	ds_write_b32 v8, v10 offset:55552
	ds_write_b32 v8, v11 offset:56068
	ds_write_b32 v8, v12 offset:56584
	ds_write_b32 v8, v13 offset:57100
	v_mad_u32_u24 v14, v18, s91, v22
	ds_read_b128 v[10:13], v14 offset:46080
	ds_read_b128 v[14:17], v14 offset:46144
	s_waitcnt lgkmcnt(1)
	v_mfma_f32_16x16x32_bf16 v[0:3], v[0:3], v[10:13], 0
	s_movk_i32 s0, 0x80
	s_waitcnt lgkmcnt(0)
	v_mfma_f32_16x16x32_bf16 v[0:3], v[4:7], v[14:17], v[0:3]
	s_nop 7
	ds_write_b32 v8, v0 offset:55616
	ds_write_b32 v8, v1 offset:56132
	ds_write_b32 v8, v2 offset:56648
	ds_write_b32 v8, v3 offset:57164
	s_waitcnt lgkmcnt(0)
	s_barrier
	s_nop 0
	v_cmp_gt_i32_e32 vcc, s0, v247
	s_and_saveexec_b64 s[0:1], vcc
	s_cbranch_execz .LBB0_720
	v_lshlrev_b32_e32 v6, 2, v247
	v_add_u32_e32 v6, 0xd800, v6
	v_and_b32_e32 v7, 15, v247
	v_lshlrev_b32_e32 v7, 2, v7
	v_add_u32_e32 v7, 0x15900, v7
	ds_read_b32 v64, v6 offset:0
	ds_read_b32 v65, v6 offset:516
	ds_read_b32 v66, v6 offset:1032
	ds_read_b32 v67, v6 offset:1548
	ds_read_b32 v68, v6 offset:2064
	ds_read_b32 v69, v6 offset:2580
	ds_read_b32 v70, v6 offset:3096
	ds_read_b32 v71, v6 offset:3612
	ds_read_b32 v72, v6 offset:4128
	ds_read_b32 v73, v6 offset:4644
	ds_read_b32 v74, v6 offset:5160
	ds_read_b32 v75, v6 offset:5676
	ds_read_b32 v76, v6 offset:6192
	ds_read_b32 v77, v6 offset:6708
	ds_read_b32 v78, v6 offset:7224
	ds_read_b32 v79, v6 offset:7740
	ds_read_b32 v80, v6 offset:8256
	ds_read_b32 v81, v6 offset:8772
	ds_read_b32 v82, v6 offset:9288
	ds_read_b32 v83, v6 offset:9804
	ds_read_b32 v84, v6 offset:10320
	ds_read_b32 v85, v6 offset:10836
	ds_read_b32 v86, v6 offset:11352
	ds_read_b32 v87, v6 offset:11868
	ds_read_b32 v88, v6 offset:12384
	ds_read_b32 v89, v6 offset:12900
	ds_read_b32 v90, v6 offset:13416
	ds_read_b32 v91, v6 offset:13932
	ds_read_b32 v92, v6 offset:14448
	ds_read_b32 v93, v6 offset:14964
	ds_read_b32 v94, v6 offset:15480
	ds_read_b32 v95, v6 offset:15996
	ds_read_b32 v96, v6 offset:16512
	ds_read_b32 v97, v6 offset:17028
	ds_read_b32 v98, v6 offset:17544
	ds_read_b32 v99, v6 offset:18060
	ds_read_b32 v100, v6 offset:18576
	ds_read_b32 v101, v6 offset:19092
	ds_read_b32 v102, v6 offset:19608
	ds_read_b32 v103, v6 offset:20124
	ds_read_b32 v104, v6 offset:20640
	ds_read_b32 v105, v6 offset:21156
	ds_read_b32 v106, v6 offset:21672
	ds_read_b32 v107, v6 offset:22188
	ds_read_b32 v108, v6 offset:22704
	ds_read_b32 v109, v6 offset:23220
	ds_read_b32 v110, v6 offset:23736
	ds_read_b32 v111, v6 offset:24252
	ds_read_b32 v112, v6 offset:24768
	ds_read_b32 v113, v6 offset:25284
	ds_read_b32 v114, v6 offset:25800
	ds_read_b32 v115, v6 offset:26316
	ds_read_b32 v116, v6 offset:26832
	ds_read_b32 v117, v6 offset:27348
	ds_read_b32 v118, v6 offset:27864
	ds_read_b32 v119, v6 offset:28380
	ds_read_b32 v120, v6 offset:28896
	ds_read_b32 v121, v6 offset:29412
	ds_read_b32 v122, v6 offset:29928
	ds_read_b32 v123, v6 offset:30444
	ds_read_b32 v124, v6 offset:30960
	ds_read_b32 v125, v6 offset:31476
	ds_read_b32 v126, v6 offset:31992
	ds_read_b32 v127, v6 offset:32508
	ds_read_b32 v148, v7 offset:272
	ds_read_b32 v149, v7 offset:544
	ds_read_b32 v150, v7 offset:816
	ds_read_b32 v151, v7 offset:1088
	ds_read_b32 v152, v7 offset:1360
	ds_read_b32 v153, v7 offset:1632
	ds_read_b32 v154, v7 offset:1904
	ds_read_b32 v155, v7 offset:2176
	ds_read_b32 v156, v7 offset:2448
	ds_read_b32 v157, v7 offset:2720
	ds_read_b32 v158, v7 offset:2992
	ds_read_b32 v159, v7 offset:3264
	v_cmp_gt_u32_e32 vcc, 64, v247
	v_mul_u32_u24_e32 v8, 0x90, v247
	v_mov_b32_e32 v4, 0x17900
	v_mov_b32_e32 v5, 0x4800
	v_cndmask_b32_e32 v4, v4, v5, vcc
	v_add_u32_e32 v8, v8, v4
	v_lshlrev_b32_e32 v10, 1, v247
	v_mov_b32_e32 v4, 0x1f80
	v_mov_b32_e32 v5, 0
	v_cndmask_b32_e32 v4, v4, v5, vcc
	v_add_u32_e32 v10, v10, v4
	s_waitcnt lgkmcnt(11)
	v_mul_f32_dpp v0, v148, v64 row_newbcast:0 row_mask:0xf bank_mask:0xf
	ds_read_b32 v160, v7 offset:3536
	v_add_f32_e32 v65, v65, v0
	s_waitcnt lgkmcnt(11)
; #define LAS __attribute__((address_space(3)))
; __device__ __forceinline__ void rw_phaseA(LAS unsigned char* lds, const RwCtx& X, int item) {
;     ...
;         for (int tt = 1; tt < 64; ++tt) { float a = x[tt];
; #pragma unroll
;             for (int s4 = 0; s4 < (tt + 3) / 4; ++s4) { const f32x4 l4 = *(const LAS f32x4*)(LABv + tt * 68 + s4 * 4);
;                 a += l4[0] * x[s4 * 4]; if (s4 * 4 + 1 < tt) a += l4[1] * x[s4 * 4 + 1]; if (s4 * 4 + 2 < tt) a += l4[2] * x[s4 * 4 + 2]; if (s4 * 4 + 3 < tt) a += l4[3] * x[s4 * 4 + 3]; }
;             x[tt] = a;
	v_mul_f32_dpp v0, v149, v64 row_newbcast:0 row_mask:0xf bank_mask:0xf
	v_mul_f32_dpp v1, v149, v65 row_newbcast:1 row_mask:0xf bank_mask:0xf
	ds_read_b32 v161, v7 offset:3808
	v_add_f32_e32 v0, v0, v1
	v_add_f32_e32 v66, v66, v0
	s_waitcnt lgkmcnt(11)
	v_mul_f32_dpp v0, v150, v64 row_newbcast:0 row_mask:0xf bank_mask:0xf
	v_mul_f32_dpp v1, v150, v65 row_newbcast:1 row_mask:0xf bank_mask:0xf
	v_mul_f32_dpp v2, v150, v66 row_newbcast:2 row_mask:0xf bank_mask:0xf
	ds_read_b32 v162, v7 offset:4080
	v_add_f32_e32 v0, v0, v1
	v_add_f32_e32 v0, v0, v2
	v_add_f32_e32 v67, v67, v0
	s_waitcnt lgkmcnt(11)
	v_mul_f32_dpp v0, v151, v64 row_newbcast:0 row_mask:0xf bank_mask:0xf
	v_mul_f32_dpp v1, v151, v65 row_newbcast:1 row_mask:0xf bank_mask:0xf
	v_mul_f32_dpp v2, v151, v66 row_newbcast:2 row_mask:0xf bank_mask:0xf
	v_mul_f32_dpp v3, v151, v67 row_newbcast:3 row_mask:0xf bank_mask:0xf
	ds_read_b32 v163, v7 offset:4352
	v_add_f32_e32 v0, v0, v1
	v_add_f32_e32 v2, v2, v3
	v_add_f32_e32 v0, v0, v2
	v_add_f32_e32 v68, v68, v0
	s_waitcnt lgkmcnt(11)
	v_mul_f32_dpp v0, v152, v64 row_newbcast:0 row_mask:0xf bank_mask:0xf
	v_mul_f32_dpp v1, v152, v65 row_newbcast:1 row_mask:0xf bank_mask:0xf
	v_mul_f32_dpp v2, v152, v66 row_newbcast:2 row_mask:0xf bank_mask:0xf
	v_mul_f32_dpp v3, v152, v67 row_newbcast:3 row_mask:0xf bank_mask:0xf
	v_fmac_f32_dpp v0, v152, v68 row_newbcast:4 row_mask:0xf bank_mask:0xf
	ds_read_b32 v164, v7 offset:4624
	v_add_f32_e32 v0, v0, v1
	v_add_f32_e32 v2, v2, v3
	v_add_f32_e32 v0, v0, v2
	v_add_f32_e32 v69, v69, v0
	s_waitcnt lgkmcnt(11)
	v_mul_f32_dpp v0, v153, v64 row_newbcast:0 row_mask:0xf bank_mask:0xf
	v_mul_f32_dpp v1, v153, v65 row_newbcast:1 row_mask:0xf bank_mask:0xf
	v_mul_f32_dpp v2, v153, v66 row_newbcast:2 row_mask:0xf bank_mask:0xf
	v_mul_f32_dpp v3, v153, v67 row_newbcast:3 row_mask:0xf bank_mask:0xf
	v_fmac_f32_dpp v0, v153, v68 row_newbcast:4 row_mask:0xf bank_mask:0xf
	v_fmac_f32_dpp v1, v153, v69 row_newbcast:5 row_mask:0xf bank_mask:0xf
	ds_read_b32 v165, v7 offset:4688
	v_add_f32_e32 v0, v0, v1
	v_add_f32_e32 v2, v2, v3
	v_add_f32_e32 v0, v0, v2
	v_add_f32_e32 v70, v70, v0
	s_waitcnt lgkmcnt(11)
	v_mul_f32_dpp v0, v154, v64 row_newbcast:0 row_mask:0xf bank_mask:0xf
	v_mul_f32_dpp v1, v154, v65 row_newbcast:1 row_mask:0xf bank_mask:0xf
	v_mul_f32_dpp v2, v154, v66 row_newbcast:2 row_mask:0xf bank_mask:0xf
	v_mul_f32_dpp v3, v154, v67 row_newbcast:3 row_mask:0xf bank_mask:0xf
	v_fmac_f32_dpp v0, v154, v68 row_newbcast:4 row_mask:0xf bank_mask:0xf
	v_fmac_f32_dpp v1, v154, v69 row_newbcast:5 row_mask:0xf bank_mask:0xf
	v_fmac_f32_dpp v2, v154, v70 row_newbcast:6 row_mask:0xf bank_mask:0xf
	ds_read_b32 v166, v7 offset:4896
	v_add_f32_e32 v0, v0, v1
	v_add_f32_e32 v2, v2, v3
	v_add_f32_e32 v0, v0, v2
	v_add_f32_e32 v71, v71, v0
	s_waitcnt lgkmcnt(11)
	v_mul_f32_dpp v0, v155, v64 row_newbcast:0 row_mask:0xf bank_mask:0xf
	v_mul_f32_dpp v1, v155, v65 row_newbcast:1 row_mask:0xf bank_mask:0xf
	v_mul_f32_dpp v2, v155, v66 row_newbcast:2 row_mask:0xf bank_mask:0xf
	v_mul_f32_dpp v3, v155, v67 row_newbcast:3 row_mask:0xf bank_mask:0xf
	v_fmac_f32_dpp v0, v155, v68 row_newbcast:4 row_mask:0xf bank_mask:0xf
	v_fmac_f32_dpp v1, v155, v69 row_newbcast:5 row_mask:0xf bank_mask:0xf
	v_fmac_f32_dpp v2, v155, v70 row_newbcast:6 row_mask:0xf bank_mask:0xf
	v_fmac_f32_dpp v3, v155, v71 row_newbcast:7 row_mask:0xf bank_mask:0xf
	ds_read_b32 v167, v7 offset:4960
	v_add_f32_e32 v0, v0, v1
	v_add_f32_e32 v2, v2, v3
	v_add_f32_e32 v0, v0, v2
	v_add_f32_e32 v72, v72, v0
	s_waitcnt lgkmcnt(11)
	v_mul_f32_dpp v0, v156, v64 row_newbcast:0 row_mask:0xf bank_mask:0xf
	v_mul_f32_dpp v1, v156, v65 row_newbcast:1 row_mask:0xf bank_mask:0xf
	v_mul_f32_dpp v2, v156, v66 row_newbcast:2 row_mask:0xf bank_mask:0xf
	v_mul_f32_dpp v3, v156, v67 row_newbcast:3 row_mask:0xf bank_mask:0xf
	v_fmac_f32_dpp v0, v156, v68 row_newbcast:4 row_mask:0xf bank_mask:0xf
	v_fmac_f32_dpp v1, v156, v69 row_newbcast:5 row_mask:0xf bank_mask:0xf
	v_fmac_f32_dpp v2, v156, v70 row_newbcast:6 row_mask:0xf bank_mask:0xf
	v_fmac_f32_dpp v3, v156, v71 row_newbcast:7 row_mask:0xf bank_mask:0xf
	v_fmac_f32_dpp v0, v156, v72 row_newbcast:8 row_mask:0xf bank_mask:0xf
	ds_read_b32 v168, v7 offset:5168
	v_add_f32_e32 v0, v0, v1
	v_add_f32_e32 v2, v2, v3
	v_add_f32_e32 v0, v0, v2
	v_add_f32_e32 v73, v73, v0
	s_waitcnt lgkmcnt(11)
	v_mul_f32_dpp v0, v157, v64 row_newbcast:0 row_mask:0xf bank_mask:0xf
	v_mul_f32_dpp v1, v157, v65 row_newbcast:1 row_mask:0xf bank_mask:0xf
	v_mul_f32_dpp v2, v157, v66 row_newbcast:2 row_mask:0xf bank_mask:0xf
	v_mul_f32_dpp v3, v157, v67 row_newbcast:3 row_mask:0xf bank_mask:0xf
	v_fmac_f32_dpp v0, v157, v68 row_newbcast:4 row_mask:0xf bank_mask:0xf
	v_fmac_f32_dpp v1, v157, v69 row_newbcast:5 row_mask:0xf bank_mask:0xf
	v_fmac_f32_dpp v2, v157, v70 row_newbcast:6 row_mask:0xf bank_mask:0xf
	v_fmac_f32_dpp v3, v157, v71 row_newbcast:7 row_mask:0xf bank_mask:0xf
	v_fmac_f32_dpp v0, v157, v72 row_newbcast:8 row_mask:0xf bank_mask:0xf
	v_fmac_f32_dpp v1, v157, v73 row_newbcast:9 row_mask:0xf bank_mask:0xf
	ds_read_b32 v169, v7 offset:5232
	v_add_f32_e32 v0, v0, v1
	v_add_f32_e32 v2, v2, v3
	v_add_f32_e32 v0, v0, v2
	v_add_f32_e32 v74, v74, v0
	s_waitcnt lgkmcnt(11)
; #define LAS __attribute__((address_space(3)))
; __device__ __forceinline__ void rw_phaseA(LAS unsigned char* lds, const RwCtx& X, int item) {
;     ...
;         for (int tt = 1; tt < 64; ++tt) { float a = x[tt];
; #pragma unroll
;             for (int s4 = 0; s4 < (tt + 3) / 4; ++s4) { const f32x4 l4 = *(const LAS f32x4*)(LABv + tt * 68 + s4 * 4);
;                 a += l4[0] * x[s4 * 4]; if (s4 * 4 + 1 < tt) a += l4[1] * x[s4 * 4 + 1]; if (s4 * 4 + 2 < tt) a += l4[2] * x[s4 * 4 + 2]; if (s4 * 4 + 3 < tt) a += l4[3] * x[s4 * 4 + 3]; }
;             x[tt] = a;
	v_mul_f32_dpp v0, v158, v64 row_newbcast:0 row_mask:0xf bank_mask:0xf
	v_mul_f32_dpp v1, v158, v65 row_newbcast:1 row_mask:0xf bank_mask:0xf
	v_mul_f32_dpp v2, v158, v66 row_newbcast:2 row_mask:0xf bank_mask:0xf
	v_mul_f32_dpp v3, v158, v67 row_newbcast:3 row_mask:0xf bank_mask:0xf
	v_fmac_f32_dpp v0, v158, v68 row_newbcast:4 row_mask:0xf bank_mask:0xf
	v_fmac_f32_dpp v1, v158, v69 row_newbcast:5 row_mask:0xf bank_mask:0xf
	v_fmac_f32_dpp v2, v158, v70 row_newbcast:6 row_mask:0xf bank_mask:0xf
	v_fmac_f32_dpp v3, v158, v71 row_newbcast:7 row_mask:0xf bank_mask:0xf
	v_fmac_f32_dpp v0, v158, v72 row_newbcast:8 row_mask:0xf bank_mask:0xf
	v_fmac_f32_dpp v1, v158, v73 row_newbcast:9 row_mask:0xf bank_mask:0xf
	v_fmac_f32_dpp v2, v158, v74 row_newbcast:10 row_mask:0xf bank_mask:0xf
	ds_read_b32 v170, v7 offset:5440
	v_add_f32_e32 v0, v0, v1
	v_add_f32_e32 v2, v2, v3
	v_add_f32_e32 v0, v0, v2
	v_add_f32_e32 v75, v75, v0
	s_waitcnt lgkmcnt(11)
	v_mul_f32_dpp v0, v159, v64 row_newbcast:0 row_mask:0xf bank_mask:0xf
	v_mul_f32_dpp v1, v159, v65 row_newbcast:1 row_mask:0xf bank_mask:0xf
	v_mul_f32_dpp v2, v159, v66 row_newbcast:2 row_mask:0xf bank_mask:0xf
	v_mul_f32_dpp v3, v159, v67 row_newbcast:3 row_mask:0xf bank_mask:0xf
	v_fmac_f32_dpp v0, v159, v68 row_newbcast:4 row_mask:0xf bank_mask:0xf
	v_fmac_f32_dpp v1, v159, v69 row_newbcast:5 row_mask:0xf bank_mask:0xf
	v_fmac_f32_dpp v2, v159, v70 row_newbcast:6 row_mask:0xf bank_mask:0xf
	v_fmac_f32_dpp v3, v159, v71 row_newbcast:7 row_mask:0xf bank_mask:0xf
	v_fmac_f32_dpp v0, v159, v72 row_newbcast:8 row_mask:0xf bank_mask:0xf
	v_fmac_f32_dpp v1, v159, v73 row_newbcast:9 row_mask:0xf bank_mask:0xf
	v_fmac_f32_dpp v2, v159, v74 row_newbcast:10 row_mask:0xf bank_mask:0xf
	v_fmac_f32_dpp v3, v159, v75 row_newbcast:11 row_mask:0xf bank_mask:0xf
	ds_read_b32 v171, v7 offset:5504
	v_add_f32_e32 v0, v0, v1
	v_add_f32_e32 v2, v2, v3
	v_add_f32_e32 v0, v0, v2
	v_add_f32_e32 v76, v76, v0
	s_waitcnt lgkmcnt(11)
	v_mul_f32_dpp v0, v160, v64 row_newbcast:0 row_mask:0xf bank_mask:0xf
	v_mul_f32_dpp v1, v160, v65 row_newbcast:1 row_mask:0xf bank_mask:0xf
	v_mul_f32_dpp v2, v160, v66 row_newbcast:2 row_mask:0xf bank_mask:0xf
	v_mul_f32_dpp v3, v160, v67 row_newbcast:3 row_mask:0xf bank_mask:0xf
	v_fmac_f32_dpp v0, v160, v68 row_newbcast:4 row_mask:0xf bank_mask:0xf
	v_fmac_f32_dpp v1, v160, v69 row_newbcast:5 row_mask:0xf bank_mask:0xf
	v_fmac_f32_dpp v2, v160, v70 row_newbcast:6 row_mask:0xf bank_mask:0xf
	v_fmac_f32_dpp v3, v160, v71 row_newbcast:7 row_mask:0xf bank_mask:0xf
	v_fmac_f32_dpp v0, v160, v72 row_newbcast:8 row_mask:0xf bank_mask:0xf
	v_fmac_f32_dpp v1, v160, v73 row_newbcast:9 row_mask:0xf bank_mask:0xf
	v_fmac_f32_dpp v2, v160, v74 row_newbcast:10 row_mask:0xf bank_mask:0xf
	v_fmac_f32_dpp v3, v160, v75 row_newbcast:11 row_mask:0xf bank_mask:0xf
	v_fmac_f32_dpp v0, v160, v76 row_newbcast:12 row_mask:0xf bank_mask:0xf
	ds_read_b32 v148, v7 offset:5712
	v_add_f32_e32 v0, v0, v1
	v_add_f32_e32 v2, v2, v3
	v_add_f32_e32 v0, v0, v2
	v_add_f32_e32 v77, v77, v0
	s_waitcnt lgkmcnt(11)
	v_mul_f32_dpp v0, v161, v64 row_newbcast:0 row_mask:0xf bank_mask:0xf
	v_mul_f32_dpp v1, v161, v65 row_newbcast:1 row_mask:0xf bank_mask:0xf
	v_mul_f32_dpp v2, v161, v66 row_newbcast:2 row_mask:0xf bank_mask:0xf
	v_mul_f32_dpp v3, v161, v67 row_newbcast:3 row_mask:0xf bank_mask:0xf
	v_fmac_f32_dpp v0, v161, v68 row_newbcast:4 row_mask:0xf bank_mask:0xf
	v_fmac_f32_dpp v1, v161, v69 row_newbcast:5 row_mask:0xf bank_mask:0xf
	v_fmac_f32_dpp v2, v161, v70 row_newbcast:6 row_mask:0xf bank_mask:0xf
	v_fmac_f32_dpp v3, v161, v71 row_newbcast:7 row_mask:0xf bank_mask:0xf
	v_fmac_f32_dpp v0, v161, v72 row_newbcast:8 row_mask:0xf bank_mask:0xf
	v_fmac_f32_dpp v1, v161, v73 row_newbcast:9 row_mask:0xf bank_mask:0xf
	v_fmac_f32_dpp v2, v161, v74 row_newbcast:10 row_mask:0xf bank_mask:0xf
	v_fmac_f32_dpp v3, v161, v75 row_newbcast:11 row_mask:0xf bank_mask:0xf
	v_fmac_f32_dpp v0, v161, v76 row_newbcast:12 row_mask:0xf bank_mask:0xf
	v_fmac_f32_dpp v1, v161, v77 row_newbcast:13 row_mask:0xf bank_mask:0xf
	ds_read_b32 v149, v7 offset:5776
	v_add_f32_e32 v0, v0, v1
	v_add_f32_e32 v2, v2, v3
	v_add_f32_e32 v0, v0, v2
	v_add_f32_e32 v78, v78, v0
	s_waitcnt lgkmcnt(11)
	v_mul_f32_dpp v0, v162, v64 row_newbcast:0 row_mask:0xf bank_mask:0xf
	v_mul_f32_dpp v1, v162, v65 row_newbcast:1 row_mask:0xf bank_mask:0xf
	v_mul_f32_dpp v2, v162, v66 row_newbcast:2 row_mask:0xf bank_mask:0xf
	v_mul_f32_dpp v3, v162, v67 row_newbcast:3 row_mask:0xf bank_mask:0xf
	v_fmac_f32_dpp v0, v162, v68 row_newbcast:4 row_mask:0xf bank_mask:0xf
	v_fmac_f32_dpp v1, v162, v69 row_newbcast:5 row_mask:0xf bank_mask:0xf
	v_fmac_f32_dpp v2, v162, v70 row_newbcast:6 row_mask:0xf bank_mask:0xf
	v_fmac_f32_dpp v3, v162, v71 row_newbcast:7 row_mask:0xf bank_mask:0xf
	v_fmac_f32_dpp v0, v162, v72 row_newbcast:8 row_mask:0xf bank_mask:0xf
	v_fmac_f32_dpp v1, v162, v73 row_newbcast:9 row_mask:0xf bank_mask:0xf
	v_fmac_f32_dpp v2, v162, v74 row_newbcast:10 row_mask:0xf bank_mask:0xf
	v_fmac_f32_dpp v3, v162, v75 row_newbcast:11 row_mask:0xf bank_mask:0xf
	v_fmac_f32_dpp v0, v162, v76 row_newbcast:12 row_mask:0xf bank_mask:0xf
	v_fmac_f32_dpp v1, v162, v77 row_newbcast:13 row_mask:0xf bank_mask:0xf
	v_fmac_f32_dpp v2, v162, v78 row_newbcast:14 row_mask:0xf bank_mask:0xf
	ds_read_b32 v150, v7 offset:5984
	v_add_f32_e32 v0, v0, v1
	v_add_f32_e32 v2, v2, v3
	v_add_f32_e32 v0, v0, v2
	v_add_f32_e32 v79, v79, v0
	s_waitcnt lgkmcnt(11)
; #define LAS __attribute__((address_space(3)))
; __device__ __forceinline__ void rw_phaseA(LAS unsigned char* lds, const RwCtx& X, int item) {
;     ...
;         for (int tt = 1; tt < 64; ++tt) { float a = x[tt];
; #pragma unroll
;             for (int s4 = 0; s4 < (tt + 3) / 4; ++s4) { const f32x4 l4 = *(const LAS f32x4*)(LABv + tt * 68 + s4 * 4);
;                 a += l4[0] * x[s4 * 4]; if (s4 * 4 + 1 < tt) a += l4[1] * x[s4 * 4 + 1]; if (s4 * 4 + 2 < tt) a += l4[2] * x[s4 * 4 + 2]; if (s4 * 4 + 3 < tt) a += l4[3] * x[s4 * 4 + 3]; }
;             x[tt] = a;
	v_mul_f32_dpp v0, v163, v64 row_newbcast:0 row_mask:0xf bank_mask:0xf
	v_mul_f32_dpp v1, v163, v65 row_newbcast:1 row_mask:0xf bank_mask:0xf
	v_mul_f32_dpp v2, v163, v66 row_newbcast:2 row_mask:0xf bank_mask:0xf
	v_mul_f32_dpp v3, v163, v67 row_newbcast:3 row_mask:0xf bank_mask:0xf
	v_fmac_f32_dpp v0, v163, v68 row_newbcast:4 row_mask:0xf bank_mask:0xf
	v_fmac_f32_dpp v1, v163, v69 row_newbcast:5 row_mask:0xf bank_mask:0xf
	v_fmac_f32_dpp v2, v163, v70 row_newbcast:6 row_mask:0xf bank_mask:0xf
	v_fmac_f32_dpp v3, v163, v71 row_newbcast:7 row_mask:0xf bank_mask:0xf
	v_fmac_f32_dpp v0, v163, v72 row_newbcast:8 row_mask:0xf bank_mask:0xf
	v_fmac_f32_dpp v1, v163, v73 row_newbcast:9 row_mask:0xf bank_mask:0xf
	v_fmac_f32_dpp v2, v163, v74 row_newbcast:10 row_mask:0xf bank_mask:0xf
	v_fmac_f32_dpp v3, v163, v75 row_newbcast:11 row_mask:0xf bank_mask:0xf
	v_fmac_f32_dpp v0, v163, v76 row_newbcast:12 row_mask:0xf bank_mask:0xf
	v_fmac_f32_dpp v1, v163, v77 row_newbcast:13 row_mask:0xf bank_mask:0xf
	v_fmac_f32_dpp v2, v163, v78 row_newbcast:14 row_mask:0xf bank_mask:0xf
	v_fmac_f32_dpp v3, v163, v79 row_newbcast:15 row_mask:0xf bank_mask:0xf
	ds_read_b32 v151, v7 offset:6048
	v_add_f32_e32 v0, v0, v1
	v_add_f32_e32 v2, v2, v3
	v_add_f32_e32 v0, v0, v2
	v_add_f32_e32 v80, v80, v0
	s_waitcnt lgkmcnt(11)
	v_mul_f32_dpp v0, v164, v64 row_newbcast:0 row_mask:0xf bank_mask:0xf
	v_mul_f32_dpp v1, v164, v65 row_newbcast:1 row_mask:0xf bank_mask:0xf
	v_mul_f32_dpp v2, v164, v66 row_newbcast:2 row_mask:0xf bank_mask:0xf
	v_mul_f32_dpp v3, v164, v67 row_newbcast:3 row_mask:0xf bank_mask:0xf
	v_fmac_f32_dpp v0, v164, v68 row_newbcast:4 row_mask:0xf bank_mask:0xf
	v_fmac_f32_dpp v1, v164, v69 row_newbcast:5 row_mask:0xf bank_mask:0xf
	v_fmac_f32_dpp v2, v164, v70 row_newbcast:6 row_mask:0xf bank_mask:0xf
	v_fmac_f32_dpp v3, v164, v71 row_newbcast:7 row_mask:0xf bank_mask:0xf
	v_fmac_f32_dpp v0, v164, v72 row_newbcast:8 row_mask:0xf bank_mask:0xf
	v_fmac_f32_dpp v1, v164, v73 row_newbcast:9 row_mask:0xf bank_mask:0xf
	v_fmac_f32_dpp v2, v164, v74 row_newbcast:10 row_mask:0xf bank_mask:0xf
	v_fmac_f32_dpp v3, v164, v75 row_newbcast:11 row_mask:0xf bank_mask:0xf
	v_fmac_f32_dpp v0, v164, v76 row_newbcast:12 row_mask:0xf bank_mask:0xf
	v_fmac_f32_dpp v1, v164, v77 row_newbcast:13 row_mask:0xf bank_mask:0xf
	v_fmac_f32_dpp v2, v164, v78 row_newbcast:14 row_mask:0xf bank_mask:0xf
	v_fmac_f32_dpp v3, v164, v79 row_newbcast:15 row_mask:0xf bank_mask:0xf
	ds_read_b32 v152, v7 offset:6256
	s_waitcnt lgkmcnt(11)
	v_fmac_f32_dpp v0, v165, v80 row_newbcast:0 row_mask:0xf bank_mask:0xf
	ds_read_b32 v153, v7 offset:6320
	v_add_f32_e32 v0, v0, v1
	v_add_f32_e32 v2, v2, v3
	v_add_f32_e32 v0, v0, v2
	v_add_f32_e32 v81, v81, v0
	s_waitcnt lgkmcnt(11)
	v_mul_f32_dpp v0, v166, v64 row_newbcast:0 row_mask:0xf bank_mask:0xf
	v_mul_f32_dpp v1, v166, v65 row_newbcast:1 row_mask:0xf bank_mask:0xf
	v_mul_f32_dpp v2, v166, v66 row_newbcast:2 row_mask:0xf bank_mask:0xf
	v_mul_f32_dpp v3, v166, v67 row_newbcast:3 row_mask:0xf bank_mask:0xf
	v_fmac_f32_dpp v0, v166, v68 row_newbcast:4 row_mask:0xf bank_mask:0xf
	v_fmac_f32_dpp v1, v166, v69 row_newbcast:5 row_mask:0xf bank_mask:0xf
	v_fmac_f32_dpp v2, v166, v70 row_newbcast:6 row_mask:0xf bank_mask:0xf
	v_fmac_f32_dpp v3, v166, v71 row_newbcast:7 row_mask:0xf bank_mask:0xf
	v_fmac_f32_dpp v0, v166, v72 row_newbcast:8 row_mask:0xf bank_mask:0xf
	v_fmac_f32_dpp v1, v166, v73 row_newbcast:9 row_mask:0xf bank_mask:0xf
	v_fmac_f32_dpp v2, v166, v74 row_newbcast:10 row_mask:0xf bank_mask:0xf
	v_fmac_f32_dpp v3, v166, v75 row_newbcast:11 row_mask:0xf bank_mask:0xf
	v_fmac_f32_dpp v0, v166, v76 row_newbcast:12 row_mask:0xf bank_mask:0xf
	v_fmac_f32_dpp v1, v166, v77 row_newbcast:13 row_mask:0xf bank_mask:0xf
	v_fmac_f32_dpp v2, v166, v78 row_newbcast:14 row_mask:0xf bank_mask:0xf
	v_fmac_f32_dpp v3, v166, v79 row_newbcast:15 row_mask:0xf bank_mask:0xf
	ds_read_b32 v154, v7 offset:6528
	s_waitcnt lgkmcnt(11)
	v_fmac_f32_dpp v0, v167, v80 row_newbcast:0 row_mask:0xf bank_mask:0xf
	v_fmac_f32_dpp v1, v167, v81 row_newbcast:1 row_mask:0xf bank_mask:0xf
	ds_read_b32 v155, v7 offset:6592
	v_add_f32_e32 v0, v0, v1
	v_add_f32_e32 v2, v2, v3
	v_add_f32_e32 v0, v0, v2
	v_add_f32_e32 v82, v82, v0
	s_waitcnt lgkmcnt(11)
	v_mul_f32_dpp v0, v168, v64 row_newbcast:0 row_mask:0xf bank_mask:0xf
	v_mul_f32_dpp v1, v168, v65 row_newbcast:1 row_mask:0xf bank_mask:0xf
	v_mul_f32_dpp v2, v168, v66 row_newbcast:2 row_mask:0xf bank_mask:0xf
	v_mul_f32_dpp v3, v168, v67 row_newbcast:3 row_mask:0xf bank_mask:0xf
	v_fmac_f32_dpp v0, v168, v68 row_newbcast:4 row_mask:0xf bank_mask:0xf
	v_fmac_f32_dpp v1, v168, v69 row_newbcast:5 row_mask:0xf bank_mask:0xf
	v_fmac_f32_dpp v2, v168, v70 row_newbcast:6 row_mask:0xf bank_mask:0xf
	v_fmac_f32_dpp v3, v168, v71 row_newbcast:7 row_mask:0xf bank_mask:0xf
	v_fmac_f32_dpp v0, v168, v72 row_newbcast:8 row_mask:0xf bank_mask:0xf
	v_fmac_f32_dpp v1, v168, v73 row_newbcast:9 row_mask:0xf bank_mask:0xf
	v_fmac_f32_dpp v2, v168, v74 row_newbcast:10 row_mask:0xf bank_mask:0xf
	v_fmac_f32_dpp v3, v168, v75 row_newbcast:11 row_mask:0xf bank_mask:0xf
	v_fmac_f32_dpp v0, v168, v76 row_newbcast:12 row_mask:0xf bank_mask:0xf
	v_fmac_f32_dpp v1, v168, v77 row_newbcast:13 row_mask:0xf bank_mask:0xf
	v_fmac_f32_dpp v2, v168, v78 row_newbcast:14 row_mask:0xf bank_mask:0xf
	v_fmac_f32_dpp v3, v168, v79 row_newbcast:15 row_mask:0xf bank_mask:0xf
	ds_read_b32 v156, v7 offset:6800
	s_waitcnt lgkmcnt(11)
; #define LAS __attribute__((address_space(3)))
; __device__ __forceinline__ void rw_phaseA(LAS unsigned char* lds, const RwCtx& X, int item) {
;     ...
;         for (int tt = 1; tt < 64; ++tt) { float a = x[tt];
; #pragma unroll
;             for (int s4 = 0; s4 < (tt + 3) / 4; ++s4) { const f32x4 l4 = *(const LAS f32x4*)(LABv + tt * 68 + s4 * 4);
;                 a += l4[0] * x[s4 * 4]; if (s4 * 4 + 1 < tt) a += l4[1] * x[s4 * 4 + 1]; if (s4 * 4 + 2 < tt) a += l4[2] * x[s4 * 4 + 2]; if (s4 * 4 + 3 < tt) a += l4[3] * x[s4 * 4 + 3]; }
;             x[tt] = a;
	v_fmac_f32_dpp v0, v169, v80 row_newbcast:0 row_mask:0xf bank_mask:0xf
	v_fmac_f32_dpp v1, v169, v81 row_newbcast:1 row_mask:0xf bank_mask:0xf
	v_fmac_f32_dpp v2, v169, v82 row_newbcast:2 row_mask:0xf bank_mask:0xf
	ds_read_b32 v157, v7 offset:6864
	v_add_f32_e32 v0, v0, v1
	v_add_f32_e32 v2, v2, v3
	v_add_f32_e32 v0, v0, v2
	v_add_f32_e32 v83, v83, v0
	s_waitcnt lgkmcnt(11)
	v_mul_f32_dpp v0, v170, v64 row_newbcast:0 row_mask:0xf bank_mask:0xf
	v_mul_f32_dpp v1, v170, v65 row_newbcast:1 row_mask:0xf bank_mask:0xf
	v_mul_f32_dpp v2, v170, v66 row_newbcast:2 row_mask:0xf bank_mask:0xf
	v_mul_f32_dpp v3, v170, v67 row_newbcast:3 row_mask:0xf bank_mask:0xf
	v_fmac_f32_dpp v0, v170, v68 row_newbcast:4 row_mask:0xf bank_mask:0xf
	v_fmac_f32_dpp v1, v170, v69 row_newbcast:5 row_mask:0xf bank_mask:0xf
	v_fmac_f32_dpp v2, v170, v70 row_newbcast:6 row_mask:0xf bank_mask:0xf
	v_fmac_f32_dpp v3, v170, v71 row_newbcast:7 row_mask:0xf bank_mask:0xf
	v_fmac_f32_dpp v0, v170, v72 row_newbcast:8 row_mask:0xf bank_mask:0xf
	v_fmac_f32_dpp v1, v170, v73 row_newbcast:9 row_mask:0xf bank_mask:0xf
	v_fmac_f32_dpp v2, v170, v74 row_newbcast:10 row_mask:0xf bank_mask:0xf
	v_fmac_f32_dpp v3, v170, v75 row_newbcast:11 row_mask:0xf bank_mask:0xf
	v_fmac_f32_dpp v0, v170, v76 row_newbcast:12 row_mask:0xf bank_mask:0xf
	v_fmac_f32_dpp v1, v170, v77 row_newbcast:13 row_mask:0xf bank_mask:0xf
	v_fmac_f32_dpp v2, v170, v78 row_newbcast:14 row_mask:0xf bank_mask:0xf
	v_fmac_f32_dpp v3, v170, v79 row_newbcast:15 row_mask:0xf bank_mask:0xf
	ds_read_b32 v158, v7 offset:7072
	s_waitcnt lgkmcnt(11)
	v_fmac_f32_dpp v0, v171, v80 row_newbcast:0 row_mask:0xf bank_mask:0xf
	v_fmac_f32_dpp v1, v171, v81 row_newbcast:1 row_mask:0xf bank_mask:0xf
	v_fmac_f32_dpp v2, v171, v82 row_newbcast:2 row_mask:0xf bank_mask:0xf
	v_fmac_f32_dpp v3, v171, v83 row_newbcast:3 row_mask:0xf bank_mask:0xf
	ds_read_b32 v159, v7 offset:7136
	v_add_f32_e32 v0, v0, v1
	v_add_f32_e32 v2, v2, v3
	v_add_f32_e32 v0, v0, v2
	v_add_f32_e32 v84, v84, v0
	s_waitcnt lgkmcnt(11)
	v_mul_f32_dpp v0, v148, v64 row_newbcast:0 row_mask:0xf bank_mask:0xf
	v_mul_f32_dpp v1, v148, v65 row_newbcast:1 row_mask:0xf bank_mask:0xf
	v_mul_f32_dpp v2, v148, v66 row_newbcast:2 row_mask:0xf bank_mask:0xf
	v_mul_f32_dpp v3, v148, v67 row_newbcast:3 row_mask:0xf bank_mask:0xf
	v_fmac_f32_dpp v0, v148, v68 row_newbcast:4 row_mask:0xf bank_mask:0xf
	v_fmac_f32_dpp v1, v148, v69 row_newbcast:5 row_mask:0xf bank_mask:0xf
	v_fmac_f32_dpp v2, v148, v70 row_newbcast:6 row_mask:0xf bank_mask:0xf
	v_fmac_f32_dpp v3, v148, v71 row_newbcast:7 row_mask:0xf bank_mask:0xf
	v_fmac_f32_dpp v0, v148, v72 row_newbcast:8 row_mask:0xf bank_mask:0xf
	v_fmac_f32_dpp v1, v148, v73 row_newbcast:9 row_mask:0xf bank_mask:0xf
	v_fmac_f32_dpp v2, v148, v74 row_newbcast:10 row_mask:0xf bank_mask:0xf
	v_fmac_f32_dpp v3, v148, v75 row_newbcast:11 row_mask:0xf bank_mask:0xf
	v_fmac_f32_dpp v0, v148, v76 row_newbcast:12 row_mask:0xf bank_mask:0xf
	v_fmac_f32_dpp v1, v148, v77 row_newbcast:13 row_mask:0xf bank_mask:0xf
	v_fmac_f32_dpp v2, v148, v78 row_newbcast:14 row_mask:0xf bank_mask:0xf
	v_fmac_f32_dpp v3, v148, v79 row_newbcast:15 row_mask:0xf bank_mask:0xf
	ds_read_b32 v160, v7 offset:7344
	s_waitcnt lgkmcnt(11)
	v_fmac_f32_dpp v0, v149, v80 row_newbcast:0 row_mask:0xf bank_mask:0xf
	v_fmac_f32_dpp v1, v149, v81 row_newbcast:1 row_mask:0xf bank_mask:0xf
	v_fmac_f32_dpp v2, v149, v82 row_newbcast:2 row_mask:0xf bank_mask:0xf
	v_fmac_f32_dpp v3, v149, v83 row_newbcast:3 row_mask:0xf bank_mask:0xf
	v_fmac_f32_dpp v0, v149, v84 row_newbcast:4 row_mask:0xf bank_mask:0xf
	ds_read_b32 v161, v7 offset:7408
	v_add_f32_e32 v0, v0, v1
	v_add_f32_e32 v2, v2, v3
	v_add_f32_e32 v0, v0, v2
	v_add_f32_e32 v85, v85, v0
	s_waitcnt lgkmcnt(11)
	v_mul_f32_dpp v0, v150, v64 row_newbcast:0 row_mask:0xf bank_mask:0xf
	v_mul_f32_dpp v1, v150, v65 row_newbcast:1 row_mask:0xf bank_mask:0xf
	v_mul_f32_dpp v2, v150, v66 row_newbcast:2 row_mask:0xf bank_mask:0xf
	v_mul_f32_dpp v3, v150, v67 row_newbcast:3 row_mask:0xf bank_mask:0xf
	v_fmac_f32_dpp v0, v150, v68 row_newbcast:4 row_mask:0xf bank_mask:0xf
	v_fmac_f32_dpp v1, v150, v69 row_newbcast:5 row_mask:0xf bank_mask:0xf
	v_fmac_f32_dpp v2, v150, v70 row_newbcast:6 row_mask:0xf bank_mask:0xf
	v_fmac_f32_dpp v3, v150, v71 row_newbcast:7 row_mask:0xf bank_mask:0xf
	v_fmac_f32_dpp v0, v150, v72 row_newbcast:8 row_mask:0xf bank_mask:0xf
	v_fmac_f32_dpp v1, v150, v73 row_newbcast:9 row_mask:0xf bank_mask:0xf
	v_fmac_f32_dpp v2, v150, v74 row_newbcast:10 row_mask:0xf bank_mask:0xf
	v_fmac_f32_dpp v3, v150, v75 row_newbcast:11 row_mask:0xf bank_mask:0xf
	v_fmac_f32_dpp v0, v150, v76 row_newbcast:12 row_mask:0xf bank_mask:0xf
	v_fmac_f32_dpp v1, v150, v77 row_newbcast:13 row_mask:0xf bank_mask:0xf
	v_fmac_f32_dpp v2, v150, v78 row_newbcast:14 row_mask:0xf bank_mask:0xf
	v_fmac_f32_dpp v3, v150, v79 row_newbcast:15 row_mask:0xf bank_mask:0xf
	ds_read_b32 v162, v7 offset:7616
	s_waitcnt lgkmcnt(11)
	v_fmac_f32_dpp v0, v151, v80 row_newbcast:0 row_mask:0xf bank_mask:0xf
	v_fmac_f32_dpp v1, v151, v81 row_newbcast:1 row_mask:0xf bank_mask:0xf
	v_fmac_f32_dpp v2, v151, v82 row_newbcast:2 row_mask:0xf bank_mask:0xf
	v_fmac_f32_dpp v3, v151, v83 row_newbcast:3 row_mask:0xf bank_mask:0xf
	v_fmac_f32_dpp v0, v151, v84 row_newbcast:4 row_mask:0xf bank_mask:0xf
	v_fmac_f32_dpp v1, v151, v85 row_newbcast:5 row_mask:0xf bank_mask:0xf
	ds_read_b32 v163, v7 offset:7680
	v_add_f32_e32 v0, v0, v1
	v_add_f32_e32 v2, v2, v3
	v_add_f32_e32 v0, v0, v2
	v_add_f32_e32 v86, v86, v0
	s_waitcnt lgkmcnt(11)
; #define LAS __attribute__((address_space(3)))
; __device__ __forceinline__ void rw_phaseA(LAS unsigned char* lds, const RwCtx& X, int item) {
;     ...
;         for (int tt = 1; tt < 64; ++tt) { float a = x[tt];
; #pragma unroll
;             for (int s4 = 0; s4 < (tt + 3) / 4; ++s4) { const f32x4 l4 = *(const LAS f32x4*)(LABv + tt * 68 + s4 * 4);
;                 a += l4[0] * x[s4 * 4]; if (s4 * 4 + 1 < tt) a += l4[1] * x[s4 * 4 + 1]; if (s4 * 4 + 2 < tt) a += l4[2] * x[s4 * 4 + 2]; if (s4 * 4 + 3 < tt) a += l4[3] * x[s4 * 4 + 3]; }
;             x[tt] = a;
	v_mul_f32_dpp v0, v152, v64 row_newbcast:0 row_mask:0xf bank_mask:0xf
	v_mul_f32_dpp v1, v152, v65 row_newbcast:1 row_mask:0xf bank_mask:0xf
	v_mul_f32_dpp v2, v152, v66 row_newbcast:2 row_mask:0xf bank_mask:0xf
	v_mul_f32_dpp v3, v152, v67 row_newbcast:3 row_mask:0xf bank_mask:0xf
	v_fmac_f32_dpp v0, v152, v68 row_newbcast:4 row_mask:0xf bank_mask:0xf
	v_fmac_f32_dpp v1, v152, v69 row_newbcast:5 row_mask:0xf bank_mask:0xf
	v_fmac_f32_dpp v2, v152, v70 row_newbcast:6 row_mask:0xf bank_mask:0xf
	v_fmac_f32_dpp v3, v152, v71 row_newbcast:7 row_mask:0xf bank_mask:0xf
	v_fmac_f32_dpp v0, v152, v72 row_newbcast:8 row_mask:0xf bank_mask:0xf
	v_fmac_f32_dpp v1, v152, v73 row_newbcast:9 row_mask:0xf bank_mask:0xf
	v_fmac_f32_dpp v2, v152, v74 row_newbcast:10 row_mask:0xf bank_mask:0xf
	v_fmac_f32_dpp v3, v152, v75 row_newbcast:11 row_mask:0xf bank_mask:0xf
	v_fmac_f32_dpp v0, v152, v76 row_newbcast:12 row_mask:0xf bank_mask:0xf
	v_fmac_f32_dpp v1, v152, v77 row_newbcast:13 row_mask:0xf bank_mask:0xf
	v_fmac_f32_dpp v2, v152, v78 row_newbcast:14 row_mask:0xf bank_mask:0xf
	v_fmac_f32_dpp v3, v152, v79 row_newbcast:15 row_mask:0xf bank_mask:0xf
	ds_read_b32 v164, v7 offset:7888
	s_waitcnt lgkmcnt(11)
	v_fmac_f32_dpp v0, v153, v80 row_newbcast:0 row_mask:0xf bank_mask:0xf
	v_fmac_f32_dpp v1, v153, v81 row_newbcast:1 row_mask:0xf bank_mask:0xf
	v_fmac_f32_dpp v2, v153, v82 row_newbcast:2 row_mask:0xf bank_mask:0xf
	v_fmac_f32_dpp v3, v153, v83 row_newbcast:3 row_mask:0xf bank_mask:0xf
	v_fmac_f32_dpp v0, v153, v84 row_newbcast:4 row_mask:0xf bank_mask:0xf
	v_fmac_f32_dpp v1, v153, v85 row_newbcast:5 row_mask:0xf bank_mask:0xf
	v_fmac_f32_dpp v2, v153, v86 row_newbcast:6 row_mask:0xf bank_mask:0xf
	ds_read_b32 v165, v7 offset:7952
	v_add_f32_e32 v0, v0, v1
	v_add_f32_e32 v2, v2, v3
	v_add_f32_e32 v0, v0, v2
	v_add_f32_e32 v87, v87, v0
	s_waitcnt lgkmcnt(11)
	v_mul_f32_dpp v0, v154, v64 row_newbcast:0 row_mask:0xf bank_mask:0xf
	v_mul_f32_dpp v1, v154, v65 row_newbcast:1 row_mask:0xf bank_mask:0xf
	v_mul_f32_dpp v2, v154, v66 row_newbcast:2 row_mask:0xf bank_mask:0xf
	v_mul_f32_dpp v3, v154, v67 row_newbcast:3 row_mask:0xf bank_mask:0xf
	v_fmac_f32_dpp v0, v154, v68 row_newbcast:4 row_mask:0xf bank_mask:0xf
	v_fmac_f32_dpp v1, v154, v69 row_newbcast:5 row_mask:0xf bank_mask:0xf
	v_fmac_f32_dpp v2, v154, v70 row_newbcast:6 row_mask:0xf bank_mask:0xf
	v_fmac_f32_dpp v3, v154, v71 row_newbcast:7 row_mask:0xf bank_mask:0xf
	v_fmac_f32_dpp v0, v154, v72 row_newbcast:8 row_mask:0xf bank_mask:0xf
	v_fmac_f32_dpp v1, v154, v73 row_newbcast:9 row_mask:0xf bank_mask:0xf
	v_fmac_f32_dpp v2, v154, v74 row_newbcast:10 row_mask:0xf bank_mask:0xf
	v_fmac_f32_dpp v3, v154, v75 row_newbcast:11 row_mask:0xf bank_mask:0xf
	v_fmac_f32_dpp v0, v154, v76 row_newbcast:12 row_mask:0xf bank_mask:0xf
	v_fmac_f32_dpp v1, v154, v77 row_newbcast:13 row_mask:0xf bank_mask:0xf
	v_fmac_f32_dpp v2, v154, v78 row_newbcast:14 row_mask:0xf bank_mask:0xf
	v_fmac_f32_dpp v3, v154, v79 row_newbcast:15 row_mask:0xf bank_mask:0xf
	ds_read_b32 v166, v7 offset:8160
	s_waitcnt lgkmcnt(11)
	v_fmac_f32_dpp v0, v155, v80 row_newbcast:0 row_mask:0xf bank_mask:0xf
	v_fmac_f32_dpp v1, v155, v81 row_newbcast:1 row_mask:0xf bank_mask:0xf
	v_fmac_f32_dpp v2, v155, v82 row_newbcast:2 row_mask:0xf bank_mask:0xf
	v_fmac_f32_dpp v3, v155, v83 row_newbcast:3 row_mask:0xf bank_mask:0xf
	v_fmac_f32_dpp v0, v155, v84 row_newbcast:4 row_mask:0xf bank_mask:0xf
	v_fmac_f32_dpp v1, v155, v85 row_newbcast:5 row_mask:0xf bank_mask:0xf
	v_fmac_f32_dpp v2, v155, v86 row_newbcast:6 row_mask:0xf bank_mask:0xf
	v_fmac_f32_dpp v3, v155, v87 row_newbcast:7 row_mask:0xf bank_mask:0xf
	ds_read_b32 v167, v7 offset:8224
	v_add_f32_e32 v0, v0, v1
	v_add_f32_e32 v2, v2, v3
	v_add_f32_e32 v0, v0, v2
	v_add_f32_e32 v88, v88, v0
	s_waitcnt lgkmcnt(11)
	v_mul_f32_dpp v0, v156, v64 row_newbcast:0 row_mask:0xf bank_mask:0xf
	v_mul_f32_dpp v1, v156, v65 row_newbcast:1 row_mask:0xf bank_mask:0xf
	v_mul_f32_dpp v2, v156, v66 row_newbcast:2 row_mask:0xf bank_mask:0xf
	v_mul_f32_dpp v3, v156, v67 row_newbcast:3 row_mask:0xf bank_mask:0xf
	v_fmac_f32_dpp v0, v156, v68 row_newbcast:4 row_mask:0xf bank_mask:0xf
	v_fmac_f32_dpp v1, v156, v69 row_newbcast:5 row_mask:0xf bank_mask:0xf
	v_fmac_f32_dpp v2, v156, v70 row_newbcast:6 row_mask:0xf bank_mask:0xf
	v_fmac_f32_dpp v3, v156, v71 row_newbcast:7 row_mask:0xf bank_mask:0xf
	v_fmac_f32_dpp v0, v156, v72 row_newbcast:8 row_mask:0xf bank_mask:0xf
	v_fmac_f32_dpp v1, v156, v73 row_newbcast:9 row_mask:0xf bank_mask:0xf
	v_fmac_f32_dpp v2, v156, v74 row_newbcast:10 row_mask:0xf bank_mask:0xf
	v_fmac_f32_dpp v3, v156, v75 row_newbcast:11 row_mask:0xf bank_mask:0xf
	v_fmac_f32_dpp v0, v156, v76 row_newbcast:12 row_mask:0xf bank_mask:0xf
	v_fmac_f32_dpp v1, v156, v77 row_newbcast:13 row_mask:0xf bank_mask:0xf
	v_fmac_f32_dpp v2, v156, v78 row_newbcast:14 row_mask:0xf bank_mask:0xf
	v_fmac_f32_dpp v3, v156, v79 row_newbcast:15 row_mask:0xf bank_mask:0xf
	ds_read_b32 v168, v7 offset:8432
	s_waitcnt lgkmcnt(11)
	v_fmac_f32_dpp v0, v157, v80 row_newbcast:0 row_mask:0xf bank_mask:0xf
	v_fmac_f32_dpp v1, v157, v81 row_newbcast:1 row_mask:0xf bank_mask:0xf
	v_fmac_f32_dpp v2, v157, v82 row_newbcast:2 row_mask:0xf bank_mask:0xf
	v_fmac_f32_dpp v3, v157, v83 row_newbcast:3 row_mask:0xf bank_mask:0xf
	v_fmac_f32_dpp v0, v157, v84 row_newbcast:4 row_mask:0xf bank_mask:0xf
	v_fmac_f32_dpp v1, v157, v85 row_newbcast:5 row_mask:0xf bank_mask:0xf
	v_fmac_f32_dpp v2, v157, v86 row_newbcast:6 row_mask:0xf bank_mask:0xf
	v_fmac_f32_dpp v3, v157, v87 row_newbcast:7 row_mask:0xf bank_mask:0xf
	v_fmac_f32_dpp v0, v157, v88 row_newbcast:8 row_mask:0xf bank_mask:0xf
	ds_read_b32 v169, v7 offset:8496
	v_add_f32_e32 v0, v0, v1
	v_add_f32_e32 v2, v2, v3
	v_add_f32_e32 v0, v0, v2
	v_add_f32_e32 v89, v89, v0
	s_waitcnt lgkmcnt(11)
; #define LAS __attribute__((address_space(3)))
; __device__ __forceinline__ void rw_phaseA(LAS unsigned char* lds, const RwCtx& X, int item) {
;     ...
;         for (int tt = 1; tt < 64; ++tt) { float a = x[tt];
; #pragma unroll
;             for (int s4 = 0; s4 < (tt + 3) / 4; ++s4) { const f32x4 l4 = *(const LAS f32x4*)(LABv + tt * 68 + s4 * 4);
;                 a += l4[0] * x[s4 * 4]; if (s4 * 4 + 1 < tt) a += l4[1] * x[s4 * 4 + 1]; if (s4 * 4 + 2 < tt) a += l4[2] * x[s4 * 4 + 2]; if (s4 * 4 + 3 < tt) a += l4[3] * x[s4 * 4 + 3]; }
;             x[tt] = a;
	v_mul_f32_dpp v0, v158, v64 row_newbcast:0 row_mask:0xf bank_mask:0xf
	v_mul_f32_dpp v1, v158, v65 row_newbcast:1 row_mask:0xf bank_mask:0xf
	v_mul_f32_dpp v2, v158, v66 row_newbcast:2 row_mask:0xf bank_mask:0xf
	v_mul_f32_dpp v3, v158, v67 row_newbcast:3 row_mask:0xf bank_mask:0xf
	v_fmac_f32_dpp v0, v158, v68 row_newbcast:4 row_mask:0xf bank_mask:0xf
	v_fmac_f32_dpp v1, v158, v69 row_newbcast:5 row_mask:0xf bank_mask:0xf
	v_fmac_f32_dpp v2, v158, v70 row_newbcast:6 row_mask:0xf bank_mask:0xf
	v_fmac_f32_dpp v3, v158, v71 row_newbcast:7 row_mask:0xf bank_mask:0xf
	v_fmac_f32_dpp v0, v158, v72 row_newbcast:8 row_mask:0xf bank_mask:0xf
	v_fmac_f32_dpp v1, v158, v73 row_newbcast:9 row_mask:0xf bank_mask:0xf
	v_fmac_f32_dpp v2, v158, v74 row_newbcast:10 row_mask:0xf bank_mask:0xf
	v_fmac_f32_dpp v3, v158, v75 row_newbcast:11 row_mask:0xf bank_mask:0xf
	v_fmac_f32_dpp v0, v158, v76 row_newbcast:12 row_mask:0xf bank_mask:0xf
	v_fmac_f32_dpp v1, v158, v77 row_newbcast:13 row_mask:0xf bank_mask:0xf
	v_fmac_f32_dpp v2, v158, v78 row_newbcast:14 row_mask:0xf bank_mask:0xf
	v_fmac_f32_dpp v3, v158, v79 row_newbcast:15 row_mask:0xf bank_mask:0xf
	ds_read_b32 v170, v7 offset:8704
	s_waitcnt lgkmcnt(11)
	v_fmac_f32_dpp v0, v159, v80 row_newbcast:0 row_mask:0xf bank_mask:0xf
	v_fmac_f32_dpp v1, v159, v81 row_newbcast:1 row_mask:0xf bank_mask:0xf
	v_fmac_f32_dpp v2, v159, v82 row_newbcast:2 row_mask:0xf bank_mask:0xf
	v_fmac_f32_dpp v3, v159, v83 row_newbcast:3 row_mask:0xf bank_mask:0xf
	v_fmac_f32_dpp v0, v159, v84 row_newbcast:4 row_mask:0xf bank_mask:0xf
	v_fmac_f32_dpp v1, v159, v85 row_newbcast:5 row_mask:0xf bank_mask:0xf
	v_fmac_f32_dpp v2, v159, v86 row_newbcast:6 row_mask:0xf bank_mask:0xf
	v_fmac_f32_dpp v3, v159, v87 row_newbcast:7 row_mask:0xf bank_mask:0xf
	v_fmac_f32_dpp v0, v159, v88 row_newbcast:8 row_mask:0xf bank_mask:0xf
	v_fmac_f32_dpp v1, v159, v89 row_newbcast:9 row_mask:0xf bank_mask:0xf
	ds_read_b32 v171, v7 offset:8768
	v_add_f32_e32 v0, v0, v1
	v_add_f32_e32 v2, v2, v3
	v_add_f32_e32 v0, v0, v2
	v_add_f32_e32 v90, v90, v0
	s_waitcnt lgkmcnt(11)
	v_mul_f32_dpp v0, v160, v64 row_newbcast:0 row_mask:0xf bank_mask:0xf
	v_mul_f32_dpp v1, v160, v65 row_newbcast:1 row_mask:0xf bank_mask:0xf
	v_mul_f32_dpp v2, v160, v66 row_newbcast:2 row_mask:0xf bank_mask:0xf
	v_mul_f32_dpp v3, v160, v67 row_newbcast:3 row_mask:0xf bank_mask:0xf
	v_fmac_f32_dpp v0, v160, v68 row_newbcast:4 row_mask:0xf bank_mask:0xf
	v_fmac_f32_dpp v1, v160, v69 row_newbcast:5 row_mask:0xf bank_mask:0xf
	v_fmac_f32_dpp v2, v160, v70 row_newbcast:6 row_mask:0xf bank_mask:0xf
	v_fmac_f32_dpp v3, v160, v71 row_newbcast:7 row_mask:0xf bank_mask:0xf
	v_fmac_f32_dpp v0, v160, v72 row_newbcast:8 row_mask:0xf bank_mask:0xf
	v_fmac_f32_dpp v1, v160, v73 row_newbcast:9 row_mask:0xf bank_mask:0xf
	v_fmac_f32_dpp v2, v160, v74 row_newbcast:10 row_mask:0xf bank_mask:0xf
	v_fmac_f32_dpp v3, v160, v75 row_newbcast:11 row_mask:0xf bank_mask:0xf
	v_fmac_f32_dpp v0, v160, v76 row_newbcast:12 row_mask:0xf bank_mask:0xf
	v_fmac_f32_dpp v1, v160, v77 row_newbcast:13 row_mask:0xf bank_mask:0xf
	v_fmac_f32_dpp v2, v160, v78 row_newbcast:14 row_mask:0xf bank_mask:0xf
	v_fmac_f32_dpp v3, v160, v79 row_newbcast:15 row_mask:0xf bank_mask:0xf
	ds_read_b32 v148, v7 offset:8976
	s_waitcnt lgkmcnt(11)
	v_fmac_f32_dpp v0, v161, v80 row_newbcast:0 row_mask:0xf bank_mask:0xf
	v_fmac_f32_dpp v1, v161, v81 row_newbcast:1 row_mask:0xf bank_mask:0xf
	v_fmac_f32_dpp v2, v161, v82 row_newbcast:2 row_mask:0xf bank_mask:0xf
	v_fmac_f32_dpp v3, v161, v83 row_newbcast:3 row_mask:0xf bank_mask:0xf
	v_fmac_f32_dpp v0, v161, v84 row_newbcast:4 row_mask:0xf bank_mask:0xf
	v_fmac_f32_dpp v1, v161, v85 row_newbcast:5 row_mask:0xf bank_mask:0xf
	v_fmac_f32_dpp v2, v161, v86 row_newbcast:6 row_mask:0xf bank_mask:0xf
	v_fmac_f32_dpp v3, v161, v87 row_newbcast:7 row_mask:0xf bank_mask:0xf
	v_fmac_f32_dpp v0, v161, v88 row_newbcast:8 row_mask:0xf bank_mask:0xf
	v_fmac_f32_dpp v1, v161, v89 row_newbcast:9 row_mask:0xf bank_mask:0xf
	v_fmac_f32_dpp v2, v161, v90 row_newbcast:10 row_mask:0xf bank_mask:0xf
	ds_read_b32 v149, v7 offset:9040
	v_add_f32_e32 v0, v0, v1
	v_add_f32_e32 v2, v2, v3
	v_add_f32_e32 v0, v0, v2
	v_add_f32_e32 v91, v91, v0
	s_waitcnt lgkmcnt(11)
	v_mul_f32_dpp v0, v162, v64 row_newbcast:0 row_mask:0xf bank_mask:0xf
	v_mul_f32_dpp v1, v162, v65 row_newbcast:1 row_mask:0xf bank_mask:0xf
	v_mul_f32_dpp v2, v162, v66 row_newbcast:2 row_mask:0xf bank_mask:0xf
	v_mul_f32_dpp v3, v162, v67 row_newbcast:3 row_mask:0xf bank_mask:0xf
	v_fmac_f32_dpp v0, v162, v68 row_newbcast:4 row_mask:0xf bank_mask:0xf
	v_fmac_f32_dpp v1, v162, v69 row_newbcast:5 row_mask:0xf bank_mask:0xf
	v_fmac_f32_dpp v2, v162, v70 row_newbcast:6 row_mask:0xf bank_mask:0xf
	v_fmac_f32_dpp v3, v162, v71 row_newbcast:7 row_mask:0xf bank_mask:0xf
	v_fmac_f32_dpp v0, v162, v72 row_newbcast:8 row_mask:0xf bank_mask:0xf
	v_fmac_f32_dpp v1, v162, v73 row_newbcast:9 row_mask:0xf bank_mask:0xf
	v_fmac_f32_dpp v2, v162, v74 row_newbcast:10 row_mask:0xf bank_mask:0xf
	v_fmac_f32_dpp v3, v162, v75 row_newbcast:11 row_mask:0xf bank_mask:0xf
	v_fmac_f32_dpp v0, v162, v76 row_newbcast:12 row_mask:0xf bank_mask:0xf
	v_fmac_f32_dpp v1, v162, v77 row_newbcast:13 row_mask:0xf bank_mask:0xf
	v_fmac_f32_dpp v2, v162, v78 row_newbcast:14 row_mask:0xf bank_mask:0xf
	v_fmac_f32_dpp v3, v162, v79 row_newbcast:15 row_mask:0xf bank_mask:0xf
	ds_read_b32 v150, v7 offset:9104
	s_waitcnt lgkmcnt(11)
; #define LAS __attribute__((address_space(3)))
; __device__ __forceinline__ void rw_phaseA(LAS unsigned char* lds, const RwCtx& X, int item) {
;     ...
;         for (int tt = 1; tt < 64; ++tt) { float a = x[tt];
; #pragma unroll
;             for (int s4 = 0; s4 < (tt + 3) / 4; ++s4) { const f32x4 l4 = *(const LAS f32x4*)(LABv + tt * 68 + s4 * 4);
;                 a += l4[0] * x[s4 * 4]; if (s4 * 4 + 1 < tt) a += l4[1] * x[s4 * 4 + 1]; if (s4 * 4 + 2 < tt) a += l4[2] * x[s4 * 4 + 2]; if (s4 * 4 + 3 < tt) a += l4[3] * x[s4 * 4 + 3]; }
;             x[tt] = a;
	v_fmac_f32_dpp v0, v163, v80 row_newbcast:0 row_mask:0xf bank_mask:0xf
	v_fmac_f32_dpp v1, v163, v81 row_newbcast:1 row_mask:0xf bank_mask:0xf
	v_fmac_f32_dpp v2, v163, v82 row_newbcast:2 row_mask:0xf bank_mask:0xf
	v_fmac_f32_dpp v3, v163, v83 row_newbcast:3 row_mask:0xf bank_mask:0xf
	v_fmac_f32_dpp v0, v163, v84 row_newbcast:4 row_mask:0xf bank_mask:0xf
	v_fmac_f32_dpp v1, v163, v85 row_newbcast:5 row_mask:0xf bank_mask:0xf
	v_fmac_f32_dpp v2, v163, v86 row_newbcast:6 row_mask:0xf bank_mask:0xf
	v_fmac_f32_dpp v3, v163, v87 row_newbcast:7 row_mask:0xf bank_mask:0xf
	v_fmac_f32_dpp v0, v163, v88 row_newbcast:8 row_mask:0xf bank_mask:0xf
	v_fmac_f32_dpp v1, v163, v89 row_newbcast:9 row_mask:0xf bank_mask:0xf
	v_fmac_f32_dpp v2, v163, v90 row_newbcast:10 row_mask:0xf bank_mask:0xf
	v_fmac_f32_dpp v3, v163, v91 row_newbcast:11 row_mask:0xf bank_mask:0xf
	ds_read_b32 v151, v7 offset:9248
	v_add_f32_e32 v0, v0, v1
	v_add_f32_e32 v2, v2, v3
	v_add_f32_e32 v0, v0, v2
	v_add_f32_e32 v92, v92, v0
	s_waitcnt lgkmcnt(11)
	v_mul_f32_dpp v0, v164, v64 row_newbcast:0 row_mask:0xf bank_mask:0xf
	v_mul_f32_dpp v1, v164, v65 row_newbcast:1 row_mask:0xf bank_mask:0xf
	v_mul_f32_dpp v2, v164, v66 row_newbcast:2 row_mask:0xf bank_mask:0xf
	v_mul_f32_dpp v3, v164, v67 row_newbcast:3 row_mask:0xf bank_mask:0xf
	v_fmac_f32_dpp v0, v164, v68 row_newbcast:4 row_mask:0xf bank_mask:0xf
	v_fmac_f32_dpp v1, v164, v69 row_newbcast:5 row_mask:0xf bank_mask:0xf
	v_fmac_f32_dpp v2, v164, v70 row_newbcast:6 row_mask:0xf bank_mask:0xf
	v_fmac_f32_dpp v3, v164, v71 row_newbcast:7 row_mask:0xf bank_mask:0xf
	v_fmac_f32_dpp v0, v164, v72 row_newbcast:8 row_mask:0xf bank_mask:0xf
	v_fmac_f32_dpp v1, v164, v73 row_newbcast:9 row_mask:0xf bank_mask:0xf
	v_fmac_f32_dpp v2, v164, v74 row_newbcast:10 row_mask:0xf bank_mask:0xf
	v_fmac_f32_dpp v3, v164, v75 row_newbcast:11 row_mask:0xf bank_mask:0xf
	v_fmac_f32_dpp v0, v164, v76 row_newbcast:12 row_mask:0xf bank_mask:0xf
	v_fmac_f32_dpp v1, v164, v77 row_newbcast:13 row_mask:0xf bank_mask:0xf
	v_fmac_f32_dpp v2, v164, v78 row_newbcast:14 row_mask:0xf bank_mask:0xf
	v_fmac_f32_dpp v3, v164, v79 row_newbcast:15 row_mask:0xf bank_mask:0xf
	ds_read_b32 v152, v7 offset:9312
	s_waitcnt lgkmcnt(11)
	v_fmac_f32_dpp v0, v165, v80 row_newbcast:0 row_mask:0xf bank_mask:0xf
	v_fmac_f32_dpp v1, v165, v81 row_newbcast:1 row_mask:0xf bank_mask:0xf
	v_fmac_f32_dpp v2, v165, v82 row_newbcast:2 row_mask:0xf bank_mask:0xf
	v_fmac_f32_dpp v3, v165, v83 row_newbcast:3 row_mask:0xf bank_mask:0xf
	v_fmac_f32_dpp v0, v165, v84 row_newbcast:4 row_mask:0xf bank_mask:0xf
	v_fmac_f32_dpp v1, v165, v85 row_newbcast:5 row_mask:0xf bank_mask:0xf
	v_fmac_f32_dpp v2, v165, v86 row_newbcast:6 row_mask:0xf bank_mask:0xf
	v_fmac_f32_dpp v3, v165, v87 row_newbcast:7 row_mask:0xf bank_mask:0xf
	v_fmac_f32_dpp v0, v165, v88 row_newbcast:8 row_mask:0xf bank_mask:0xf
	v_fmac_f32_dpp v1, v165, v89 row_newbcast:9 row_mask:0xf bank_mask:0xf
	v_fmac_f32_dpp v2, v165, v90 row_newbcast:10 row_mask:0xf bank_mask:0xf
	v_fmac_f32_dpp v3, v165, v91 row_newbcast:11 row_mask:0xf bank_mask:0xf
	v_fmac_f32_dpp v0, v165, v92 row_newbcast:12 row_mask:0xf bank_mask:0xf
	ds_read_b32 v153, v7 offset:9376
	v_add_f32_e32 v0, v0, v1
	v_add_f32_e32 v2, v2, v3
	v_add_f32_e32 v0, v0, v2
	v_add_f32_e32 v93, v93, v0
	s_waitcnt lgkmcnt(11)
	v_mul_f32_dpp v0, v166, v64 row_newbcast:0 row_mask:0xf bank_mask:0xf
	v_mul_f32_dpp v1, v166, v65 row_newbcast:1 row_mask:0xf bank_mask:0xf
	v_mul_f32_dpp v2, v166, v66 row_newbcast:2 row_mask:0xf bank_mask:0xf
	v_mul_f32_dpp v3, v166, v67 row_newbcast:3 row_mask:0xf bank_mask:0xf
	v_fmac_f32_dpp v0, v166, v68 row_newbcast:4 row_mask:0xf bank_mask:0xf
	v_fmac_f32_dpp v1, v166, v69 row_newbcast:5 row_mask:0xf bank_mask:0xf
	v_fmac_f32_dpp v2, v166, v70 row_newbcast:6 row_mask:0xf bank_mask:0xf
	v_fmac_f32_dpp v3, v166, v71 row_newbcast:7 row_mask:0xf bank_mask:0xf
	v_fmac_f32_dpp v0, v166, v72 row_newbcast:8 row_mask:0xf bank_mask:0xf
	v_fmac_f32_dpp v1, v166, v73 row_newbcast:9 row_mask:0xf bank_mask:0xf
	v_fmac_f32_dpp v2, v166, v74 row_newbcast:10 row_mask:0xf bank_mask:0xf
	v_fmac_f32_dpp v3, v166, v75 row_newbcast:11 row_mask:0xf bank_mask:0xf
	v_fmac_f32_dpp v0, v166, v76 row_newbcast:12 row_mask:0xf bank_mask:0xf
	v_fmac_f32_dpp v1, v166, v77 row_newbcast:13 row_mask:0xf bank_mask:0xf
	v_fmac_f32_dpp v2, v166, v78 row_newbcast:14 row_mask:0xf bank_mask:0xf
	v_fmac_f32_dpp v3, v166, v79 row_newbcast:15 row_mask:0xf bank_mask:0xf
	ds_read_b32 v154, v7 offset:9520
	s_waitcnt lgkmcnt(11)
	v_fmac_f32_dpp v0, v167, v80 row_newbcast:0 row_mask:0xf bank_mask:0xf
	v_fmac_f32_dpp v1, v167, v81 row_newbcast:1 row_mask:0xf bank_mask:0xf
	v_fmac_f32_dpp v2, v167, v82 row_newbcast:2 row_mask:0xf bank_mask:0xf
	v_fmac_f32_dpp v3, v167, v83 row_newbcast:3 row_mask:0xf bank_mask:0xf
	v_fmac_f32_dpp v0, v167, v84 row_newbcast:4 row_mask:0xf bank_mask:0xf
	v_fmac_f32_dpp v1, v167, v85 row_newbcast:5 row_mask:0xf bank_mask:0xf
	v_fmac_f32_dpp v2, v167, v86 row_newbcast:6 row_mask:0xf bank_mask:0xf
	v_fmac_f32_dpp v3, v167, v87 row_newbcast:7 row_mask:0xf bank_mask:0xf
	v_fmac_f32_dpp v0, v167, v88 row_newbcast:8 row_mask:0xf bank_mask:0xf
	v_fmac_f32_dpp v1, v167, v89 row_newbcast:9 row_mask:0xf bank_mask:0xf
	v_fmac_f32_dpp v2, v167, v90 row_newbcast:10 row_mask:0xf bank_mask:0xf
	v_fmac_f32_dpp v3, v167, v91 row_newbcast:11 row_mask:0xf bank_mask:0xf
	v_fmac_f32_dpp v0, v167, v92 row_newbcast:12 row_mask:0xf bank_mask:0xf
	v_fmac_f32_dpp v1, v167, v93 row_newbcast:13 row_mask:0xf bank_mask:0xf
	ds_read_b32 v155, v7 offset:9584
	v_add_f32_e32 v0, v0, v1
	v_add_f32_e32 v2, v2, v3
	v_add_f32_e32 v0, v0, v2
	v_add_f32_e32 v94, v94, v0
	s_waitcnt lgkmcnt(11)
; #define LAS __attribute__((address_space(3)))
; __device__ __forceinline__ void rw_phaseA(LAS unsigned char* lds, const RwCtx& X, int item) {
;     ...
;         for (int tt = 1; tt < 64; ++tt) { float a = x[tt];
; #pragma unroll
;             for (int s4 = 0; s4 < (tt + 3) / 4; ++s4) { const f32x4 l4 = *(const LAS f32x4*)(LABv + tt * 68 + s4 * 4);
;                 a += l4[0] * x[s4 * 4]; if (s4 * 4 + 1 < tt) a += l4[1] * x[s4 * 4 + 1]; if (s4 * 4 + 2 < tt) a += l4[2] * x[s4 * 4 + 2]; if (s4 * 4 + 3 < tt) a += l4[3] * x[s4 * 4 + 3]; }
;             x[tt] = a;
	v_mul_f32_dpp v0, v168, v64 row_newbcast:0 row_mask:0xf bank_mask:0xf
	v_mul_f32_dpp v1, v168, v65 row_newbcast:1 row_mask:0xf bank_mask:0xf
	v_mul_f32_dpp v2, v168, v66 row_newbcast:2 row_mask:0xf bank_mask:0xf
	v_mul_f32_dpp v3, v168, v67 row_newbcast:3 row_mask:0xf bank_mask:0xf
	v_fmac_f32_dpp v0, v168, v68 row_newbcast:4 row_mask:0xf bank_mask:0xf
	v_fmac_f32_dpp v1, v168, v69 row_newbcast:5 row_mask:0xf bank_mask:0xf
	v_fmac_f32_dpp v2, v168, v70 row_newbcast:6 row_mask:0xf bank_mask:0xf
	v_fmac_f32_dpp v3, v168, v71 row_newbcast:7 row_mask:0xf bank_mask:0xf
	v_fmac_f32_dpp v0, v168, v72 row_newbcast:8 row_mask:0xf bank_mask:0xf
	v_fmac_f32_dpp v1, v168, v73 row_newbcast:9 row_mask:0xf bank_mask:0xf
	v_fmac_f32_dpp v2, v168, v74 row_newbcast:10 row_mask:0xf bank_mask:0xf
	v_fmac_f32_dpp v3, v168, v75 row_newbcast:11 row_mask:0xf bank_mask:0xf
	v_fmac_f32_dpp v0, v168, v76 row_newbcast:12 row_mask:0xf bank_mask:0xf
	v_fmac_f32_dpp v1, v168, v77 row_newbcast:13 row_mask:0xf bank_mask:0xf
	v_fmac_f32_dpp v2, v168, v78 row_newbcast:14 row_mask:0xf bank_mask:0xf
	v_fmac_f32_dpp v3, v168, v79 row_newbcast:15 row_mask:0xf bank_mask:0xf
	ds_read_b32 v156, v7 offset:9648
	s_waitcnt lgkmcnt(11)
	v_fmac_f32_dpp v0, v169, v80 row_newbcast:0 row_mask:0xf bank_mask:0xf
	v_fmac_f32_dpp v1, v169, v81 row_newbcast:1 row_mask:0xf bank_mask:0xf
	v_fmac_f32_dpp v2, v169, v82 row_newbcast:2 row_mask:0xf bank_mask:0xf
	v_fmac_f32_dpp v3, v169, v83 row_newbcast:3 row_mask:0xf bank_mask:0xf
	v_fmac_f32_dpp v0, v169, v84 row_newbcast:4 row_mask:0xf bank_mask:0xf
	v_fmac_f32_dpp v1, v169, v85 row_newbcast:5 row_mask:0xf bank_mask:0xf
	v_fmac_f32_dpp v2, v169, v86 row_newbcast:6 row_mask:0xf bank_mask:0xf
	v_fmac_f32_dpp v3, v169, v87 row_newbcast:7 row_mask:0xf bank_mask:0xf
	v_fmac_f32_dpp v0, v169, v88 row_newbcast:8 row_mask:0xf bank_mask:0xf
	v_fmac_f32_dpp v1, v169, v89 row_newbcast:9 row_mask:0xf bank_mask:0xf
	v_fmac_f32_dpp v2, v169, v90 row_newbcast:10 row_mask:0xf bank_mask:0xf
	v_fmac_f32_dpp v3, v169, v91 row_newbcast:11 row_mask:0xf bank_mask:0xf
	v_fmac_f32_dpp v0, v169, v92 row_newbcast:12 row_mask:0xf bank_mask:0xf
	v_fmac_f32_dpp v1, v169, v93 row_newbcast:13 row_mask:0xf bank_mask:0xf
	v_fmac_f32_dpp v2, v169, v94 row_newbcast:14 row_mask:0xf bank_mask:0xf
	ds_read_b32 v157, v7 offset:9792
	v_add_f32_e32 v0, v0, v1
	v_add_f32_e32 v2, v2, v3
	v_add_f32_e32 v0, v0, v2
	v_add_f32_e32 v95, v95, v0
	s_waitcnt lgkmcnt(11)
	v_mul_f32_dpp v0, v170, v64 row_newbcast:0 row_mask:0xf bank_mask:0xf
	v_mul_f32_dpp v1, v170, v65 row_newbcast:1 row_mask:0xf bank_mask:0xf
	v_mul_f32_dpp v2, v170, v66 row_newbcast:2 row_mask:0xf bank_mask:0xf
	v_mul_f32_dpp v3, v170, v67 row_newbcast:3 row_mask:0xf bank_mask:0xf
	v_fmac_f32_dpp v0, v170, v68 row_newbcast:4 row_mask:0xf bank_mask:0xf
	v_fmac_f32_dpp v1, v170, v69 row_newbcast:5 row_mask:0xf bank_mask:0xf
	v_fmac_f32_dpp v2, v170, v70 row_newbcast:6 row_mask:0xf bank_mask:0xf
	v_fmac_f32_dpp v3, v170, v71 row_newbcast:7 row_mask:0xf bank_mask:0xf
	v_fmac_f32_dpp v0, v170, v72 row_newbcast:8 row_mask:0xf bank_mask:0xf
	v_fmac_f32_dpp v1, v170, v73 row_newbcast:9 row_mask:0xf bank_mask:0xf
	v_fmac_f32_dpp v2, v170, v74 row_newbcast:10 row_mask:0xf bank_mask:0xf
	v_fmac_f32_dpp v3, v170, v75 row_newbcast:11 row_mask:0xf bank_mask:0xf
	v_fmac_f32_dpp v0, v170, v76 row_newbcast:12 row_mask:0xf bank_mask:0xf
	v_fmac_f32_dpp v1, v170, v77 row_newbcast:13 row_mask:0xf bank_mask:0xf
	v_fmac_f32_dpp v2, v170, v78 row_newbcast:14 row_mask:0xf bank_mask:0xf
	v_fmac_f32_dpp v3, v170, v79 row_newbcast:15 row_mask:0xf bank_mask:0xf
	ds_read_b32 v158, v7 offset:9856
	s_waitcnt lgkmcnt(11)
	v_fmac_f32_dpp v0, v171, v80 row_newbcast:0 row_mask:0xf bank_mask:0xf
	v_fmac_f32_dpp v1, v171, v81 row_newbcast:1 row_mask:0xf bank_mask:0xf
	v_fmac_f32_dpp v2, v171, v82 row_newbcast:2 row_mask:0xf bank_mask:0xf
	v_fmac_f32_dpp v3, v171, v83 row_newbcast:3 row_mask:0xf bank_mask:0xf
	v_fmac_f32_dpp v0, v171, v84 row_newbcast:4 row_mask:0xf bank_mask:0xf
	v_fmac_f32_dpp v1, v171, v85 row_newbcast:5 row_mask:0xf bank_mask:0xf
	v_fmac_f32_dpp v2, v171, v86 row_newbcast:6 row_mask:0xf bank_mask:0xf
	v_fmac_f32_dpp v3, v171, v87 row_newbcast:7 row_mask:0xf bank_mask:0xf
	v_fmac_f32_dpp v0, v171, v88 row_newbcast:8 row_mask:0xf bank_mask:0xf
	v_fmac_f32_dpp v1, v171, v89 row_newbcast:9 row_mask:0xf bank_mask:0xf
	v_fmac_f32_dpp v2, v171, v90 row_newbcast:10 row_mask:0xf bank_mask:0xf
	v_fmac_f32_dpp v3, v171, v91 row_newbcast:11 row_mask:0xf bank_mask:0xf
	v_fmac_f32_dpp v0, v171, v92 row_newbcast:12 row_mask:0xf bank_mask:0xf
	v_fmac_f32_dpp v1, v171, v93 row_newbcast:13 row_mask:0xf bank_mask:0xf
	v_fmac_f32_dpp v2, v171, v94 row_newbcast:14 row_mask:0xf bank_mask:0xf
	v_fmac_f32_dpp v3, v171, v95 row_newbcast:15 row_mask:0xf bank_mask:0xf
	ds_read_b32 v159, v7 offset:9920
	v_add_f32_e32 v0, v0, v1
	v_add_f32_e32 v2, v2, v3
	v_add_f32_e32 v0, v0, v2
	v_add_f32_e32 v96, v96, v0
	s_waitcnt lgkmcnt(11)
	v_mul_f32_dpp v0, v148, v64 row_newbcast:0 row_mask:0xf bank_mask:0xf
	v_mul_f32_dpp v1, v148, v65 row_newbcast:1 row_mask:0xf bank_mask:0xf
	v_mul_f32_dpp v2, v148, v66 row_newbcast:2 row_mask:0xf bank_mask:0xf
	v_mul_f32_dpp v3, v148, v67 row_newbcast:3 row_mask:0xf bank_mask:0xf
	v_fmac_f32_dpp v0, v148, v68 row_newbcast:4 row_mask:0xf bank_mask:0xf
	v_fmac_f32_dpp v1, v148, v69 row_newbcast:5 row_mask:0xf bank_mask:0xf
	v_fmac_f32_dpp v2, v148, v70 row_newbcast:6 row_mask:0xf bank_mask:0xf
	v_fmac_f32_dpp v3, v148, v71 row_newbcast:7 row_mask:0xf bank_mask:0xf
	v_fmac_f32_dpp v0, v148, v72 row_newbcast:8 row_mask:0xf bank_mask:0xf
	v_fmac_f32_dpp v1, v148, v73 row_newbcast:9 row_mask:0xf bank_mask:0xf
	v_fmac_f32_dpp v2, v148, v74 row_newbcast:10 row_mask:0xf bank_mask:0xf
	v_fmac_f32_dpp v3, v148, v75 row_newbcast:11 row_mask:0xf bank_mask:0xf
	v_fmac_f32_dpp v0, v148, v76 row_newbcast:12 row_mask:0xf bank_mask:0xf
	v_fmac_f32_dpp v1, v148, v77 row_newbcast:13 row_mask:0xf bank_mask:0xf
	v_fmac_f32_dpp v2, v148, v78 row_newbcast:14 row_mask:0xf bank_mask:0xf
	v_fmac_f32_dpp v3, v148, v79 row_newbcast:15 row_mask:0xf bank_mask:0xf
	ds_read_b32 v160, v7 offset:10064
	s_waitcnt lgkmcnt(11)
; #define LAS __attribute__((address_space(3)))
; __device__ __forceinline__ void rw_phaseA(LAS unsigned char* lds, const RwCtx& X, int item) {
;     ...
;         for (int tt = 1; tt < 64; ++tt) { float a = x[tt];
; #pragma unroll
;             for (int s4 = 0; s4 < (tt + 3) / 4; ++s4) { const f32x4 l4 = *(const LAS f32x4*)(LABv + tt * 68 + s4 * 4);
;                 a += l4[0] * x[s4 * 4]; if (s4 * 4 + 1 < tt) a += l4[1] * x[s4 * 4 + 1]; if (s4 * 4 + 2 < tt) a += l4[2] * x[s4 * 4 + 2]; if (s4 * 4 + 3 < tt) a += l4[3] * x[s4 * 4 + 3]; }
;             x[tt] = a;
	v_fmac_f32_dpp v0, v149, v80 row_newbcast:0 row_mask:0xf bank_mask:0xf
	v_fmac_f32_dpp v1, v149, v81 row_newbcast:1 row_mask:0xf bank_mask:0xf
	v_fmac_f32_dpp v2, v149, v82 row_newbcast:2 row_mask:0xf bank_mask:0xf
	v_fmac_f32_dpp v3, v149, v83 row_newbcast:3 row_mask:0xf bank_mask:0xf
	v_fmac_f32_dpp v0, v149, v84 row_newbcast:4 row_mask:0xf bank_mask:0xf
	v_fmac_f32_dpp v1, v149, v85 row_newbcast:5 row_mask:0xf bank_mask:0xf
	v_fmac_f32_dpp v2, v149, v86 row_newbcast:6 row_mask:0xf bank_mask:0xf
	v_fmac_f32_dpp v3, v149, v87 row_newbcast:7 row_mask:0xf bank_mask:0xf
	v_fmac_f32_dpp v0, v149, v88 row_newbcast:8 row_mask:0xf bank_mask:0xf
	v_fmac_f32_dpp v1, v149, v89 row_newbcast:9 row_mask:0xf bank_mask:0xf
	v_fmac_f32_dpp v2, v149, v90 row_newbcast:10 row_mask:0xf bank_mask:0xf
	v_fmac_f32_dpp v3, v149, v91 row_newbcast:11 row_mask:0xf bank_mask:0xf
	v_fmac_f32_dpp v0, v149, v92 row_newbcast:12 row_mask:0xf bank_mask:0xf
	v_fmac_f32_dpp v1, v149, v93 row_newbcast:13 row_mask:0xf bank_mask:0xf
	v_fmac_f32_dpp v2, v149, v94 row_newbcast:14 row_mask:0xf bank_mask:0xf
	v_fmac_f32_dpp v3, v149, v95 row_newbcast:15 row_mask:0xf bank_mask:0xf
	ds_read_b32 v161, v7 offset:10128
	s_waitcnt lgkmcnt(11)
	v_fmac_f32_dpp v0, v150, v96 row_newbcast:0 row_mask:0xf bank_mask:0xf
	ds_read_b32 v162, v7 offset:10192
	v_add_f32_e32 v0, v0, v1
	v_add_f32_e32 v2, v2, v3
	v_add_f32_e32 v0, v0, v2
	v_add_f32_e32 v97, v97, v0
	s_waitcnt lgkmcnt(11)
	v_mul_f32_dpp v0, v151, v64 row_newbcast:0 row_mask:0xf bank_mask:0xf
	v_mul_f32_dpp v1, v151, v65 row_newbcast:1 row_mask:0xf bank_mask:0xf
	v_mul_f32_dpp v2, v151, v66 row_newbcast:2 row_mask:0xf bank_mask:0xf
	v_mul_f32_dpp v3, v151, v67 row_newbcast:3 row_mask:0xf bank_mask:0xf
	v_fmac_f32_dpp v0, v151, v68 row_newbcast:4 row_mask:0xf bank_mask:0xf
	v_fmac_f32_dpp v1, v151, v69 row_newbcast:5 row_mask:0xf bank_mask:0xf
	v_fmac_f32_dpp v2, v151, v70 row_newbcast:6 row_mask:0xf bank_mask:0xf
	v_fmac_f32_dpp v3, v151, v71 row_newbcast:7 row_mask:0xf bank_mask:0xf
	v_fmac_f32_dpp v0, v151, v72 row_newbcast:8 row_mask:0xf bank_mask:0xf
	v_fmac_f32_dpp v1, v151, v73 row_newbcast:9 row_mask:0xf bank_mask:0xf
	v_fmac_f32_dpp v2, v151, v74 row_newbcast:10 row_mask:0xf bank_mask:0xf
	v_fmac_f32_dpp v3, v151, v75 row_newbcast:11 row_mask:0xf bank_mask:0xf
	v_fmac_f32_dpp v0, v151, v76 row_newbcast:12 row_mask:0xf bank_mask:0xf
	v_fmac_f32_dpp v1, v151, v77 row_newbcast:13 row_mask:0xf bank_mask:0xf
	v_fmac_f32_dpp v2, v151, v78 row_newbcast:14 row_mask:0xf bank_mask:0xf
	v_fmac_f32_dpp v3, v151, v79 row_newbcast:15 row_mask:0xf bank_mask:0xf
	ds_read_b32 v163, v7 offset:10336
	s_waitcnt lgkmcnt(11)
	v_fmac_f32_dpp v0, v152, v80 row_newbcast:0 row_mask:0xf bank_mask:0xf
	v_fmac_f32_dpp v1, v152, v81 row_newbcast:1 row_mask:0xf bank_mask:0xf
	v_fmac_f32_dpp v2, v152, v82 row_newbcast:2 row_mask:0xf bank_mask:0xf
	v_fmac_f32_dpp v3, v152, v83 row_newbcast:3 row_mask:0xf bank_mask:0xf
	v_fmac_f32_dpp v0, v152, v84 row_newbcast:4 row_mask:0xf bank_mask:0xf
	v_fmac_f32_dpp v1, v152, v85 row_newbcast:5 row_mask:0xf bank_mask:0xf
	v_fmac_f32_dpp v2, v152, v86 row_newbcast:6 row_mask:0xf bank_mask:0xf
	v_fmac_f32_dpp v3, v152, v87 row_newbcast:7 row_mask:0xf bank_mask:0xf
	v_fmac_f32_dpp v0, v152, v88 row_newbcast:8 row_mask:0xf bank_mask:0xf
	v_fmac_f32_dpp v1, v152, v89 row_newbcast:9 row_mask:0xf bank_mask:0xf
	v_fmac_f32_dpp v2, v152, v90 row_newbcast:10 row_mask:0xf bank_mask:0xf
	v_fmac_f32_dpp v3, v152, v91 row_newbcast:11 row_mask:0xf bank_mask:0xf
	v_fmac_f32_dpp v0, v152, v92 row_newbcast:12 row_mask:0xf bank_mask:0xf
	v_fmac_f32_dpp v1, v152, v93 row_newbcast:13 row_mask:0xf bank_mask:0xf
	v_fmac_f32_dpp v2, v152, v94 row_newbcast:14 row_mask:0xf bank_mask:0xf
	v_fmac_f32_dpp v3, v152, v95 row_newbcast:15 row_mask:0xf bank_mask:0xf
	ds_read_b32 v164, v7 offset:10400
	s_waitcnt lgkmcnt(11)
	v_fmac_f32_dpp v0, v153, v96 row_newbcast:0 row_mask:0xf bank_mask:0xf
	v_fmac_f32_dpp v1, v153, v97 row_newbcast:1 row_mask:0xf bank_mask:0xf
	ds_read_b32 v165, v7 offset:10464
	v_add_f32_e32 v0, v0, v1
	v_add_f32_e32 v2, v2, v3
	v_add_f32_e32 v0, v0, v2
	v_add_f32_e32 v98, v98, v0
	s_waitcnt lgkmcnt(11)
	v_mul_f32_dpp v0, v154, v64 row_newbcast:0 row_mask:0xf bank_mask:0xf
	v_mul_f32_dpp v1, v154, v65 row_newbcast:1 row_mask:0xf bank_mask:0xf
	v_mul_f32_dpp v2, v154, v66 row_newbcast:2 row_mask:0xf bank_mask:0xf
	v_mul_f32_dpp v3, v154, v67 row_newbcast:3 row_mask:0xf bank_mask:0xf
	v_fmac_f32_dpp v0, v154, v68 row_newbcast:4 row_mask:0xf bank_mask:0xf
	v_fmac_f32_dpp v1, v154, v69 row_newbcast:5 row_mask:0xf bank_mask:0xf
	v_fmac_f32_dpp v2, v154, v70 row_newbcast:6 row_mask:0xf bank_mask:0xf
	v_fmac_f32_dpp v3, v154, v71 row_newbcast:7 row_mask:0xf bank_mask:0xf
	v_fmac_f32_dpp v0, v154, v72 row_newbcast:8 row_mask:0xf bank_mask:0xf
	v_fmac_f32_dpp v1, v154, v73 row_newbcast:9 row_mask:0xf bank_mask:0xf
	v_fmac_f32_dpp v2, v154, v74 row_newbcast:10 row_mask:0xf bank_mask:0xf
	v_fmac_f32_dpp v3, v154, v75 row_newbcast:11 row_mask:0xf bank_mask:0xf
	v_fmac_f32_dpp v0, v154, v76 row_newbcast:12 row_mask:0xf bank_mask:0xf
	v_fmac_f32_dpp v1, v154, v77 row_newbcast:13 row_mask:0xf bank_mask:0xf
	v_fmac_f32_dpp v2, v154, v78 row_newbcast:14 row_mask:0xf bank_mask:0xf
	v_fmac_f32_dpp v3, v154, v79 row_newbcast:15 row_mask:0xf bank_mask:0xf
	ds_read_b32 v166, v7 offset:10608
	s_waitcnt lgkmcnt(11)
; #define LAS __attribute__((address_space(3)))
; __device__ __forceinline__ void rw_phaseA(LAS unsigned char* lds, const RwCtx& X, int item) {
;     ...
;         for (int tt = 1; tt < 64; ++tt) { float a = x[tt];
; #pragma unroll
;             for (int s4 = 0; s4 < (tt + 3) / 4; ++s4) { const f32x4 l4 = *(const LAS f32x4*)(LABv + tt * 68 + s4 * 4);
;                 a += l4[0] * x[s4 * 4]; if (s4 * 4 + 1 < tt) a += l4[1] * x[s4 * 4 + 1]; if (s4 * 4 + 2 < tt) a += l4[2] * x[s4 * 4 + 2]; if (s4 * 4 + 3 < tt) a += l4[3] * x[s4 * 4 + 3]; }
;             x[tt] = a;
	v_fmac_f32_dpp v0, v155, v80 row_newbcast:0 row_mask:0xf bank_mask:0xf
	v_fmac_f32_dpp v1, v155, v81 row_newbcast:1 row_mask:0xf bank_mask:0xf
	v_fmac_f32_dpp v2, v155, v82 row_newbcast:2 row_mask:0xf bank_mask:0xf
	v_fmac_f32_dpp v3, v155, v83 row_newbcast:3 row_mask:0xf bank_mask:0xf
	v_fmac_f32_dpp v0, v155, v84 row_newbcast:4 row_mask:0xf bank_mask:0xf
	v_fmac_f32_dpp v1, v155, v85 row_newbcast:5 row_mask:0xf bank_mask:0xf
	v_fmac_f32_dpp v2, v155, v86 row_newbcast:6 row_mask:0xf bank_mask:0xf
	v_fmac_f32_dpp v3, v155, v87 row_newbcast:7 row_mask:0xf bank_mask:0xf
	v_fmac_f32_dpp v0, v155, v88 row_newbcast:8 row_mask:0xf bank_mask:0xf
	v_fmac_f32_dpp v1, v155, v89 row_newbcast:9 row_mask:0xf bank_mask:0xf
	v_fmac_f32_dpp v2, v155, v90 row_newbcast:10 row_mask:0xf bank_mask:0xf
	v_fmac_f32_dpp v3, v155, v91 row_newbcast:11 row_mask:0xf bank_mask:0xf
	v_fmac_f32_dpp v0, v155, v92 row_newbcast:12 row_mask:0xf bank_mask:0xf
	v_fmac_f32_dpp v1, v155, v93 row_newbcast:13 row_mask:0xf bank_mask:0xf
	v_fmac_f32_dpp v2, v155, v94 row_newbcast:14 row_mask:0xf bank_mask:0xf
	v_fmac_f32_dpp v3, v155, v95 row_newbcast:15 row_mask:0xf bank_mask:0xf
	ds_read_b32 v167, v7 offset:10672
	s_waitcnt lgkmcnt(11)
	v_fmac_f32_dpp v0, v156, v96 row_newbcast:0 row_mask:0xf bank_mask:0xf
	v_fmac_f32_dpp v1, v156, v97 row_newbcast:1 row_mask:0xf bank_mask:0xf
	v_fmac_f32_dpp v2, v156, v98 row_newbcast:2 row_mask:0xf bank_mask:0xf
	ds_read_b32 v168, v7 offset:10736
	v_add_f32_e32 v0, v0, v1
	v_add_f32_e32 v2, v2, v3
	v_add_f32_e32 v0, v0, v2
	v_add_f32_e32 v99, v99, v0
	s_waitcnt lgkmcnt(11)
	v_mul_f32_dpp v0, v157, v64 row_newbcast:0 row_mask:0xf bank_mask:0xf
	v_mul_f32_dpp v1, v157, v65 row_newbcast:1 row_mask:0xf bank_mask:0xf
	v_mul_f32_dpp v2, v157, v66 row_newbcast:2 row_mask:0xf bank_mask:0xf
	v_mul_f32_dpp v3, v157, v67 row_newbcast:3 row_mask:0xf bank_mask:0xf
	v_fmac_f32_dpp v0, v157, v68 row_newbcast:4 row_mask:0xf bank_mask:0xf
	v_fmac_f32_dpp v1, v157, v69 row_newbcast:5 row_mask:0xf bank_mask:0xf
	v_fmac_f32_dpp v2, v157, v70 row_newbcast:6 row_mask:0xf bank_mask:0xf
	v_fmac_f32_dpp v3, v157, v71 row_newbcast:7 row_mask:0xf bank_mask:0xf
	v_fmac_f32_dpp v0, v157, v72 row_newbcast:8 row_mask:0xf bank_mask:0xf
	v_fmac_f32_dpp v1, v157, v73 row_newbcast:9 row_mask:0xf bank_mask:0xf
	v_fmac_f32_dpp v2, v157, v74 row_newbcast:10 row_mask:0xf bank_mask:0xf
	v_fmac_f32_dpp v3, v157, v75 row_newbcast:11 row_mask:0xf bank_mask:0xf
	v_fmac_f32_dpp v0, v157, v76 row_newbcast:12 row_mask:0xf bank_mask:0xf
	v_fmac_f32_dpp v1, v157, v77 row_newbcast:13 row_mask:0xf bank_mask:0xf
	v_fmac_f32_dpp v2, v157, v78 row_newbcast:14 row_mask:0xf bank_mask:0xf
	v_fmac_f32_dpp v3, v157, v79 row_newbcast:15 row_mask:0xf bank_mask:0xf
	ds_read_b32 v169, v7 offset:10880
	s_waitcnt lgkmcnt(11)
	v_fmac_f32_dpp v0, v158, v80 row_newbcast:0 row_mask:0xf bank_mask:0xf
	v_fmac_f32_dpp v1, v158, v81 row_newbcast:1 row_mask:0xf bank_mask:0xf
	v_fmac_f32_dpp v2, v158, v82 row_newbcast:2 row_mask:0xf bank_mask:0xf
	v_fmac_f32_dpp v3, v158, v83 row_newbcast:3 row_mask:0xf bank_mask:0xf
	v_fmac_f32_dpp v0, v158, v84 row_newbcast:4 row_mask:0xf bank_mask:0xf
	v_fmac_f32_dpp v1, v158, v85 row_newbcast:5 row_mask:0xf bank_mask:0xf
	v_fmac_f32_dpp v2, v158, v86 row_newbcast:6 row_mask:0xf bank_mask:0xf
	v_fmac_f32_dpp v3, v158, v87 row_newbcast:7 row_mask:0xf bank_mask:0xf
	v_fmac_f32_dpp v0, v158, v88 row_newbcast:8 row_mask:0xf bank_mask:0xf
	v_fmac_f32_dpp v1, v158, v89 row_newbcast:9 row_mask:0xf bank_mask:0xf
	v_fmac_f32_dpp v2, v158, v90 row_newbcast:10 row_mask:0xf bank_mask:0xf
	v_fmac_f32_dpp v3, v158, v91 row_newbcast:11 row_mask:0xf bank_mask:0xf
	v_fmac_f32_dpp v0, v158, v92 row_newbcast:12 row_mask:0xf bank_mask:0xf
	v_fmac_f32_dpp v1, v158, v93 row_newbcast:13 row_mask:0xf bank_mask:0xf
	v_fmac_f32_dpp v2, v158, v94 row_newbcast:14 row_mask:0xf bank_mask:0xf
	v_fmac_f32_dpp v3, v158, v95 row_newbcast:15 row_mask:0xf bank_mask:0xf
	ds_read_b32 v170, v7 offset:10944
	s_waitcnt lgkmcnt(11)
	v_fmac_f32_dpp v0, v159, v96 row_newbcast:0 row_mask:0xf bank_mask:0xf
	v_fmac_f32_dpp v1, v159, v97 row_newbcast:1 row_mask:0xf bank_mask:0xf
	v_fmac_f32_dpp v2, v159, v98 row_newbcast:2 row_mask:0xf bank_mask:0xf
	v_fmac_f32_dpp v3, v159, v99 row_newbcast:3 row_mask:0xf bank_mask:0xf
	ds_read_b32 v171, v7 offset:11008
	v_add_f32_e32 v0, v0, v1
	v_add_f32_e32 v2, v2, v3
	v_add_f32_e32 v0, v0, v2
	v_add_f32_e32 v100, v100, v0
	s_waitcnt lgkmcnt(11)
	v_mul_f32_dpp v0, v160, v64 row_newbcast:0 row_mask:0xf bank_mask:0xf
	v_mul_f32_dpp v1, v160, v65 row_newbcast:1 row_mask:0xf bank_mask:0xf
	v_mul_f32_dpp v2, v160, v66 row_newbcast:2 row_mask:0xf bank_mask:0xf
	v_mul_f32_dpp v3, v160, v67 row_newbcast:3 row_mask:0xf bank_mask:0xf
	v_fmac_f32_dpp v0, v160, v68 row_newbcast:4 row_mask:0xf bank_mask:0xf
	v_fmac_f32_dpp v1, v160, v69 row_newbcast:5 row_mask:0xf bank_mask:0xf
	v_fmac_f32_dpp v2, v160, v70 row_newbcast:6 row_mask:0xf bank_mask:0xf
	v_fmac_f32_dpp v3, v160, v71 row_newbcast:7 row_mask:0xf bank_mask:0xf
	v_fmac_f32_dpp v0, v160, v72 row_newbcast:8 row_mask:0xf bank_mask:0xf
	v_fmac_f32_dpp v1, v160, v73 row_newbcast:9 row_mask:0xf bank_mask:0xf
	v_fmac_f32_dpp v2, v160, v74 row_newbcast:10 row_mask:0xf bank_mask:0xf
	v_fmac_f32_dpp v3, v160, v75 row_newbcast:11 row_mask:0xf bank_mask:0xf
	v_fmac_f32_dpp v0, v160, v76 row_newbcast:12 row_mask:0xf bank_mask:0xf
	v_fmac_f32_dpp v1, v160, v77 row_newbcast:13 row_mask:0xf bank_mask:0xf
	v_fmac_f32_dpp v2, v160, v78 row_newbcast:14 row_mask:0xf bank_mask:0xf
	v_fmac_f32_dpp v3, v160, v79 row_newbcast:15 row_mask:0xf bank_mask:0xf
	ds_read_b32 v148, v7 offset:11152
	s_waitcnt lgkmcnt(11)
; #define LAS __attribute__((address_space(3)))
; __device__ __forceinline__ void rw_phaseA(LAS unsigned char* lds, const RwCtx& X, int item) {
;     ...
;         for (int tt = 1; tt < 64; ++tt) { float a = x[tt];
; #pragma unroll
;             for (int s4 = 0; s4 < (tt + 3) / 4; ++s4) { const f32x4 l4 = *(const LAS f32x4*)(LABv + tt * 68 + s4 * 4);
;                 a += l4[0] * x[s4 * 4]; if (s4 * 4 + 1 < tt) a += l4[1] * x[s4 * 4 + 1]; if (s4 * 4 + 2 < tt) a += l4[2] * x[s4 * 4 + 2]; if (s4 * 4 + 3 < tt) a += l4[3] * x[s4 * 4 + 3]; }
;             x[tt] = a;
	v_fmac_f32_dpp v0, v161, v80 row_newbcast:0 row_mask:0xf bank_mask:0xf
	v_fmac_f32_dpp v1, v161, v81 row_newbcast:1 row_mask:0xf bank_mask:0xf
	v_fmac_f32_dpp v2, v161, v82 row_newbcast:2 row_mask:0xf bank_mask:0xf
	v_fmac_f32_dpp v3, v161, v83 row_newbcast:3 row_mask:0xf bank_mask:0xf
	v_fmac_f32_dpp v0, v161, v84 row_newbcast:4 row_mask:0xf bank_mask:0xf
	v_fmac_f32_dpp v1, v161, v85 row_newbcast:5 row_mask:0xf bank_mask:0xf
	v_fmac_f32_dpp v2, v161, v86 row_newbcast:6 row_mask:0xf bank_mask:0xf
	v_fmac_f32_dpp v3, v161, v87 row_newbcast:7 row_mask:0xf bank_mask:0xf
	v_fmac_f32_dpp v0, v161, v88 row_newbcast:8 row_mask:0xf bank_mask:0xf
	v_fmac_f32_dpp v1, v161, v89 row_newbcast:9 row_mask:0xf bank_mask:0xf
	v_fmac_f32_dpp v2, v161, v90 row_newbcast:10 row_mask:0xf bank_mask:0xf
	v_fmac_f32_dpp v3, v161, v91 row_newbcast:11 row_mask:0xf bank_mask:0xf
	v_fmac_f32_dpp v0, v161, v92 row_newbcast:12 row_mask:0xf bank_mask:0xf
	v_fmac_f32_dpp v1, v161, v93 row_newbcast:13 row_mask:0xf bank_mask:0xf
	v_fmac_f32_dpp v2, v161, v94 row_newbcast:14 row_mask:0xf bank_mask:0xf
	v_fmac_f32_dpp v3, v161, v95 row_newbcast:15 row_mask:0xf bank_mask:0xf
	ds_read_b32 v149, v7 offset:11216
	s_waitcnt lgkmcnt(11)
	v_fmac_f32_dpp v0, v162, v96 row_newbcast:0 row_mask:0xf bank_mask:0xf
	v_fmac_f32_dpp v1, v162, v97 row_newbcast:1 row_mask:0xf bank_mask:0xf
	v_fmac_f32_dpp v2, v162, v98 row_newbcast:2 row_mask:0xf bank_mask:0xf
	v_fmac_f32_dpp v3, v162, v99 row_newbcast:3 row_mask:0xf bank_mask:0xf
	v_fmac_f32_dpp v0, v162, v100 row_newbcast:4 row_mask:0xf bank_mask:0xf
	ds_read_b32 v150, v7 offset:11280
	v_add_f32_e32 v0, v0, v1
	v_add_f32_e32 v2, v2, v3
	v_add_f32_e32 v0, v0, v2
	v_add_f32_e32 v101, v101, v0
	s_waitcnt lgkmcnt(11)
	v_mul_f32_dpp v0, v163, v64 row_newbcast:0 row_mask:0xf bank_mask:0xf
	v_mul_f32_dpp v1, v163, v65 row_newbcast:1 row_mask:0xf bank_mask:0xf
	v_mul_f32_dpp v2, v163, v66 row_newbcast:2 row_mask:0xf bank_mask:0xf
	v_mul_f32_dpp v3, v163, v67 row_newbcast:3 row_mask:0xf bank_mask:0xf
	v_fmac_f32_dpp v0, v163, v68 row_newbcast:4 row_mask:0xf bank_mask:0xf
	v_fmac_f32_dpp v1, v163, v69 row_newbcast:5 row_mask:0xf bank_mask:0xf
	v_fmac_f32_dpp v2, v163, v70 row_newbcast:6 row_mask:0xf bank_mask:0xf
	v_fmac_f32_dpp v3, v163, v71 row_newbcast:7 row_mask:0xf bank_mask:0xf
	v_fmac_f32_dpp v0, v163, v72 row_newbcast:8 row_mask:0xf bank_mask:0xf
	v_fmac_f32_dpp v1, v163, v73 row_newbcast:9 row_mask:0xf bank_mask:0xf
	v_fmac_f32_dpp v2, v163, v74 row_newbcast:10 row_mask:0xf bank_mask:0xf
	v_fmac_f32_dpp v3, v163, v75 row_newbcast:11 row_mask:0xf bank_mask:0xf
	v_fmac_f32_dpp v0, v163, v76 row_newbcast:12 row_mask:0xf bank_mask:0xf
	v_fmac_f32_dpp v1, v163, v77 row_newbcast:13 row_mask:0xf bank_mask:0xf
	v_fmac_f32_dpp v2, v163, v78 row_newbcast:14 row_mask:0xf bank_mask:0xf
	v_fmac_f32_dpp v3, v163, v79 row_newbcast:15 row_mask:0xf bank_mask:0xf
	ds_read_b32 v151, v7 offset:11424
	s_waitcnt lgkmcnt(11)
	v_fmac_f32_dpp v0, v164, v80 row_newbcast:0 row_mask:0xf bank_mask:0xf
	v_fmac_f32_dpp v1, v164, v81 row_newbcast:1 row_mask:0xf bank_mask:0xf
	v_fmac_f32_dpp v2, v164, v82 row_newbcast:2 row_mask:0xf bank_mask:0xf
	v_fmac_f32_dpp v3, v164, v83 row_newbcast:3 row_mask:0xf bank_mask:0xf
	v_fmac_f32_dpp v0, v164, v84 row_newbcast:4 row_mask:0xf bank_mask:0xf
	v_fmac_f32_dpp v1, v164, v85 row_newbcast:5 row_mask:0xf bank_mask:0xf
	v_fmac_f32_dpp v2, v164, v86 row_newbcast:6 row_mask:0xf bank_mask:0xf
	v_fmac_f32_dpp v3, v164, v87 row_newbcast:7 row_mask:0xf bank_mask:0xf
	v_fmac_f32_dpp v0, v164, v88 row_newbcast:8 row_mask:0xf bank_mask:0xf
	v_fmac_f32_dpp v1, v164, v89 row_newbcast:9 row_mask:0xf bank_mask:0xf
	v_fmac_f32_dpp v2, v164, v90 row_newbcast:10 row_mask:0xf bank_mask:0xf
	v_fmac_f32_dpp v3, v164, v91 row_newbcast:11 row_mask:0xf bank_mask:0xf
	v_fmac_f32_dpp v0, v164, v92 row_newbcast:12 row_mask:0xf bank_mask:0xf
	v_fmac_f32_dpp v1, v164, v93 row_newbcast:13 row_mask:0xf bank_mask:0xf
	v_fmac_f32_dpp v2, v164, v94 row_newbcast:14 row_mask:0xf bank_mask:0xf
	v_fmac_f32_dpp v3, v164, v95 row_newbcast:15 row_mask:0xf bank_mask:0xf
	ds_read_b32 v152, v7 offset:11488
	s_waitcnt lgkmcnt(11)
	v_fmac_f32_dpp v0, v165, v96 row_newbcast:0 row_mask:0xf bank_mask:0xf
	v_fmac_f32_dpp v1, v165, v97 row_newbcast:1 row_mask:0xf bank_mask:0xf
	v_fmac_f32_dpp v2, v165, v98 row_newbcast:2 row_mask:0xf bank_mask:0xf
	v_fmac_f32_dpp v3, v165, v99 row_newbcast:3 row_mask:0xf bank_mask:0xf
	v_fmac_f32_dpp v0, v165, v100 row_newbcast:4 row_mask:0xf bank_mask:0xf
	v_fmac_f32_dpp v1, v165, v101 row_newbcast:5 row_mask:0xf bank_mask:0xf
	ds_read_b32 v153, v7 offset:11552
	v_add_f32_e32 v0, v0, v1
	v_add_f32_e32 v2, v2, v3
	v_add_f32_e32 v0, v0, v2
	v_add_f32_e32 v102, v102, v0
	s_waitcnt lgkmcnt(11)
	v_mul_f32_dpp v0, v166, v64 row_newbcast:0 row_mask:0xf bank_mask:0xf
	v_mul_f32_dpp v1, v166, v65 row_newbcast:1 row_mask:0xf bank_mask:0xf
	v_mul_f32_dpp v2, v166, v66 row_newbcast:2 row_mask:0xf bank_mask:0xf
	v_mul_f32_dpp v3, v166, v67 row_newbcast:3 row_mask:0xf bank_mask:0xf
	v_fmac_f32_dpp v0, v166, v68 row_newbcast:4 row_mask:0xf bank_mask:0xf
	v_fmac_f32_dpp v1, v166, v69 row_newbcast:5 row_mask:0xf bank_mask:0xf
	v_fmac_f32_dpp v2, v166, v70 row_newbcast:6 row_mask:0xf bank_mask:0xf
	v_fmac_f32_dpp v3, v166, v71 row_newbcast:7 row_mask:0xf bank_mask:0xf
	v_fmac_f32_dpp v0, v166, v72 row_newbcast:8 row_mask:0xf bank_mask:0xf
	v_fmac_f32_dpp v1, v166, v73 row_newbcast:9 row_mask:0xf bank_mask:0xf
	v_fmac_f32_dpp v2, v166, v74 row_newbcast:10 row_mask:0xf bank_mask:0xf
	v_fmac_f32_dpp v3, v166, v75 row_newbcast:11 row_mask:0xf bank_mask:0xf
	v_fmac_f32_dpp v0, v166, v76 row_newbcast:12 row_mask:0xf bank_mask:0xf
	v_fmac_f32_dpp v1, v166, v77 row_newbcast:13 row_mask:0xf bank_mask:0xf
	v_fmac_f32_dpp v2, v166, v78 row_newbcast:14 row_mask:0xf bank_mask:0xf
	v_fmac_f32_dpp v3, v166, v79 row_newbcast:15 row_mask:0xf bank_mask:0xf
	ds_read_b32 v154, v7 offset:11696
	s_waitcnt lgkmcnt(11)
; #define LAS __attribute__((address_space(3)))
; __device__ __forceinline__ void rw_phaseA(LAS unsigned char* lds, const RwCtx& X, int item) {
;     ...
;         for (int tt = 1; tt < 64; ++tt) { float a = x[tt];
; #pragma unroll
;             for (int s4 = 0; s4 < (tt + 3) / 4; ++s4) { const f32x4 l4 = *(const LAS f32x4*)(LABv + tt * 68 + s4 * 4);
;                 a += l4[0] * x[s4 * 4]; if (s4 * 4 + 1 < tt) a += l4[1] * x[s4 * 4 + 1]; if (s4 * 4 + 2 < tt) a += l4[2] * x[s4 * 4 + 2]; if (s4 * 4 + 3 < tt) a += l4[3] * x[s4 * 4 + 3]; }
;             x[tt] = a;
	v_fmac_f32_dpp v0, v167, v80 row_newbcast:0 row_mask:0xf bank_mask:0xf
	v_fmac_f32_dpp v1, v167, v81 row_newbcast:1 row_mask:0xf bank_mask:0xf
	v_fmac_f32_dpp v2, v167, v82 row_newbcast:2 row_mask:0xf bank_mask:0xf
	v_fmac_f32_dpp v3, v167, v83 row_newbcast:3 row_mask:0xf bank_mask:0xf
	v_fmac_f32_dpp v0, v167, v84 row_newbcast:4 row_mask:0xf bank_mask:0xf
	v_fmac_f32_dpp v1, v167, v85 row_newbcast:5 row_mask:0xf bank_mask:0xf
	v_fmac_f32_dpp v2, v167, v86 row_newbcast:6 row_mask:0xf bank_mask:0xf
	v_fmac_f32_dpp v3, v167, v87 row_newbcast:7 row_mask:0xf bank_mask:0xf
	v_fmac_f32_dpp v0, v167, v88 row_newbcast:8 row_mask:0xf bank_mask:0xf
	v_fmac_f32_dpp v1, v167, v89 row_newbcast:9 row_mask:0xf bank_mask:0xf
	v_fmac_f32_dpp v2, v167, v90 row_newbcast:10 row_mask:0xf bank_mask:0xf
	v_fmac_f32_dpp v3, v167, v91 row_newbcast:11 row_mask:0xf bank_mask:0xf
	v_fmac_f32_dpp v0, v167, v92 row_newbcast:12 row_mask:0xf bank_mask:0xf
	v_fmac_f32_dpp v1, v167, v93 row_newbcast:13 row_mask:0xf bank_mask:0xf
	v_fmac_f32_dpp v2, v167, v94 row_newbcast:14 row_mask:0xf bank_mask:0xf
	v_fmac_f32_dpp v3, v167, v95 row_newbcast:15 row_mask:0xf bank_mask:0xf
	ds_read_b32 v155, v7 offset:11760
	s_waitcnt lgkmcnt(11)
	v_fmac_f32_dpp v0, v168, v96 row_newbcast:0 row_mask:0xf bank_mask:0xf
	v_fmac_f32_dpp v1, v168, v97 row_newbcast:1 row_mask:0xf bank_mask:0xf
	v_fmac_f32_dpp v2, v168, v98 row_newbcast:2 row_mask:0xf bank_mask:0xf
	v_fmac_f32_dpp v3, v168, v99 row_newbcast:3 row_mask:0xf bank_mask:0xf
	v_fmac_f32_dpp v0, v168, v100 row_newbcast:4 row_mask:0xf bank_mask:0xf
	v_fmac_f32_dpp v1, v168, v101 row_newbcast:5 row_mask:0xf bank_mask:0xf
	v_fmac_f32_dpp v2, v168, v102 row_newbcast:6 row_mask:0xf bank_mask:0xf
	ds_read_b32 v156, v7 offset:11824
	v_add_f32_e32 v0, v0, v1
	v_add_f32_e32 v2, v2, v3
	v_add_f32_e32 v0, v0, v2
	v_add_f32_e32 v103, v103, v0
	s_waitcnt lgkmcnt(11)
	v_mul_f32_dpp v0, v169, v64 row_newbcast:0 row_mask:0xf bank_mask:0xf
	v_mul_f32_dpp v1, v169, v65 row_newbcast:1 row_mask:0xf bank_mask:0xf
	v_mul_f32_dpp v2, v169, v66 row_newbcast:2 row_mask:0xf bank_mask:0xf
	v_mul_f32_dpp v3, v169, v67 row_newbcast:3 row_mask:0xf bank_mask:0xf
	v_fmac_f32_dpp v0, v169, v68 row_newbcast:4 row_mask:0xf bank_mask:0xf
	v_fmac_f32_dpp v1, v169, v69 row_newbcast:5 row_mask:0xf bank_mask:0xf
	v_fmac_f32_dpp v2, v169, v70 row_newbcast:6 row_mask:0xf bank_mask:0xf
	v_fmac_f32_dpp v3, v169, v71 row_newbcast:7 row_mask:0xf bank_mask:0xf
	v_fmac_f32_dpp v0, v169, v72 row_newbcast:8 row_mask:0xf bank_mask:0xf
	v_fmac_f32_dpp v1, v169, v73 row_newbcast:9 row_mask:0xf bank_mask:0xf
	v_fmac_f32_dpp v2, v169, v74 row_newbcast:10 row_mask:0xf bank_mask:0xf
	v_fmac_f32_dpp v3, v169, v75 row_newbcast:11 row_mask:0xf bank_mask:0xf
	v_fmac_f32_dpp v0, v169, v76 row_newbcast:12 row_mask:0xf bank_mask:0xf
	v_fmac_f32_dpp v1, v169, v77 row_newbcast:13 row_mask:0xf bank_mask:0xf
	v_fmac_f32_dpp v2, v169, v78 row_newbcast:14 row_mask:0xf bank_mask:0xf
	v_fmac_f32_dpp v3, v169, v79 row_newbcast:15 row_mask:0xf bank_mask:0xf
	ds_read_b32 v157, v7 offset:11968
	s_waitcnt lgkmcnt(11)
	v_fmac_f32_dpp v0, v170, v80 row_newbcast:0 row_mask:0xf bank_mask:0xf
	v_fmac_f32_dpp v1, v170, v81 row_newbcast:1 row_mask:0xf bank_mask:0xf
	v_fmac_f32_dpp v2, v170, v82 row_newbcast:2 row_mask:0xf bank_mask:0xf
	v_fmac_f32_dpp v3, v170, v83 row_newbcast:3 row_mask:0xf bank_mask:0xf
	v_fmac_f32_dpp v0, v170, v84 row_newbcast:4 row_mask:0xf bank_mask:0xf
	v_fmac_f32_dpp v1, v170, v85 row_newbcast:5 row_mask:0xf bank_mask:0xf
	v_fmac_f32_dpp v2, v170, v86 row_newbcast:6 row_mask:0xf bank_mask:0xf
	v_fmac_f32_dpp v3, v170, v87 row_newbcast:7 row_mask:0xf bank_mask:0xf
	v_fmac_f32_dpp v0, v170, v88 row_newbcast:8 row_mask:0xf bank_mask:0xf
	v_fmac_f32_dpp v1, v170, v89 row_newbcast:9 row_mask:0xf bank_mask:0xf
	v_fmac_f32_dpp v2, v170, v90 row_newbcast:10 row_mask:0xf bank_mask:0xf
	v_fmac_f32_dpp v3, v170, v91 row_newbcast:11 row_mask:0xf bank_mask:0xf
	v_fmac_f32_dpp v0, v170, v92 row_newbcast:12 row_mask:0xf bank_mask:0xf
	v_fmac_f32_dpp v1, v170, v93 row_newbcast:13 row_mask:0xf bank_mask:0xf
	v_fmac_f32_dpp v2, v170, v94 row_newbcast:14 row_mask:0xf bank_mask:0xf
	v_fmac_f32_dpp v3, v170, v95 row_newbcast:15 row_mask:0xf bank_mask:0xf
	ds_read_b32 v158, v7 offset:12032
	s_waitcnt lgkmcnt(11)
	v_fmac_f32_dpp v0, v171, v96 row_newbcast:0 row_mask:0xf bank_mask:0xf
	v_fmac_f32_dpp v1, v171, v97 row_newbcast:1 row_mask:0xf bank_mask:0xf
	v_fmac_f32_dpp v2, v171, v98 row_newbcast:2 row_mask:0xf bank_mask:0xf
	v_fmac_f32_dpp v3, v171, v99 row_newbcast:3 row_mask:0xf bank_mask:0xf
	v_fmac_f32_dpp v0, v171, v100 row_newbcast:4 row_mask:0xf bank_mask:0xf
	v_fmac_f32_dpp v1, v171, v101 row_newbcast:5 row_mask:0xf bank_mask:0xf
	v_fmac_f32_dpp v2, v171, v102 row_newbcast:6 row_mask:0xf bank_mask:0xf
	v_fmac_f32_dpp v3, v171, v103 row_newbcast:7 row_mask:0xf bank_mask:0xf
	ds_read_b32 v159, v7 offset:12096
	v_add_f32_e32 v0, v0, v1
	v_add_f32_e32 v2, v2, v3
	v_add_f32_e32 v0, v0, v2
	v_add_f32_e32 v104, v104, v0
	s_waitcnt lgkmcnt(11)
; #define LAS __attribute__((address_space(3)))
; __device__ __forceinline__ void rw_phaseA(LAS unsigned char* lds, const RwCtx& X, int item) {
;     ...
;         for (int tt = 1; tt < 64; ++tt) { float a = x[tt];
; #pragma unroll
;             for (int s4 = 0; s4 < (tt + 3) / 4; ++s4) { const f32x4 l4 = *(const LAS f32x4*)(LABv + tt * 68 + s4 * 4);
;                 a += l4[0] * x[s4 * 4]; if (s4 * 4 + 1 < tt) a += l4[1] * x[s4 * 4 + 1]; if (s4 * 4 + 2 < tt) a += l4[2] * x[s4 * 4 + 2]; if (s4 * 4 + 3 < tt) a += l4[3] * x[s4 * 4 + 3]; }
;             x[tt] = a;
	v_mul_f32_dpp v0, v148, v64 row_newbcast:0 row_mask:0xf bank_mask:0xf
	v_mul_f32_dpp v1, v148, v65 row_newbcast:1 row_mask:0xf bank_mask:0xf
	v_mul_f32_dpp v2, v148, v66 row_newbcast:2 row_mask:0xf bank_mask:0xf
	v_mul_f32_dpp v3, v148, v67 row_newbcast:3 row_mask:0xf bank_mask:0xf
	v_fmac_f32_dpp v0, v148, v68 row_newbcast:4 row_mask:0xf bank_mask:0xf
	v_fmac_f32_dpp v1, v148, v69 row_newbcast:5 row_mask:0xf bank_mask:0xf
	v_fmac_f32_dpp v2, v148, v70 row_newbcast:6 row_mask:0xf bank_mask:0xf
	v_fmac_f32_dpp v3, v148, v71 row_newbcast:7 row_mask:0xf bank_mask:0xf
	v_fmac_f32_dpp v0, v148, v72 row_newbcast:8 row_mask:0xf bank_mask:0xf
	v_fmac_f32_dpp v1, v148, v73 row_newbcast:9 row_mask:0xf bank_mask:0xf
	v_fmac_f32_dpp v2, v148, v74 row_newbcast:10 row_mask:0xf bank_mask:0xf
	v_fmac_f32_dpp v3, v148, v75 row_newbcast:11 row_mask:0xf bank_mask:0xf
	v_fmac_f32_dpp v0, v148, v76 row_newbcast:12 row_mask:0xf bank_mask:0xf
	v_fmac_f32_dpp v1, v148, v77 row_newbcast:13 row_mask:0xf bank_mask:0xf
	v_fmac_f32_dpp v2, v148, v78 row_newbcast:14 row_mask:0xf bank_mask:0xf
	v_fmac_f32_dpp v3, v148, v79 row_newbcast:15 row_mask:0xf bank_mask:0xf
	ds_read_b32 v160, v7 offset:12240
	s_waitcnt lgkmcnt(11)
	v_fmac_f32_dpp v0, v149, v80 row_newbcast:0 row_mask:0xf bank_mask:0xf
	v_fmac_f32_dpp v1, v149, v81 row_newbcast:1 row_mask:0xf bank_mask:0xf
	v_fmac_f32_dpp v2, v149, v82 row_newbcast:2 row_mask:0xf bank_mask:0xf
	v_fmac_f32_dpp v3, v149, v83 row_newbcast:3 row_mask:0xf bank_mask:0xf
	v_fmac_f32_dpp v0, v149, v84 row_newbcast:4 row_mask:0xf bank_mask:0xf
	v_fmac_f32_dpp v1, v149, v85 row_newbcast:5 row_mask:0xf bank_mask:0xf
	v_fmac_f32_dpp v2, v149, v86 row_newbcast:6 row_mask:0xf bank_mask:0xf
	v_fmac_f32_dpp v3, v149, v87 row_newbcast:7 row_mask:0xf bank_mask:0xf
	v_fmac_f32_dpp v0, v149, v88 row_newbcast:8 row_mask:0xf bank_mask:0xf
	v_fmac_f32_dpp v1, v149, v89 row_newbcast:9 row_mask:0xf bank_mask:0xf
	v_fmac_f32_dpp v2, v149, v90 row_newbcast:10 row_mask:0xf bank_mask:0xf
	v_fmac_f32_dpp v3, v149, v91 row_newbcast:11 row_mask:0xf bank_mask:0xf
	v_fmac_f32_dpp v0, v149, v92 row_newbcast:12 row_mask:0xf bank_mask:0xf
	v_fmac_f32_dpp v1, v149, v93 row_newbcast:13 row_mask:0xf bank_mask:0xf
	v_fmac_f32_dpp v2, v149, v94 row_newbcast:14 row_mask:0xf bank_mask:0xf
	v_fmac_f32_dpp v3, v149, v95 row_newbcast:15 row_mask:0xf bank_mask:0xf
	ds_read_b32 v161, v7 offset:12304
	s_waitcnt lgkmcnt(11)
	v_fmac_f32_dpp v0, v150, v96 row_newbcast:0 row_mask:0xf bank_mask:0xf
	v_fmac_f32_dpp v1, v150, v97 row_newbcast:1 row_mask:0xf bank_mask:0xf
	v_fmac_f32_dpp v2, v150, v98 row_newbcast:2 row_mask:0xf bank_mask:0xf
	v_fmac_f32_dpp v3, v150, v99 row_newbcast:3 row_mask:0xf bank_mask:0xf
	v_fmac_f32_dpp v0, v150, v100 row_newbcast:4 row_mask:0xf bank_mask:0xf
	v_fmac_f32_dpp v1, v150, v101 row_newbcast:5 row_mask:0xf bank_mask:0xf
	v_fmac_f32_dpp v2, v150, v102 row_newbcast:6 row_mask:0xf bank_mask:0xf
	v_fmac_f32_dpp v3, v150, v103 row_newbcast:7 row_mask:0xf bank_mask:0xf
	v_fmac_f32_dpp v0, v150, v104 row_newbcast:8 row_mask:0xf bank_mask:0xf
	ds_read_b32 v162, v7 offset:12368
	v_add_f32_e32 v0, v0, v1
	v_add_f32_e32 v2, v2, v3
	v_add_f32_e32 v0, v0, v2
	v_add_f32_e32 v105, v105, v0
	s_waitcnt lgkmcnt(11)
	v_mul_f32_dpp v0, v151, v64 row_newbcast:0 row_mask:0xf bank_mask:0xf
	v_mul_f32_dpp v1, v151, v65 row_newbcast:1 row_mask:0xf bank_mask:0xf
	v_mul_f32_dpp v2, v151, v66 row_newbcast:2 row_mask:0xf bank_mask:0xf
	v_mul_f32_dpp v3, v151, v67 row_newbcast:3 row_mask:0xf bank_mask:0xf
	v_fmac_f32_dpp v0, v151, v68 row_newbcast:4 row_mask:0xf bank_mask:0xf
	v_fmac_f32_dpp v1, v151, v69 row_newbcast:5 row_mask:0xf bank_mask:0xf
	v_fmac_f32_dpp v2, v151, v70 row_newbcast:6 row_mask:0xf bank_mask:0xf
	v_fmac_f32_dpp v3, v151, v71 row_newbcast:7 row_mask:0xf bank_mask:0xf
	v_fmac_f32_dpp v0, v151, v72 row_newbcast:8 row_mask:0xf bank_mask:0xf
	v_fmac_f32_dpp v1, v151, v73 row_newbcast:9 row_mask:0xf bank_mask:0xf
	v_fmac_f32_dpp v2, v151, v74 row_newbcast:10 row_mask:0xf bank_mask:0xf
	v_fmac_f32_dpp v3, v151, v75 row_newbcast:11 row_mask:0xf bank_mask:0xf
	v_fmac_f32_dpp v0, v151, v76 row_newbcast:12 row_mask:0xf bank_mask:0xf
	v_fmac_f32_dpp v1, v151, v77 row_newbcast:13 row_mask:0xf bank_mask:0xf
	v_fmac_f32_dpp v2, v151, v78 row_newbcast:14 row_mask:0xf bank_mask:0xf
	v_fmac_f32_dpp v3, v151, v79 row_newbcast:15 row_mask:0xf bank_mask:0xf
	ds_read_b32 v163, v7 offset:12512
	s_waitcnt lgkmcnt(11)
	v_fmac_f32_dpp v0, v152, v80 row_newbcast:0 row_mask:0xf bank_mask:0xf
	v_fmac_f32_dpp v1, v152, v81 row_newbcast:1 row_mask:0xf bank_mask:0xf
	v_fmac_f32_dpp v2, v152, v82 row_newbcast:2 row_mask:0xf bank_mask:0xf
	v_fmac_f32_dpp v3, v152, v83 row_newbcast:3 row_mask:0xf bank_mask:0xf
	v_fmac_f32_dpp v0, v152, v84 row_newbcast:4 row_mask:0xf bank_mask:0xf
	v_fmac_f32_dpp v1, v152, v85 row_newbcast:5 row_mask:0xf bank_mask:0xf
	v_fmac_f32_dpp v2, v152, v86 row_newbcast:6 row_mask:0xf bank_mask:0xf
	v_fmac_f32_dpp v3, v152, v87 row_newbcast:7 row_mask:0xf bank_mask:0xf
	v_fmac_f32_dpp v0, v152, v88 row_newbcast:8 row_mask:0xf bank_mask:0xf
	v_fmac_f32_dpp v1, v152, v89 row_newbcast:9 row_mask:0xf bank_mask:0xf
	v_fmac_f32_dpp v2, v152, v90 row_newbcast:10 row_mask:0xf bank_mask:0xf
	v_fmac_f32_dpp v3, v152, v91 row_newbcast:11 row_mask:0xf bank_mask:0xf
	v_fmac_f32_dpp v0, v152, v92 row_newbcast:12 row_mask:0xf bank_mask:0xf
	v_fmac_f32_dpp v1, v152, v93 row_newbcast:13 row_mask:0xf bank_mask:0xf
	v_fmac_f32_dpp v2, v152, v94 row_newbcast:14 row_mask:0xf bank_mask:0xf
	v_fmac_f32_dpp v3, v152, v95 row_newbcast:15 row_mask:0xf bank_mask:0xf
	ds_read_b32 v164, v7 offset:12576
	s_waitcnt lgkmcnt(11)
; #define LAS __attribute__((address_space(3)))
; __device__ __forceinline__ void rw_phaseA(LAS unsigned char* lds, const RwCtx& X, int item) {
;     ...
;         for (int tt = 1; tt < 64; ++tt) { float a = x[tt];
; #pragma unroll
;             for (int s4 = 0; s4 < (tt + 3) / 4; ++s4) { const f32x4 l4 = *(const LAS f32x4*)(LABv + tt * 68 + s4 * 4);
;                 a += l4[0] * x[s4 * 4]; if (s4 * 4 + 1 < tt) a += l4[1] * x[s4 * 4 + 1]; if (s4 * 4 + 2 < tt) a += l4[2] * x[s4 * 4 + 2]; if (s4 * 4 + 3 < tt) a += l4[3] * x[s4 * 4 + 3]; }
;             x[tt] = a;
	v_fmac_f32_dpp v0, v153, v96 row_newbcast:0 row_mask:0xf bank_mask:0xf
	v_fmac_f32_dpp v1, v153, v97 row_newbcast:1 row_mask:0xf bank_mask:0xf
	v_fmac_f32_dpp v2, v153, v98 row_newbcast:2 row_mask:0xf bank_mask:0xf
	v_fmac_f32_dpp v3, v153, v99 row_newbcast:3 row_mask:0xf bank_mask:0xf
	v_fmac_f32_dpp v0, v153, v100 row_newbcast:4 row_mask:0xf bank_mask:0xf
	v_fmac_f32_dpp v1, v153, v101 row_newbcast:5 row_mask:0xf bank_mask:0xf
	v_fmac_f32_dpp v2, v153, v102 row_newbcast:6 row_mask:0xf bank_mask:0xf
	v_fmac_f32_dpp v3, v153, v103 row_newbcast:7 row_mask:0xf bank_mask:0xf
	v_fmac_f32_dpp v0, v153, v104 row_newbcast:8 row_mask:0xf bank_mask:0xf
	v_fmac_f32_dpp v1, v153, v105 row_newbcast:9 row_mask:0xf bank_mask:0xf
	ds_read_b32 v165, v7 offset:12640
	v_add_f32_e32 v0, v0, v1
	v_add_f32_e32 v2, v2, v3
	v_add_f32_e32 v0, v0, v2
	v_add_f32_e32 v106, v106, v0
	s_waitcnt lgkmcnt(11)
	v_mul_f32_dpp v0, v154, v64 row_newbcast:0 row_mask:0xf bank_mask:0xf
	v_mul_f32_dpp v1, v154, v65 row_newbcast:1 row_mask:0xf bank_mask:0xf
	v_mul_f32_dpp v2, v154, v66 row_newbcast:2 row_mask:0xf bank_mask:0xf
	v_mul_f32_dpp v3, v154, v67 row_newbcast:3 row_mask:0xf bank_mask:0xf
	v_fmac_f32_dpp v0, v154, v68 row_newbcast:4 row_mask:0xf bank_mask:0xf
	v_fmac_f32_dpp v1, v154, v69 row_newbcast:5 row_mask:0xf bank_mask:0xf
	v_fmac_f32_dpp v2, v154, v70 row_newbcast:6 row_mask:0xf bank_mask:0xf
	v_fmac_f32_dpp v3, v154, v71 row_newbcast:7 row_mask:0xf bank_mask:0xf
	v_fmac_f32_dpp v0, v154, v72 row_newbcast:8 row_mask:0xf bank_mask:0xf
	v_fmac_f32_dpp v1, v154, v73 row_newbcast:9 row_mask:0xf bank_mask:0xf
	v_fmac_f32_dpp v2, v154, v74 row_newbcast:10 row_mask:0xf bank_mask:0xf
	v_fmac_f32_dpp v3, v154, v75 row_newbcast:11 row_mask:0xf bank_mask:0xf
	v_fmac_f32_dpp v0, v154, v76 row_newbcast:12 row_mask:0xf bank_mask:0xf
	v_fmac_f32_dpp v1, v154, v77 row_newbcast:13 row_mask:0xf bank_mask:0xf
	v_fmac_f32_dpp v2, v154, v78 row_newbcast:14 row_mask:0xf bank_mask:0xf
	v_fmac_f32_dpp v3, v154, v79 row_newbcast:15 row_mask:0xf bank_mask:0xf
	ds_read_b32 v166, v7 offset:12784
	s_waitcnt lgkmcnt(11)
	v_fmac_f32_dpp v0, v155, v80 row_newbcast:0 row_mask:0xf bank_mask:0xf
	v_fmac_f32_dpp v1, v155, v81 row_newbcast:1 row_mask:0xf bank_mask:0xf
	v_fmac_f32_dpp v2, v155, v82 row_newbcast:2 row_mask:0xf bank_mask:0xf
	v_fmac_f32_dpp v3, v155, v83 row_newbcast:3 row_mask:0xf bank_mask:0xf
	v_fmac_f32_dpp v0, v155, v84 row_newbcast:4 row_mask:0xf bank_mask:0xf
	v_fmac_f32_dpp v1, v155, v85 row_newbcast:5 row_mask:0xf bank_mask:0xf
	v_fmac_f32_dpp v2, v155, v86 row_newbcast:6 row_mask:0xf bank_mask:0xf
	v_fmac_f32_dpp v3, v155, v87 row_newbcast:7 row_mask:0xf bank_mask:0xf
	v_fmac_f32_dpp v0, v155, v88 row_newbcast:8 row_mask:0xf bank_mask:0xf
	v_fmac_f32_dpp v1, v155, v89 row_newbcast:9 row_mask:0xf bank_mask:0xf
	v_fmac_f32_dpp v2, v155, v90 row_newbcast:10 row_mask:0xf bank_mask:0xf
	v_fmac_f32_dpp v3, v155, v91 row_newbcast:11 row_mask:0xf bank_mask:0xf
	v_fmac_f32_dpp v0, v155, v92 row_newbcast:12 row_mask:0xf bank_mask:0xf
	v_fmac_f32_dpp v1, v155, v93 row_newbcast:13 row_mask:0xf bank_mask:0xf
	v_fmac_f32_dpp v2, v155, v94 row_newbcast:14 row_mask:0xf bank_mask:0xf
	v_fmac_f32_dpp v3, v155, v95 row_newbcast:15 row_mask:0xf bank_mask:0xf
	ds_read_b32 v167, v7 offset:12848
	s_waitcnt lgkmcnt(11)
	v_fmac_f32_dpp v0, v156, v96 row_newbcast:0 row_mask:0xf bank_mask:0xf
	v_fmac_f32_dpp v1, v156, v97 row_newbcast:1 row_mask:0xf bank_mask:0xf
	v_fmac_f32_dpp v2, v156, v98 row_newbcast:2 row_mask:0xf bank_mask:0xf
	v_fmac_f32_dpp v3, v156, v99 row_newbcast:3 row_mask:0xf bank_mask:0xf
	v_fmac_f32_dpp v0, v156, v100 row_newbcast:4 row_mask:0xf bank_mask:0xf
	v_fmac_f32_dpp v1, v156, v101 row_newbcast:5 row_mask:0xf bank_mask:0xf
	v_fmac_f32_dpp v2, v156, v102 row_newbcast:6 row_mask:0xf bank_mask:0xf
	v_fmac_f32_dpp v3, v156, v103 row_newbcast:7 row_mask:0xf bank_mask:0xf
	v_fmac_f32_dpp v0, v156, v104 row_newbcast:8 row_mask:0xf bank_mask:0xf
	v_fmac_f32_dpp v1, v156, v105 row_newbcast:9 row_mask:0xf bank_mask:0xf
	v_fmac_f32_dpp v2, v156, v106 row_newbcast:10 row_mask:0xf bank_mask:0xf
	ds_read_b32 v168, v7 offset:12912
	v_add_f32_e32 v0, v0, v1
	v_add_f32_e32 v2, v2, v3
	v_add_f32_e32 v0, v0, v2
	v_add_f32_e32 v107, v107, v0
	s_waitcnt lgkmcnt(11)
	v_mul_f32_dpp v0, v157, v64 row_newbcast:0 row_mask:0xf bank_mask:0xf
	v_mul_f32_dpp v1, v157, v65 row_newbcast:1 row_mask:0xf bank_mask:0xf
	v_mul_f32_dpp v2, v157, v66 row_newbcast:2 row_mask:0xf bank_mask:0xf
	v_mul_f32_dpp v3, v157, v67 row_newbcast:3 row_mask:0xf bank_mask:0xf
	v_fmac_f32_dpp v0, v157, v68 row_newbcast:4 row_mask:0xf bank_mask:0xf
	v_fmac_f32_dpp v1, v157, v69 row_newbcast:5 row_mask:0xf bank_mask:0xf
	v_fmac_f32_dpp v2, v157, v70 row_newbcast:6 row_mask:0xf bank_mask:0xf
	v_fmac_f32_dpp v3, v157, v71 row_newbcast:7 row_mask:0xf bank_mask:0xf
	v_fmac_f32_dpp v0, v157, v72 row_newbcast:8 row_mask:0xf bank_mask:0xf
	v_fmac_f32_dpp v1, v157, v73 row_newbcast:9 row_mask:0xf bank_mask:0xf
	v_fmac_f32_dpp v2, v157, v74 row_newbcast:10 row_mask:0xf bank_mask:0xf
	v_fmac_f32_dpp v3, v157, v75 row_newbcast:11 row_mask:0xf bank_mask:0xf
	v_fmac_f32_dpp v0, v157, v76 row_newbcast:12 row_mask:0xf bank_mask:0xf
	v_fmac_f32_dpp v1, v157, v77 row_newbcast:13 row_mask:0xf bank_mask:0xf
	v_fmac_f32_dpp v2, v157, v78 row_newbcast:14 row_mask:0xf bank_mask:0xf
	v_fmac_f32_dpp v3, v157, v79 row_newbcast:15 row_mask:0xf bank_mask:0xf
	ds_read_b32 v169, v7 offset:13056
	s_waitcnt lgkmcnt(11)
; #define LAS __attribute__((address_space(3)))
; __device__ __forceinline__ void rw_phaseA(LAS unsigned char* lds, const RwCtx& X, int item) {
;     ...
;         for (int tt = 1; tt < 64; ++tt) { float a = x[tt];
; #pragma unroll
;             for (int s4 = 0; s4 < (tt + 3) / 4; ++s4) { const f32x4 l4 = *(const LAS f32x4*)(LABv + tt * 68 + s4 * 4);
;                 a += l4[0] * x[s4 * 4]; if (s4 * 4 + 1 < tt) a += l4[1] * x[s4 * 4 + 1]; if (s4 * 4 + 2 < tt) a += l4[2] * x[s4 * 4 + 2]; if (s4 * 4 + 3 < tt) a += l4[3] * x[s4 * 4 + 3]; }
;             x[tt] = a;
	v_fmac_f32_dpp v0, v158, v80 row_newbcast:0 row_mask:0xf bank_mask:0xf
	v_fmac_f32_dpp v1, v158, v81 row_newbcast:1 row_mask:0xf bank_mask:0xf
	v_fmac_f32_dpp v2, v158, v82 row_newbcast:2 row_mask:0xf bank_mask:0xf
	v_fmac_f32_dpp v3, v158, v83 row_newbcast:3 row_mask:0xf bank_mask:0xf
	v_fmac_f32_dpp v0, v158, v84 row_newbcast:4 row_mask:0xf bank_mask:0xf
	v_fmac_f32_dpp v1, v158, v85 row_newbcast:5 row_mask:0xf bank_mask:0xf
	v_fmac_f32_dpp v2, v158, v86 row_newbcast:6 row_mask:0xf bank_mask:0xf
	v_fmac_f32_dpp v3, v158, v87 row_newbcast:7 row_mask:0xf bank_mask:0xf
	v_fmac_f32_dpp v0, v158, v88 row_newbcast:8 row_mask:0xf bank_mask:0xf
	v_fmac_f32_dpp v1, v158, v89 row_newbcast:9 row_mask:0xf bank_mask:0xf
	v_fmac_f32_dpp v2, v158, v90 row_newbcast:10 row_mask:0xf bank_mask:0xf
	v_fmac_f32_dpp v3, v158, v91 row_newbcast:11 row_mask:0xf bank_mask:0xf
	v_fmac_f32_dpp v0, v158, v92 row_newbcast:12 row_mask:0xf bank_mask:0xf
	v_fmac_f32_dpp v1, v158, v93 row_newbcast:13 row_mask:0xf bank_mask:0xf
	v_fmac_f32_dpp v2, v158, v94 row_newbcast:14 row_mask:0xf bank_mask:0xf
	v_fmac_f32_dpp v3, v158, v95 row_newbcast:15 row_mask:0xf bank_mask:0xf
	ds_read_b32 v170, v7 offset:13120
	s_waitcnt lgkmcnt(11)
	v_fmac_f32_dpp v0, v159, v96 row_newbcast:0 row_mask:0xf bank_mask:0xf
	v_fmac_f32_dpp v1, v159, v97 row_newbcast:1 row_mask:0xf bank_mask:0xf
	v_fmac_f32_dpp v2, v159, v98 row_newbcast:2 row_mask:0xf bank_mask:0xf
	v_fmac_f32_dpp v3, v159, v99 row_newbcast:3 row_mask:0xf bank_mask:0xf
	v_fmac_f32_dpp v0, v159, v100 row_newbcast:4 row_mask:0xf bank_mask:0xf
	v_fmac_f32_dpp v1, v159, v101 row_newbcast:5 row_mask:0xf bank_mask:0xf
	v_fmac_f32_dpp v2, v159, v102 row_newbcast:6 row_mask:0xf bank_mask:0xf
	v_fmac_f32_dpp v3, v159, v103 row_newbcast:7 row_mask:0xf bank_mask:0xf
	v_fmac_f32_dpp v0, v159, v104 row_newbcast:8 row_mask:0xf bank_mask:0xf
	v_fmac_f32_dpp v1, v159, v105 row_newbcast:9 row_mask:0xf bank_mask:0xf
	v_fmac_f32_dpp v2, v159, v106 row_newbcast:10 row_mask:0xf bank_mask:0xf
	v_fmac_f32_dpp v3, v159, v107 row_newbcast:11 row_mask:0xf bank_mask:0xf
	ds_read_b32 v171, v7 offset:13184
	v_add_f32_e32 v0, v0, v1
	v_add_f32_e32 v2, v2, v3
	v_add_f32_e32 v0, v0, v2
	v_add_f32_e32 v108, v108, v0
	s_waitcnt lgkmcnt(11)
	v_mul_f32_dpp v0, v160, v64 row_newbcast:0 row_mask:0xf bank_mask:0xf
	v_mul_f32_dpp v1, v160, v65 row_newbcast:1 row_mask:0xf bank_mask:0xf
	v_mul_f32_dpp v2, v160, v66 row_newbcast:2 row_mask:0xf bank_mask:0xf
	v_mul_f32_dpp v3, v160, v67 row_newbcast:3 row_mask:0xf bank_mask:0xf
	v_fmac_f32_dpp v0, v160, v68 row_newbcast:4 row_mask:0xf bank_mask:0xf
	v_fmac_f32_dpp v1, v160, v69 row_newbcast:5 row_mask:0xf bank_mask:0xf
	v_fmac_f32_dpp v2, v160, v70 row_newbcast:6 row_mask:0xf bank_mask:0xf
	v_fmac_f32_dpp v3, v160, v71 row_newbcast:7 row_mask:0xf bank_mask:0xf
	v_fmac_f32_dpp v0, v160, v72 row_newbcast:8 row_mask:0xf bank_mask:0xf
	v_fmac_f32_dpp v1, v160, v73 row_newbcast:9 row_mask:0xf bank_mask:0xf
	v_fmac_f32_dpp v2, v160, v74 row_newbcast:10 row_mask:0xf bank_mask:0xf
	v_fmac_f32_dpp v3, v160, v75 row_newbcast:11 row_mask:0xf bank_mask:0xf
	v_fmac_f32_dpp v0, v160, v76 row_newbcast:12 row_mask:0xf bank_mask:0xf
	v_fmac_f32_dpp v1, v160, v77 row_newbcast:13 row_mask:0xf bank_mask:0xf
	v_fmac_f32_dpp v2, v160, v78 row_newbcast:14 row_mask:0xf bank_mask:0xf
	v_fmac_f32_dpp v3, v160, v79 row_newbcast:15 row_mask:0xf bank_mask:0xf
	ds_read_b32 v148, v7 offset:13328
	s_waitcnt lgkmcnt(11)
	v_fmac_f32_dpp v0, v161, v80 row_newbcast:0 row_mask:0xf bank_mask:0xf
	v_fmac_f32_dpp v1, v161, v81 row_newbcast:1 row_mask:0xf bank_mask:0xf
	v_fmac_f32_dpp v2, v161, v82 row_newbcast:2 row_mask:0xf bank_mask:0xf
	v_fmac_f32_dpp v3, v161, v83 row_newbcast:3 row_mask:0xf bank_mask:0xf
	v_fmac_f32_dpp v0, v161, v84 row_newbcast:4 row_mask:0xf bank_mask:0xf
	v_fmac_f32_dpp v1, v161, v85 row_newbcast:5 row_mask:0xf bank_mask:0xf
	v_fmac_f32_dpp v2, v161, v86 row_newbcast:6 row_mask:0xf bank_mask:0xf
	v_fmac_f32_dpp v3, v161, v87 row_newbcast:7 row_mask:0xf bank_mask:0xf
	v_fmac_f32_dpp v0, v161, v88 row_newbcast:8 row_mask:0xf bank_mask:0xf
	v_fmac_f32_dpp v1, v161, v89 row_newbcast:9 row_mask:0xf bank_mask:0xf
	v_fmac_f32_dpp v2, v161, v90 row_newbcast:10 row_mask:0xf bank_mask:0xf
	v_fmac_f32_dpp v3, v161, v91 row_newbcast:11 row_mask:0xf bank_mask:0xf
	v_fmac_f32_dpp v0, v161, v92 row_newbcast:12 row_mask:0xf bank_mask:0xf
	v_fmac_f32_dpp v1, v161, v93 row_newbcast:13 row_mask:0xf bank_mask:0xf
	v_fmac_f32_dpp v2, v161, v94 row_newbcast:14 row_mask:0xf bank_mask:0xf
	v_fmac_f32_dpp v3, v161, v95 row_newbcast:15 row_mask:0xf bank_mask:0xf
	ds_read_b32 v149, v7 offset:13392
	s_waitcnt lgkmcnt(11)
	v_fmac_f32_dpp v0, v162, v96 row_newbcast:0 row_mask:0xf bank_mask:0xf
	v_fmac_f32_dpp v1, v162, v97 row_newbcast:1 row_mask:0xf bank_mask:0xf
	v_fmac_f32_dpp v2, v162, v98 row_newbcast:2 row_mask:0xf bank_mask:0xf
	v_fmac_f32_dpp v3, v162, v99 row_newbcast:3 row_mask:0xf bank_mask:0xf
	v_fmac_f32_dpp v0, v162, v100 row_newbcast:4 row_mask:0xf bank_mask:0xf
	v_fmac_f32_dpp v1, v162, v101 row_newbcast:5 row_mask:0xf bank_mask:0xf
	v_fmac_f32_dpp v2, v162, v102 row_newbcast:6 row_mask:0xf bank_mask:0xf
	v_fmac_f32_dpp v3, v162, v103 row_newbcast:7 row_mask:0xf bank_mask:0xf
	v_fmac_f32_dpp v0, v162, v104 row_newbcast:8 row_mask:0xf bank_mask:0xf
	v_fmac_f32_dpp v1, v162, v105 row_newbcast:9 row_mask:0xf bank_mask:0xf
	v_fmac_f32_dpp v2, v162, v106 row_newbcast:10 row_mask:0xf bank_mask:0xf
	v_fmac_f32_dpp v3, v162, v107 row_newbcast:11 row_mask:0xf bank_mask:0xf
	v_fmac_f32_dpp v0, v162, v108 row_newbcast:12 row_mask:0xf bank_mask:0xf
	ds_read_b32 v150, v7 offset:13456
	v_add_f32_e32 v0, v0, v1
	v_add_f32_e32 v2, v2, v3
	v_add_f32_e32 v0, v0, v2
	v_add_f32_e32 v109, v109, v0
	s_waitcnt lgkmcnt(11)
; #define LAS __attribute__((address_space(3)))
; __device__ __forceinline__ void rw_phaseA(LAS unsigned char* lds, const RwCtx& X, int item) {
;     ...
;         for (int tt = 1; tt < 64; ++tt) { float a = x[tt];
; #pragma unroll
;             for (int s4 = 0; s4 < (tt + 3) / 4; ++s4) { const f32x4 l4 = *(const LAS f32x4*)(LABv + tt * 68 + s4 * 4);
;                 a += l4[0] * x[s4 * 4]; if (s4 * 4 + 1 < tt) a += l4[1] * x[s4 * 4 + 1]; if (s4 * 4 + 2 < tt) a += l4[2] * x[s4 * 4 + 2]; if (s4 * 4 + 3 < tt) a += l4[3] * x[s4 * 4 + 3]; }
;             x[tt] = a;
	v_mul_f32_dpp v0, v163, v64 row_newbcast:0 row_mask:0xf bank_mask:0xf
	v_mul_f32_dpp v1, v163, v65 row_newbcast:1 row_mask:0xf bank_mask:0xf
	v_mul_f32_dpp v2, v163, v66 row_newbcast:2 row_mask:0xf bank_mask:0xf
	v_mul_f32_dpp v3, v163, v67 row_newbcast:3 row_mask:0xf bank_mask:0xf
	v_fmac_f32_dpp v0, v163, v68 row_newbcast:4 row_mask:0xf bank_mask:0xf
	v_fmac_f32_dpp v1, v163, v69 row_newbcast:5 row_mask:0xf bank_mask:0xf
	v_fmac_f32_dpp v2, v163, v70 row_newbcast:6 row_mask:0xf bank_mask:0xf
	v_fmac_f32_dpp v3, v163, v71 row_newbcast:7 row_mask:0xf bank_mask:0xf
	v_fmac_f32_dpp v0, v163, v72 row_newbcast:8 row_mask:0xf bank_mask:0xf
	v_fmac_f32_dpp v1, v163, v73 row_newbcast:9 row_mask:0xf bank_mask:0xf
	v_fmac_f32_dpp v2, v163, v74 row_newbcast:10 row_mask:0xf bank_mask:0xf
	v_fmac_f32_dpp v3, v163, v75 row_newbcast:11 row_mask:0xf bank_mask:0xf
	v_fmac_f32_dpp v0, v163, v76 row_newbcast:12 row_mask:0xf bank_mask:0xf
	v_fmac_f32_dpp v1, v163, v77 row_newbcast:13 row_mask:0xf bank_mask:0xf
	v_fmac_f32_dpp v2, v163, v78 row_newbcast:14 row_mask:0xf bank_mask:0xf
	v_fmac_f32_dpp v3, v163, v79 row_newbcast:15 row_mask:0xf bank_mask:0xf
	ds_read_b32 v151, v7 offset:13520
	s_waitcnt lgkmcnt(11)
	v_fmac_f32_dpp v0, v164, v80 row_newbcast:0 row_mask:0xf bank_mask:0xf
	v_fmac_f32_dpp v1, v164, v81 row_newbcast:1 row_mask:0xf bank_mask:0xf
	v_fmac_f32_dpp v2, v164, v82 row_newbcast:2 row_mask:0xf bank_mask:0xf
	v_fmac_f32_dpp v3, v164, v83 row_newbcast:3 row_mask:0xf bank_mask:0xf
	v_fmac_f32_dpp v0, v164, v84 row_newbcast:4 row_mask:0xf bank_mask:0xf
	v_fmac_f32_dpp v1, v164, v85 row_newbcast:5 row_mask:0xf bank_mask:0xf
	v_fmac_f32_dpp v2, v164, v86 row_newbcast:6 row_mask:0xf bank_mask:0xf
	v_fmac_f32_dpp v3, v164, v87 row_newbcast:7 row_mask:0xf bank_mask:0xf
	v_fmac_f32_dpp v0, v164, v88 row_newbcast:8 row_mask:0xf bank_mask:0xf
	v_fmac_f32_dpp v1, v164, v89 row_newbcast:9 row_mask:0xf bank_mask:0xf
	v_fmac_f32_dpp v2, v164, v90 row_newbcast:10 row_mask:0xf bank_mask:0xf
	v_fmac_f32_dpp v3, v164, v91 row_newbcast:11 row_mask:0xf bank_mask:0xf
	v_fmac_f32_dpp v0, v164, v92 row_newbcast:12 row_mask:0xf bank_mask:0xf
	v_fmac_f32_dpp v1, v164, v93 row_newbcast:13 row_mask:0xf bank_mask:0xf
	v_fmac_f32_dpp v2, v164, v94 row_newbcast:14 row_mask:0xf bank_mask:0xf
	v_fmac_f32_dpp v3, v164, v95 row_newbcast:15 row_mask:0xf bank_mask:0xf
	ds_read_b32 v152, v7 offset:13600
	s_waitcnt lgkmcnt(11)
	v_fmac_f32_dpp v0, v165, v96 row_newbcast:0 row_mask:0xf bank_mask:0xf
	v_fmac_f32_dpp v1, v165, v97 row_newbcast:1 row_mask:0xf bank_mask:0xf
	v_fmac_f32_dpp v2, v165, v98 row_newbcast:2 row_mask:0xf bank_mask:0xf
	v_fmac_f32_dpp v3, v165, v99 row_newbcast:3 row_mask:0xf bank_mask:0xf
	v_fmac_f32_dpp v0, v165, v100 row_newbcast:4 row_mask:0xf bank_mask:0xf
	v_fmac_f32_dpp v1, v165, v101 row_newbcast:5 row_mask:0xf bank_mask:0xf
	v_fmac_f32_dpp v2, v165, v102 row_newbcast:6 row_mask:0xf bank_mask:0xf
	v_fmac_f32_dpp v3, v165, v103 row_newbcast:7 row_mask:0xf bank_mask:0xf
	v_fmac_f32_dpp v0, v165, v104 row_newbcast:8 row_mask:0xf bank_mask:0xf
	v_fmac_f32_dpp v1, v165, v105 row_newbcast:9 row_mask:0xf bank_mask:0xf
	v_fmac_f32_dpp v2, v165, v106 row_newbcast:10 row_mask:0xf bank_mask:0xf
	v_fmac_f32_dpp v3, v165, v107 row_newbcast:11 row_mask:0xf bank_mask:0xf
	v_fmac_f32_dpp v0, v165, v108 row_newbcast:12 row_mask:0xf bank_mask:0xf
	v_fmac_f32_dpp v1, v165, v109 row_newbcast:13 row_mask:0xf bank_mask:0xf
	ds_read_b32 v153, v7 offset:13664
	v_add_f32_e32 v0, v0, v1
	v_add_f32_e32 v2, v2, v3
	v_add_f32_e32 v0, v0, v2
	v_add_f32_e32 v110, v110, v0
	s_waitcnt lgkmcnt(11)
	v_mul_f32_dpp v0, v166, v64 row_newbcast:0 row_mask:0xf bank_mask:0xf
	v_mul_f32_dpp v1, v166, v65 row_newbcast:1 row_mask:0xf bank_mask:0xf
	v_mul_f32_dpp v2, v166, v66 row_newbcast:2 row_mask:0xf bank_mask:0xf
	v_mul_f32_dpp v3, v166, v67 row_newbcast:3 row_mask:0xf bank_mask:0xf
	v_fmac_f32_dpp v0, v166, v68 row_newbcast:4 row_mask:0xf bank_mask:0xf
	v_fmac_f32_dpp v1, v166, v69 row_newbcast:5 row_mask:0xf bank_mask:0xf
	v_fmac_f32_dpp v2, v166, v70 row_newbcast:6 row_mask:0xf bank_mask:0xf
	v_fmac_f32_dpp v3, v166, v71 row_newbcast:7 row_mask:0xf bank_mask:0xf
	v_fmac_f32_dpp v0, v166, v72 row_newbcast:8 row_mask:0xf bank_mask:0xf
	v_fmac_f32_dpp v1, v166, v73 row_newbcast:9 row_mask:0xf bank_mask:0xf
	v_fmac_f32_dpp v2, v166, v74 row_newbcast:10 row_mask:0xf bank_mask:0xf
	v_fmac_f32_dpp v3, v166, v75 row_newbcast:11 row_mask:0xf bank_mask:0xf
	v_fmac_f32_dpp v0, v166, v76 row_newbcast:12 row_mask:0xf bank_mask:0xf
	v_fmac_f32_dpp v1, v166, v77 row_newbcast:13 row_mask:0xf bank_mask:0xf
	v_fmac_f32_dpp v2, v166, v78 row_newbcast:14 row_mask:0xf bank_mask:0xf
	v_fmac_f32_dpp v3, v166, v79 row_newbcast:15 row_mask:0xf bank_mask:0xf
	ds_read_b32 v154, v7 offset:13728
	s_waitcnt lgkmcnt(11)
	v_fmac_f32_dpp v0, v167, v80 row_newbcast:0 row_mask:0xf bank_mask:0xf
	v_fmac_f32_dpp v1, v167, v81 row_newbcast:1 row_mask:0xf bank_mask:0xf
	v_fmac_f32_dpp v2, v167, v82 row_newbcast:2 row_mask:0xf bank_mask:0xf
	v_fmac_f32_dpp v3, v167, v83 row_newbcast:3 row_mask:0xf bank_mask:0xf
	v_fmac_f32_dpp v0, v167, v84 row_newbcast:4 row_mask:0xf bank_mask:0xf
	v_fmac_f32_dpp v1, v167, v85 row_newbcast:5 row_mask:0xf bank_mask:0xf
	v_fmac_f32_dpp v2, v167, v86 row_newbcast:6 row_mask:0xf bank_mask:0xf
	v_fmac_f32_dpp v3, v167, v87 row_newbcast:7 row_mask:0xf bank_mask:0xf
	v_fmac_f32_dpp v0, v167, v88 row_newbcast:8 row_mask:0xf bank_mask:0xf
	v_fmac_f32_dpp v1, v167, v89 row_newbcast:9 row_mask:0xf bank_mask:0xf
	v_fmac_f32_dpp v2, v167, v90 row_newbcast:10 row_mask:0xf bank_mask:0xf
	v_fmac_f32_dpp v3, v167, v91 row_newbcast:11 row_mask:0xf bank_mask:0xf
	v_fmac_f32_dpp v0, v167, v92 row_newbcast:12 row_mask:0xf bank_mask:0xf
	v_fmac_f32_dpp v1, v167, v93 row_newbcast:13 row_mask:0xf bank_mask:0xf
	v_fmac_f32_dpp v2, v167, v94 row_newbcast:14 row_mask:0xf bank_mask:0xf
	v_fmac_f32_dpp v3, v167, v95 row_newbcast:15 row_mask:0xf bank_mask:0xf
	ds_read_b32 v155, v7 offset:13792
	s_waitcnt lgkmcnt(11)
; #define LAS __attribute__((address_space(3)))
; __device__ __forceinline__ void rw_phaseA(LAS unsigned char* lds, const RwCtx& X, int item) {
;     ...
;         for (int tt = 1; tt < 64; ++tt) { float a = x[tt];
; #pragma unroll
;             for (int s4 = 0; s4 < (tt + 3) / 4; ++s4) { const f32x4 l4 = *(const LAS f32x4*)(LABv + tt * 68 + s4 * 4);
;                 a += l4[0] * x[s4 * 4]; if (s4 * 4 + 1 < tt) a += l4[1] * x[s4 * 4 + 1]; if (s4 * 4 + 2 < tt) a += l4[2] * x[s4 * 4 + 2]; if (s4 * 4 + 3 < tt) a += l4[3] * x[s4 * 4 + 3]; }
;             x[tt] = a;
	v_fmac_f32_dpp v0, v168, v96 row_newbcast:0 row_mask:0xf bank_mask:0xf
	v_fmac_f32_dpp v1, v168, v97 row_newbcast:1 row_mask:0xf bank_mask:0xf
	v_fmac_f32_dpp v2, v168, v98 row_newbcast:2 row_mask:0xf bank_mask:0xf
	v_fmac_f32_dpp v3, v168, v99 row_newbcast:3 row_mask:0xf bank_mask:0xf
	v_fmac_f32_dpp v0, v168, v100 row_newbcast:4 row_mask:0xf bank_mask:0xf
	v_fmac_f32_dpp v1, v168, v101 row_newbcast:5 row_mask:0xf bank_mask:0xf
	v_fmac_f32_dpp v2, v168, v102 row_newbcast:6 row_mask:0xf bank_mask:0xf
	v_fmac_f32_dpp v3, v168, v103 row_newbcast:7 row_mask:0xf bank_mask:0xf
	v_fmac_f32_dpp v0, v168, v104 row_newbcast:8 row_mask:0xf bank_mask:0xf
	v_fmac_f32_dpp v1, v168, v105 row_newbcast:9 row_mask:0xf bank_mask:0xf
	v_fmac_f32_dpp v2, v168, v106 row_newbcast:10 row_mask:0xf bank_mask:0xf
	v_fmac_f32_dpp v3, v168, v107 row_newbcast:11 row_mask:0xf bank_mask:0xf
	v_fmac_f32_dpp v0, v168, v108 row_newbcast:12 row_mask:0xf bank_mask:0xf
	v_fmac_f32_dpp v1, v168, v109 row_newbcast:13 row_mask:0xf bank_mask:0xf
	v_fmac_f32_dpp v2, v168, v110 row_newbcast:14 row_mask:0xf bank_mask:0xf
	ds_read_b32 v156, v7 offset:13872
	v_add_f32_e32 v0, v0, v1
	v_add_f32_e32 v2, v2, v3
	v_add_f32_e32 v0, v0, v2
	v_add_f32_e32 v111, v111, v0
	s_waitcnt lgkmcnt(11)
	v_mul_f32_dpp v0, v169, v64 row_newbcast:0 row_mask:0xf bank_mask:0xf
	v_mul_f32_dpp v1, v169, v65 row_newbcast:1 row_mask:0xf bank_mask:0xf
	v_mul_f32_dpp v2, v169, v66 row_newbcast:2 row_mask:0xf bank_mask:0xf
	v_mul_f32_dpp v3, v169, v67 row_newbcast:3 row_mask:0xf bank_mask:0xf
	v_fmac_f32_dpp v0, v169, v68 row_newbcast:4 row_mask:0xf bank_mask:0xf
	v_fmac_f32_dpp v1, v169, v69 row_newbcast:5 row_mask:0xf bank_mask:0xf
	v_fmac_f32_dpp v2, v169, v70 row_newbcast:6 row_mask:0xf bank_mask:0xf
	v_fmac_f32_dpp v3, v169, v71 row_newbcast:7 row_mask:0xf bank_mask:0xf
	v_fmac_f32_dpp v0, v169, v72 row_newbcast:8 row_mask:0xf bank_mask:0xf
	v_fmac_f32_dpp v1, v169, v73 row_newbcast:9 row_mask:0xf bank_mask:0xf
	v_fmac_f32_dpp v2, v169, v74 row_newbcast:10 row_mask:0xf bank_mask:0xf
	v_fmac_f32_dpp v3, v169, v75 row_newbcast:11 row_mask:0xf bank_mask:0xf
	v_fmac_f32_dpp v0, v169, v76 row_newbcast:12 row_mask:0xf bank_mask:0xf
	v_fmac_f32_dpp v1, v169, v77 row_newbcast:13 row_mask:0xf bank_mask:0xf
	v_fmac_f32_dpp v2, v169, v78 row_newbcast:14 row_mask:0xf bank_mask:0xf
	v_fmac_f32_dpp v3, v169, v79 row_newbcast:15 row_mask:0xf bank_mask:0xf
	ds_read_b32 v157, v7 offset:13936
	s_waitcnt lgkmcnt(11)
	v_fmac_f32_dpp v0, v170, v80 row_newbcast:0 row_mask:0xf bank_mask:0xf
	v_fmac_f32_dpp v1, v170, v81 row_newbcast:1 row_mask:0xf bank_mask:0xf
	v_fmac_f32_dpp v2, v170, v82 row_newbcast:2 row_mask:0xf bank_mask:0xf
	v_fmac_f32_dpp v3, v170, v83 row_newbcast:3 row_mask:0xf bank_mask:0xf
	v_fmac_f32_dpp v0, v170, v84 row_newbcast:4 row_mask:0xf bank_mask:0xf
	v_fmac_f32_dpp v1, v170, v85 row_newbcast:5 row_mask:0xf bank_mask:0xf
	v_fmac_f32_dpp v2, v170, v86 row_newbcast:6 row_mask:0xf bank_mask:0xf
	v_fmac_f32_dpp v3, v170, v87 row_newbcast:7 row_mask:0xf bank_mask:0xf
	v_fmac_f32_dpp v0, v170, v88 row_newbcast:8 row_mask:0xf bank_mask:0xf
	v_fmac_f32_dpp v1, v170, v89 row_newbcast:9 row_mask:0xf bank_mask:0xf
	v_fmac_f32_dpp v2, v170, v90 row_newbcast:10 row_mask:0xf bank_mask:0xf
	v_fmac_f32_dpp v3, v170, v91 row_newbcast:11 row_mask:0xf bank_mask:0xf
	v_fmac_f32_dpp v0, v170, v92 row_newbcast:12 row_mask:0xf bank_mask:0xf
	v_fmac_f32_dpp v1, v170, v93 row_newbcast:13 row_mask:0xf bank_mask:0xf
	v_fmac_f32_dpp v2, v170, v94 row_newbcast:14 row_mask:0xf bank_mask:0xf
	v_fmac_f32_dpp v3, v170, v95 row_newbcast:15 row_mask:0xf bank_mask:0xf
	ds_read_b32 v158, v7 offset:14000
	s_waitcnt lgkmcnt(11)
	v_fmac_f32_dpp v0, v171, v96 row_newbcast:0 row_mask:0xf bank_mask:0xf
	v_fmac_f32_dpp v1, v171, v97 row_newbcast:1 row_mask:0xf bank_mask:0xf
	v_fmac_f32_dpp v2, v171, v98 row_newbcast:2 row_mask:0xf bank_mask:0xf
	v_fmac_f32_dpp v3, v171, v99 row_newbcast:3 row_mask:0xf bank_mask:0xf
	v_fmac_f32_dpp v0, v171, v100 row_newbcast:4 row_mask:0xf bank_mask:0xf
	v_fmac_f32_dpp v1, v171, v101 row_newbcast:5 row_mask:0xf bank_mask:0xf
	v_fmac_f32_dpp v2, v171, v102 row_newbcast:6 row_mask:0xf bank_mask:0xf
	v_fmac_f32_dpp v3, v171, v103 row_newbcast:7 row_mask:0xf bank_mask:0xf
	v_fmac_f32_dpp v0, v171, v104 row_newbcast:8 row_mask:0xf bank_mask:0xf
	v_fmac_f32_dpp v1, v171, v105 row_newbcast:9 row_mask:0xf bank_mask:0xf
	v_fmac_f32_dpp v2, v171, v106 row_newbcast:10 row_mask:0xf bank_mask:0xf
	v_fmac_f32_dpp v3, v171, v107 row_newbcast:11 row_mask:0xf bank_mask:0xf
	v_fmac_f32_dpp v0, v171, v108 row_newbcast:12 row_mask:0xf bank_mask:0xf
	v_fmac_f32_dpp v1, v171, v109 row_newbcast:13 row_mask:0xf bank_mask:0xf
	v_fmac_f32_dpp v2, v171, v110 row_newbcast:14 row_mask:0xf bank_mask:0xf
	v_fmac_f32_dpp v3, v171, v111 row_newbcast:15 row_mask:0xf bank_mask:0xf
	ds_read_b32 v159, v7 offset:14064
	v_add_f32_e32 v0, v0, v1
	v_add_f32_e32 v2, v2, v3
	v_add_f32_e32 v0, v0, v2
	v_add_f32_e32 v112, v112, v0
	s_waitcnt lgkmcnt(11)
	v_mul_f32_dpp v0, v148, v64 row_newbcast:0 row_mask:0xf bank_mask:0xf
	v_mul_f32_dpp v1, v148, v65 row_newbcast:1 row_mask:0xf bank_mask:0xf
	v_mul_f32_dpp v2, v148, v66 row_newbcast:2 row_mask:0xf bank_mask:0xf
	v_mul_f32_dpp v3, v148, v67 row_newbcast:3 row_mask:0xf bank_mask:0xf
	v_fmac_f32_dpp v0, v148, v68 row_newbcast:4 row_mask:0xf bank_mask:0xf
	v_fmac_f32_dpp v1, v148, v69 row_newbcast:5 row_mask:0xf bank_mask:0xf
	v_fmac_f32_dpp v2, v148, v70 row_newbcast:6 row_mask:0xf bank_mask:0xf
	v_fmac_f32_dpp v3, v148, v71 row_newbcast:7 row_mask:0xf bank_mask:0xf
	v_fmac_f32_dpp v0, v148, v72 row_newbcast:8 row_mask:0xf bank_mask:0xf
	v_fmac_f32_dpp v1, v148, v73 row_newbcast:9 row_mask:0xf bank_mask:0xf
	v_fmac_f32_dpp v2, v148, v74 row_newbcast:10 row_mask:0xf bank_mask:0xf
	v_fmac_f32_dpp v3, v148, v75 row_newbcast:11 row_mask:0xf bank_mask:0xf
	v_fmac_f32_dpp v0, v148, v76 row_newbcast:12 row_mask:0xf bank_mask:0xf
	v_fmac_f32_dpp v1, v148, v77 row_newbcast:13 row_mask:0xf bank_mask:0xf
	v_fmac_f32_dpp v2, v148, v78 row_newbcast:14 row_mask:0xf bank_mask:0xf
	v_fmac_f32_dpp v3, v148, v79 row_newbcast:15 row_mask:0xf bank_mask:0xf
	ds_read_b32 v160, v7 offset:14144
	s_waitcnt lgkmcnt(11)
; #define LAS __attribute__((address_space(3)))
; __device__ __forceinline__ void rw_phaseA(LAS unsigned char* lds, const RwCtx& X, int item) {
;     ...
;         for (int tt = 1; tt < 64; ++tt) { float a = x[tt];
; #pragma unroll
;             for (int s4 = 0; s4 < (tt + 3) / 4; ++s4) { const f32x4 l4 = *(const LAS f32x4*)(LABv + tt * 68 + s4 * 4);
;                 a += l4[0] * x[s4 * 4]; if (s4 * 4 + 1 < tt) a += l4[1] * x[s4 * 4 + 1]; if (s4 * 4 + 2 < tt) a += l4[2] * x[s4 * 4 + 2]; if (s4 * 4 + 3 < tt) a += l4[3] * x[s4 * 4 + 3]; }
;             x[tt] = a;
	v_fmac_f32_dpp v0, v149, v80 row_newbcast:0 row_mask:0xf bank_mask:0xf
	v_fmac_f32_dpp v1, v149, v81 row_newbcast:1 row_mask:0xf bank_mask:0xf
	v_fmac_f32_dpp v2, v149, v82 row_newbcast:2 row_mask:0xf bank_mask:0xf
	v_fmac_f32_dpp v3, v149, v83 row_newbcast:3 row_mask:0xf bank_mask:0xf
	v_fmac_f32_dpp v0, v149, v84 row_newbcast:4 row_mask:0xf bank_mask:0xf
	v_fmac_f32_dpp v1, v149, v85 row_newbcast:5 row_mask:0xf bank_mask:0xf
	v_fmac_f32_dpp v2, v149, v86 row_newbcast:6 row_mask:0xf bank_mask:0xf
	v_fmac_f32_dpp v3, v149, v87 row_newbcast:7 row_mask:0xf bank_mask:0xf
	v_fmac_f32_dpp v0, v149, v88 row_newbcast:8 row_mask:0xf bank_mask:0xf
	v_fmac_f32_dpp v1, v149, v89 row_newbcast:9 row_mask:0xf bank_mask:0xf
	v_fmac_f32_dpp v2, v149, v90 row_newbcast:10 row_mask:0xf bank_mask:0xf
	v_fmac_f32_dpp v3, v149, v91 row_newbcast:11 row_mask:0xf bank_mask:0xf
	v_fmac_f32_dpp v0, v149, v92 row_newbcast:12 row_mask:0xf bank_mask:0xf
	v_fmac_f32_dpp v1, v149, v93 row_newbcast:13 row_mask:0xf bank_mask:0xf
	v_fmac_f32_dpp v2, v149, v94 row_newbcast:14 row_mask:0xf bank_mask:0xf
	v_fmac_f32_dpp v3, v149, v95 row_newbcast:15 row_mask:0xf bank_mask:0xf
	ds_read_b32 v161, v7 offset:14208
	s_waitcnt lgkmcnt(11)
	v_fmac_f32_dpp v0, v150, v96 row_newbcast:0 row_mask:0xf bank_mask:0xf
	v_fmac_f32_dpp v1, v150, v97 row_newbcast:1 row_mask:0xf bank_mask:0xf
	v_fmac_f32_dpp v2, v150, v98 row_newbcast:2 row_mask:0xf bank_mask:0xf
	v_fmac_f32_dpp v3, v150, v99 row_newbcast:3 row_mask:0xf bank_mask:0xf
	v_fmac_f32_dpp v0, v150, v100 row_newbcast:4 row_mask:0xf bank_mask:0xf
	v_fmac_f32_dpp v1, v150, v101 row_newbcast:5 row_mask:0xf bank_mask:0xf
	v_fmac_f32_dpp v2, v150, v102 row_newbcast:6 row_mask:0xf bank_mask:0xf
	v_fmac_f32_dpp v3, v150, v103 row_newbcast:7 row_mask:0xf bank_mask:0xf
	v_fmac_f32_dpp v0, v150, v104 row_newbcast:8 row_mask:0xf bank_mask:0xf
	v_fmac_f32_dpp v1, v150, v105 row_newbcast:9 row_mask:0xf bank_mask:0xf
	v_fmac_f32_dpp v2, v150, v106 row_newbcast:10 row_mask:0xf bank_mask:0xf
	v_fmac_f32_dpp v3, v150, v107 row_newbcast:11 row_mask:0xf bank_mask:0xf
	v_fmac_f32_dpp v0, v150, v108 row_newbcast:12 row_mask:0xf bank_mask:0xf
	v_fmac_f32_dpp v1, v150, v109 row_newbcast:13 row_mask:0xf bank_mask:0xf
	v_fmac_f32_dpp v2, v150, v110 row_newbcast:14 row_mask:0xf bank_mask:0xf
	v_fmac_f32_dpp v3, v150, v111 row_newbcast:15 row_mask:0xf bank_mask:0xf
	ds_read_b32 v162, v7 offset:14272
	s_waitcnt lgkmcnt(11)
	v_fmac_f32_dpp v0, v151, v112 row_newbcast:0 row_mask:0xf bank_mask:0xf
	ds_read_b32 v163, v7 offset:14336
	v_add_f32_e32 v0, v0, v1
	v_add_f32_e32 v2, v2, v3
	v_add_f32_e32 v0, v0, v2
	v_add_f32_e32 v113, v113, v0
	s_waitcnt lgkmcnt(11)
	v_mul_f32_dpp v0, v152, v64 row_newbcast:0 row_mask:0xf bank_mask:0xf
	v_mul_f32_dpp v1, v152, v65 row_newbcast:1 row_mask:0xf bank_mask:0xf
	v_mul_f32_dpp v2, v152, v66 row_newbcast:2 row_mask:0xf bank_mask:0xf
	v_mul_f32_dpp v3, v152, v67 row_newbcast:3 row_mask:0xf bank_mask:0xf
	v_fmac_f32_dpp v0, v152, v68 row_newbcast:4 row_mask:0xf bank_mask:0xf
	v_fmac_f32_dpp v1, v152, v69 row_newbcast:5 row_mask:0xf bank_mask:0xf
	v_fmac_f32_dpp v2, v152, v70 row_newbcast:6 row_mask:0xf bank_mask:0xf
	v_fmac_f32_dpp v3, v152, v71 row_newbcast:7 row_mask:0xf bank_mask:0xf
	v_fmac_f32_dpp v0, v152, v72 row_newbcast:8 row_mask:0xf bank_mask:0xf
	v_fmac_f32_dpp v1, v152, v73 row_newbcast:9 row_mask:0xf bank_mask:0xf
	v_fmac_f32_dpp v2, v152, v74 row_newbcast:10 row_mask:0xf bank_mask:0xf
	v_fmac_f32_dpp v3, v152, v75 row_newbcast:11 row_mask:0xf bank_mask:0xf
	v_fmac_f32_dpp v0, v152, v76 row_newbcast:12 row_mask:0xf bank_mask:0xf
	v_fmac_f32_dpp v1, v152, v77 row_newbcast:13 row_mask:0xf bank_mask:0xf
	v_fmac_f32_dpp v2, v152, v78 row_newbcast:14 row_mask:0xf bank_mask:0xf
	v_fmac_f32_dpp v3, v152, v79 row_newbcast:15 row_mask:0xf bank_mask:0xf
	ds_read_b32 v164, v7 offset:14416
	s_waitcnt lgkmcnt(11)
	v_fmac_f32_dpp v0, v153, v80 row_newbcast:0 row_mask:0xf bank_mask:0xf
	v_fmac_f32_dpp v1, v153, v81 row_newbcast:1 row_mask:0xf bank_mask:0xf
	v_fmac_f32_dpp v2, v153, v82 row_newbcast:2 row_mask:0xf bank_mask:0xf
	v_fmac_f32_dpp v3, v153, v83 row_newbcast:3 row_mask:0xf bank_mask:0xf
	v_fmac_f32_dpp v0, v153, v84 row_newbcast:4 row_mask:0xf bank_mask:0xf
	v_fmac_f32_dpp v1, v153, v85 row_newbcast:5 row_mask:0xf bank_mask:0xf
	v_fmac_f32_dpp v2, v153, v86 row_newbcast:6 row_mask:0xf bank_mask:0xf
	v_fmac_f32_dpp v3, v153, v87 row_newbcast:7 row_mask:0xf bank_mask:0xf
	v_fmac_f32_dpp v0, v153, v88 row_newbcast:8 row_mask:0xf bank_mask:0xf
	v_fmac_f32_dpp v1, v153, v89 row_newbcast:9 row_mask:0xf bank_mask:0xf
	v_fmac_f32_dpp v2, v153, v90 row_newbcast:10 row_mask:0xf bank_mask:0xf
	v_fmac_f32_dpp v3, v153, v91 row_newbcast:11 row_mask:0xf bank_mask:0xf
	v_fmac_f32_dpp v0, v153, v92 row_newbcast:12 row_mask:0xf bank_mask:0xf
	v_fmac_f32_dpp v1, v153, v93 row_newbcast:13 row_mask:0xf bank_mask:0xf
	v_fmac_f32_dpp v2, v153, v94 row_newbcast:14 row_mask:0xf bank_mask:0xf
	v_fmac_f32_dpp v3, v153, v95 row_newbcast:15 row_mask:0xf bank_mask:0xf
	ds_read_b32 v165, v7 offset:14480
	s_waitcnt lgkmcnt(11)
; #define LAS __attribute__((address_space(3)))
; __device__ __forceinline__ void rw_phaseA(LAS unsigned char* lds, const RwCtx& X, int item) {
;     ...
;         for (int tt = 1; tt < 64; ++tt) { float a = x[tt];
; #pragma unroll
;             for (int s4 = 0; s4 < (tt + 3) / 4; ++s4) { const f32x4 l4 = *(const LAS f32x4*)(LABv + tt * 68 + s4 * 4);
;                 a += l4[0] * x[s4 * 4]; if (s4 * 4 + 1 < tt) a += l4[1] * x[s4 * 4 + 1]; if (s4 * 4 + 2 < tt) a += l4[2] * x[s4 * 4 + 2]; if (s4 * 4 + 3 < tt) a += l4[3] * x[s4 * 4 + 3]; }
;             x[tt] = a;
	v_fmac_f32_dpp v0, v154, v96 row_newbcast:0 row_mask:0xf bank_mask:0xf
	v_fmac_f32_dpp v1, v154, v97 row_newbcast:1 row_mask:0xf bank_mask:0xf
	v_fmac_f32_dpp v2, v154, v98 row_newbcast:2 row_mask:0xf bank_mask:0xf
	v_fmac_f32_dpp v3, v154, v99 row_newbcast:3 row_mask:0xf bank_mask:0xf
	v_fmac_f32_dpp v0, v154, v100 row_newbcast:4 row_mask:0xf bank_mask:0xf
	v_fmac_f32_dpp v1, v154, v101 row_newbcast:5 row_mask:0xf bank_mask:0xf
	v_fmac_f32_dpp v2, v154, v102 row_newbcast:6 row_mask:0xf bank_mask:0xf
	v_fmac_f32_dpp v3, v154, v103 row_newbcast:7 row_mask:0xf bank_mask:0xf
	v_fmac_f32_dpp v0, v154, v104 row_newbcast:8 row_mask:0xf bank_mask:0xf
	v_fmac_f32_dpp v1, v154, v105 row_newbcast:9 row_mask:0xf bank_mask:0xf
	v_fmac_f32_dpp v2, v154, v106 row_newbcast:10 row_mask:0xf bank_mask:0xf
	v_fmac_f32_dpp v3, v154, v107 row_newbcast:11 row_mask:0xf bank_mask:0xf
	v_fmac_f32_dpp v0, v154, v108 row_newbcast:12 row_mask:0xf bank_mask:0xf
	v_fmac_f32_dpp v1, v154, v109 row_newbcast:13 row_mask:0xf bank_mask:0xf
	v_fmac_f32_dpp v2, v154, v110 row_newbcast:14 row_mask:0xf bank_mask:0xf
	v_fmac_f32_dpp v3, v154, v111 row_newbcast:15 row_mask:0xf bank_mask:0xf
	ds_read_b32 v166, v7 offset:14544
	s_waitcnt lgkmcnt(11)
	v_fmac_f32_dpp v0, v155, v112 row_newbcast:0 row_mask:0xf bank_mask:0xf
	v_fmac_f32_dpp v1, v155, v113 row_newbcast:1 row_mask:0xf bank_mask:0xf
	ds_read_b32 v167, v7 offset:14608
	v_add_f32_e32 v0, v0, v1
	v_add_f32_e32 v2, v2, v3
	v_add_f32_e32 v0, v0, v2
	v_add_f32_e32 v114, v114, v0
	s_waitcnt lgkmcnt(11)
	v_mul_f32_dpp v0, v156, v64 row_newbcast:0 row_mask:0xf bank_mask:0xf
	v_mul_f32_dpp v1, v156, v65 row_newbcast:1 row_mask:0xf bank_mask:0xf
	v_mul_f32_dpp v2, v156, v66 row_newbcast:2 row_mask:0xf bank_mask:0xf
	v_mul_f32_dpp v3, v156, v67 row_newbcast:3 row_mask:0xf bank_mask:0xf
	v_fmac_f32_dpp v0, v156, v68 row_newbcast:4 row_mask:0xf bank_mask:0xf
	v_fmac_f32_dpp v1, v156, v69 row_newbcast:5 row_mask:0xf bank_mask:0xf
	v_fmac_f32_dpp v2, v156, v70 row_newbcast:6 row_mask:0xf bank_mask:0xf
	v_fmac_f32_dpp v3, v156, v71 row_newbcast:7 row_mask:0xf bank_mask:0xf
	v_fmac_f32_dpp v0, v156, v72 row_newbcast:8 row_mask:0xf bank_mask:0xf
	v_fmac_f32_dpp v1, v156, v73 row_newbcast:9 row_mask:0xf bank_mask:0xf
	v_fmac_f32_dpp v2, v156, v74 row_newbcast:10 row_mask:0xf bank_mask:0xf
	v_fmac_f32_dpp v3, v156, v75 row_newbcast:11 row_mask:0xf bank_mask:0xf
	v_fmac_f32_dpp v0, v156, v76 row_newbcast:12 row_mask:0xf bank_mask:0xf
	v_fmac_f32_dpp v1, v156, v77 row_newbcast:13 row_mask:0xf bank_mask:0xf
	v_fmac_f32_dpp v2, v156, v78 row_newbcast:14 row_mask:0xf bank_mask:0xf
	v_fmac_f32_dpp v3, v156, v79 row_newbcast:15 row_mask:0xf bank_mask:0xf
	ds_read_b32 v168, v7 offset:14688
	s_waitcnt lgkmcnt(11)
	v_fmac_f32_dpp v0, v157, v80 row_newbcast:0 row_mask:0xf bank_mask:0xf
	v_fmac_f32_dpp v1, v157, v81 row_newbcast:1 row_mask:0xf bank_mask:0xf
	v_fmac_f32_dpp v2, v157, v82 row_newbcast:2 row_mask:0xf bank_mask:0xf
	v_fmac_f32_dpp v3, v157, v83 row_newbcast:3 row_mask:0xf bank_mask:0xf
	v_fmac_f32_dpp v0, v157, v84 row_newbcast:4 row_mask:0xf bank_mask:0xf
	v_fmac_f32_dpp v1, v157, v85 row_newbcast:5 row_mask:0xf bank_mask:0xf
	v_fmac_f32_dpp v2, v157, v86 row_newbcast:6 row_mask:0xf bank_mask:0xf
	v_fmac_f32_dpp v3, v157, v87 row_newbcast:7 row_mask:0xf bank_mask:0xf
	v_fmac_f32_dpp v0, v157, v88 row_newbcast:8 row_mask:0xf bank_mask:0xf
	v_fmac_f32_dpp v1, v157, v89 row_newbcast:9 row_mask:0xf bank_mask:0xf
	v_fmac_f32_dpp v2, v157, v90 row_newbcast:10 row_mask:0xf bank_mask:0xf
	v_fmac_f32_dpp v3, v157, v91 row_newbcast:11 row_mask:0xf bank_mask:0xf
	v_fmac_f32_dpp v0, v157, v92 row_newbcast:12 row_mask:0xf bank_mask:0xf
	v_fmac_f32_dpp v1, v157, v93 row_newbcast:13 row_mask:0xf bank_mask:0xf
	v_fmac_f32_dpp v2, v157, v94 row_newbcast:14 row_mask:0xf bank_mask:0xf
	v_fmac_f32_dpp v3, v157, v95 row_newbcast:15 row_mask:0xf bank_mask:0xf
	ds_read_b32 v169, v7 offset:14752
	s_waitcnt lgkmcnt(11)
	v_fmac_f32_dpp v0, v158, v96 row_newbcast:0 row_mask:0xf bank_mask:0xf
	v_fmac_f32_dpp v1, v158, v97 row_newbcast:1 row_mask:0xf bank_mask:0xf
	v_fmac_f32_dpp v2, v158, v98 row_newbcast:2 row_mask:0xf bank_mask:0xf
	v_fmac_f32_dpp v3, v158, v99 row_newbcast:3 row_mask:0xf bank_mask:0xf
	v_fmac_f32_dpp v0, v158, v100 row_newbcast:4 row_mask:0xf bank_mask:0xf
	v_fmac_f32_dpp v1, v158, v101 row_newbcast:5 row_mask:0xf bank_mask:0xf
	v_fmac_f32_dpp v2, v158, v102 row_newbcast:6 row_mask:0xf bank_mask:0xf
	v_fmac_f32_dpp v3, v158, v103 row_newbcast:7 row_mask:0xf bank_mask:0xf
	v_fmac_f32_dpp v0, v158, v104 row_newbcast:8 row_mask:0xf bank_mask:0xf
	v_fmac_f32_dpp v1, v158, v105 row_newbcast:9 row_mask:0xf bank_mask:0xf
	v_fmac_f32_dpp v2, v158, v106 row_newbcast:10 row_mask:0xf bank_mask:0xf
	v_fmac_f32_dpp v3, v158, v107 row_newbcast:11 row_mask:0xf bank_mask:0xf
	v_fmac_f32_dpp v0, v158, v108 row_newbcast:12 row_mask:0xf bank_mask:0xf
	v_fmac_f32_dpp v1, v158, v109 row_newbcast:13 row_mask:0xf bank_mask:0xf
	v_fmac_f32_dpp v2, v158, v110 row_newbcast:14 row_mask:0xf bank_mask:0xf
	v_fmac_f32_dpp v3, v158, v111 row_newbcast:15 row_mask:0xf bank_mask:0xf
	ds_read_b32 v170, v7 offset:14816
	s_waitcnt lgkmcnt(11)
	v_fmac_f32_dpp v0, v159, v112 row_newbcast:0 row_mask:0xf bank_mask:0xf
	v_fmac_f32_dpp v1, v159, v113 row_newbcast:1 row_mask:0xf bank_mask:0xf
	v_fmac_f32_dpp v2, v159, v114 row_newbcast:2 row_mask:0xf bank_mask:0xf
	ds_read_b32 v171, v7 offset:14880
	v_add_f32_e32 v0, v0, v1
	v_add_f32_e32 v2, v2, v3
	v_add_f32_e32 v0, v0, v2
	v_add_f32_e32 v115, v115, v0
	s_waitcnt lgkmcnt(11)
; #define LAS __attribute__((address_space(3)))
; __device__ __forceinline__ void rw_phaseA(LAS unsigned char* lds, const RwCtx& X, int item) {
;     ...
;         for (int tt = 1; tt < 64; ++tt) { float a = x[tt];
; #pragma unroll
;             for (int s4 = 0; s4 < (tt + 3) / 4; ++s4) { const f32x4 l4 = *(const LAS f32x4*)(LABv + tt * 68 + s4 * 4);
;                 a += l4[0] * x[s4 * 4]; if (s4 * 4 + 1 < tt) a += l4[1] * x[s4 * 4 + 1]; if (s4 * 4 + 2 < tt) a += l4[2] * x[s4 * 4 + 2]; if (s4 * 4 + 3 < tt) a += l4[3] * x[s4 * 4 + 3]; }
;             x[tt] = a;
	v_mul_f32_dpp v0, v160, v64 row_newbcast:0 row_mask:0xf bank_mask:0xf
	v_mul_f32_dpp v1, v160, v65 row_newbcast:1 row_mask:0xf bank_mask:0xf
	v_mul_f32_dpp v2, v160, v66 row_newbcast:2 row_mask:0xf bank_mask:0xf
	v_mul_f32_dpp v3, v160, v67 row_newbcast:3 row_mask:0xf bank_mask:0xf
	v_fmac_f32_dpp v0, v160, v68 row_newbcast:4 row_mask:0xf bank_mask:0xf
	v_fmac_f32_dpp v1, v160, v69 row_newbcast:5 row_mask:0xf bank_mask:0xf
	v_fmac_f32_dpp v2, v160, v70 row_newbcast:6 row_mask:0xf bank_mask:0xf
	v_fmac_f32_dpp v3, v160, v71 row_newbcast:7 row_mask:0xf bank_mask:0xf
	v_fmac_f32_dpp v0, v160, v72 row_newbcast:8 row_mask:0xf bank_mask:0xf
	v_fmac_f32_dpp v1, v160, v73 row_newbcast:9 row_mask:0xf bank_mask:0xf
	v_fmac_f32_dpp v2, v160, v74 row_newbcast:10 row_mask:0xf bank_mask:0xf
	v_fmac_f32_dpp v3, v160, v75 row_newbcast:11 row_mask:0xf bank_mask:0xf
	v_fmac_f32_dpp v0, v160, v76 row_newbcast:12 row_mask:0xf bank_mask:0xf
	v_fmac_f32_dpp v1, v160, v77 row_newbcast:13 row_mask:0xf bank_mask:0xf
	v_fmac_f32_dpp v2, v160, v78 row_newbcast:14 row_mask:0xf bank_mask:0xf
	v_fmac_f32_dpp v3, v160, v79 row_newbcast:15 row_mask:0xf bank_mask:0xf
	ds_read_b32 v148, v7 offset:14960
	s_waitcnt lgkmcnt(11)
	v_fmac_f32_dpp v0, v161, v80 row_newbcast:0 row_mask:0xf bank_mask:0xf
	v_fmac_f32_dpp v1, v161, v81 row_newbcast:1 row_mask:0xf bank_mask:0xf
	v_fmac_f32_dpp v2, v161, v82 row_newbcast:2 row_mask:0xf bank_mask:0xf
	v_fmac_f32_dpp v3, v161, v83 row_newbcast:3 row_mask:0xf bank_mask:0xf
	v_fmac_f32_dpp v0, v161, v84 row_newbcast:4 row_mask:0xf bank_mask:0xf
	v_fmac_f32_dpp v1, v161, v85 row_newbcast:5 row_mask:0xf bank_mask:0xf
	v_fmac_f32_dpp v2, v161, v86 row_newbcast:6 row_mask:0xf bank_mask:0xf
	v_fmac_f32_dpp v3, v161, v87 row_newbcast:7 row_mask:0xf bank_mask:0xf
	v_fmac_f32_dpp v0, v161, v88 row_newbcast:8 row_mask:0xf bank_mask:0xf
	v_fmac_f32_dpp v1, v161, v89 row_newbcast:9 row_mask:0xf bank_mask:0xf
	v_fmac_f32_dpp v2, v161, v90 row_newbcast:10 row_mask:0xf bank_mask:0xf
	v_fmac_f32_dpp v3, v161, v91 row_newbcast:11 row_mask:0xf bank_mask:0xf
	v_fmac_f32_dpp v0, v161, v92 row_newbcast:12 row_mask:0xf bank_mask:0xf
	v_fmac_f32_dpp v1, v161, v93 row_newbcast:13 row_mask:0xf bank_mask:0xf
	v_fmac_f32_dpp v2, v161, v94 row_newbcast:14 row_mask:0xf bank_mask:0xf
	v_fmac_f32_dpp v3, v161, v95 row_newbcast:15 row_mask:0xf bank_mask:0xf
	ds_read_b32 v149, v7 offset:15024
	s_waitcnt lgkmcnt(11)
	v_fmac_f32_dpp v0, v162, v96 row_newbcast:0 row_mask:0xf bank_mask:0xf
	v_fmac_f32_dpp v1, v162, v97 row_newbcast:1 row_mask:0xf bank_mask:0xf
	v_fmac_f32_dpp v2, v162, v98 row_newbcast:2 row_mask:0xf bank_mask:0xf
	v_fmac_f32_dpp v3, v162, v99 row_newbcast:3 row_mask:0xf bank_mask:0xf
	v_fmac_f32_dpp v0, v162, v100 row_newbcast:4 row_mask:0xf bank_mask:0xf
	v_fmac_f32_dpp v1, v162, v101 row_newbcast:5 row_mask:0xf bank_mask:0xf
	v_fmac_f32_dpp v2, v162, v102 row_newbcast:6 row_mask:0xf bank_mask:0xf
	v_fmac_f32_dpp v3, v162, v103 row_newbcast:7 row_mask:0xf bank_mask:0xf
	v_fmac_f32_dpp v0, v162, v104 row_newbcast:8 row_mask:0xf bank_mask:0xf
	v_fmac_f32_dpp v1, v162, v105 row_newbcast:9 row_mask:0xf bank_mask:0xf
	v_fmac_f32_dpp v2, v162, v106 row_newbcast:10 row_mask:0xf bank_mask:0xf
	v_fmac_f32_dpp v3, v162, v107 row_newbcast:11 row_mask:0xf bank_mask:0xf
	v_fmac_f32_dpp v0, v162, v108 row_newbcast:12 row_mask:0xf bank_mask:0xf
	v_fmac_f32_dpp v1, v162, v109 row_newbcast:13 row_mask:0xf bank_mask:0xf
	v_fmac_f32_dpp v2, v162, v110 row_newbcast:14 row_mask:0xf bank_mask:0xf
	v_fmac_f32_dpp v3, v162, v111 row_newbcast:15 row_mask:0xf bank_mask:0xf
	ds_read_b32 v150, v7 offset:15088
	s_waitcnt lgkmcnt(11)
	v_fmac_f32_dpp v0, v163, v112 row_newbcast:0 row_mask:0xf bank_mask:0xf
	v_fmac_f32_dpp v1, v163, v113 row_newbcast:1 row_mask:0xf bank_mask:0xf
	v_fmac_f32_dpp v2, v163, v114 row_newbcast:2 row_mask:0xf bank_mask:0xf
	v_fmac_f32_dpp v3, v163, v115 row_newbcast:3 row_mask:0xf bank_mask:0xf
	ds_read_b32 v151, v7 offset:15152
	v_add_f32_e32 v0, v0, v1
	v_add_f32_e32 v2, v2, v3
	v_add_f32_e32 v0, v0, v2
	v_add_f32_e32 v116, v116, v0
	s_waitcnt lgkmcnt(11)
	v_mul_f32_dpp v0, v164, v64 row_newbcast:0 row_mask:0xf bank_mask:0xf
	v_mul_f32_dpp v1, v164, v65 row_newbcast:1 row_mask:0xf bank_mask:0xf
	v_mul_f32_dpp v2, v164, v66 row_newbcast:2 row_mask:0xf bank_mask:0xf
	v_mul_f32_dpp v3, v164, v67 row_newbcast:3 row_mask:0xf bank_mask:0xf
	v_fmac_f32_dpp v0, v164, v68 row_newbcast:4 row_mask:0xf bank_mask:0xf
	v_fmac_f32_dpp v1, v164, v69 row_newbcast:5 row_mask:0xf bank_mask:0xf
	v_fmac_f32_dpp v2, v164, v70 row_newbcast:6 row_mask:0xf bank_mask:0xf
	v_fmac_f32_dpp v3, v164, v71 row_newbcast:7 row_mask:0xf bank_mask:0xf
	v_fmac_f32_dpp v0, v164, v72 row_newbcast:8 row_mask:0xf bank_mask:0xf
	v_fmac_f32_dpp v1, v164, v73 row_newbcast:9 row_mask:0xf bank_mask:0xf
	v_fmac_f32_dpp v2, v164, v74 row_newbcast:10 row_mask:0xf bank_mask:0xf
	v_fmac_f32_dpp v3, v164, v75 row_newbcast:11 row_mask:0xf bank_mask:0xf
	v_fmac_f32_dpp v0, v164, v76 row_newbcast:12 row_mask:0xf bank_mask:0xf
	v_fmac_f32_dpp v1, v164, v77 row_newbcast:13 row_mask:0xf bank_mask:0xf
	v_fmac_f32_dpp v2, v164, v78 row_newbcast:14 row_mask:0xf bank_mask:0xf
	v_fmac_f32_dpp v3, v164, v79 row_newbcast:15 row_mask:0xf bank_mask:0xf
	ds_read_b32 v152, v7 offset:15232
	s_waitcnt lgkmcnt(11)
; #define LAS __attribute__((address_space(3)))
; __device__ __forceinline__ void rw_phaseA(LAS unsigned char* lds, const RwCtx& X, int item) {
;     ...
;         for (int tt = 1; tt < 64; ++tt) { float a = x[tt];
; #pragma unroll
;             for (int s4 = 0; s4 < (tt + 3) / 4; ++s4) { const f32x4 l4 = *(const LAS f32x4*)(LABv + tt * 68 + s4 * 4);
;                 a += l4[0] * x[s4 * 4]; if (s4 * 4 + 1 < tt) a += l4[1] * x[s4 * 4 + 1]; if (s4 * 4 + 2 < tt) a += l4[2] * x[s4 * 4 + 2]; if (s4 * 4 + 3 < tt) a += l4[3] * x[s4 * 4 + 3]; }
;             x[tt] = a;
	v_fmac_f32_dpp v0, v165, v80 row_newbcast:0 row_mask:0xf bank_mask:0xf
	v_fmac_f32_dpp v1, v165, v81 row_newbcast:1 row_mask:0xf bank_mask:0xf
	v_fmac_f32_dpp v2, v165, v82 row_newbcast:2 row_mask:0xf bank_mask:0xf
	v_fmac_f32_dpp v3, v165, v83 row_newbcast:3 row_mask:0xf bank_mask:0xf
	v_fmac_f32_dpp v0, v165, v84 row_newbcast:4 row_mask:0xf bank_mask:0xf
	v_fmac_f32_dpp v1, v165, v85 row_newbcast:5 row_mask:0xf bank_mask:0xf
	v_fmac_f32_dpp v2, v165, v86 row_newbcast:6 row_mask:0xf bank_mask:0xf
	v_fmac_f32_dpp v3, v165, v87 row_newbcast:7 row_mask:0xf bank_mask:0xf
	v_fmac_f32_dpp v0, v165, v88 row_newbcast:8 row_mask:0xf bank_mask:0xf
	v_fmac_f32_dpp v1, v165, v89 row_newbcast:9 row_mask:0xf bank_mask:0xf
	v_fmac_f32_dpp v2, v165, v90 row_newbcast:10 row_mask:0xf bank_mask:0xf
	v_fmac_f32_dpp v3, v165, v91 row_newbcast:11 row_mask:0xf bank_mask:0xf
	v_fmac_f32_dpp v0, v165, v92 row_newbcast:12 row_mask:0xf bank_mask:0xf
	v_fmac_f32_dpp v1, v165, v93 row_newbcast:13 row_mask:0xf bank_mask:0xf
	v_fmac_f32_dpp v2, v165, v94 row_newbcast:14 row_mask:0xf bank_mask:0xf
	v_fmac_f32_dpp v3, v165, v95 row_newbcast:15 row_mask:0xf bank_mask:0xf
	ds_read_b32 v153, v7 offset:15296
	s_waitcnt lgkmcnt(11)
	v_fmac_f32_dpp v0, v166, v96 row_newbcast:0 row_mask:0xf bank_mask:0xf
	v_fmac_f32_dpp v1, v166, v97 row_newbcast:1 row_mask:0xf bank_mask:0xf
	v_fmac_f32_dpp v2, v166, v98 row_newbcast:2 row_mask:0xf bank_mask:0xf
	v_fmac_f32_dpp v3, v166, v99 row_newbcast:3 row_mask:0xf bank_mask:0xf
	v_fmac_f32_dpp v0, v166, v100 row_newbcast:4 row_mask:0xf bank_mask:0xf
	v_fmac_f32_dpp v1, v166, v101 row_newbcast:5 row_mask:0xf bank_mask:0xf
	v_fmac_f32_dpp v2, v166, v102 row_newbcast:6 row_mask:0xf bank_mask:0xf
	v_fmac_f32_dpp v3, v166, v103 row_newbcast:7 row_mask:0xf bank_mask:0xf
	v_fmac_f32_dpp v0, v166, v104 row_newbcast:8 row_mask:0xf bank_mask:0xf
	v_fmac_f32_dpp v1, v166, v105 row_newbcast:9 row_mask:0xf bank_mask:0xf
	v_fmac_f32_dpp v2, v166, v106 row_newbcast:10 row_mask:0xf bank_mask:0xf
	v_fmac_f32_dpp v3, v166, v107 row_newbcast:11 row_mask:0xf bank_mask:0xf
	v_fmac_f32_dpp v0, v166, v108 row_newbcast:12 row_mask:0xf bank_mask:0xf
	v_fmac_f32_dpp v1, v166, v109 row_newbcast:13 row_mask:0xf bank_mask:0xf
	v_fmac_f32_dpp v2, v166, v110 row_newbcast:14 row_mask:0xf bank_mask:0xf
	v_fmac_f32_dpp v3, v166, v111 row_newbcast:15 row_mask:0xf bank_mask:0xf
	ds_read_b32 v154, v7 offset:15360
	s_waitcnt lgkmcnt(11)
	v_fmac_f32_dpp v0, v167, v112 row_newbcast:0 row_mask:0xf bank_mask:0xf
	v_fmac_f32_dpp v1, v167, v113 row_newbcast:1 row_mask:0xf bank_mask:0xf
	v_fmac_f32_dpp v2, v167, v114 row_newbcast:2 row_mask:0xf bank_mask:0xf
	v_fmac_f32_dpp v3, v167, v115 row_newbcast:3 row_mask:0xf bank_mask:0xf
	v_fmac_f32_dpp v0, v167, v116 row_newbcast:4 row_mask:0xf bank_mask:0xf
	ds_read_b32 v155, v7 offset:15424
	v_add_f32_e32 v0, v0, v1
	v_add_f32_e32 v2, v2, v3
	v_add_f32_e32 v0, v0, v2
	v_add_f32_e32 v117, v117, v0
	s_waitcnt lgkmcnt(11)
	v_mul_f32_dpp v0, v168, v64 row_newbcast:0 row_mask:0xf bank_mask:0xf
	v_mul_f32_dpp v1, v168, v65 row_newbcast:1 row_mask:0xf bank_mask:0xf
	v_mul_f32_dpp v2, v168, v66 row_newbcast:2 row_mask:0xf bank_mask:0xf
	v_mul_f32_dpp v3, v168, v67 row_newbcast:3 row_mask:0xf bank_mask:0xf
	v_fmac_f32_dpp v0, v168, v68 row_newbcast:4 row_mask:0xf bank_mask:0xf
	v_fmac_f32_dpp v1, v168, v69 row_newbcast:5 row_mask:0xf bank_mask:0xf
	v_fmac_f32_dpp v2, v168, v70 row_newbcast:6 row_mask:0xf bank_mask:0xf
	v_fmac_f32_dpp v3, v168, v71 row_newbcast:7 row_mask:0xf bank_mask:0xf
	v_fmac_f32_dpp v0, v168, v72 row_newbcast:8 row_mask:0xf bank_mask:0xf
	v_fmac_f32_dpp v1, v168, v73 row_newbcast:9 row_mask:0xf bank_mask:0xf
	v_fmac_f32_dpp v2, v168, v74 row_newbcast:10 row_mask:0xf bank_mask:0xf
	v_fmac_f32_dpp v3, v168, v75 row_newbcast:11 row_mask:0xf bank_mask:0xf
	v_fmac_f32_dpp v0, v168, v76 row_newbcast:12 row_mask:0xf bank_mask:0xf
	v_fmac_f32_dpp v1, v168, v77 row_newbcast:13 row_mask:0xf bank_mask:0xf
	v_fmac_f32_dpp v2, v168, v78 row_newbcast:14 row_mask:0xf bank_mask:0xf
	v_fmac_f32_dpp v3, v168, v79 row_newbcast:15 row_mask:0xf bank_mask:0xf
	ds_read_b32 v156, v7 offset:15504
	s_waitcnt lgkmcnt(11)
	v_fmac_f32_dpp v0, v169, v80 row_newbcast:0 row_mask:0xf bank_mask:0xf
	v_fmac_f32_dpp v1, v169, v81 row_newbcast:1 row_mask:0xf bank_mask:0xf
	v_fmac_f32_dpp v2, v169, v82 row_newbcast:2 row_mask:0xf bank_mask:0xf
	v_fmac_f32_dpp v3, v169, v83 row_newbcast:3 row_mask:0xf bank_mask:0xf
	v_fmac_f32_dpp v0, v169, v84 row_newbcast:4 row_mask:0xf bank_mask:0xf
	v_fmac_f32_dpp v1, v169, v85 row_newbcast:5 row_mask:0xf bank_mask:0xf
	v_fmac_f32_dpp v2, v169, v86 row_newbcast:6 row_mask:0xf bank_mask:0xf
	v_fmac_f32_dpp v3, v169, v87 row_newbcast:7 row_mask:0xf bank_mask:0xf
	v_fmac_f32_dpp v0, v169, v88 row_newbcast:8 row_mask:0xf bank_mask:0xf
	v_fmac_f32_dpp v1, v169, v89 row_newbcast:9 row_mask:0xf bank_mask:0xf
	v_fmac_f32_dpp v2, v169, v90 row_newbcast:10 row_mask:0xf bank_mask:0xf
	v_fmac_f32_dpp v3, v169, v91 row_newbcast:11 row_mask:0xf bank_mask:0xf
	v_fmac_f32_dpp v0, v169, v92 row_newbcast:12 row_mask:0xf bank_mask:0xf
	v_fmac_f32_dpp v1, v169, v93 row_newbcast:13 row_mask:0xf bank_mask:0xf
	v_fmac_f32_dpp v2, v169, v94 row_newbcast:14 row_mask:0xf bank_mask:0xf
	v_fmac_f32_dpp v3, v169, v95 row_newbcast:15 row_mask:0xf bank_mask:0xf
	ds_read_b32 v157, v7 offset:15568
	s_waitcnt lgkmcnt(11)
; #define LAS __attribute__((address_space(3)))
; __device__ __forceinline__ void rw_phaseA(LAS unsigned char* lds, const RwCtx& X, int item) {
;     ...
;         for (int tt = 1; tt < 64; ++tt) { float a = x[tt];
; #pragma unroll
;             for (int s4 = 0; s4 < (tt + 3) / 4; ++s4) { const f32x4 l4 = *(const LAS f32x4*)(LABv + tt * 68 + s4 * 4);
;                 a += l4[0] * x[s4 * 4]; if (s4 * 4 + 1 < tt) a += l4[1] * x[s4 * 4 + 1]; if (s4 * 4 + 2 < tt) a += l4[2] * x[s4 * 4 + 2]; if (s4 * 4 + 3 < tt) a += l4[3] * x[s4 * 4 + 3]; }
;             x[tt] = a;
	v_fmac_f32_dpp v0, v170, v96 row_newbcast:0 row_mask:0xf bank_mask:0xf
	v_fmac_f32_dpp v1, v170, v97 row_newbcast:1 row_mask:0xf bank_mask:0xf
	v_fmac_f32_dpp v2, v170, v98 row_newbcast:2 row_mask:0xf bank_mask:0xf
	v_fmac_f32_dpp v3, v170, v99 row_newbcast:3 row_mask:0xf bank_mask:0xf
	v_fmac_f32_dpp v0, v170, v100 row_newbcast:4 row_mask:0xf bank_mask:0xf
	v_fmac_f32_dpp v1, v170, v101 row_newbcast:5 row_mask:0xf bank_mask:0xf
	v_fmac_f32_dpp v2, v170, v102 row_newbcast:6 row_mask:0xf bank_mask:0xf
	v_fmac_f32_dpp v3, v170, v103 row_newbcast:7 row_mask:0xf bank_mask:0xf
	v_fmac_f32_dpp v0, v170, v104 row_newbcast:8 row_mask:0xf bank_mask:0xf
	v_fmac_f32_dpp v1, v170, v105 row_newbcast:9 row_mask:0xf bank_mask:0xf
	v_fmac_f32_dpp v2, v170, v106 row_newbcast:10 row_mask:0xf bank_mask:0xf
	v_fmac_f32_dpp v3, v170, v107 row_newbcast:11 row_mask:0xf bank_mask:0xf
	v_fmac_f32_dpp v0, v170, v108 row_newbcast:12 row_mask:0xf bank_mask:0xf
	v_fmac_f32_dpp v1, v170, v109 row_newbcast:13 row_mask:0xf bank_mask:0xf
	v_fmac_f32_dpp v2, v170, v110 row_newbcast:14 row_mask:0xf bank_mask:0xf
	v_fmac_f32_dpp v3, v170, v111 row_newbcast:15 row_mask:0xf bank_mask:0xf
	ds_read_b32 v158, v7 offset:15632
	s_waitcnt lgkmcnt(11)
	v_fmac_f32_dpp v0, v171, v112 row_newbcast:0 row_mask:0xf bank_mask:0xf
	v_fmac_f32_dpp v1, v171, v113 row_newbcast:1 row_mask:0xf bank_mask:0xf
	v_fmac_f32_dpp v2, v171, v114 row_newbcast:2 row_mask:0xf bank_mask:0xf
	v_fmac_f32_dpp v3, v171, v115 row_newbcast:3 row_mask:0xf bank_mask:0xf
	v_fmac_f32_dpp v0, v171, v116 row_newbcast:4 row_mask:0xf bank_mask:0xf
	v_fmac_f32_dpp v1, v171, v117 row_newbcast:5 row_mask:0xf bank_mask:0xf
	ds_read_b32 v159, v7 offset:15696
	v_add_f32_e32 v0, v0, v1
	v_add_f32_e32 v2, v2, v3
	v_add_f32_e32 v0, v0, v2
	v_add_f32_e32 v118, v118, v0
	s_waitcnt lgkmcnt(11)
	v_mul_f32_dpp v0, v148, v64 row_newbcast:0 row_mask:0xf bank_mask:0xf
	v_mul_f32_dpp v1, v148, v65 row_newbcast:1 row_mask:0xf bank_mask:0xf
	v_mul_f32_dpp v2, v148, v66 row_newbcast:2 row_mask:0xf bank_mask:0xf
	v_mul_f32_dpp v3, v148, v67 row_newbcast:3 row_mask:0xf bank_mask:0xf
	v_fmac_f32_dpp v0, v148, v68 row_newbcast:4 row_mask:0xf bank_mask:0xf
	v_fmac_f32_dpp v1, v148, v69 row_newbcast:5 row_mask:0xf bank_mask:0xf
	v_fmac_f32_dpp v2, v148, v70 row_newbcast:6 row_mask:0xf bank_mask:0xf
	v_fmac_f32_dpp v3, v148, v71 row_newbcast:7 row_mask:0xf bank_mask:0xf
	v_fmac_f32_dpp v0, v148, v72 row_newbcast:8 row_mask:0xf bank_mask:0xf
	v_fmac_f32_dpp v1, v148, v73 row_newbcast:9 row_mask:0xf bank_mask:0xf
	v_fmac_f32_dpp v2, v148, v74 row_newbcast:10 row_mask:0xf bank_mask:0xf
	v_fmac_f32_dpp v3, v148, v75 row_newbcast:11 row_mask:0xf bank_mask:0xf
	v_fmac_f32_dpp v0, v148, v76 row_newbcast:12 row_mask:0xf bank_mask:0xf
	v_fmac_f32_dpp v1, v148, v77 row_newbcast:13 row_mask:0xf bank_mask:0xf
	v_fmac_f32_dpp v2, v148, v78 row_newbcast:14 row_mask:0xf bank_mask:0xf
	v_fmac_f32_dpp v3, v148, v79 row_newbcast:15 row_mask:0xf bank_mask:0xf
	ds_read_b32 v160, v7 offset:15776
	s_waitcnt lgkmcnt(11)
	v_fmac_f32_dpp v0, v149, v80 row_newbcast:0 row_mask:0xf bank_mask:0xf
	v_fmac_f32_dpp v1, v149, v81 row_newbcast:1 row_mask:0xf bank_mask:0xf
	v_fmac_f32_dpp v2, v149, v82 row_newbcast:2 row_mask:0xf bank_mask:0xf
	v_fmac_f32_dpp v3, v149, v83 row_newbcast:3 row_mask:0xf bank_mask:0xf
	v_fmac_f32_dpp v0, v149, v84 row_newbcast:4 row_mask:0xf bank_mask:0xf
	v_fmac_f32_dpp v1, v149, v85 row_newbcast:5 row_mask:0xf bank_mask:0xf
	v_fmac_f32_dpp v2, v149, v86 row_newbcast:6 row_mask:0xf bank_mask:0xf
	v_fmac_f32_dpp v3, v149, v87 row_newbcast:7 row_mask:0xf bank_mask:0xf
	v_fmac_f32_dpp v0, v149, v88 row_newbcast:8 row_mask:0xf bank_mask:0xf
	v_fmac_f32_dpp v1, v149, v89 row_newbcast:9 row_mask:0xf bank_mask:0xf
	v_fmac_f32_dpp v2, v149, v90 row_newbcast:10 row_mask:0xf bank_mask:0xf
	v_fmac_f32_dpp v3, v149, v91 row_newbcast:11 row_mask:0xf bank_mask:0xf
	v_fmac_f32_dpp v0, v149, v92 row_newbcast:12 row_mask:0xf bank_mask:0xf
	v_fmac_f32_dpp v1, v149, v93 row_newbcast:13 row_mask:0xf bank_mask:0xf
	v_fmac_f32_dpp v2, v149, v94 row_newbcast:14 row_mask:0xf bank_mask:0xf
	v_fmac_f32_dpp v3, v149, v95 row_newbcast:15 row_mask:0xf bank_mask:0xf
	ds_read_b32 v161, v7 offset:15840
	s_waitcnt lgkmcnt(11)
	v_fmac_f32_dpp v0, v150, v96 row_newbcast:0 row_mask:0xf bank_mask:0xf
	v_fmac_f32_dpp v1, v150, v97 row_newbcast:1 row_mask:0xf bank_mask:0xf
	v_fmac_f32_dpp v2, v150, v98 row_newbcast:2 row_mask:0xf bank_mask:0xf
	v_fmac_f32_dpp v3, v150, v99 row_newbcast:3 row_mask:0xf bank_mask:0xf
	v_fmac_f32_dpp v0, v150, v100 row_newbcast:4 row_mask:0xf bank_mask:0xf
	v_fmac_f32_dpp v1, v150, v101 row_newbcast:5 row_mask:0xf bank_mask:0xf
	v_fmac_f32_dpp v2, v150, v102 row_newbcast:6 row_mask:0xf bank_mask:0xf
	v_fmac_f32_dpp v3, v150, v103 row_newbcast:7 row_mask:0xf bank_mask:0xf
	v_fmac_f32_dpp v0, v150, v104 row_newbcast:8 row_mask:0xf bank_mask:0xf
	v_fmac_f32_dpp v1, v150, v105 row_newbcast:9 row_mask:0xf bank_mask:0xf
	v_fmac_f32_dpp v2, v150, v106 row_newbcast:10 row_mask:0xf bank_mask:0xf
	v_fmac_f32_dpp v3, v150, v107 row_newbcast:11 row_mask:0xf bank_mask:0xf
	v_fmac_f32_dpp v0, v150, v108 row_newbcast:12 row_mask:0xf bank_mask:0xf
	v_fmac_f32_dpp v1, v150, v109 row_newbcast:13 row_mask:0xf bank_mask:0xf
	v_fmac_f32_dpp v2, v150, v110 row_newbcast:14 row_mask:0xf bank_mask:0xf
	v_fmac_f32_dpp v3, v150, v111 row_newbcast:15 row_mask:0xf bank_mask:0xf
	ds_read_b32 v162, v7 offset:15904
	s_waitcnt lgkmcnt(11)
; #define LAS __attribute__((address_space(3)))
; __device__ __forceinline__ void rw_phaseA(LAS unsigned char* lds, const RwCtx& X, int item) {
;     ...
;         for (int tt = 1; tt < 64; ++tt) { float a = x[tt];
; #pragma unroll
;             for (int s4 = 0; s4 < (tt + 3) / 4; ++s4) { const f32x4 l4 = *(const LAS f32x4*)(LABv + tt * 68 + s4 * 4);
;                 a += l4[0] * x[s4 * 4]; if (s4 * 4 + 1 < tt) a += l4[1] * x[s4 * 4 + 1]; if (s4 * 4 + 2 < tt) a += l4[2] * x[s4 * 4 + 2]; if (s4 * 4 + 3 < tt) a += l4[3] * x[s4 * 4 + 3]; }
;             x[tt] = a;
	v_fmac_f32_dpp v0, v151, v112 row_newbcast:0 row_mask:0xf bank_mask:0xf
	v_fmac_f32_dpp v1, v151, v113 row_newbcast:1 row_mask:0xf bank_mask:0xf
	v_fmac_f32_dpp v2, v151, v114 row_newbcast:2 row_mask:0xf bank_mask:0xf
	v_fmac_f32_dpp v3, v151, v115 row_newbcast:3 row_mask:0xf bank_mask:0xf
	v_fmac_f32_dpp v0, v151, v116 row_newbcast:4 row_mask:0xf bank_mask:0xf
	v_fmac_f32_dpp v1, v151, v117 row_newbcast:5 row_mask:0xf bank_mask:0xf
	v_fmac_f32_dpp v2, v151, v118 row_newbcast:6 row_mask:0xf bank_mask:0xf
	ds_read_b32 v163, v7 offset:15968
	v_add_f32_e32 v0, v0, v1
	v_add_f32_e32 v2, v2, v3
	v_add_f32_e32 v0, v0, v2
	v_add_f32_e32 v119, v119, v0
	s_waitcnt lgkmcnt(11)
	v_mul_f32_dpp v0, v152, v64 row_newbcast:0 row_mask:0xf bank_mask:0xf
	v_mul_f32_dpp v1, v152, v65 row_newbcast:1 row_mask:0xf bank_mask:0xf
	v_mul_f32_dpp v2, v152, v66 row_newbcast:2 row_mask:0xf bank_mask:0xf
	v_mul_f32_dpp v3, v152, v67 row_newbcast:3 row_mask:0xf bank_mask:0xf
	v_fmac_f32_dpp v0, v152, v68 row_newbcast:4 row_mask:0xf bank_mask:0xf
	v_fmac_f32_dpp v1, v152, v69 row_newbcast:5 row_mask:0xf bank_mask:0xf
	v_fmac_f32_dpp v2, v152, v70 row_newbcast:6 row_mask:0xf bank_mask:0xf
	v_fmac_f32_dpp v3, v152, v71 row_newbcast:7 row_mask:0xf bank_mask:0xf
	v_fmac_f32_dpp v0, v152, v72 row_newbcast:8 row_mask:0xf bank_mask:0xf
	v_fmac_f32_dpp v1, v152, v73 row_newbcast:9 row_mask:0xf bank_mask:0xf
	v_fmac_f32_dpp v2, v152, v74 row_newbcast:10 row_mask:0xf bank_mask:0xf
	v_fmac_f32_dpp v3, v152, v75 row_newbcast:11 row_mask:0xf bank_mask:0xf
	v_fmac_f32_dpp v0, v152, v76 row_newbcast:12 row_mask:0xf bank_mask:0xf
	v_fmac_f32_dpp v1, v152, v77 row_newbcast:13 row_mask:0xf bank_mask:0xf
	v_fmac_f32_dpp v2, v152, v78 row_newbcast:14 row_mask:0xf bank_mask:0xf
	v_fmac_f32_dpp v3, v152, v79 row_newbcast:15 row_mask:0xf bank_mask:0xf
	ds_read_b32 v164, v7 offset:16048
	s_waitcnt lgkmcnt(11)
	v_fmac_f32_dpp v0, v153, v80 row_newbcast:0 row_mask:0xf bank_mask:0xf
	v_fmac_f32_dpp v1, v153, v81 row_newbcast:1 row_mask:0xf bank_mask:0xf
	v_fmac_f32_dpp v2, v153, v82 row_newbcast:2 row_mask:0xf bank_mask:0xf
	v_fmac_f32_dpp v3, v153, v83 row_newbcast:3 row_mask:0xf bank_mask:0xf
	v_fmac_f32_dpp v0, v153, v84 row_newbcast:4 row_mask:0xf bank_mask:0xf
	v_fmac_f32_dpp v1, v153, v85 row_newbcast:5 row_mask:0xf bank_mask:0xf
	v_fmac_f32_dpp v2, v153, v86 row_newbcast:6 row_mask:0xf bank_mask:0xf
	v_fmac_f32_dpp v3, v153, v87 row_newbcast:7 row_mask:0xf bank_mask:0xf
	v_fmac_f32_dpp v0, v153, v88 row_newbcast:8 row_mask:0xf bank_mask:0xf
	v_fmac_f32_dpp v1, v153, v89 row_newbcast:9 row_mask:0xf bank_mask:0xf
	v_fmac_f32_dpp v2, v153, v90 row_newbcast:10 row_mask:0xf bank_mask:0xf
	v_fmac_f32_dpp v3, v153, v91 row_newbcast:11 row_mask:0xf bank_mask:0xf
	v_fmac_f32_dpp v0, v153, v92 row_newbcast:12 row_mask:0xf bank_mask:0xf
	v_fmac_f32_dpp v1, v153, v93 row_newbcast:13 row_mask:0xf bank_mask:0xf
	v_fmac_f32_dpp v2, v153, v94 row_newbcast:14 row_mask:0xf bank_mask:0xf
	v_fmac_f32_dpp v3, v153, v95 row_newbcast:15 row_mask:0xf bank_mask:0xf
	ds_read_b32 v165, v7 offset:16112
	s_waitcnt lgkmcnt(11)
	v_fmac_f32_dpp v0, v154, v96 row_newbcast:0 row_mask:0xf bank_mask:0xf
	v_fmac_f32_dpp v1, v154, v97 row_newbcast:1 row_mask:0xf bank_mask:0xf
	v_fmac_f32_dpp v2, v154, v98 row_newbcast:2 row_mask:0xf bank_mask:0xf
	v_fmac_f32_dpp v3, v154, v99 row_newbcast:3 row_mask:0xf bank_mask:0xf
	v_fmac_f32_dpp v0, v154, v100 row_newbcast:4 row_mask:0xf bank_mask:0xf
	v_fmac_f32_dpp v1, v154, v101 row_newbcast:5 row_mask:0xf bank_mask:0xf
	v_fmac_f32_dpp v2, v154, v102 row_newbcast:6 row_mask:0xf bank_mask:0xf
	v_fmac_f32_dpp v3, v154, v103 row_newbcast:7 row_mask:0xf bank_mask:0xf
	v_fmac_f32_dpp v0, v154, v104 row_newbcast:8 row_mask:0xf bank_mask:0xf
	v_fmac_f32_dpp v1, v154, v105 row_newbcast:9 row_mask:0xf bank_mask:0xf
	v_fmac_f32_dpp v2, v154, v106 row_newbcast:10 row_mask:0xf bank_mask:0xf
	v_fmac_f32_dpp v3, v154, v107 row_newbcast:11 row_mask:0xf bank_mask:0xf
	v_fmac_f32_dpp v0, v154, v108 row_newbcast:12 row_mask:0xf bank_mask:0xf
	v_fmac_f32_dpp v1, v154, v109 row_newbcast:13 row_mask:0xf bank_mask:0xf
	v_fmac_f32_dpp v2, v154, v110 row_newbcast:14 row_mask:0xf bank_mask:0xf
	v_fmac_f32_dpp v3, v154, v111 row_newbcast:15 row_mask:0xf bank_mask:0xf
	ds_read_b32 v166, v7 offset:16176
	s_waitcnt lgkmcnt(11)
	v_fmac_f32_dpp v0, v155, v112 row_newbcast:0 row_mask:0xf bank_mask:0xf
	v_fmac_f32_dpp v1, v155, v113 row_newbcast:1 row_mask:0xf bank_mask:0xf
	v_fmac_f32_dpp v2, v155, v114 row_newbcast:2 row_mask:0xf bank_mask:0xf
	v_fmac_f32_dpp v3, v155, v115 row_newbcast:3 row_mask:0xf bank_mask:0xf
	v_fmac_f32_dpp v0, v155, v116 row_newbcast:4 row_mask:0xf bank_mask:0xf
	v_fmac_f32_dpp v1, v155, v117 row_newbcast:5 row_mask:0xf bank_mask:0xf
	v_fmac_f32_dpp v2, v155, v118 row_newbcast:6 row_mask:0xf bank_mask:0xf
	v_fmac_f32_dpp v3, v155, v119 row_newbcast:7 row_mask:0xf bank_mask:0xf
	ds_read_b32 v167, v7 offset:16240
	v_add_f32_e32 v0, v0, v1
	v_add_f32_e32 v2, v2, v3
	v_add_f32_e32 v0, v0, v2
	v_add_f32_e32 v120, v120, v0
	s_waitcnt lgkmcnt(11)
; #define LAS __attribute__((address_space(3)))
; __device__ __forceinline__ void rw_phaseA(LAS unsigned char* lds, const RwCtx& X, int item) {
;     ...
;         for (int tt = 1; tt < 64; ++tt) { float a = x[tt];
; #pragma unroll
;             for (int s4 = 0; s4 < (tt + 3) / 4; ++s4) { const f32x4 l4 = *(const LAS f32x4*)(LABv + tt * 68 + s4 * 4);
;                 a += l4[0] * x[s4 * 4]; if (s4 * 4 + 1 < tt) a += l4[1] * x[s4 * 4 + 1]; if (s4 * 4 + 2 < tt) a += l4[2] * x[s4 * 4 + 2]; if (s4 * 4 + 3 < tt) a += l4[3] * x[s4 * 4 + 3]; }
;             x[tt] = a;
	v_mul_f32_dpp v0, v156, v64 row_newbcast:0 row_mask:0xf bank_mask:0xf
	v_mul_f32_dpp v1, v156, v65 row_newbcast:1 row_mask:0xf bank_mask:0xf
	v_mul_f32_dpp v2, v156, v66 row_newbcast:2 row_mask:0xf bank_mask:0xf
	v_mul_f32_dpp v3, v156, v67 row_newbcast:3 row_mask:0xf bank_mask:0xf
	v_fmac_f32_dpp v0, v156, v68 row_newbcast:4 row_mask:0xf bank_mask:0xf
	v_fmac_f32_dpp v1, v156, v69 row_newbcast:5 row_mask:0xf bank_mask:0xf
	v_fmac_f32_dpp v2, v156, v70 row_newbcast:6 row_mask:0xf bank_mask:0xf
	v_fmac_f32_dpp v3, v156, v71 row_newbcast:7 row_mask:0xf bank_mask:0xf
	v_fmac_f32_dpp v0, v156, v72 row_newbcast:8 row_mask:0xf bank_mask:0xf
	v_fmac_f32_dpp v1, v156, v73 row_newbcast:9 row_mask:0xf bank_mask:0xf
	v_fmac_f32_dpp v2, v156, v74 row_newbcast:10 row_mask:0xf bank_mask:0xf
	v_fmac_f32_dpp v3, v156, v75 row_newbcast:11 row_mask:0xf bank_mask:0xf
	v_fmac_f32_dpp v0, v156, v76 row_newbcast:12 row_mask:0xf bank_mask:0xf
	v_fmac_f32_dpp v1, v156, v77 row_newbcast:13 row_mask:0xf bank_mask:0xf
	v_fmac_f32_dpp v2, v156, v78 row_newbcast:14 row_mask:0xf bank_mask:0xf
	v_fmac_f32_dpp v3, v156, v79 row_newbcast:15 row_mask:0xf bank_mask:0xf
	ds_read_b32 v168, v7 offset:16320
	s_waitcnt lgkmcnt(11)
	v_fmac_f32_dpp v0, v157, v80 row_newbcast:0 row_mask:0xf bank_mask:0xf
	v_fmac_f32_dpp v1, v157, v81 row_newbcast:1 row_mask:0xf bank_mask:0xf
	v_fmac_f32_dpp v2, v157, v82 row_newbcast:2 row_mask:0xf bank_mask:0xf
	v_fmac_f32_dpp v3, v157, v83 row_newbcast:3 row_mask:0xf bank_mask:0xf
	v_fmac_f32_dpp v0, v157, v84 row_newbcast:4 row_mask:0xf bank_mask:0xf
	v_fmac_f32_dpp v1, v157, v85 row_newbcast:5 row_mask:0xf bank_mask:0xf
	v_fmac_f32_dpp v2, v157, v86 row_newbcast:6 row_mask:0xf bank_mask:0xf
	v_fmac_f32_dpp v3, v157, v87 row_newbcast:7 row_mask:0xf bank_mask:0xf
	v_fmac_f32_dpp v0, v157, v88 row_newbcast:8 row_mask:0xf bank_mask:0xf
	v_fmac_f32_dpp v1, v157, v89 row_newbcast:9 row_mask:0xf bank_mask:0xf
	v_fmac_f32_dpp v2, v157, v90 row_newbcast:10 row_mask:0xf bank_mask:0xf
	v_fmac_f32_dpp v3, v157, v91 row_newbcast:11 row_mask:0xf bank_mask:0xf
	v_fmac_f32_dpp v0, v157, v92 row_newbcast:12 row_mask:0xf bank_mask:0xf
	v_fmac_f32_dpp v1, v157, v93 row_newbcast:13 row_mask:0xf bank_mask:0xf
	v_fmac_f32_dpp v2, v157, v94 row_newbcast:14 row_mask:0xf bank_mask:0xf
	v_fmac_f32_dpp v3, v157, v95 row_newbcast:15 row_mask:0xf bank_mask:0xf
	ds_read_b32 v169, v7 offset:16384
	s_waitcnt lgkmcnt(11)
	v_fmac_f32_dpp v0, v158, v96 row_newbcast:0 row_mask:0xf bank_mask:0xf
	v_fmac_f32_dpp v1, v158, v97 row_newbcast:1 row_mask:0xf bank_mask:0xf
	v_fmac_f32_dpp v2, v158, v98 row_newbcast:2 row_mask:0xf bank_mask:0xf
	v_fmac_f32_dpp v3, v158, v99 row_newbcast:3 row_mask:0xf bank_mask:0xf
	v_fmac_f32_dpp v0, v158, v100 row_newbcast:4 row_mask:0xf bank_mask:0xf
	v_fmac_f32_dpp v1, v158, v101 row_newbcast:5 row_mask:0xf bank_mask:0xf
	v_fmac_f32_dpp v2, v158, v102 row_newbcast:6 row_mask:0xf bank_mask:0xf
	v_fmac_f32_dpp v3, v158, v103 row_newbcast:7 row_mask:0xf bank_mask:0xf
	v_fmac_f32_dpp v0, v158, v104 row_newbcast:8 row_mask:0xf bank_mask:0xf
	v_fmac_f32_dpp v1, v158, v105 row_newbcast:9 row_mask:0xf bank_mask:0xf
	v_fmac_f32_dpp v2, v158, v106 row_newbcast:10 row_mask:0xf bank_mask:0xf
	v_fmac_f32_dpp v3, v158, v107 row_newbcast:11 row_mask:0xf bank_mask:0xf
	v_fmac_f32_dpp v0, v158, v108 row_newbcast:12 row_mask:0xf bank_mask:0xf
	v_fmac_f32_dpp v1, v158, v109 row_newbcast:13 row_mask:0xf bank_mask:0xf
	v_fmac_f32_dpp v2, v158, v110 row_newbcast:14 row_mask:0xf bank_mask:0xf
	v_fmac_f32_dpp v3, v158, v111 row_newbcast:15 row_mask:0xf bank_mask:0xf
	ds_read_b32 v170, v7 offset:16448
	s_waitcnt lgkmcnt(11)
	v_fmac_f32_dpp v0, v159, v112 row_newbcast:0 row_mask:0xf bank_mask:0xf
	v_fmac_f32_dpp v1, v159, v113 row_newbcast:1 row_mask:0xf bank_mask:0xf
	v_fmac_f32_dpp v2, v159, v114 row_newbcast:2 row_mask:0xf bank_mask:0xf
	v_fmac_f32_dpp v3, v159, v115 row_newbcast:3 row_mask:0xf bank_mask:0xf
	v_fmac_f32_dpp v0, v159, v116 row_newbcast:4 row_mask:0xf bank_mask:0xf
	v_fmac_f32_dpp v1, v159, v117 row_newbcast:5 row_mask:0xf bank_mask:0xf
	v_fmac_f32_dpp v2, v159, v118 row_newbcast:6 row_mask:0xf bank_mask:0xf
	v_fmac_f32_dpp v3, v159, v119 row_newbcast:7 row_mask:0xf bank_mask:0xf
	v_fmac_f32_dpp v0, v159, v120 row_newbcast:8 row_mask:0xf bank_mask:0xf
	ds_read_b32 v171, v7 offset:16512
	v_add_f32_e32 v0, v0, v1
	v_add_f32_e32 v2, v2, v3
	v_add_f32_e32 v0, v0, v2
	v_add_f32_e32 v121, v121, v0
	s_waitcnt lgkmcnt(11)
	v_mul_f32_dpp v0, v160, v64 row_newbcast:0 row_mask:0xf bank_mask:0xf
	v_mul_f32_dpp v1, v160, v65 row_newbcast:1 row_mask:0xf bank_mask:0xf
	v_mul_f32_dpp v2, v160, v66 row_newbcast:2 row_mask:0xf bank_mask:0xf
	v_mul_f32_dpp v3, v160, v67 row_newbcast:3 row_mask:0xf bank_mask:0xf
	v_fmac_f32_dpp v0, v160, v68 row_newbcast:4 row_mask:0xf bank_mask:0xf
	v_fmac_f32_dpp v1, v160, v69 row_newbcast:5 row_mask:0xf bank_mask:0xf
	v_fmac_f32_dpp v2, v160, v70 row_newbcast:6 row_mask:0xf bank_mask:0xf
	v_fmac_f32_dpp v3, v160, v71 row_newbcast:7 row_mask:0xf bank_mask:0xf
	v_fmac_f32_dpp v0, v160, v72 row_newbcast:8 row_mask:0xf bank_mask:0xf
	v_fmac_f32_dpp v1, v160, v73 row_newbcast:9 row_mask:0xf bank_mask:0xf
	v_fmac_f32_dpp v2, v160, v74 row_newbcast:10 row_mask:0xf bank_mask:0xf
	v_fmac_f32_dpp v3, v160, v75 row_newbcast:11 row_mask:0xf bank_mask:0xf
	v_fmac_f32_dpp v0, v160, v76 row_newbcast:12 row_mask:0xf bank_mask:0xf
	v_fmac_f32_dpp v1, v160, v77 row_newbcast:13 row_mask:0xf bank_mask:0xf
	v_fmac_f32_dpp v2, v160, v78 row_newbcast:14 row_mask:0xf bank_mask:0xf
	v_fmac_f32_dpp v3, v160, v79 row_newbcast:15 row_mask:0xf bank_mask:0xf
	ds_read_b32 v148, v7 offset:16592
	s_waitcnt lgkmcnt(11)
; #define LAS __attribute__((address_space(3)))
; __device__ __forceinline__ void rw_phaseA(LAS unsigned char* lds, const RwCtx& X, int item) {
;     ...
;         for (int tt = 1; tt < 64; ++tt) { float a = x[tt];
; #pragma unroll
;             for (int s4 = 0; s4 < (tt + 3) / 4; ++s4) { const f32x4 l4 = *(const LAS f32x4*)(LABv + tt * 68 + s4 * 4);
;                 a += l4[0] * x[s4 * 4]; if (s4 * 4 + 1 < tt) a += l4[1] * x[s4 * 4 + 1]; if (s4 * 4 + 2 < tt) a += l4[2] * x[s4 * 4 + 2]; if (s4 * 4 + 3 < tt) a += l4[3] * x[s4 * 4 + 3]; }
;             x[tt] = a;
	v_fmac_f32_dpp v0, v161, v80 row_newbcast:0 row_mask:0xf bank_mask:0xf
	v_fmac_f32_dpp v1, v161, v81 row_newbcast:1 row_mask:0xf bank_mask:0xf
	v_fmac_f32_dpp v2, v161, v82 row_newbcast:2 row_mask:0xf bank_mask:0xf
	v_fmac_f32_dpp v3, v161, v83 row_newbcast:3 row_mask:0xf bank_mask:0xf
	v_fmac_f32_dpp v0, v161, v84 row_newbcast:4 row_mask:0xf bank_mask:0xf
	v_fmac_f32_dpp v1, v161, v85 row_newbcast:5 row_mask:0xf bank_mask:0xf
	v_fmac_f32_dpp v2, v161, v86 row_newbcast:6 row_mask:0xf bank_mask:0xf
	v_fmac_f32_dpp v3, v161, v87 row_newbcast:7 row_mask:0xf bank_mask:0xf
	v_fmac_f32_dpp v0, v161, v88 row_newbcast:8 row_mask:0xf bank_mask:0xf
	v_fmac_f32_dpp v1, v161, v89 row_newbcast:9 row_mask:0xf bank_mask:0xf
	v_fmac_f32_dpp v2, v161, v90 row_newbcast:10 row_mask:0xf bank_mask:0xf
	v_fmac_f32_dpp v3, v161, v91 row_newbcast:11 row_mask:0xf bank_mask:0xf
	v_fmac_f32_dpp v0, v161, v92 row_newbcast:12 row_mask:0xf bank_mask:0xf
	v_fmac_f32_dpp v1, v161, v93 row_newbcast:13 row_mask:0xf bank_mask:0xf
	v_fmac_f32_dpp v2, v161, v94 row_newbcast:14 row_mask:0xf bank_mask:0xf
	v_fmac_f32_dpp v3, v161, v95 row_newbcast:15 row_mask:0xf bank_mask:0xf
	ds_read_b32 v149, v7 offset:16656
	s_waitcnt lgkmcnt(11)
	v_fmac_f32_dpp v0, v162, v96 row_newbcast:0 row_mask:0xf bank_mask:0xf
	v_fmac_f32_dpp v1, v162, v97 row_newbcast:1 row_mask:0xf bank_mask:0xf
	v_fmac_f32_dpp v2, v162, v98 row_newbcast:2 row_mask:0xf bank_mask:0xf
	v_fmac_f32_dpp v3, v162, v99 row_newbcast:3 row_mask:0xf bank_mask:0xf
	v_fmac_f32_dpp v0, v162, v100 row_newbcast:4 row_mask:0xf bank_mask:0xf
	v_fmac_f32_dpp v1, v162, v101 row_newbcast:5 row_mask:0xf bank_mask:0xf
	v_fmac_f32_dpp v2, v162, v102 row_newbcast:6 row_mask:0xf bank_mask:0xf
	v_fmac_f32_dpp v3, v162, v103 row_newbcast:7 row_mask:0xf bank_mask:0xf
	v_fmac_f32_dpp v0, v162, v104 row_newbcast:8 row_mask:0xf bank_mask:0xf
	v_fmac_f32_dpp v1, v162, v105 row_newbcast:9 row_mask:0xf bank_mask:0xf
	v_fmac_f32_dpp v2, v162, v106 row_newbcast:10 row_mask:0xf bank_mask:0xf
	v_fmac_f32_dpp v3, v162, v107 row_newbcast:11 row_mask:0xf bank_mask:0xf
	v_fmac_f32_dpp v0, v162, v108 row_newbcast:12 row_mask:0xf bank_mask:0xf
	v_fmac_f32_dpp v1, v162, v109 row_newbcast:13 row_mask:0xf bank_mask:0xf
	v_fmac_f32_dpp v2, v162, v110 row_newbcast:14 row_mask:0xf bank_mask:0xf
	v_fmac_f32_dpp v3, v162, v111 row_newbcast:15 row_mask:0xf bank_mask:0xf
	ds_read_b32 v150, v7 offset:16720
	s_waitcnt lgkmcnt(11)
	v_fmac_f32_dpp v0, v163, v112 row_newbcast:0 row_mask:0xf bank_mask:0xf
	v_fmac_f32_dpp v1, v163, v113 row_newbcast:1 row_mask:0xf bank_mask:0xf
	v_fmac_f32_dpp v2, v163, v114 row_newbcast:2 row_mask:0xf bank_mask:0xf
	v_fmac_f32_dpp v3, v163, v115 row_newbcast:3 row_mask:0xf bank_mask:0xf
	v_fmac_f32_dpp v0, v163, v116 row_newbcast:4 row_mask:0xf bank_mask:0xf
	v_fmac_f32_dpp v1, v163, v117 row_newbcast:5 row_mask:0xf bank_mask:0xf
	v_fmac_f32_dpp v2, v163, v118 row_newbcast:6 row_mask:0xf bank_mask:0xf
	v_fmac_f32_dpp v3, v163, v119 row_newbcast:7 row_mask:0xf bank_mask:0xf
	v_fmac_f32_dpp v0, v163, v120 row_newbcast:8 row_mask:0xf bank_mask:0xf
	v_fmac_f32_dpp v1, v163, v121 row_newbcast:9 row_mask:0xf bank_mask:0xf
	ds_read_b32 v151, v7 offset:16784
	v_add_f32_e32 v0, v0, v1
	v_add_f32_e32 v2, v2, v3
	v_add_f32_e32 v0, v0, v2
	v_add_f32_e32 v122, v122, v0
	s_waitcnt lgkmcnt(11)
	v_mul_f32_dpp v0, v164, v64 row_newbcast:0 row_mask:0xf bank_mask:0xf
	v_mul_f32_dpp v1, v164, v65 row_newbcast:1 row_mask:0xf bank_mask:0xf
	v_mul_f32_dpp v2, v164, v66 row_newbcast:2 row_mask:0xf bank_mask:0xf
	v_mul_f32_dpp v3, v164, v67 row_newbcast:3 row_mask:0xf bank_mask:0xf
	v_fmac_f32_dpp v0, v164, v68 row_newbcast:4 row_mask:0xf bank_mask:0xf
	v_fmac_f32_dpp v1, v164, v69 row_newbcast:5 row_mask:0xf bank_mask:0xf
	v_fmac_f32_dpp v2, v164, v70 row_newbcast:6 row_mask:0xf bank_mask:0xf
	v_fmac_f32_dpp v3, v164, v71 row_newbcast:7 row_mask:0xf bank_mask:0xf
	v_fmac_f32_dpp v0, v164, v72 row_newbcast:8 row_mask:0xf bank_mask:0xf
	v_fmac_f32_dpp v1, v164, v73 row_newbcast:9 row_mask:0xf bank_mask:0xf
	v_fmac_f32_dpp v2, v164, v74 row_newbcast:10 row_mask:0xf bank_mask:0xf
	v_fmac_f32_dpp v3, v164, v75 row_newbcast:11 row_mask:0xf bank_mask:0xf
	v_fmac_f32_dpp v0, v164, v76 row_newbcast:12 row_mask:0xf bank_mask:0xf
	v_fmac_f32_dpp v1, v164, v77 row_newbcast:13 row_mask:0xf bank_mask:0xf
	v_fmac_f32_dpp v2, v164, v78 row_newbcast:14 row_mask:0xf bank_mask:0xf
	v_fmac_f32_dpp v3, v164, v79 row_newbcast:15 row_mask:0xf bank_mask:0xf
	ds_read_b32 v152, v7 offset:16864
	s_waitcnt lgkmcnt(11)
	v_fmac_f32_dpp v0, v165, v80 row_newbcast:0 row_mask:0xf bank_mask:0xf
	v_fmac_f32_dpp v1, v165, v81 row_newbcast:1 row_mask:0xf bank_mask:0xf
	v_fmac_f32_dpp v2, v165, v82 row_newbcast:2 row_mask:0xf bank_mask:0xf
	v_fmac_f32_dpp v3, v165, v83 row_newbcast:3 row_mask:0xf bank_mask:0xf
	v_fmac_f32_dpp v0, v165, v84 row_newbcast:4 row_mask:0xf bank_mask:0xf
	v_fmac_f32_dpp v1, v165, v85 row_newbcast:5 row_mask:0xf bank_mask:0xf
	v_fmac_f32_dpp v2, v165, v86 row_newbcast:6 row_mask:0xf bank_mask:0xf
	v_fmac_f32_dpp v3, v165, v87 row_newbcast:7 row_mask:0xf bank_mask:0xf
	v_fmac_f32_dpp v0, v165, v88 row_newbcast:8 row_mask:0xf bank_mask:0xf
	v_fmac_f32_dpp v1, v165, v89 row_newbcast:9 row_mask:0xf bank_mask:0xf
	v_fmac_f32_dpp v2, v165, v90 row_newbcast:10 row_mask:0xf bank_mask:0xf
	v_fmac_f32_dpp v3, v165, v91 row_newbcast:11 row_mask:0xf bank_mask:0xf
	v_fmac_f32_dpp v0, v165, v92 row_newbcast:12 row_mask:0xf bank_mask:0xf
	v_fmac_f32_dpp v1, v165, v93 row_newbcast:13 row_mask:0xf bank_mask:0xf
	v_fmac_f32_dpp v2, v165, v94 row_newbcast:14 row_mask:0xf bank_mask:0xf
	v_fmac_f32_dpp v3, v165, v95 row_newbcast:15 row_mask:0xf bank_mask:0xf
	ds_read_b32 v153, v7 offset:16928
	s_waitcnt lgkmcnt(11)
; #define LAS __attribute__((address_space(3)))
; __device__ __forceinline__ void rw_phaseA(LAS unsigned char* lds, const RwCtx& X, int item) {
;     ...
;         for (int tt = 1; tt < 64; ++tt) { float a = x[tt];
; #pragma unroll
;             for (int s4 = 0; s4 < (tt + 3) / 4; ++s4) { const f32x4 l4 = *(const LAS f32x4*)(LABv + tt * 68 + s4 * 4);
;                 a += l4[0] * x[s4 * 4]; if (s4 * 4 + 1 < tt) a += l4[1] * x[s4 * 4 + 1]; if (s4 * 4 + 2 < tt) a += l4[2] * x[s4 * 4 + 2]; if (s4 * 4 + 3 < tt) a += l4[3] * x[s4 * 4 + 3]; }
;             x[tt] = a;
	v_fmac_f32_dpp v0, v166, v96 row_newbcast:0 row_mask:0xf bank_mask:0xf
	v_fmac_f32_dpp v1, v166, v97 row_newbcast:1 row_mask:0xf bank_mask:0xf
	v_fmac_f32_dpp v2, v166, v98 row_newbcast:2 row_mask:0xf bank_mask:0xf
	v_fmac_f32_dpp v3, v166, v99 row_newbcast:3 row_mask:0xf bank_mask:0xf
	v_fmac_f32_dpp v0, v166, v100 row_newbcast:4 row_mask:0xf bank_mask:0xf
	v_fmac_f32_dpp v1, v166, v101 row_newbcast:5 row_mask:0xf bank_mask:0xf
	v_fmac_f32_dpp v2, v166, v102 row_newbcast:6 row_mask:0xf bank_mask:0xf
	v_fmac_f32_dpp v3, v166, v103 row_newbcast:7 row_mask:0xf bank_mask:0xf
	v_fmac_f32_dpp v0, v166, v104 row_newbcast:8 row_mask:0xf bank_mask:0xf
	v_fmac_f32_dpp v1, v166, v105 row_newbcast:9 row_mask:0xf bank_mask:0xf
	v_fmac_f32_dpp v2, v166, v106 row_newbcast:10 row_mask:0xf bank_mask:0xf
	v_fmac_f32_dpp v3, v166, v107 row_newbcast:11 row_mask:0xf bank_mask:0xf
	v_fmac_f32_dpp v0, v166, v108 row_newbcast:12 row_mask:0xf bank_mask:0xf
	v_fmac_f32_dpp v1, v166, v109 row_newbcast:13 row_mask:0xf bank_mask:0xf
	v_fmac_f32_dpp v2, v166, v110 row_newbcast:14 row_mask:0xf bank_mask:0xf
	v_fmac_f32_dpp v3, v166, v111 row_newbcast:15 row_mask:0xf bank_mask:0xf
	ds_read_b32 v154, v7 offset:16992
	s_waitcnt lgkmcnt(11)
	v_fmac_f32_dpp v0, v167, v112 row_newbcast:0 row_mask:0xf bank_mask:0xf
	v_fmac_f32_dpp v1, v167, v113 row_newbcast:1 row_mask:0xf bank_mask:0xf
	v_fmac_f32_dpp v2, v167, v114 row_newbcast:2 row_mask:0xf bank_mask:0xf
	v_fmac_f32_dpp v3, v167, v115 row_newbcast:3 row_mask:0xf bank_mask:0xf
	v_fmac_f32_dpp v0, v167, v116 row_newbcast:4 row_mask:0xf bank_mask:0xf
	v_fmac_f32_dpp v1, v167, v117 row_newbcast:5 row_mask:0xf bank_mask:0xf
	v_fmac_f32_dpp v2, v167, v118 row_newbcast:6 row_mask:0xf bank_mask:0xf
	v_fmac_f32_dpp v3, v167, v119 row_newbcast:7 row_mask:0xf bank_mask:0xf
	v_fmac_f32_dpp v0, v167, v120 row_newbcast:8 row_mask:0xf bank_mask:0xf
	v_fmac_f32_dpp v1, v167, v121 row_newbcast:9 row_mask:0xf bank_mask:0xf
	v_fmac_f32_dpp v2, v167, v122 row_newbcast:10 row_mask:0xf bank_mask:0xf
	ds_read_b32 v155, v7 offset:17056
	v_add_f32_e32 v0, v0, v1
	v_add_f32_e32 v2, v2, v3
	v_add_f32_e32 v0, v0, v2
	v_add_f32_e32 v123, v123, v0
	s_waitcnt lgkmcnt(11)
	v_mul_f32_dpp v0, v168, v64 row_newbcast:0 row_mask:0xf bank_mask:0xf
	v_mul_f32_dpp v1, v168, v65 row_newbcast:1 row_mask:0xf bank_mask:0xf
	v_mul_f32_dpp v2, v168, v66 row_newbcast:2 row_mask:0xf bank_mask:0xf
	v_mul_f32_dpp v3, v168, v67 row_newbcast:3 row_mask:0xf bank_mask:0xf
	v_fmac_f32_dpp v0, v168, v68 row_newbcast:4 row_mask:0xf bank_mask:0xf
	v_fmac_f32_dpp v1, v168, v69 row_newbcast:5 row_mask:0xf bank_mask:0xf
	v_fmac_f32_dpp v2, v168, v70 row_newbcast:6 row_mask:0xf bank_mask:0xf
	v_fmac_f32_dpp v3, v168, v71 row_newbcast:7 row_mask:0xf bank_mask:0xf
	v_fmac_f32_dpp v0, v168, v72 row_newbcast:8 row_mask:0xf bank_mask:0xf
	v_fmac_f32_dpp v1, v168, v73 row_newbcast:9 row_mask:0xf bank_mask:0xf
	v_fmac_f32_dpp v2, v168, v74 row_newbcast:10 row_mask:0xf bank_mask:0xf
	v_fmac_f32_dpp v3, v168, v75 row_newbcast:11 row_mask:0xf bank_mask:0xf
	v_fmac_f32_dpp v0, v168, v76 row_newbcast:12 row_mask:0xf bank_mask:0xf
	v_fmac_f32_dpp v1, v168, v77 row_newbcast:13 row_mask:0xf bank_mask:0xf
	v_fmac_f32_dpp v2, v168, v78 row_newbcast:14 row_mask:0xf bank_mask:0xf
	v_fmac_f32_dpp v3, v168, v79 row_newbcast:15 row_mask:0xf bank_mask:0xf
	ds_read_b32 v156, v7 offset:17136
	s_waitcnt lgkmcnt(11)
	v_fmac_f32_dpp v0, v169, v80 row_newbcast:0 row_mask:0xf bank_mask:0xf
	v_fmac_f32_dpp v1, v169, v81 row_newbcast:1 row_mask:0xf bank_mask:0xf
	v_fmac_f32_dpp v2, v169, v82 row_newbcast:2 row_mask:0xf bank_mask:0xf
	v_fmac_f32_dpp v3, v169, v83 row_newbcast:3 row_mask:0xf bank_mask:0xf
	v_fmac_f32_dpp v0, v169, v84 row_newbcast:4 row_mask:0xf bank_mask:0xf
	v_fmac_f32_dpp v1, v169, v85 row_newbcast:5 row_mask:0xf bank_mask:0xf
	v_fmac_f32_dpp v2, v169, v86 row_newbcast:6 row_mask:0xf bank_mask:0xf
	v_fmac_f32_dpp v3, v169, v87 row_newbcast:7 row_mask:0xf bank_mask:0xf
	v_fmac_f32_dpp v0, v169, v88 row_newbcast:8 row_mask:0xf bank_mask:0xf
	v_fmac_f32_dpp v1, v169, v89 row_newbcast:9 row_mask:0xf bank_mask:0xf
	v_fmac_f32_dpp v2, v169, v90 row_newbcast:10 row_mask:0xf bank_mask:0xf
	v_fmac_f32_dpp v3, v169, v91 row_newbcast:11 row_mask:0xf bank_mask:0xf
	v_fmac_f32_dpp v0, v169, v92 row_newbcast:12 row_mask:0xf bank_mask:0xf
	v_fmac_f32_dpp v1, v169, v93 row_newbcast:13 row_mask:0xf bank_mask:0xf
	v_fmac_f32_dpp v2, v169, v94 row_newbcast:14 row_mask:0xf bank_mask:0xf
	v_fmac_f32_dpp v3, v169, v95 row_newbcast:15 row_mask:0xf bank_mask:0xf
	ds_read_b32 v157, v7 offset:17200
	s_waitcnt lgkmcnt(11)
	v_fmac_f32_dpp v0, v170, v96 row_newbcast:0 row_mask:0xf bank_mask:0xf
	v_fmac_f32_dpp v1, v170, v97 row_newbcast:1 row_mask:0xf bank_mask:0xf
	v_fmac_f32_dpp v2, v170, v98 row_newbcast:2 row_mask:0xf bank_mask:0xf
	v_fmac_f32_dpp v3, v170, v99 row_newbcast:3 row_mask:0xf bank_mask:0xf
	v_fmac_f32_dpp v0, v170, v100 row_newbcast:4 row_mask:0xf bank_mask:0xf
	v_fmac_f32_dpp v1, v170, v101 row_newbcast:5 row_mask:0xf bank_mask:0xf
	v_fmac_f32_dpp v2, v170, v102 row_newbcast:6 row_mask:0xf bank_mask:0xf
	v_fmac_f32_dpp v3, v170, v103 row_newbcast:7 row_mask:0xf bank_mask:0xf
	v_fmac_f32_dpp v0, v170, v104 row_newbcast:8 row_mask:0xf bank_mask:0xf
	v_fmac_f32_dpp v1, v170, v105 row_newbcast:9 row_mask:0xf bank_mask:0xf
	v_fmac_f32_dpp v2, v170, v106 row_newbcast:10 row_mask:0xf bank_mask:0xf
	v_fmac_f32_dpp v3, v170, v107 row_newbcast:11 row_mask:0xf bank_mask:0xf
	v_fmac_f32_dpp v0, v170, v108 row_newbcast:12 row_mask:0xf bank_mask:0xf
	v_fmac_f32_dpp v1, v170, v109 row_newbcast:13 row_mask:0xf bank_mask:0xf
	v_fmac_f32_dpp v2, v170, v110 row_newbcast:14 row_mask:0xf bank_mask:0xf
	v_fmac_f32_dpp v3, v170, v111 row_newbcast:15 row_mask:0xf bank_mask:0xf
	ds_read_b32 v158, v7 offset:17264
	s_waitcnt lgkmcnt(11)
; #define LAS __attribute__((address_space(3)))
; __device__ __forceinline__ void rw_phaseA(LAS unsigned char* lds, const RwCtx& X, int item) {
;     ...
;         for (int tt = 1; tt < 64; ++tt) { float a = x[tt];
; #pragma unroll
;             for (int s4 = 0; s4 < (tt + 3) / 4; ++s4) { const f32x4 l4 = *(const LAS f32x4*)(LABv + tt * 68 + s4 * 4);
;                 a += l4[0] * x[s4 * 4]; if (s4 * 4 + 1 < tt) a += l4[1] * x[s4 * 4 + 1]; if (s4 * 4 + 2 < tt) a += l4[2] * x[s4 * 4 + 2]; if (s4 * 4 + 3 < tt) a += l4[3] * x[s4 * 4 + 3]; }
;             x[tt] = a;
	v_fmac_f32_dpp v0, v171, v112 row_newbcast:0 row_mask:0xf bank_mask:0xf
	v_fmac_f32_dpp v1, v171, v113 row_newbcast:1 row_mask:0xf bank_mask:0xf
	v_fmac_f32_dpp v2, v171, v114 row_newbcast:2 row_mask:0xf bank_mask:0xf
	v_fmac_f32_dpp v3, v171, v115 row_newbcast:3 row_mask:0xf bank_mask:0xf
	v_fmac_f32_dpp v0, v171, v116 row_newbcast:4 row_mask:0xf bank_mask:0xf
	v_fmac_f32_dpp v1, v171, v117 row_newbcast:5 row_mask:0xf bank_mask:0xf
	v_fmac_f32_dpp v2, v171, v118 row_newbcast:6 row_mask:0xf bank_mask:0xf
	v_fmac_f32_dpp v3, v171, v119 row_newbcast:7 row_mask:0xf bank_mask:0xf
	v_fmac_f32_dpp v0, v171, v120 row_newbcast:8 row_mask:0xf bank_mask:0xf
	v_fmac_f32_dpp v1, v171, v121 row_newbcast:9 row_mask:0xf bank_mask:0xf
	v_fmac_f32_dpp v2, v171, v122 row_newbcast:10 row_mask:0xf bank_mask:0xf
	v_fmac_f32_dpp v3, v171, v123 row_newbcast:11 row_mask:0xf bank_mask:0xf
	ds_read_b32 v159, v7 offset:17328
	v_add_f32_e32 v0, v0, v1
	v_add_f32_e32 v2, v2, v3
	v_add_f32_e32 v0, v0, v2
	v_add_f32_e32 v124, v124, v0
	s_waitcnt lgkmcnt(11)
	v_mul_f32_dpp v0, v148, v64 row_newbcast:0 row_mask:0xf bank_mask:0xf
	v_mul_f32_dpp v1, v148, v65 row_newbcast:1 row_mask:0xf bank_mask:0xf
	v_mul_f32_dpp v2, v148, v66 row_newbcast:2 row_mask:0xf bank_mask:0xf
	v_mul_f32_dpp v3, v148, v67 row_newbcast:3 row_mask:0xf bank_mask:0xf
	v_fmac_f32_dpp v0, v148, v68 row_newbcast:4 row_mask:0xf bank_mask:0xf
	v_fmac_f32_dpp v1, v148, v69 row_newbcast:5 row_mask:0xf bank_mask:0xf
	v_fmac_f32_dpp v2, v148, v70 row_newbcast:6 row_mask:0xf bank_mask:0xf
	v_fmac_f32_dpp v3, v148, v71 row_newbcast:7 row_mask:0xf bank_mask:0xf
	v_fmac_f32_dpp v0, v148, v72 row_newbcast:8 row_mask:0xf bank_mask:0xf
	v_fmac_f32_dpp v1, v148, v73 row_newbcast:9 row_mask:0xf bank_mask:0xf
	v_fmac_f32_dpp v2, v148, v74 row_newbcast:10 row_mask:0xf bank_mask:0xf
	v_fmac_f32_dpp v3, v148, v75 row_newbcast:11 row_mask:0xf bank_mask:0xf
	v_fmac_f32_dpp v0, v148, v76 row_newbcast:12 row_mask:0xf bank_mask:0xf
	v_fmac_f32_dpp v1, v148, v77 row_newbcast:13 row_mask:0xf bank_mask:0xf
	v_fmac_f32_dpp v2, v148, v78 row_newbcast:14 row_mask:0xf bank_mask:0xf
	v_fmac_f32_dpp v3, v148, v79 row_newbcast:15 row_mask:0xf bank_mask:0xf
	s_waitcnt lgkmcnt(10)
	v_fmac_f32_dpp v0, v149, v80 row_newbcast:0 row_mask:0xf bank_mask:0xf
	v_fmac_f32_dpp v1, v149, v81 row_newbcast:1 row_mask:0xf bank_mask:0xf
	v_fmac_f32_dpp v2, v149, v82 row_newbcast:2 row_mask:0xf bank_mask:0xf
	v_fmac_f32_dpp v3, v149, v83 row_newbcast:3 row_mask:0xf bank_mask:0xf
	v_fmac_f32_dpp v0, v149, v84 row_newbcast:4 row_mask:0xf bank_mask:0xf
	v_fmac_f32_dpp v1, v149, v85 row_newbcast:5 row_mask:0xf bank_mask:0xf
	v_fmac_f32_dpp v2, v149, v86 row_newbcast:6 row_mask:0xf bank_mask:0xf
	v_fmac_f32_dpp v3, v149, v87 row_newbcast:7 row_mask:0xf bank_mask:0xf
	v_fmac_f32_dpp v0, v149, v88 row_newbcast:8 row_mask:0xf bank_mask:0xf
	v_fmac_f32_dpp v1, v149, v89 row_newbcast:9 row_mask:0xf bank_mask:0xf
	v_fmac_f32_dpp v2, v149, v90 row_newbcast:10 row_mask:0xf bank_mask:0xf
	v_fmac_f32_dpp v3, v149, v91 row_newbcast:11 row_mask:0xf bank_mask:0xf
	v_fmac_f32_dpp v0, v149, v92 row_newbcast:12 row_mask:0xf bank_mask:0xf
	v_fmac_f32_dpp v1, v149, v93 row_newbcast:13 row_mask:0xf bank_mask:0xf
	v_fmac_f32_dpp v2, v149, v94 row_newbcast:14 row_mask:0xf bank_mask:0xf
	v_fmac_f32_dpp v3, v149, v95 row_newbcast:15 row_mask:0xf bank_mask:0xf
	s_waitcnt lgkmcnt(9)
	v_fmac_f32_dpp v0, v150, v96 row_newbcast:0 row_mask:0xf bank_mask:0xf
	v_fmac_f32_dpp v1, v150, v97 row_newbcast:1 row_mask:0xf bank_mask:0xf
	v_fmac_f32_dpp v2, v150, v98 row_newbcast:2 row_mask:0xf bank_mask:0xf
	v_fmac_f32_dpp v3, v150, v99 row_newbcast:3 row_mask:0xf bank_mask:0xf
	v_fmac_f32_dpp v0, v150, v100 row_newbcast:4 row_mask:0xf bank_mask:0xf
	v_fmac_f32_dpp v1, v150, v101 row_newbcast:5 row_mask:0xf bank_mask:0xf
	v_fmac_f32_dpp v2, v150, v102 row_newbcast:6 row_mask:0xf bank_mask:0xf
	v_fmac_f32_dpp v3, v150, v103 row_newbcast:7 row_mask:0xf bank_mask:0xf
	v_fmac_f32_dpp v0, v150, v104 row_newbcast:8 row_mask:0xf bank_mask:0xf
	v_fmac_f32_dpp v1, v150, v105 row_newbcast:9 row_mask:0xf bank_mask:0xf
	v_fmac_f32_dpp v2, v150, v106 row_newbcast:10 row_mask:0xf bank_mask:0xf
	v_fmac_f32_dpp v3, v150, v107 row_newbcast:11 row_mask:0xf bank_mask:0xf
	v_fmac_f32_dpp v0, v150, v108 row_newbcast:12 row_mask:0xf bank_mask:0xf
	v_fmac_f32_dpp v1, v150, v109 row_newbcast:13 row_mask:0xf bank_mask:0xf
	v_fmac_f32_dpp v2, v150, v110 row_newbcast:14 row_mask:0xf bank_mask:0xf
	v_fmac_f32_dpp v3, v150, v111 row_newbcast:15 row_mask:0xf bank_mask:0xf
	s_waitcnt lgkmcnt(8)
	v_fmac_f32_dpp v0, v151, v112 row_newbcast:0 row_mask:0xf bank_mask:0xf
	v_fmac_f32_dpp v1, v151, v113 row_newbcast:1 row_mask:0xf bank_mask:0xf
	v_fmac_f32_dpp v2, v151, v114 row_newbcast:2 row_mask:0xf bank_mask:0xf
	v_fmac_f32_dpp v3, v151, v115 row_newbcast:3 row_mask:0xf bank_mask:0xf
	v_fmac_f32_dpp v0, v151, v116 row_newbcast:4 row_mask:0xf bank_mask:0xf
	v_fmac_f32_dpp v1, v151, v117 row_newbcast:5 row_mask:0xf bank_mask:0xf
	v_fmac_f32_dpp v2, v151, v118 row_newbcast:6 row_mask:0xf bank_mask:0xf
	v_fmac_f32_dpp v3, v151, v119 row_newbcast:7 row_mask:0xf bank_mask:0xf
	v_fmac_f32_dpp v0, v151, v120 row_newbcast:8 row_mask:0xf bank_mask:0xf
	v_fmac_f32_dpp v1, v151, v121 row_newbcast:9 row_mask:0xf bank_mask:0xf
	v_fmac_f32_dpp v2, v151, v122 row_newbcast:10 row_mask:0xf bank_mask:0xf
	v_fmac_f32_dpp v3, v151, v123 row_newbcast:11 row_mask:0xf bank_mask:0xf
	v_fmac_f32_dpp v0, v151, v124 row_newbcast:12 row_mask:0xf bank_mask:0xf
	v_add_f32_e32 v0, v0, v1
	v_add_f32_e32 v2, v2, v3
	v_add_f32_e32 v0, v0, v2
	v_add_f32_e32 v125, v125, v0
	s_waitcnt lgkmcnt(7)
; #define LAS __attribute__((address_space(3)))
; __device__ __forceinline__ void rw_phaseA(LAS unsigned char* lds, const RwCtx& X, int item) {
;     ...
;         for (int tt = 1; tt < 64; ++tt) { float a = x[tt];
; #pragma unroll
;             for (int s4 = 0; s4 < (tt + 3) / 4; ++s4) { const f32x4 l4 = *(const LAS f32x4*)(LABv + tt * 68 + s4 * 4);
;                 a += l4[0] * x[s4 * 4]; if (s4 * 4 + 1 < tt) a += l4[1] * x[s4 * 4 + 1]; if (s4 * 4 + 2 < tt) a += l4[2] * x[s4 * 4 + 2]; if (s4 * 4 + 3 < tt) a += l4[3] * x[s4 * 4 + 3]; }
;             x[tt] = a;
	v_mul_f32_dpp v0, v152, v64 row_newbcast:0 row_mask:0xf bank_mask:0xf
	v_mul_f32_dpp v1, v152, v65 row_newbcast:1 row_mask:0xf bank_mask:0xf
	v_mul_f32_dpp v2, v152, v66 row_newbcast:2 row_mask:0xf bank_mask:0xf
	v_mul_f32_dpp v3, v152, v67 row_newbcast:3 row_mask:0xf bank_mask:0xf
	v_fmac_f32_dpp v0, v152, v68 row_newbcast:4 row_mask:0xf bank_mask:0xf
	v_fmac_f32_dpp v1, v152, v69 row_newbcast:5 row_mask:0xf bank_mask:0xf
	v_fmac_f32_dpp v2, v152, v70 row_newbcast:6 row_mask:0xf bank_mask:0xf
	v_fmac_f32_dpp v3, v152, v71 row_newbcast:7 row_mask:0xf bank_mask:0xf
	v_fmac_f32_dpp v0, v152, v72 row_newbcast:8 row_mask:0xf bank_mask:0xf
	v_fmac_f32_dpp v1, v152, v73 row_newbcast:9 row_mask:0xf bank_mask:0xf
	v_fmac_f32_dpp v2, v152, v74 row_newbcast:10 row_mask:0xf bank_mask:0xf
	v_fmac_f32_dpp v3, v152, v75 row_newbcast:11 row_mask:0xf bank_mask:0xf
	v_fmac_f32_dpp v0, v152, v76 row_newbcast:12 row_mask:0xf bank_mask:0xf
	v_fmac_f32_dpp v1, v152, v77 row_newbcast:13 row_mask:0xf bank_mask:0xf
	v_fmac_f32_dpp v2, v152, v78 row_newbcast:14 row_mask:0xf bank_mask:0xf
	v_fmac_f32_dpp v3, v152, v79 row_newbcast:15 row_mask:0xf bank_mask:0xf
	s_waitcnt lgkmcnt(6)
	v_fmac_f32_dpp v0, v153, v80 row_newbcast:0 row_mask:0xf bank_mask:0xf
	v_fmac_f32_dpp v1, v153, v81 row_newbcast:1 row_mask:0xf bank_mask:0xf
	v_fmac_f32_dpp v2, v153, v82 row_newbcast:2 row_mask:0xf bank_mask:0xf
	v_fmac_f32_dpp v3, v153, v83 row_newbcast:3 row_mask:0xf bank_mask:0xf
	v_fmac_f32_dpp v0, v153, v84 row_newbcast:4 row_mask:0xf bank_mask:0xf
	v_fmac_f32_dpp v1, v153, v85 row_newbcast:5 row_mask:0xf bank_mask:0xf
	v_fmac_f32_dpp v2, v153, v86 row_newbcast:6 row_mask:0xf bank_mask:0xf
	v_fmac_f32_dpp v3, v153, v87 row_newbcast:7 row_mask:0xf bank_mask:0xf
	v_fmac_f32_dpp v0, v153, v88 row_newbcast:8 row_mask:0xf bank_mask:0xf
	v_fmac_f32_dpp v1, v153, v89 row_newbcast:9 row_mask:0xf bank_mask:0xf
	v_fmac_f32_dpp v2, v153, v90 row_newbcast:10 row_mask:0xf bank_mask:0xf
	v_fmac_f32_dpp v3, v153, v91 row_newbcast:11 row_mask:0xf bank_mask:0xf
	v_fmac_f32_dpp v0, v153, v92 row_newbcast:12 row_mask:0xf bank_mask:0xf
	v_fmac_f32_dpp v1, v153, v93 row_newbcast:13 row_mask:0xf bank_mask:0xf
	v_fmac_f32_dpp v2, v153, v94 row_newbcast:14 row_mask:0xf bank_mask:0xf
	v_fmac_f32_dpp v3, v153, v95 row_newbcast:15 row_mask:0xf bank_mask:0xf
	s_waitcnt lgkmcnt(5)
	v_fmac_f32_dpp v0, v154, v96 row_newbcast:0 row_mask:0xf bank_mask:0xf
	v_fmac_f32_dpp v1, v154, v97 row_newbcast:1 row_mask:0xf bank_mask:0xf
	v_fmac_f32_dpp v2, v154, v98 row_newbcast:2 row_mask:0xf bank_mask:0xf
	v_fmac_f32_dpp v3, v154, v99 row_newbcast:3 row_mask:0xf bank_mask:0xf
	v_fmac_f32_dpp v0, v154, v100 row_newbcast:4 row_mask:0xf bank_mask:0xf
	v_fmac_f32_dpp v1, v154, v101 row_newbcast:5 row_mask:0xf bank_mask:0xf
	v_fmac_f32_dpp v2, v154, v102 row_newbcast:6 row_mask:0xf bank_mask:0xf
	v_fmac_f32_dpp v3, v154, v103 row_newbcast:7 row_mask:0xf bank_mask:0xf
	v_fmac_f32_dpp v0, v154, v104 row_newbcast:8 row_mask:0xf bank_mask:0xf
	v_fmac_f32_dpp v1, v154, v105 row_newbcast:9 row_mask:0xf bank_mask:0xf
	v_fmac_f32_dpp v2, v154, v106 row_newbcast:10 row_mask:0xf bank_mask:0xf
	v_fmac_f32_dpp v3, v154, v107 row_newbcast:11 row_mask:0xf bank_mask:0xf
	v_fmac_f32_dpp v0, v154, v108 row_newbcast:12 row_mask:0xf bank_mask:0xf
	v_fmac_f32_dpp v1, v154, v109 row_newbcast:13 row_mask:0xf bank_mask:0xf
	v_fmac_f32_dpp v2, v154, v110 row_newbcast:14 row_mask:0xf bank_mask:0xf
	v_fmac_f32_dpp v3, v154, v111 row_newbcast:15 row_mask:0xf bank_mask:0xf
	s_waitcnt lgkmcnt(4)
	v_fmac_f32_dpp v0, v155, v112 row_newbcast:0 row_mask:0xf bank_mask:0xf
	v_fmac_f32_dpp v1, v155, v113 row_newbcast:1 row_mask:0xf bank_mask:0xf
	v_fmac_f32_dpp v2, v155, v114 row_newbcast:2 row_mask:0xf bank_mask:0xf
	v_fmac_f32_dpp v3, v155, v115 row_newbcast:3 row_mask:0xf bank_mask:0xf
	v_fmac_f32_dpp v0, v155, v116 row_newbcast:4 row_mask:0xf bank_mask:0xf
	v_fmac_f32_dpp v1, v155, v117 row_newbcast:5 row_mask:0xf bank_mask:0xf
	v_fmac_f32_dpp v2, v155, v118 row_newbcast:6 row_mask:0xf bank_mask:0xf
	v_fmac_f32_dpp v3, v155, v119 row_newbcast:7 row_mask:0xf bank_mask:0xf
	v_fmac_f32_dpp v0, v155, v120 row_newbcast:8 row_mask:0xf bank_mask:0xf
	v_fmac_f32_dpp v1, v155, v121 row_newbcast:9 row_mask:0xf bank_mask:0xf
	v_fmac_f32_dpp v2, v155, v122 row_newbcast:10 row_mask:0xf bank_mask:0xf
	v_fmac_f32_dpp v3, v155, v123 row_newbcast:11 row_mask:0xf bank_mask:0xf
	v_fmac_f32_dpp v0, v155, v124 row_newbcast:12 row_mask:0xf bank_mask:0xf
	v_fmac_f32_dpp v1, v155, v125 row_newbcast:13 row_mask:0xf bank_mask:0xf
	v_add_f32_e32 v0, v0, v1
	v_add_f32_e32 v2, v2, v3
	v_add_f32_e32 v0, v0, v2
	v_add_f32_e32 v126, v126, v0
	s_waitcnt lgkmcnt(3)
	v_mul_f32_dpp v0, v156, v64 row_newbcast:0 row_mask:0xf bank_mask:0xf
	v_mul_f32_dpp v1, v156, v65 row_newbcast:1 row_mask:0xf bank_mask:0xf
	v_mul_f32_dpp v2, v156, v66 row_newbcast:2 row_mask:0xf bank_mask:0xf
	v_mul_f32_dpp v3, v156, v67 row_newbcast:3 row_mask:0xf bank_mask:0xf
	v_fmac_f32_dpp v0, v156, v68 row_newbcast:4 row_mask:0xf bank_mask:0xf
	v_fmac_f32_dpp v1, v156, v69 row_newbcast:5 row_mask:0xf bank_mask:0xf
	v_fmac_f32_dpp v2, v156, v70 row_newbcast:6 row_mask:0xf bank_mask:0xf
	v_fmac_f32_dpp v3, v156, v71 row_newbcast:7 row_mask:0xf bank_mask:0xf
	v_fmac_f32_dpp v0, v156, v72 row_newbcast:8 row_mask:0xf bank_mask:0xf
	v_fmac_f32_dpp v1, v156, v73 row_newbcast:9 row_mask:0xf bank_mask:0xf
	v_fmac_f32_dpp v2, v156, v74 row_newbcast:10 row_mask:0xf bank_mask:0xf
	v_fmac_f32_dpp v3, v156, v75 row_newbcast:11 row_mask:0xf bank_mask:0xf
	v_fmac_f32_dpp v0, v156, v76 row_newbcast:12 row_mask:0xf bank_mask:0xf
	v_fmac_f32_dpp v1, v156, v77 row_newbcast:13 row_mask:0xf bank_mask:0xf
	v_fmac_f32_dpp v2, v156, v78 row_newbcast:14 row_mask:0xf bank_mask:0xf
	v_fmac_f32_dpp v3, v156, v79 row_newbcast:15 row_mask:0xf bank_mask:0xf
	s_waitcnt lgkmcnt(2)
; #define LAS __attribute__((address_space(3)))
; __device__ __forceinline__ void rw_phaseA(LAS unsigned char* lds, const RwCtx& X, int item) {
;     ...
;         for (int tt = 1; tt < 64; ++tt) { float a = x[tt];
; #pragma unroll
;             for (int s4 = 0; s4 < (tt + 3) / 4; ++s4) { const f32x4 l4 = *(const LAS f32x4*)(LABv + tt * 68 + s4 * 4);
;                 a += l4[0] * x[s4 * 4]; if (s4 * 4 + 1 < tt) a += l4[1] * x[s4 * 4 + 1]; if (s4 * 4 + 2 < tt) a += l4[2] * x[s4 * 4 + 2]; if (s4 * 4 + 3 < tt) a += l4[3] * x[s4 * 4 + 3]; }
;             x[tt] = a;
	v_fmac_f32_dpp v0, v157, v80 row_newbcast:0 row_mask:0xf bank_mask:0xf
	v_fmac_f32_dpp v1, v157, v81 row_newbcast:1 row_mask:0xf bank_mask:0xf
	v_fmac_f32_dpp v2, v157, v82 row_newbcast:2 row_mask:0xf bank_mask:0xf
	v_fmac_f32_dpp v3, v157, v83 row_newbcast:3 row_mask:0xf bank_mask:0xf
	v_fmac_f32_dpp v0, v157, v84 row_newbcast:4 row_mask:0xf bank_mask:0xf
	v_fmac_f32_dpp v1, v157, v85 row_newbcast:5 row_mask:0xf bank_mask:0xf
	v_fmac_f32_dpp v2, v157, v86 row_newbcast:6 row_mask:0xf bank_mask:0xf
	v_fmac_f32_dpp v3, v157, v87 row_newbcast:7 row_mask:0xf bank_mask:0xf
	v_fmac_f32_dpp v0, v157, v88 row_newbcast:8 row_mask:0xf bank_mask:0xf
	v_fmac_f32_dpp v1, v157, v89 row_newbcast:9 row_mask:0xf bank_mask:0xf
	v_fmac_f32_dpp v2, v157, v90 row_newbcast:10 row_mask:0xf bank_mask:0xf
	v_fmac_f32_dpp v3, v157, v91 row_newbcast:11 row_mask:0xf bank_mask:0xf
	v_fmac_f32_dpp v0, v157, v92 row_newbcast:12 row_mask:0xf bank_mask:0xf
	v_fmac_f32_dpp v1, v157, v93 row_newbcast:13 row_mask:0xf bank_mask:0xf
	v_fmac_f32_dpp v2, v157, v94 row_newbcast:14 row_mask:0xf bank_mask:0xf
	v_fmac_f32_dpp v3, v157, v95 row_newbcast:15 row_mask:0xf bank_mask:0xf
	s_waitcnt lgkmcnt(1)
	v_fmac_f32_dpp v0, v158, v96 row_newbcast:0 row_mask:0xf bank_mask:0xf
	v_fmac_f32_dpp v1, v158, v97 row_newbcast:1 row_mask:0xf bank_mask:0xf
	v_fmac_f32_dpp v2, v158, v98 row_newbcast:2 row_mask:0xf bank_mask:0xf
	v_fmac_f32_dpp v3, v158, v99 row_newbcast:3 row_mask:0xf bank_mask:0xf
	v_fmac_f32_dpp v0, v158, v100 row_newbcast:4 row_mask:0xf bank_mask:0xf
	v_fmac_f32_dpp v1, v158, v101 row_newbcast:5 row_mask:0xf bank_mask:0xf
	v_fmac_f32_dpp v2, v158, v102 row_newbcast:6 row_mask:0xf bank_mask:0xf
	v_fmac_f32_dpp v3, v158, v103 row_newbcast:7 row_mask:0xf bank_mask:0xf
	v_fmac_f32_dpp v0, v158, v104 row_newbcast:8 row_mask:0xf bank_mask:0xf
	v_fmac_f32_dpp v1, v158, v105 row_newbcast:9 row_mask:0xf bank_mask:0xf
	v_fmac_f32_dpp v2, v158, v106 row_newbcast:10 row_mask:0xf bank_mask:0xf
	v_fmac_f32_dpp v3, v158, v107 row_newbcast:11 row_mask:0xf bank_mask:0xf
	v_fmac_f32_dpp v0, v158, v108 row_newbcast:12 row_mask:0xf bank_mask:0xf
	v_fmac_f32_dpp v1, v158, v109 row_newbcast:13 row_mask:0xf bank_mask:0xf
	v_fmac_f32_dpp v2, v158, v110 row_newbcast:14 row_mask:0xf bank_mask:0xf
	v_fmac_f32_dpp v3, v158, v111 row_newbcast:15 row_mask:0xf bank_mask:0xf
	s_waitcnt lgkmcnt(0)
; #define LAS __attribute__((address_space(3)))
; __device__ __forceinline__ unsigned cvt_pk_bf16(float lo, float hi) { const bf16x2_t r = __builtin_convertvector((f32x2){lo, hi}, bf16x2_t); return __builtin_bit_cast(unsigned, r); }
; __device__ __forceinline__ bf16_t f2bf(float x) { return (bf16_t)(cvt_pk_bf16(x, 0.f) & 0xffffu); }
; __device__ __forceinline__ void rw_prep(LAS float* SCR, const RwCtx& X, int b, int h, int t0, int tid, RwTok& K) {
;     ...
;     for (int i = 0; i < 8; ++i) { float off = 0.f;
; #pragma unroll
;         for (int w = 0; w < 7; ++w) if (w < wave) off += SCR[w * 64 + dq * 8 + i];
;         K.cw[i] += off; }
; __device__ __forceinline__ void rw_phaseA(LAS unsigned char* lds, const RwCtx& X, int item) {
;     ...
;         for (int tt = 1; tt < 64; ++tt) { float a = x[tt];
; #pragma unroll
;             for (int s4 = 0; s4 < (tt + 3) / 4; ++s4) { const f32x4 l4 = *(const LAS f32x4*)(LABv + tt * 68 + s4 * 4);
;                 a += l4[0] * x[s4 * 4]; if (s4 * 4 + 1 < tt) a += l4[1] * x[s4 * 4 + 1]; if (s4 * 4 + 2 < tt) a += l4[2] * x[s4 * 4 + 2]; if (s4 * 4 + 3 < tt) a += l4[3] * x[s4 * 4 + 3]; }
;             x[tt] = a;
;     ...
;             __builtin_amdgcn_sched_barrier(0);
;     ...
;         }
;         LAS bf16_t* rowT = (tid_s < 64) ? (WT + tid_s * 72) : (UT + (tid_s - 64) * 72);
;         LAS bf16_t* colN = (tid_s < 64) ? (Wt + tid_s) : (Ut + (tid_s - 64));
; #pragma unroll
;         for (int g = 0; g < 8; ++g) { u32x4 o; o.x = cvt_pk_bf16(x[8 * g], x[8 * g + 1]); o.y = cvt_pk_bf16(x[8 * g + 2], x[8 * g + 3]); o.z = cvt_pk_bf16(x[8 * g + 4], x[8 * g + 5]); o.w = cvt_pk_bf16(x[8 * g + 6], x[8 * g + 7]);
;             *(LAS u32x4*)(rowT + 8 * g) = o; }
; #pragma unroll
;         for (int i = 0; i < 64; ++i) colN[i * 64] = f2bf(x[i]);
	v_fmac_f32_dpp v0, v159, v112 row_newbcast:0 row_mask:0xf bank_mask:0xf
	v_fmac_f32_dpp v1, v159, v113 row_newbcast:1 row_mask:0xf bank_mask:0xf
	v_fmac_f32_dpp v2, v159, v114 row_newbcast:2 row_mask:0xf bank_mask:0xf
	v_fmac_f32_dpp v3, v159, v115 row_newbcast:3 row_mask:0xf bank_mask:0xf
	v_fmac_f32_dpp v0, v159, v116 row_newbcast:4 row_mask:0xf bank_mask:0xf
	v_fmac_f32_dpp v1, v159, v117 row_newbcast:5 row_mask:0xf bank_mask:0xf
	v_fmac_f32_dpp v2, v159, v118 row_newbcast:6 row_mask:0xf bank_mask:0xf
	v_fmac_f32_dpp v3, v159, v119 row_newbcast:7 row_mask:0xf bank_mask:0xf
	v_fmac_f32_dpp v0, v159, v120 row_newbcast:8 row_mask:0xf bank_mask:0xf
	v_fmac_f32_dpp v1, v159, v121 row_newbcast:9 row_mask:0xf bank_mask:0xf
	v_fmac_f32_dpp v2, v159, v122 row_newbcast:10 row_mask:0xf bank_mask:0xf
	v_fmac_f32_dpp v3, v159, v123 row_newbcast:11 row_mask:0xf bank_mask:0xf
	v_fmac_f32_dpp v0, v159, v124 row_newbcast:12 row_mask:0xf bank_mask:0xf
	v_fmac_f32_dpp v1, v159, v125 row_newbcast:13 row_mask:0xf bank_mask:0xf
	v_fmac_f32_dpp v2, v159, v126 row_newbcast:14 row_mask:0xf bank_mask:0xf
	v_add_f32_e32 v0, v0, v1
	v_add_f32_e32 v2, v2, v3
	v_add_f32_e32 v0, v0, v2
	v_add_f32_e32 v127, v127, v0
	v_cvt_pk_bf16_f32 v16, v64, v65
	v_cvt_pk_bf16_f32 v17, v66, v67
	v_cvt_pk_bf16_f32 v18, v68, v69
	v_cvt_pk_bf16_f32 v19, v70, v71
	ds_write_b128 v8, v[16:19] offset:0
	v_cvt_pk_bf16_f32 v20, v72, v73
	v_cvt_pk_bf16_f32 v21, v74, v75
	v_cvt_pk_bf16_f32 v22, v76, v77
	v_cvt_pk_bf16_f32 v23, v78, v79
	ds_write_b128 v8, v[20:23] offset:16
	v_cvt_pk_bf16_f32 v24, v80, v81
	v_cvt_pk_bf16_f32 v25, v82, v83
	v_cvt_pk_bf16_f32 v26, v84, v85
	v_cvt_pk_bf16_f32 v27, v86, v87
	ds_write_b128 v8, v[24:27] offset:32
	v_cvt_pk_bf16_f32 v28, v88, v89
	v_cvt_pk_bf16_f32 v29, v90, v91
	v_cvt_pk_bf16_f32 v30, v92, v93
	v_cvt_pk_bf16_f32 v31, v94, v95
	ds_write_b128 v8, v[28:31] offset:48
	v_cvt_pk_bf16_f32 v32, v96, v97
	v_cvt_pk_bf16_f32 v33, v98, v99
	v_cvt_pk_bf16_f32 v34, v100, v101
	v_cvt_pk_bf16_f32 v35, v102, v103
	ds_write_b128 v8, v[32:35] offset:64
	v_cvt_pk_bf16_f32 v36, v104, v105
	v_cvt_pk_bf16_f32 v37, v106, v107
	v_cvt_pk_bf16_f32 v38, v108, v109
	v_cvt_pk_bf16_f32 v39, v110, v111
	ds_write_b128 v8, v[36:39] offset:80
	v_cvt_pk_bf16_f32 v40, v112, v113
	v_cvt_pk_bf16_f32 v41, v114, v115
	v_cvt_pk_bf16_f32 v42, v116, v117
	v_cvt_pk_bf16_f32 v43, v118, v119
	ds_write_b128 v8, v[40:43] offset:96
	v_cvt_pk_bf16_f32 v44, v120, v121
	v_cvt_pk_bf16_f32 v45, v122, v123
	v_cvt_pk_bf16_f32 v46, v124, v125
	v_cvt_pk_bf16_f32 v47, v126, v127
	ds_write_b128 v8, v[44:47] offset:112
	ds_write_b16 v10, v16 offset:0
	ds_write_b16_d16_hi v10, v16 offset:128
	ds_write_b16 v10, v17 offset:256
	ds_write_b16_d16_hi v10, v17 offset:384
	ds_write_b16 v10, v18 offset:512
	ds_write_b16_d16_hi v10, v18 offset:640
	ds_write_b16 v10, v19 offset:768
	ds_write_b16_d16_hi v10, v19 offset:896
	ds_write_b16 v10, v20 offset:1024
	ds_write_b16_d16_hi v10, v20 offset:1152
	ds_write_b16 v10, v21 offset:1280
	ds_write_b16_d16_hi v10, v21 offset:1408
	ds_write_b16 v10, v22 offset:1536
	ds_write_b16_d16_hi v10, v22 offset:1664
	ds_write_b16 v10, v23 offset:1792
	ds_write_b16_d16_hi v10, v23 offset:1920
	ds_write_b16 v10, v24 offset:2048
	ds_write_b16_d16_hi v10, v24 offset:2176
	ds_write_b16 v10, v25 offset:2304
	ds_write_b16_d16_hi v10, v25 offset:2432
	ds_write_b16 v10, v26 offset:2560
	ds_write_b16_d16_hi v10, v26 offset:2688
	ds_write_b16 v10, v27 offset:2816
	ds_write_b16_d16_hi v10, v27 offset:2944
	ds_write_b16 v10, v28 offset:3072
	ds_write_b16_d16_hi v10, v28 offset:3200
	ds_write_b16 v10, v29 offset:3328
	ds_write_b16_d16_hi v10, v29 offset:3456
	ds_write_b16 v10, v30 offset:3584
	ds_write_b16_d16_hi v10, v30 offset:3712
	ds_write_b16 v10, v31 offset:3840
	ds_write_b16_d16_hi v10, v31 offset:3968
	ds_write_b16 v10, v32 offset:4096
	ds_write_b16_d16_hi v10, v32 offset:4224
	ds_write_b16 v10, v33 offset:4352
	ds_write_b16_d16_hi v10, v33 offset:4480
	ds_write_b16 v10, v34 offset:4608
	ds_write_b16_d16_hi v10, v34 offset:4736
	ds_write_b16 v10, v35 offset:4864
	ds_write_b16_d16_hi v10, v35 offset:4992
	ds_write_b16 v10, v36 offset:5120
	ds_write_b16_d16_hi v10, v36 offset:5248
	ds_write_b16 v10, v37 offset:5376
	ds_write_b16_d16_hi v10, v37 offset:5504
	ds_write_b16 v10, v38 offset:5632
	ds_write_b16_d16_hi v10, v38 offset:5760
	ds_write_b16 v10, v39 offset:5888
	ds_write_b16_d16_hi v10, v39 offset:6016
	ds_write_b16 v10, v40 offset:6144
	ds_write_b16_d16_hi v10, v40 offset:6272
	ds_write_b16 v10, v41 offset:6400
	ds_write_b16_d16_hi v10, v41 offset:6528
	ds_write_b16 v10, v42 offset:6656
	ds_write_b16_d16_hi v10, v42 offset:6784
	ds_write_b16 v10, v43 offset:6912
	ds_write_b16_d16_hi v10, v43 offset:7040
	ds_write_b16 v10, v44 offset:7168
	ds_write_b16_d16_hi v10, v44 offset:7296
	ds_write_b16 v10, v45 offset:7424
	ds_write_b16_d16_hi v10, v45 offset:7552
	ds_write_b16 v10, v46 offset:7680
	ds_write_b16_d16_hi v10, v46 offset:7808
	ds_write_b16 v10, v47 offset:7936
	ds_write_b16_d16_hi v10, v47 offset:8064
	s_branch .LBB0_720

; __device__ __forceinline__ void la_scan(const LaCtx& X) {
;     ...
;         for (int j = 0; j < 4; ++j) { const int cn = c0 + 4 + j;
;             if (cn < NCH) { y[j] = *(const u32x4*)(ibase + (size_t)cn * ITEM_ELEMS);
;                 if (mode == 0) { ea[j] = *(const f32x4*)(decb + cn * 128); eb[j] = *(const f32x4*)(decb + cn * 128 + 4); be2[j] = 0.f; ml2[j] = 0.f; }
;                 else { be2[j] = bendp[cn]; ml2[j] = mlocp[cn]; ea[j] = (f32x4){0.f, 0.f, 0.f, 0.f}; eb[j] = ea[j]; } }
;             else { y[j] = (u32x4){0u, 0u, 0u, 0u}; ea[j] = (f32x4){0.f, 0.f, 0.f, 0.f}; eb[j] = ea[j]; be2[j] = 0.f; ml2[j] = 0.f; } }
.LBB0_1106:
	s_or_saveexec_b64 s[48:49], s[48:49]
	v_mov_b32_e32 v27, 0
	v_mov_b32_e32 v26, 0
	v_mov_b32_e32 v25, 0
	v_mov_b32_e32 v24, 0
	v_mov_b32_e32 v23, 0
	v_mov_b32_e32 v22, 0
	v_mov_b32_e32 v21, 0
	v_mov_b32_e32 v20, 0
	s_xor_b64 exec, exec, s[48:49]
	s_cbranch_execz .LBB0_1108
	v_lshl_add_u64 v[10:11], s[92:93], 0, v[104:105]
	s_mov_b64 s[24:25], 0x8c64e800
	v_lshl_add_u64 v[20:21], v[10:11], 0, s[24:25]
	v_add_co_u32_e32 v10, vcc, 0x8c64e000, v10
	v_mov_b32_e32 v127, 0
	v_addc_co_u32_e32 v11, vcc, 0, v11, vcc
	global_load_dwordx4 v[24:27], v[10:11], off offset:2048
	s_nop 0
	global_load_dwordx4 v[20:23], v[20:21], off offset:16
	v_mov_b32_e32 v126, 0

; __device__ __forceinline__ void la_scan(const LaCtx& X) {
;     ...
;         for (int j = 0; j < 4; ++j) { const int cn = c0 + 4 + j;
;             if (cn < NCH) { y[j] = *(const u32x4*)(ibase + (size_t)cn * ITEM_ELEMS);
;                 if (mode == 0) { ea[j] = *(const f32x4*)(decb + cn * 128); eb[j] = *(const f32x4*)(decb + cn * 128 + 4); be2[j] = 0.f; ml2[j] = 0.f; }
;                 else { be2[j] = bendp[cn]; ml2[j] = mlocp[cn]; ea[j] = (f32x4){0.f, 0.f, 0.f, 0.f}; eb[j] = ea[j]; } }
;             else { y[j] = (u32x4){0u, 0u, 0u, 0u}; ea[j] = (f32x4){0.f, 0.f, 0.f, 0.f}; eb[j] = ea[j]; be2[j] = 0.f; ml2[j] = 0.f; } }
.LBB0_1114:
	s_or_saveexec_b64 s[48:49], s[48:49]
	v_mov_b32_e32 v51, 0
	v_mov_b32_e32 v50, 0
	v_mov_b32_e32 v49, 0
	v_mov_b32_e32 v48, 0
	v_mov_b32_e32 v47, 0
	v_mov_b32_e32 v46, 0
	v_mov_b32_e32 v45, 0
	v_mov_b32_e32 v44, 0
	s_xor_b64 exec, exec, s[48:49]
	s_cbranch_execz .LBB0_1116
	v_lshl_add_u64 v[10:11], s[92:93], 0, v[104:105]
	s_mov_b64 s[24:25], 0x8c64ea00
	v_lshl_add_u64 v[44:45], v[10:11], 0, s[24:25]
	v_add_co_u32_e32 v10, vcc, 0x8c64e000, v10
	v_mov_b32_e32 v131, 0
	v_addc_co_u32_e32 v11, vcc, 0, v11, vcc
	global_load_dwordx4 v[48:51], v[10:11], off offset:2560
	s_nop 0
	global_load_dwordx4 v[44:47], v[44:45], off offset:16
	v_mov_b32_e32 v130, 0

; __device__ __forceinline__ void la_scan(const LaCtx& X) {
;     ...
;         for (int j = 0; j < 4; ++j) { const int cn = c0 + 4 + j;
;             if (cn < NCH) { y[j] = *(const u32x4*)(ibase + (size_t)cn * ITEM_ELEMS);
;                 if (mode == 0) { ea[j] = *(const f32x4*)(decb + cn * 128); eb[j] = *(const f32x4*)(decb + cn * 128 + 4); be2[j] = 0.f; ml2[j] = 0.f; }
;                 else { be2[j] = bendp[cn]; ml2[j] = mlocp[cn]; ea[j] = (f32x4){0.f, 0.f, 0.f, 0.f}; eb[j] = ea[j]; } }
;             else { y[j] = (u32x4){0u, 0u, 0u, 0u}; ea[j] = (f32x4){0.f, 0.f, 0.f, 0.f}; eb[j] = ea[j]; be2[j] = 0.f; ml2[j] = 0.f; } }
.LBB0_1122:
	s_or_saveexec_b64 s[48:49], s[48:49]
	v_mov_b32_e32 v75, 0
	v_mov_b32_e32 v74, 0
	v_mov_b32_e32 v73, 0
	v_mov_b32_e32 v72, 0
	v_mov_b32_e32 v67, 0
	v_mov_b32_e32 v66, 0
	v_mov_b32_e32 v65, 0
	v_mov_b32_e32 v64, 0
	s_xor_b64 exec, exec, s[48:49]
	s_cbranch_execz .LBB0_1124
	v_lshl_add_u64 v[10:11], s[92:93], 0, v[104:105]
	s_mov_b64 s[24:25], 0x8c64ec00
	v_lshl_add_u64 v[64:65], v[10:11], 0, s[24:25]
	v_add_co_u32_e32 v10, vcc, 0x8c64e000, v10
	v_mov_b32_e32 v135, 0
	v_addc_co_u32_e32 v11, vcc, 0, v11, vcc
	global_load_dwordx4 v[72:75], v[10:11], off offset:3072
	s_nop 0
	global_load_dwordx4 v[64:67], v[64:65], off offset:16
	v_mov_b32_e32 v134, 0

; __device__ __forceinline__ void la_scan(const LaCtx& X) {
;     ...
;         for (int j = 0; j < 4; ++j) { const int cn = c0 + 4 + j;
;             if (cn < NCH) { y[j] = *(const u32x4*)(ibase + (size_t)cn * ITEM_ELEMS);
;                 if (mode == 0) { ea[j] = *(const f32x4*)(decb + cn * 128); eb[j] = *(const f32x4*)(decb + cn * 128 + 4); be2[j] = 0.f; ml2[j] = 0.f; }
;                 else { be2[j] = bendp[cn]; ml2[j] = mlocp[cn]; ea[j] = (f32x4){0.f, 0.f, 0.f, 0.f}; eb[j] = ea[j]; } }
;             else { y[j] = (u32x4){0u, 0u, 0u, 0u}; ea[j] = (f32x4){0.f, 0.f, 0.f, 0.f}; eb[j] = ea[j]; be2[j] = 0.f; ml2[j] = 0.f; } }
.LBB0_1130:
	s_or_saveexec_b64 s[48:49], s[48:49]
	v_mov_b32_e32 v99, 0
	v_mov_b32_e32 v98, 0
	v_mov_b32_e32 v97, 0
	v_mov_b32_e32 v96, 0
	v_mov_b32_e32 v95, 0
	v_mov_b32_e32 v94, 0
	v_mov_b32_e32 v93, 0
	v_mov_b32_e32 v92, 0
	s_xor_b64 exec, exec, s[48:49]
	s_cbranch_execz .LBB0_1132
	v_lshl_add_u64 v[10:11], s[92:93], 0, v[104:105]
	s_mov_b64 s[24:25], 0x8c64ee00
	v_lshl_add_u64 v[92:93], v[10:11], 0, s[24:25]
	v_add_co_u32_e32 v10, vcc, 0x8c64e000, v10
	v_mov_b32_e32 v148, 0
	v_addc_co_u32_e32 v11, vcc, 0, v11, vcc
	global_load_dwordx4 v[96:99], v[10:11], off offset:3584
	s_nop 0
	global_load_dwordx4 v[92:95], v[92:93], off offset:16
	v_mov_b32_e32 v146, 0

; __device__ __forceinline__ void rw_phaseB(LAS unsigned char* lds, const RwCtx& X, int bh) {
;     ...
;     bf16x8 pa[4][2], pn[4][2]; u32x2 rf[4][2], rn[4][2]; f32x4 dc[4], dn[4];
;     ...
; #pragma unroll
;     for (int j = 0; j < 4; ++j) RWB_LOAD(pa[j], rf[j], dc[j], j);
;     for (int c0 = 0; c0 < NCH; c0 += 4) {
; #pragma unroll
;         for (int j = 0; j < 4; ++j) { const int cn = c0 + 4 + j;
;             if (cn < NCH) RWB_LOAD(pn[j], rn[j], dn[j], cn);
;             else { pn[j][0] = pa[j][0]; pn[j][1] = pa[j][1]; rn[j][0] = rf[j][0]; rn[j][1] = rf[j][1]; dn[j] = dc[j]; } }
;     ...
; #pragma unroll
;         for (int j = 0; j < 4; ++j) { pa[j][0] = pn[j][0]; pa[j][1] = pn[j][1]; rf[j][0] = rn[j][0]; rf[j][1] = rn[j][1]; dc[j] = dn[j]; }
.LBB0_1163:
	s_or_b64 exec, exec, s[6:7]
	v_readlane_b32 s0, v253, 42
	v_readlane_b32 s1, v253, 43
	s_and_b64 vcc, exec, s[0:1]
	s_cbranch_vccz .LBB0_1187
	v_mov_b32_e32 v34, v226
	v_readlane_b32 s0, v253, 46
	v_ashrrev_i32_e32 v0, 3, v34
	v_ashrrev_i32_e32 v35, 6, v34
	v_and_b32_e32 v2, 63, v34
	v_and_b32_e32 v18, -16, v0
	v_bfi_b32 v0, -16, v0, v34
	v_ashrrev_i32_e32 v1, 31, v0
	v_lshl_or_b32 v2, v35, 7, v2
	v_and_b32_e32 v8, 48, v34
	v_ashrrev_i32_e32 v3, 31, v2
	v_lshlrev_b64 v[24:25], 7, v[0:1]
	v_lshlrev_b64 v[22:23], 3, v[2:3]
	v_or_b32_e32 v0, v24, v8
	v_mov_b32_e32 v1, v25
	v_readlane_b32 s1, v253, 47
	v_or_b32_e32 v2, 64, v2
	v_ashrrev_i32_e32 v3, 31, v2
	v_lshl_add_u64 v[4:5], s[0:1], 0, v[0:1]
	v_readlane_b32 s0, v253, 48
	v_readlane_b32 s1, v253, 49
	v_lshlrev_b64 v[26:27], 3, v[2:3]
	v_lshl_or_b32 v20, v18, 2, v8
	global_load_dwordx4 v[94:97], v[4:5], off
	global_load_dwordx4 v[90:93], v[4:5], off offset:64
	v_lshl_add_u64 v[4:5], s[0:1], 0, v[22:23]
	v_lshl_add_u64 v[2:3], s[0:1], 0, v[26:27]
	v_readlane_b32 s0, v253, 50
	v_ashrrev_i32_e32 v21, 31, v20
	v_readlane_b32 s1, v253, 51
	global_load_dwordx2 v[158:159], v[4:5], off
	global_load_dwordx2 v[156:157], v[2:3], off
	v_lshl_add_u64 v[2:3], s[0:1], 0, v[20:21]
	v_readlane_b32 s0, v253, 52
	v_or_b32_e32 v6, 64, v0
	v_mov_b32_e32 v7, v25
	v_readlane_b32 s1, v253, 53
	v_readlane_b32 s6, v254, 2
	v_readlane_b32 s8, v254, 4
	v_lshl_add_u64 v[4:5], s[0:1], 0, v[0:1]
	global_load_dwordx4 v[98:101], v[2:3], off
	global_load_dwordx4 v[74:77], v[4:5], off
	v_lshl_add_u64 v[2:3], s[0:1], 0, v[6:7]
	v_readlane_b32 s0, v253, 54
	v_readlane_b32 s1, v253, 55
	v_readlane_b32 s7, v254, 3
	v_readlane_b32 s9, v254, 5
	v_lshl_add_u64 v[4:5], s[0:1], 0, v[22:23]
	global_load_dwordx4 v[70:73], v[2:3], off
	global_load_dwordx2 v[154:155], v[4:5], off
	v_lshl_add_u64 v[2:3], s[0:1], 0, v[26:27]
	v_readlane_b32 s0, v253, 56
	v_readlane_b32 s1, v253, 57
	v_lshl_add_u64 v[28:29], s[6:7], 0, v[22:23]
	v_and_b32_e32 v36, 15, v34
	v_lshl_add_u64 v[4:5], s[0:1], 0, v[20:21]
	v_readlane_b32 s0, v253, 58
	v_readlane_b32 s1, v253, 59
	global_load_dwordx2 v[148:149], v[2:3], off
	global_load_dwordx4 v[86:89], v[4:5], off
	v_lshl_add_u64 v[2:3], s[0:1], 0, v[0:1]
	v_lshl_add_u64 v[4:5], s[0:1], 0, v[6:7]
	v_readlane_b32 s0, v253, 60
	v_readlane_b32 s1, v253, 61
	global_load_dwordx4 v[30:33], v[2:3], off
	global_load_dwordx4 v[14:17], v[4:5], off
	v_lshl_add_u64 v[2:3], s[0:1], 0, v[22:23]
	v_lshl_add_u64 v[4:5], s[0:1], 0, v[26:27]
	v_readlane_b32 s0, v253, 62
	v_readlane_b32 s1, v253, 63
	global_load_dwordx2 v[132:133], v[2:3], off
	global_load_dwordx2 v[126:127], v[4:5], off
	v_lshl_add_u64 v[2:3], s[0:1], 0, v[20:21]
	v_readlane_b32 s0, v254, 0
	v_readlane_b32 s1, v254, 1
	v_ashrrev_i32_e32 v19, 31, v18
	v_lshlrev_b32_e32 v37, 1, v18
	v_lshl_add_u64 v[0:1], s[0:1], 0, v[0:1]
	global_load_dwordx4 v[46:49], v[2:3], off
	global_load_dwordx4 v[10:13], v[0:1], off
	v_lshl_add_u64 v[0:1], s[6:7], 0, v[26:27]
	v_lshl_add_u64 v[2:3], s[8:9], 0, v[20:21]
	global_load_dwordx2 v[114:115], v[0:1], off
	s_nop 0
	global_load_dwordx4 v[0:3], v[2:3], off
	v_lshl_add_u64 v[4:5], s[0:1], 0, v[6:7]
	global_load_dwordx4 v[4:7], v[4:5], off
	s_nop 0
	global_load_dwordx2 v[116:117], v[28:29], off
	v_readlane_b32 s0, v253, 44
	v_readlane_b32 s1, v253, 45
	v_lshlrev_b32_e32 v29, 5, v35
	v_lshrrev_b32_e32 v28, 1, v34
	v_lshl_add_u64 v[24:25], s[0:1], 0, v[24:25]
	v_lshl_add_u64 v[104:105], s[0:1], 0, v[22:23]
	v_lshl_add_u64 v[106:107], s[0:1], 0, v[26:27]
	v_lshl_add_u64 v[108:109], s[0:1], 0, v[20:21]
	v_readlane_b32 s0, v254, 36
	v_and_b32_e32 v28, 24, v28
	v_and_or_b32 v34, v29, 32, v36
	v_mov_b32_e32 v29, v9
	v_readlane_b32 s1, v254, 37
	v_add_u32_e32 v39, 0, v8
	v_lshl_add_u64 v[102:103], v[24:25], 0, v[8:9]
	v_lshl_add_u64 v[20:21], s[0:1], 0, v[28:29]
	v_lshl_add_u64 v[18:19], v[18:19], 1, v[20:21]
	v_lshlrev_b32_e32 v8, 7, v36
	v_lshlrev_b32_e32 v20, 12, v35
	s_movk_i32 s0, 0x1000
	v_and_or_b32 v8, v20, s0, v8
	v_lshl_add_u64 v[110:111], v[18:19], 0, v[8:9]
	v_mov_b32_e32 v8, 0x800
	v_add3_u32 v37, 0, v37, v28
	v_mul_u32_u24_e32 v38, 0x90, v34
	v_lshl_or_b32 v8, v34, 7, v8
	v_mov_b32_e32 v34, 0
	s_mov_b32 s6, 3
	v_lshl_add_u64 v[112:113], v[18:19], 0, v[8:9]
	v_add_u32_e32 v8, v37, v38
	v_add_u32_e32 v146, v39, v38
	v_mov_b32_e32 v35, v34
	v_mov_b32_e32 v36, v34
	v_mov_b32_e32 v37, v34
	v_mov_b32_e32 v38, v34
	v_mov_b32_e32 v39, v34
	v_mov_b32_e32 v40, v34
	v_mov_b32_e32 v41, v34
	s_mov_b32 s8, 0x7814c000
	s_waitcnt vmcnt(0)
	v_mov_b32_e32 v120, v0
	v_mov_b32_e32 v121, v1
	v_mov_b32_e32 v122, v2
	v_mov_b32_e32 v123, v3
	s_branch .LBB0_1166
.LBB0_1165:
	s_mov_b64 s[0:1], 0x20400
	v_lshl_add_u64 v[102:103], v[102:103], 0, s[0:1]
	v_lshl_add_u64 v[104:105], v[104:105], 0, s[0:1]
	v_lshl_add_u64 v[106:107], v[106:107], 0, s[0:1]
	v_lshl_add_u64 v[108:109], v[108:109], 0, s[0:1]
	s_add_i32 s6, s6, 4
	s_mov_b64 s[0:1], 0x8000
	s_waitcnt vmcnt(11)
	v_mov_b64_e32 v[4:5], v[82:83]
	v_mov_b64_e32 v[10:11], v[78:79]
	v_mov_b64_e32 v[14:15], v[66:67]
	v_mov_b64_e32 v[30:31], v[58:59]
	v_mov_b64_e32 v[72:73], v[52:53]
	v_mov_b64_e32 v[76:77], v[44:45]
	v_mov_b64_e32 v[92:93], v[24:25]
	v_mov_b64_e32 v[96:97], v[20:21]
	v_lshl_add_u64 v[110:111], v[110:111], 0, s[0:1]
	s_mov_b64 s[34:35], 0x8000
	v_lshl_add_u64 v[112:113], v[112:113], 0, s[0:1]
	s_cmpk_lt_u32 s7, 0x7d
	v_mov_b64_e32 v[6:7], v[84:85]
	v_mov_b64_e32 v[12:13], v[80:81]
	v_mov_b64_e32 v[16:17], v[68:69]
	v_mov_b64_e32 v[32:33], v[60:61]
	v_mov_b64_e32 v[70:71], v[50:51]
	v_mov_b64_e32 v[74:75], v[42:43]
	v_mov_b64_e32 v[90:91], v[22:23]
	v_mov_b64_e32 v[94:95], v[18:19]
	s_waitcnt vmcnt(8)
	v_mov_b64_e32 v[114:115], v[152:153]
	v_mov_b64_e32 v[116:117], v[150:151]
	v_mov_b64_e32 v[126:127], v[136:137]
	v_mov_b64_e32 v[132:133], v[134:135]
	v_mov_b64_e32 v[148:149], v[130:131]
	v_mov_b64_e32 v[154:155], v[128:129]
	v_mov_b64_e32 v[156:157], v[124:125]
	v_mov_b64_e32 v[158:159], v[118:119]
	v_mov_b32_e32 v98, v26
	v_mov_b32_e32 v99, v27
	v_mov_b32_e32 v100, v28
	v_mov_b32_e32 v101, v29
	v_mov_b32_e32 v86, v54
	v_mov_b32_e32 v87, v55
	v_mov_b32_e32 v88, v56
	v_mov_b32_e32 v89, v57
	v_mov_b32_e32 v46, v62
	v_mov_b32_e32 v47, v63
	v_mov_b32_e32 v48, v64
	v_mov_b32_e32 v49, v65
	s_waitcnt vmcnt(8)
	v_mov_b32_e32 v120, v0
	v_mov_b32_e32 v121, v1
	v_mov_b32_e32 v122, v2
	v_mov_b32_e32 v123, v3
	s_cbranch_scc0 .LBB0_1186

; #define LAS __attribute__((address_space(3)))
; __device__ __forceinline__ unsigned cvt_pk_bf16(float lo, float hi) { const bf16x2_t r = __builtin_convertvector((f32x2){lo, hi}, bf16x2_t); return __builtin_bit_cast(unsigned, r); }
; __device__ __forceinline__ float bflo(unsigned u) { return __uint_as_float(u << 16); }
; __device__ __forceinline__ float bfhi(unsigned u) { return __uint_as_float(u & 0xffff0000u); }
; #define LDS_BAR() do { asm volatile("s_waitcnt lgkmcnt(0)" ::: "memory"); __builtin_amdgcn_s_barrier(); asm volatile("" ::: "memory"); } while (0)
; __device__ __forceinline__ void rw_phaseB(LAS unsigned char* lds, const RwCtx& X, int bh) {
;     ...
;         for (int j = 0; j < 4; ++j) { const int cn = c0 + 4 + j;
;             if (cn < NCH) RWB_LOAD(pn[j], rn[j], dn[j], cn);
;             else { pn[j][0] = pa[j][0]; pn[j][1] = pa[j][1]; rn[j][0] = rf[j][0]; rn[j][1] = rf[j][1]; dn[j] = dc[j]; } }
; #pragma unroll
;         for (int j = 0; j < 4; ++j) { const int c = c0 + j;
;             if (c < NCH) {
;                 LAS bf16_t* STb = (LAS bf16_t*)(lds + (c & 1) * 9216);
;                 bf16_t* sg = X.SRW + ((size_t)bh * NCH + c) * 4096;
; #pragma unroll
;                 for (int bi = 0; bi < 2; ++bi) { const int v0 = (vb0 + bi) * 16; u32x2 o; o.x = cvt_pk_bf16(acc[bi][0], acc[bi][1]); o.y = cvt_pk_bf16(acc[bi][2], acc[bi][3]);
;                     *(LAS u32x2*)(STb + (v0 + fr) * 72 + d0 + fq * 4) = o; *(u32x2*)(sg + (v0 + fr) * 64 + d0 + fq * 4) = o; }
;                 LDS_BAR();
; #pragma unroll
;                 for (int bi = 0; bi < 2; ++bi) { const int v0 = (vb0 + bi) * 16;
;                     f32x4 n = (f32x4){dc[j][0] * acc[bi][0] + bflo(rf[j][bi].x), dc[j][1] * acc[bi][1] + bfhi(rf[j][bi].x), dc[j][2] * acc[bi][2] + bflo(rf[j][bi].y), dc[j][3] * acc[bi][3] + bfhi(rf[j][bi].y)};
; #pragma unroll
;                     for (int k = 0; k < 2; ++k) { const bf16x8 fs = *(const LAS bf16x8*)(STb + (v0 + fr) * 72 + k * 32 + fq * 8); n = __builtin_amdgcn_mfma_f32_16x16x32_bf16(pa[j][k], fs, n, 0, 0, 0); }
;                     acc[bi] = n; }
.LBB0_1178:
	v_mov_b64_e32 v[84:85], v[6:7]
	v_mov_b64_e32 v[80:81], v[12:13]
	s_cmpk_gt_u32 s7, 0x79
	v_mov_b64_e32 v[82:83], v[4:5]
	v_mov_b64_e32 v[78:79], v[10:11]
	v_mov_b64_e32 v[152:153], v[114:115]
	v_mov_b64_e32 v[150:151], v[116:117]
	s_cbranch_scc1 .LBB0_1180
	v_add_co_u32_e32 v0, vcc, 0x6ff82000, v166
	s_nop 1
	v_addc_co_u32_e32 v1, vcc, 0, v167, vcc
	global_load_dwordx4 v[78:81], v[0:1], off offset:1792
	global_load_dwordx4 v[82:85], v[0:1], off offset:1856
	v_add_co_u32_e32 v0, vcc, 0x6ff84000, v164
	s_nop 1
	v_addc_co_u32_e32 v1, vcc, 0, v165, vcc
	v_add_co_u32_e32 v2, vcc, 0x6ff84000, v162
	s_nop 1
	v_addc_co_u32_e32 v3, vcc, 0, v163, vcc
	global_load_dwordx2 v[150:151], v[0:1], off offset:1792
	global_load_dwordx2 v[152:153], v[2:3], off offset:1792
	v_add_co_u32_e32 v0, vcc, 0x6ff86000, v160
	s_nop 1
	v_addc_co_u32_e32 v1, vcc, 0, v161, vcc
	global_load_dwordx4 v[0:3], v[0:1], off offset:1792
.LBB0_1180:
	v_lshl_add_u64 v[162:163], s[92:93], 0, v[110:111]
	v_add_co_u32_e32 v140, vcc, s8, v162
	v_cvt_pk_bf16_f32 v138, v34, v35
	v_cvt_pk_bf16_f32 v139, v36, v37
	v_addc_co_u32_e32 v141, vcc, 0, v163, vcc
	v_lshl_add_u64 v[160:161], s[92:93], 0, v[112:113]
	global_store_dwordx2 v[140:141], v[138:139], off
	v_add_co_u32_e32 v140, vcc, s8, v160
	ds_write_b64 v8, v[138:139]
	v_cvt_pk_bf16_f32 v138, v38, v39
	v_cvt_pk_bf16_f32 v139, v40, v41
	v_addc_co_u32_e32 v141, vcc, 0, v161, vcc
	ds_write_b64 v8, v[138:139] offset:2304
	global_store_dwordx2 v[140:141], v[138:139], off
	v_lshlrev_b32_e32 v138, 16, v158
	v_and_b32_e32 v139, 0xffff0000, v158
	s_waitcnt lgkmcnt(0)
	s_barrier
	ds_read_b128 v[168:171], v146
	ds_read_b128 v[172:175], v146 offset:64
	ds_read_b128 v[176:179], v146 offset:2304
	ds_read_b128 v[180:183], v146 offset:2368
	v_pk_fma_f32 v[34:35], v[34:35], v[98:99], v[138:139]
	v_lshlrev_b32_e32 v138, 16, v159
	v_and_b32_e32 v139, 0xffff0000, v159
	v_pk_fma_f32 v[36:37], v[36:37], v[100:101], v[138:139]
	s_nop 0
	s_add_i32 s0, s6, -2
	s_waitcnt lgkmcnt(3)
	v_mfma_f32_16x16x32_bf16 v[34:37], v[94:97], v[168:171], v[34:37]
	s_nop 0
	s_cmpk_gt_u32 s0, 0x80
	s_waitcnt lgkmcnt(2)
	v_mfma_f32_16x16x32_bf16 v[34:37], v[90:93], v[172:175], v[34:37]
	v_lshlrev_b32_e32 v138, 16, v156
	v_and_b32_e32 v139, 0xffff0000, v156
	v_pk_fma_f32 v[38:39], v[38:39], v[98:99], v[138:139]
	v_lshlrev_b32_e32 v98, 16, v157
	v_and_b32_e32 v99, 0xffff0000, v157
	v_pk_fma_f32 v[40:41], v[40:41], v[100:101], v[98:99]
	s_nop 0
	s_waitcnt lgkmcnt(1)
	v_mfma_f32_16x16x32_bf16 v[38:41], v[94:97], v[176:179], v[38:41]
	s_nop 0
	s_waitcnt lgkmcnt(0)
	v_mfma_f32_16x16x32_bf16 v[38:41], v[90:93], v[180:183], v[38:41]
	s_cbranch_scc0 .LBB0_1183
	s_add_i32 s0, s6, -1
	s_cmpk_gt_u32 s0, 0x80
	s_cbranch_scc0 .LBB0_1184

; #define LAS __attribute__((address_space(3)))
; __device__ __forceinline__ unsigned cvt_pk_bf16(float lo, float hi) { const bf16x2_t r = __builtin_convertvector((f32x2){lo, hi}, bf16x2_t); return __builtin_bit_cast(unsigned, r); }
; __device__ __forceinline__ float bflo(unsigned u) { return __uint_as_float(u << 16); }
; __device__ __forceinline__ float bfhi(unsigned u) { return __uint_as_float(u & 0xffff0000u); }
; #define LDS_BAR() do { asm volatile("s_waitcnt lgkmcnt(0)" ::: "memory"); __builtin_amdgcn_s_barrier(); asm volatile("" ::: "memory"); } while (0)
; __device__ __forceinline__ void rw_phaseB(LAS unsigned char* lds, const RwCtx& X, int bh) {
;     ...
;         for (int j = 0; j < 4; ++j) { const int c = c0 + j;
;             if (c < NCH) {
;                 LAS bf16_t* STb = (LAS bf16_t*)(lds + (c & 1) * 9216);
;                 bf16_t* sg = X.SRW + ((size_t)bh * NCH + c) * 4096;
; #pragma unroll
;                 for (int bi = 0; bi < 2; ++bi) { const int v0 = (vb0 + bi) * 16; u32x2 o; o.x = cvt_pk_bf16(acc[bi][0], acc[bi][1]); o.y = cvt_pk_bf16(acc[bi][2], acc[bi][3]);
;                     *(LAS u32x2*)(STb + (v0 + fr) * 72 + d0 + fq * 4) = o; *(u32x2*)(sg + (v0 + fr) * 64 + d0 + fq * 4) = o; }
;                 LDS_BAR();
; #pragma unroll
;                 for (int bi = 0; bi < 2; ++bi) { const int v0 = (vb0 + bi) * 16;
;                     f32x4 n = (f32x4){dc[j][0] * acc[bi][0] + bflo(rf[j][bi].x), dc[j][1] * acc[bi][1] + bfhi(rf[j][bi].x), dc[j][2] * acc[bi][2] + bflo(rf[j][bi].y), dc[j][3] * acc[bi][3] + bfhi(rf[j][bi].y)};
; #pragma unroll
;                     for (int k = 0; k < 2; ++k) { const bf16x8 fs = *(const LAS bf16x8*)(STb + (v0 + fr) * 72 + k * 32 + fq * 8); n = __builtin_amdgcn_mfma_f32_16x16x32_bf16(pa[j][k], fs, n, 0, 0, 0); }
;                     acc[bi] = n; }
.LBB0_1183:
	v_add_co_u32_e32 v92, vcc, 0x7814e000, v162
	v_cvt_pk_bf16_f32 v90, v34, v35
	v_cvt_pk_bf16_f32 v91, v36, v37
	v_addc_co_u32_e32 v93, vcc, 0, v163, vcc
	s_mov_b32 s0, 0x7814e000
	global_store_dwordx2 v[92:93], v[90:91], off
	v_add_co_u32_e32 v92, vcc, s0, v160
	ds_write_b64 v8, v[90:91] offset:9216
	v_cvt_pk_bf16_f32 v90, v38, v39
	v_cvt_pk_bf16_f32 v91, v40, v41
	v_addc_co_u32_e32 v93, vcc, 0, v161, vcc
	ds_write_b64 v8, v[90:91] offset:11520
	global_store_dwordx2 v[92:93], v[90:91], off
	v_lshlrev_b32_e32 v90, 16, v154
	v_and_b32_e32 v91, 0xffff0000, v154
	s_waitcnt lgkmcnt(0)
	s_barrier
	ds_read_b128 v[168:171], v146 offset:9216
	ds_read_b128 v[172:175], v146 offset:9280
	ds_read_b128 v[176:179], v146 offset:11520
	ds_read_b128 v[180:183], v146 offset:11584
	v_pk_fma_f32 v[34:35], v[86:87], v[34:35], v[90:91]
	v_lshlrev_b32_e32 v90, 16, v155
	v_and_b32_e32 v91, 0xffff0000, v155
	v_pk_fma_f32 v[36:37], v[88:89], v[36:37], v[90:91]
	s_nop 0
	s_waitcnt lgkmcnt(3)
	v_mfma_f32_16x16x32_bf16 v[34:37], v[74:77], v[168:171], v[34:37]
	s_nop 0
	s_waitcnt lgkmcnt(2)
	v_mfma_f32_16x16x32_bf16 v[34:37], v[70:73], v[172:175], v[34:37]
	v_lshlrev_b32_e32 v90, 16, v148
	v_and_b32_e32 v91, 0xffff0000, v148
	v_pk_fma_f32 v[38:39], v[86:87], v[38:39], v[90:91]
	v_lshlrev_b32_e32 v86, 16, v149
	v_and_b32_e32 v87, 0xffff0000, v149
	v_pk_fma_f32 v[40:41], v[88:89], v[40:41], v[86:87]
	s_nop 0
	s_waitcnt lgkmcnt(1)
	v_mfma_f32_16x16x32_bf16 v[38:41], v[74:77], v[176:179], v[38:41]
	s_nop 0
	s_waitcnt lgkmcnt(0)
	v_mfma_f32_16x16x32_bf16 v[38:41], v[70:73], v[180:183], v[38:41]
	s_add_i32 s0, s6, -1
	s_cmpk_gt_u32 s0, 0x80
	s_cbranch_scc1 .LBB0_1182
.LBB0_1184:
	v_add_co_u32_e32 v72, vcc, 0x78150000, v162
	v_cvt_pk_bf16_f32 v70, v34, v35
	v_cvt_pk_bf16_f32 v71, v36, v37
	v_addc_co_u32_e32 v73, vcc, 0, v163, vcc
	s_mov_b32 s0, 0x78150000
	global_store_dwordx2 v[72:73], v[70:71], off
	v_add_co_u32_e32 v72, vcc, s0, v160
	ds_write_b64 v8, v[70:71]
	v_cvt_pk_bf16_f32 v70, v38, v39
	v_cvt_pk_bf16_f32 v71, v40, v41
	v_addc_co_u32_e32 v73, vcc, 0, v161, vcc
	ds_write_b64 v8, v[70:71] offset:2304
	global_store_dwordx2 v[72:73], v[70:71], off
	v_lshlrev_b32_e32 v70, 16, v132
	v_and_b32_e32 v71, 0xffff0000, v132
	s_waitcnt lgkmcnt(0)
	s_barrier
	ds_read_b128 v[168:171], v146
	ds_read_b128 v[172:175], v146 offset:64
	ds_read_b128 v[176:179], v146 offset:2304
	ds_read_b128 v[180:183], v146 offset:2368
	v_pk_fma_f32 v[34:35], v[46:47], v[34:35], v[70:71]
	v_lshlrev_b32_e32 v70, 16, v133
	v_and_b32_e32 v71, 0xffff0000, v133
	v_pk_fma_f32 v[36:37], v[48:49], v[36:37], v[70:71]
	s_nop 0
	s_waitcnt lgkmcnt(3)
	v_mfma_f32_16x16x32_bf16 v[34:37], v[30:33], v[168:171], v[34:37]
	s_nop 0
	s_waitcnt lgkmcnt(2)
	v_mfma_f32_16x16x32_bf16 v[34:37], v[14:17], v[172:175], v[34:37]
	v_lshlrev_b32_e32 v70, 16, v126
	v_and_b32_e32 v71, 0xffff0000, v126
	v_pk_fma_f32 v[38:39], v[46:47], v[38:39], v[70:71]
	v_lshlrev_b32_e32 v46, 16, v127
	v_and_b32_e32 v47, 0xffff0000, v127
	v_pk_fma_f32 v[40:41], v[48:49], v[40:41], v[46:47]
	s_nop 0
	s_waitcnt lgkmcnt(1)
	v_mfma_f32_16x16x32_bf16 v[30:33], v[30:33], v[176:179], v[38:41]
	s_nop 2
	s_nop 0
	s_waitcnt lgkmcnt(0)
	v_mfma_f32_16x16x32_bf16 v[38:41], v[14:17], v[180:183], v[30:33]
	s_cmpk_gt_u32 s6, 0x80
	s_cbranch_scc1 .LBB0_1165
.LBB0_1185:
	v_add_co_u32_e32 v16, vcc, 0x78152000, v162
	v_cvt_pk_bf16_f32 v14, v34, v35
	v_cvt_pk_bf16_f32 v15, v36, v37
	v_addc_co_u32_e32 v17, vcc, 0, v163, vcc
	s_mov_b32 s0, 0x78152000
	global_store_dwordx2 v[16:17], v[14:15], off
	v_add_co_u32_e32 v16, vcc, s0, v160
	ds_write_b64 v8, v[14:15] offset:9216
	v_cvt_pk_bf16_f32 v14, v38, v39
	v_cvt_pk_bf16_f32 v15, v40, v41
	v_addc_co_u32_e32 v17, vcc, 0, v161, vcc
	ds_write_b64 v8, v[14:15] offset:11520
	global_store_dwordx2 v[16:17], v[14:15], off
	s_waitcnt lgkmcnt(0)
	s_barrier
	ds_read_b128 v[168:171], v146 offset:9216
	ds_read_b128 v[172:175], v146 offset:9280
	ds_read_b128 v[176:179], v146 offset:11520
	ds_read_b128 v[180:183], v146 offset:11584
	s_nop 0
	v_lshlrev_b32_e32 v14, 16, v116
	v_and_b32_e32 v15, 0xffff0000, v116
	v_lshlrev_b32_e32 v16, 16, v117
	v_and_b32_e32 v17, 0xffff0000, v117
	v_pk_fma_f32 v[14:15], v[120:121], v[34:35], v[14:15]
	v_pk_fma_f32 v[16:17], v[122:123], v[36:37], v[16:17]
	s_waitcnt lgkmcnt(3)
	s_nop 0
	v_mfma_f32_16x16x32_bf16 v[14:17], v[10:13], v[168:171], v[14:17]
	s_nop 0
	s_waitcnt lgkmcnt(2)
	v_mfma_f32_16x16x32_bf16 v[34:37], v[4:7], v[172:175], v[14:17]
	s_nop 0
	s_nop 3
	v_lshlrev_b32_e32 v14, 16, v114
	v_and_b32_e32 v15, 0xffff0000, v114
	v_lshlrev_b32_e32 v16, 16, v115
	v_and_b32_e32 v17, 0xffff0000, v115
	v_pk_fma_f32 v[14:15], v[120:121], v[38:39], v[14:15]
	v_pk_fma_f32 v[16:17], v[122:123], v[40:41], v[16:17]
	s_waitcnt lgkmcnt(1)
	s_nop 0
	v_mfma_f32_16x16x32_bf16 v[10:13], v[10:13], v[176:179], v[14:17]
	s_nop 2
	s_nop 0
	s_waitcnt lgkmcnt(0)
	v_mfma_f32_16x16x32_bf16 v[38:41], v[4:7], v[180:183], v[10:13]
	s_branch .LBB0_1165

; __device__ __forceinline__ void rw_prep(LAS float* SCR, const RwCtx& X, int b, int h, int t0, int tid, RwTok& K) {
;     ...
;     for (int i = 0; i < 8; ++i) { float off = 0.f;
; #pragma unroll
;         for (int w = 0; w < 7; ++w) if (w < wave) off += SCR[w * 64 + dq * 8 + i];
;         K.cw[i] += off; }
.LBB0_1247:
	s_or_b64 exec, exec, s[0:1]
	s_waitcnt lgkmcnt(0)
	s_barrier
	v_readlane_b32 s0, v254, 49
	v_cmp_lt_i32_e32 vcc, 0, v36
	s_nop 0
	v_lshl_add_u32 v47, v35, 2, s0
	v_cmp_lt_i32_e64 s[46:47], 1, v36
	v_cmp_lt_i32_e64 s[48:49], 2, v36
	v_cmp_lt_i32_e64 s[50:51], 3, v36
	v_cmp_lt_i32_e64 s[52:53], 4, v36
	v_cmp_lt_i32_e64 s[54:55], 5, v36
	v_cmp_lt_i32_e64 s[56:57], 6, v36
	ds_read_b128 v[156:159], v47 offset:0
	ds_read_b128 v[160:163], v47 offset:16
	ds_read_b128 v[164:167], v47 offset:256
	ds_read_b128 v[168:171], v47 offset:272
	ds_read_b128 v[172:175], v47 offset:512
	ds_read_b128 v[176:179], v47 offset:528
	ds_read_b128 v[180:183], v47 offset:768
	ds_read_b128 v[184:187], v47 offset:784
	ds_read_b128 v[188:191], v47 offset:1024
	ds_read_b128 v[192:195], v47 offset:1040
	ds_read_b128 v[196:199], v47 offset:1280
	ds_read_b128 v[200:203], v47 offset:1296
	ds_read_b128 v[204:207], v47 offset:1536
	ds_read_b128 v[208:211], v47 offset:1552
	v_cndmask_b32_e64 v212, 0, 1.0, vcc
	v_cndmask_b32_e64 v213, 0, 1.0, s[46:47]
	v_cndmask_b32_e64 v214, 0, 1.0, s[48:49]
	v_cndmask_b32_e64 v215, 0, 1.0, s[50:51]
	v_cndmask_b32_e64 v216, 0, 1.0, s[52:53]
	v_cndmask_b32_e64 v217, 0, 1.0, s[54:55]
	v_cndmask_b32_e64 v218, 0, 1.0, s[56:57]
	v_mov_b32_e32 v35, 0
	v_mov_b32_e32 v36, 0
	v_mov_b32_e32 v72, 0
	v_mov_b32_e32 v74, 0
	v_mov_b32_e32 v73, 0
	v_mov_b32_e32 v71, 0
	v_mov_b32_e32 v70, 0
	v_mov_b32_e32 v53, 0
	s_waitcnt lgkmcnt(0)
	v_fmac_f32_e32 v35, v212, v156
	v_fmac_f32_e32 v36, v212, v157
	v_fmac_f32_e32 v72, v212, v158
	v_fmac_f32_e32 v74, v212, v159
	v_fmac_f32_e32 v73, v212, v160
	v_fmac_f32_e32 v71, v212, v161
	v_fmac_f32_e32 v70, v212, v162
	v_fmac_f32_e32 v53, v212, v163
	v_fmac_f32_e32 v35, v213, v164
	v_fmac_f32_e32 v36, v213, v165
	v_fmac_f32_e32 v72, v213, v166
	v_fmac_f32_e32 v74, v213, v167
	v_fmac_f32_e32 v73, v213, v168
	v_fmac_f32_e32 v71, v213, v169
	v_fmac_f32_e32 v70, v213, v170
	v_fmac_f32_e32 v53, v213, v171
	v_fmac_f32_e32 v35, v214, v172
	v_fmac_f32_e32 v36, v214, v173
	v_fmac_f32_e32 v72, v214, v174
	v_fmac_f32_e32 v74, v214, v175
	v_fmac_f32_e32 v73, v214, v176
	v_fmac_f32_e32 v71, v214, v177
	v_fmac_f32_e32 v70, v214, v178
	v_fmac_f32_e32 v53, v214, v179
	v_fmac_f32_e32 v35, v215, v180
	v_fmac_f32_e32 v36, v215, v181
	v_fmac_f32_e32 v72, v215, v182
	v_fmac_f32_e32 v74, v215, v183
	v_fmac_f32_e32 v73, v215, v184
	v_fmac_f32_e32 v71, v215, v185
	v_fmac_f32_e32 v70, v215, v186
	v_fmac_f32_e32 v53, v215, v187
	v_fmac_f32_e32 v35, v216, v188
	v_fmac_f32_e32 v36, v216, v189
	v_fmac_f32_e32 v72, v216, v190
	v_fmac_f32_e32 v74, v216, v191
	v_fmac_f32_e32 v73, v216, v192
	v_fmac_f32_e32 v71, v216, v193
	v_fmac_f32_e32 v70, v216, v194
	v_fmac_f32_e32 v53, v216, v195
	v_fmac_f32_e32 v35, v217, v196
	v_fmac_f32_e32 v36, v217, v197
	v_fmac_f32_e32 v72, v217, v198
	v_fmac_f32_e32 v74, v217, v199
	v_fmac_f32_e32 v73, v217, v200
	v_fmac_f32_e32 v71, v217, v201
	v_fmac_f32_e32 v70, v217, v202
	v_fmac_f32_e32 v53, v217, v203
	v_fmac_f32_e32 v35, v218, v204
	v_fmac_f32_e32 v36, v218, v205
	v_fmac_f32_e32 v72, v218, v206
	v_fmac_f32_e32 v74, v218, v207
	v_fmac_f32_e32 v73, v218, v208
	v_fmac_f32_e32 v71, v218, v209
	v_fmac_f32_e32 v70, v218, v210
	v_fmac_f32_e32 v53, v218, v211

; #define LAS __attribute__((address_space(3)))
; __device__ __forceinline__ unsigned cvt_pk_bf16(float lo, float hi) { const bf16x2_t r = __builtin_convertvector((f32x2){lo, hi}, bf16x2_t); return __builtin_bit_cast(unsigned, r); }
; #define LDS_BAR() do { asm volatile("s_waitcnt lgkmcnt(0)" ::: "memory"); __builtin_amdgcn_s_barrier(); asm volatile("" ::: "memory"); } while (0)
; __device__ __forceinline__ void rw_phaseC(LAS unsigned char* lds, const RwCtx& X, int item) {
;     ...
;         for (int bi = 0; bi < 2; ++bi) { const int v0 = ((wave & 1) * 2 + bi) * 16; f32x4 acc = (f32x4){0.f, 0.f, 0.f, 0.f};
; #pragma unroll
;             for (int k = 0; k < 2; ++k) { const bf16x8 a1 = *(const LAS bf16x8*)(ST + (v0 + fr) * 72 + k * 32 + fq * 8), a2 = *(const LAS bf16x8*)(UT + (v0 + fr) * 72 + k * 32 + fq * 8), a3 = *(const LAS bf16x8*)(VT + (v0 + fr) * 72 + k * 32 + fq * 8);
;                 acc = __builtin_amdgcn_mfma_f32_16x16x32_bf16(a1, f1[k], acc, 0, 0, 0); acc = __builtin_amdgcn_mfma_f32_16x16x32_bf16(a2, f2[k], acc, 0, 0, 0); acc = __builtin_amdgcn_mfma_f32_16x16x32_bf16(a3, f3[k], acc, 0, 0, 0); }
;             if (tt < T) { u32x2 o; o.x = cvt_pk_bf16(acc[0], acc[1]); o.y = cvt_pk_bf16(acc[2], acc[3]); *(u32x2*)(X.ORAW + ((size_t)b * T + tt) * 3072 + 2048 + h * 64 + v0 + fq * 4) = o; } }
;     }
;     LDS_BAR();
.LBB0_1310:
	s_or_b64 exec, exec, s[0:1]
	v_lshlrev_b32_e32 v31, 1, v31
	v_add_u32_e32 v30, v30, v31
	ds_read_b128 v[26:29], v30 offset:46080
	v_add_u32_e32 v31, v36, v31
	s_waitcnt lgkmcnt(0)
	v_mfma_f32_16x16x32_bf16 v[14:17], v[26:29], v[14:17], 0
	ds_read_b128 v[26:29], v31
	s_waitcnt lgkmcnt(0)
	v_mfma_f32_16x16x32_bf16 v[14:17], v[26:29], v[18:21], v[14:17]
	ds_read_b128 v[18:21], v30 offset:36864
	s_waitcnt lgkmcnt(0)
	v_mfma_f32_16x16x32_bf16 v[14:17], v[18:21], v[22:25], v[14:17]
	ds_read_b128 v[18:21], v30 offset:46144
	s_waitcnt lgkmcnt(0)
	v_mfma_f32_16x16x32_bf16 v[10:13], v[18:21], v[10:13], v[14:17]
	s_nop 4
	ds_read_b128 v[14:17], v31 offset:64
	s_waitcnt lgkmcnt(0)
	v_mfma_f32_16x16x32_bf16 v[4:7], v[14:17], v[4:7], v[10:13]
	s_nop 2
	ds_read_b128 v[10:13], v30 offset:36928
	s_waitcnt lgkmcnt(0)
	v_mfma_f32_16x16x32_bf16 v[0:3], v[10:13], v[0:3], v[4:7]
	s_and_saveexec_b64 s[0:1], s[42:43]
	s_cbranch_execz .LBB0_1244
	s_nop 5
	v_cvt_pk_bf16_f32 v0, v0, v1
	v_cvt_pk_bf16_f32 v1, v2, v3
	v_lshl_add_u64 v[2:3], v[34:35], 0, s[68:69]
	v_lshl_add_u64 v[2:3], v[2:3], 0, v[8:9]
	v_mov_b32_e32 v33, v9
	v_lshl_add_u64 v[2:3], v[2:3], 0, v[32:33]
	v_add_co_u32_e32 v2, vcc, 0x1000, v2
	s_nop 1
	v_addc_co_u32_e32 v3, vcc, 0, v3, vcc
	global_store_dwordx2 v[2:3], v[0:1], off offset:32
	s_branch .LBB0_1244
.LBB0_1367:
	s_or_b64 exec, exec, s[42:43]
	s_add_i32 s62, s62, s94
	s_add_i32 s61, s61, s33
	s_mul_i32 s0, s20, 0x8100
	s_waitcnt lgkmcnt(0)
	s_barrier
	s_add_u32 s6, s6, s0
	s_mul_hi_i32 s0, s20, 0x8100
	s_addc_u32 s7, s7, s0
	s_cmpk_gt_i32 s62, 0x101f
	s_cbranch_scc1 .LBB0_1241

;     __device__ __forceinline__ void operator()(const f32x4 (&acc)[2][2][4][2], const pg8::Unit& u, int wr, int wc, int fr, int fq) const {
;         const int z = u.z;
;         EPI_LOOP_BEGIN
;             float g[8]; unpack8(*(const u32x4*)(PROJ + (size_t)row * NP + C_G + z * 2048 + col), g);
;             bf16_t* mp = MERGED + (size_t)row * D + col;
;             if (z == 0) {
; #pragma unroll
;                 for (int i = 0; i < 8; ++i) v[i] *= g[i];
;             } else {
;                 float mm[8]; unpack8(*(const u32x4*)mp, mm);
; #pragma unroll
;                 for (int i = 0; i < 8; ++i) v[i] = mm[i] + v[i] * g[i];
;             }
;             *(u32x4*)mp = pack8(v);
.LBB0_1593:
	v_lshl_or_b32 v138, s75, 8, v175
	v_lshl_add_u32 v152, s86, 8, v146
	s_lshl_b32 s54, s74, 11
	s_ashr_i32 s55, s54, 31
	v_mul_lo_u32 v150, v152, s58
	v_lshlrev_b32_e32 v151, 12, v152
	v_lshl_add_u32 v150, v138, 1, v150
	v_lshl_add_u32 v151, v138, 1, v151
	s_lshl_b32 s100, s74, 12
	s_add_u32 s100, s100, s85
	s_add_u32 s100, s78, s100
	s_addc_u32 s101, s79, 0
	s_cmp_lg_u32 s74, 0
	s_cselect_b64 s[56:57], -1, 0
	s_cbranch_scc0 .Lg2epi_z0
	v_add_u32_e32 v152, 0x0, v150
	v_add_u32_e32 v153, 0x0, v151
	global_load_dwordx4 v[182:185], v152, s[100:101] offset:0
	global_load_dwordx4 v[186:189], v153, s[80:81] offset:0
	global_load_dwordx4 v[190:193], v152, s[100:101] offset:256
	global_load_dwordx4 v[194:197], v153, s[80:81] offset:256
	v_add_u32_e32 v152, 0x92000, v150
	v_add_u32_e32 v153, 0x10000, v151
	global_load_dwordx4 v[198:201], v152, s[100:101] offset:0
	global_load_dwordx4 v[202:205], v153, s[80:81] offset:0
	global_load_dwordx4 v[206:209], v152, s[100:101] offset:256
	global_load_dwordx4 v[210:213], v153, s[80:81] offset:256
	v_add_u32_e32 v153, 0x0, v151
	s_waitcnt vmcnt(6)
	v_lshlrev_b32_e32 v154, 16, v182
	v_and_b32_e32 v155, 0xffff0000, v182
	v_lshlrev_b32_e32 v156, 16, v183
	v_and_b32_e32 v157, 0xffff0000, v183
	v_lshlrev_b32_e32 v158, 16, v184
	v_and_b32_e32 v159, 0xffff0000, v184
	v_lshlrev_b32_e32 v160, 16, v185
	v_and_b32_e32 v161, 0xffff0000, v185
	v_lshlrev_b32_e32 v162, 16, v186
	v_and_b32_e32 v163, 0xffff0000, v186
	v_lshlrev_b32_e32 v164, 16, v187
	v_and_b32_e32 v165, 0xffff0000, v187
	v_lshlrev_b32_e32 v166, 16, v188
	v_and_b32_e32 v167, 0xffff0000, v188
	v_lshlrev_b32_e32 v168, 16, v189
	v_and_b32_e32 v169, 0xffff0000, v189
	v_pk_fma_f32 v[126:127], v[126:127], v[154:155], v[162:163]
	v_pk_fma_f32 v[128:129], v[128:129], v[156:157], v[164:165]
	v_pk_fma_f32 v[122:123], v[122:123], v[158:159], v[166:167]
	v_pk_fma_f32 v[124:125], v[124:125], v[160:161], v[168:169]
	v_cvt_pk_bf16_f32 v182, v126, v127
	v_cvt_pk_bf16_f32 v183, v128, v129
	v_cvt_pk_bf16_f32 v184, v122, v123
	v_cvt_pk_bf16_f32 v185, v124, v125
	global_store_dwordx4 v153, v[182:185], s[80:81] offset:0
	s_waitcnt vmcnt(5)
	v_lshlrev_b32_e32 v154, 16, v190
	v_and_b32_e32 v155, 0xffff0000, v190
	v_lshlrev_b32_e32 v156, 16, v191
	v_and_b32_e32 v157, 0xffff0000, v191
	v_lshlrev_b32_e32 v158, 16, v192
	v_and_b32_e32 v159, 0xffff0000, v192
	v_lshlrev_b32_e32 v160, 16, v193
	v_and_b32_e32 v161, 0xffff0000, v193
	v_lshlrev_b32_e32 v162, 16, v194
	v_and_b32_e32 v163, 0xffff0000, v194
	v_lshlrev_b32_e32 v164, 16, v195
	v_and_b32_e32 v165, 0xffff0000, v195
	v_lshlrev_b32_e32 v166, 16, v196
	v_and_b32_e32 v167, 0xffff0000, v196
	v_lshlrev_b32_e32 v168, 16, v197
	v_and_b32_e32 v169, 0xffff0000, v197
	v_pk_fma_f32 v[118:119], v[118:119], v[154:155], v[162:163]
	v_pk_fma_f32 v[120:121], v[120:121], v[156:157], v[164:165]
	v_pk_fma_f32 v[114:115], v[114:115], v[158:159], v[166:167]
	v_pk_fma_f32 v[116:117], v[116:117], v[160:161], v[168:169]
	v_cvt_pk_bf16_f32 v190, v118, v119
	v_cvt_pk_bf16_f32 v191, v120, v121
	v_cvt_pk_bf16_f32 v192, v114, v115
	v_cvt_pk_bf16_f32 v193, v116, v117
	global_store_dwordx4 v153, v[190:193], s[80:81] offset:256
	v_add_u32_e32 v153, 0x10000, v151
	s_waitcnt vmcnt(4)
	v_lshlrev_b32_e32 v154, 16, v198
	v_and_b32_e32 v155, 0xffff0000, v198
	v_lshlrev_b32_e32 v156, 16, v199
	v_and_b32_e32 v157, 0xffff0000, v199
	v_lshlrev_b32_e32 v158, 16, v200
	v_and_b32_e32 v159, 0xffff0000, v200
	v_lshlrev_b32_e32 v160, 16, v201
	v_and_b32_e32 v161, 0xffff0000, v201
	v_lshlrev_b32_e32 v162, 16, v202
	v_and_b32_e32 v163, 0xffff0000, v202
	v_lshlrev_b32_e32 v164, 16, v203
	v_and_b32_e32 v165, 0xffff0000, v203
	v_lshlrev_b32_e32 v166, 16, v204
	v_and_b32_e32 v167, 0xffff0000, v204
	v_lshlrev_b32_e32 v168, 16, v205
	v_and_b32_e32 v169, 0xffff0000, v205
	v_pk_fma_f32 v[110:111], v[110:111], v[154:155], v[162:163]
	v_pk_fma_f32 v[112:113], v[112:113], v[156:157], v[164:165]
	v_pk_fma_f32 v[106:107], v[106:107], v[158:159], v[166:167]
	v_pk_fma_f32 v[108:109], v[108:109], v[160:161], v[168:169]
	v_cvt_pk_bf16_f32 v198, v110, v111
	v_cvt_pk_bf16_f32 v199, v112, v113
	v_cvt_pk_bf16_f32 v200, v106, v107
	v_cvt_pk_bf16_f32 v201, v108, v109
	global_store_dwordx4 v153, v[198:201], s[80:81] offset:0
	s_waitcnt vmcnt(3)
	v_lshlrev_b32_e32 v154, 16, v206
	v_and_b32_e32 v155, 0xffff0000, v206
	v_lshlrev_b32_e32 v156, 16, v207
	v_and_b32_e32 v157, 0xffff0000, v207
	v_lshlrev_b32_e32 v158, 16, v208
	v_and_b32_e32 v159, 0xffff0000, v208
	v_lshlrev_b32_e32 v160, 16, v209
	v_and_b32_e32 v161, 0xffff0000, v209
	v_lshlrev_b32_e32 v162, 16, v210
	v_and_b32_e32 v163, 0xffff0000, v210
	v_lshlrev_b32_e32 v164, 16, v211
	v_and_b32_e32 v165, 0xffff0000, v211
	v_lshlrev_b32_e32 v166, 16, v212
	v_and_b32_e32 v167, 0xffff0000, v212
	v_lshlrev_b32_e32 v168, 16, v213
	v_and_b32_e32 v169, 0xffff0000, v213
	v_pk_fma_f32 v[102:103], v[102:103], v[154:155], v[162:163]
	v_pk_fma_f32 v[104:105], v[104:105], v[156:157], v[164:165]
	v_pk_fma_f32 v[98:99], v[98:99], v[158:159], v[166:167]
	v_pk_fma_f32 v[100:101], v[100:101], v[160:161], v[168:169]
	v_cvt_pk_bf16_f32 v206, v102, v103
	v_cvt_pk_bf16_f32 v207, v104, v105
	v_cvt_pk_bf16_f32 v208, v98, v99
	v_cvt_pk_bf16_f32 v209, v100, v101
	global_store_dwordx4 v153, v[206:209], s[80:81] offset:256
	v_add_u32_e32 v152, 0x124000, v150
	v_add_u32_e32 v153, 0x20000, v151
	global_load_dwordx4 v[182:185], v152, s[100:101] offset:0
	global_load_dwordx4 v[186:189], v153, s[80:81] offset:0
	global_load_dwordx4 v[190:193], v152, s[100:101] offset:256
	global_load_dwordx4 v[194:197], v153, s[80:81] offset:256
	v_add_u32_e32 v152, 0x1b6000, v150
	v_add_u32_e32 v153, 0x30000, v151
	global_load_dwordx4 v[198:201], v152, s[100:101] offset:0
	global_load_dwordx4 v[202:205], v153, s[80:81] offset:0
	global_load_dwordx4 v[206:209], v152, s[100:101] offset:256
	global_load_dwordx4 v[210:213], v153, s[80:81] offset:256
	v_add_u32_e32 v153, 0x20000, v151
	s_waitcnt vmcnt(6)
;     __device__ __forceinline__ void operator()(const f32x4 (&acc)[2][2][4][2], const pg8::Unit& u, int wr, int wc, int fr, int fq) const {
;         const int z = u.z;
;         EPI_LOOP_BEGIN
;             float g[8]; unpack8(*(const u32x4*)(PROJ + (size_t)row * NP + C_G + z * 2048 + col), g);
;             bf16_t* mp = MERGED + (size_t)row * D + col;
;             if (z == 0) {
; #pragma unroll
;                 for (int i = 0; i < 8; ++i) v[i] *= g[i];
;             } else {
;                 float mm[8]; unpack8(*(const u32x4*)mp, mm);
; #pragma unroll
;                 for (int i = 0; i < 8; ++i) v[i] = mm[i] + v[i] * g[i];
;             }
;             *(u32x4*)mp = pack8(v);
;         EPI_LOOP_END
	v_lshlrev_b32_e32 v154, 16, v182
	v_and_b32_e32 v155, 0xffff0000, v182
	v_lshlrev_b32_e32 v156, 16, v183
	v_and_b32_e32 v157, 0xffff0000, v183
	v_lshlrev_b32_e32 v158, 16, v184
	v_and_b32_e32 v159, 0xffff0000, v184
	v_lshlrev_b32_e32 v160, 16, v185
	v_and_b32_e32 v161, 0xffff0000, v185
	v_lshlrev_b32_e32 v162, 16, v186
	v_and_b32_e32 v163, 0xffff0000, v186
	v_lshlrev_b32_e32 v164, 16, v187
	v_and_b32_e32 v165, 0xffff0000, v187
	v_lshlrev_b32_e32 v166, 16, v188
	v_and_b32_e32 v167, 0xffff0000, v188
	v_lshlrev_b32_e32 v168, 16, v189
	v_and_b32_e32 v169, 0xffff0000, v189
	v_pk_fma_f32 v[94:95], v[94:95], v[154:155], v[162:163]
	v_pk_fma_f32 v[96:97], v[96:97], v[156:157], v[164:165]
	v_pk_fma_f32 v[90:91], v[90:91], v[158:159], v[166:167]
	v_pk_fma_f32 v[92:93], v[92:93], v[160:161], v[168:169]
	v_cvt_pk_bf16_f32 v182, v94, v95
	v_cvt_pk_bf16_f32 v183, v96, v97
	v_cvt_pk_bf16_f32 v184, v90, v91
	v_cvt_pk_bf16_f32 v185, v92, v93
	global_store_dwordx4 v153, v[182:185], s[80:81] offset:0
	s_waitcnt vmcnt(5)
	v_lshlrev_b32_e32 v154, 16, v190
	v_and_b32_e32 v155, 0xffff0000, v190
	v_lshlrev_b32_e32 v156, 16, v191
	v_and_b32_e32 v157, 0xffff0000, v191
	v_lshlrev_b32_e32 v158, 16, v192
	v_and_b32_e32 v159, 0xffff0000, v192
	v_lshlrev_b32_e32 v160, 16, v193
	v_and_b32_e32 v161, 0xffff0000, v193
	v_lshlrev_b32_e32 v162, 16, v194
	v_and_b32_e32 v163, 0xffff0000, v194
	v_lshlrev_b32_e32 v164, 16, v195
	v_and_b32_e32 v165, 0xffff0000, v195
	v_lshlrev_b32_e32 v166, 16, v196
	v_and_b32_e32 v167, 0xffff0000, v196
	v_lshlrev_b32_e32 v168, 16, v197
	v_and_b32_e32 v169, 0xffff0000, v197
	v_pk_fma_f32 v[86:87], v[86:87], v[154:155], v[162:163]
	v_pk_fma_f32 v[88:89], v[88:89], v[156:157], v[164:165]
	v_pk_fma_f32 v[82:83], v[82:83], v[158:159], v[166:167]
	v_pk_fma_f32 v[84:85], v[84:85], v[160:161], v[168:169]
	v_cvt_pk_bf16_f32 v190, v86, v87
	v_cvt_pk_bf16_f32 v191, v88, v89
	v_cvt_pk_bf16_f32 v192, v82, v83
	v_cvt_pk_bf16_f32 v193, v84, v85
	global_store_dwordx4 v153, v[190:193], s[80:81] offset:256
	v_add_u32_e32 v153, 0x30000, v151
	s_waitcnt vmcnt(4)
	v_lshlrev_b32_e32 v154, 16, v198
	v_and_b32_e32 v155, 0xffff0000, v198
	v_lshlrev_b32_e32 v156, 16, v199
	v_and_b32_e32 v157, 0xffff0000, v199
	v_lshlrev_b32_e32 v158, 16, v200
	v_and_b32_e32 v159, 0xffff0000, v200
	v_lshlrev_b32_e32 v160, 16, v201
	v_and_b32_e32 v161, 0xffff0000, v201
	v_lshlrev_b32_e32 v162, 16, v202
	v_and_b32_e32 v163, 0xffff0000, v202
	v_lshlrev_b32_e32 v164, 16, v203
	v_and_b32_e32 v165, 0xffff0000, v203
	v_lshlrev_b32_e32 v166, 16, v204
	v_and_b32_e32 v167, 0xffff0000, v204
	v_lshlrev_b32_e32 v168, 16, v205
	v_and_b32_e32 v169, 0xffff0000, v205
	v_pk_fma_f32 v[78:79], v[78:79], v[154:155], v[162:163]
	v_pk_fma_f32 v[80:81], v[80:81], v[156:157], v[164:165]
	v_pk_fma_f32 v[74:75], v[74:75], v[158:159], v[166:167]
	v_pk_fma_f32 v[76:77], v[76:77], v[160:161], v[168:169]
	v_cvt_pk_bf16_f32 v198, v78, v79
	v_cvt_pk_bf16_f32 v199, v80, v81
	v_cvt_pk_bf16_f32 v200, v74, v75
	v_cvt_pk_bf16_f32 v201, v76, v77
	global_store_dwordx4 v153, v[198:201], s[80:81] offset:0
	s_waitcnt vmcnt(3)
	v_lshlrev_b32_e32 v154, 16, v206
	v_and_b32_e32 v155, 0xffff0000, v206
	v_lshlrev_b32_e32 v156, 16, v207
	v_and_b32_e32 v157, 0xffff0000, v207
	v_lshlrev_b32_e32 v158, 16, v208
	v_and_b32_e32 v159, 0xffff0000, v208
	v_lshlrev_b32_e32 v160, 16, v209
	v_and_b32_e32 v161, 0xffff0000, v209
	v_lshlrev_b32_e32 v162, 16, v210
	v_and_b32_e32 v163, 0xffff0000, v210
	v_lshlrev_b32_e32 v164, 16, v211
	v_and_b32_e32 v165, 0xffff0000, v211
	v_lshlrev_b32_e32 v166, 16, v212
	v_and_b32_e32 v167, 0xffff0000, v212
	v_lshlrev_b32_e32 v168, 16, v213
	v_and_b32_e32 v169, 0xffff0000, v213
	v_pk_fma_f32 v[70:71], v[70:71], v[154:155], v[162:163]
	v_pk_fma_f32 v[72:73], v[72:73], v[156:157], v[164:165]
	v_pk_fma_f32 v[66:67], v[66:67], v[158:159], v[166:167]
	v_pk_fma_f32 v[68:69], v[68:69], v[160:161], v[168:169]
	v_cvt_pk_bf16_f32 v206, v70, v71
	v_cvt_pk_bf16_f32 v207, v72, v73
	v_cvt_pk_bf16_f32 v208, v66, v67
	v_cvt_pk_bf16_f32 v209, v68, v69
	global_store_dwordx4 v153, v[206:209], s[80:81] offset:256
	v_add_u32_e32 v152, 0x490000, v150
	v_add_u32_e32 v153, 0x80000, v151
	global_load_dwordx4 v[182:185], v152, s[100:101] offset:0
	global_load_dwordx4 v[186:189], v153, s[80:81] offset:0
	global_load_dwordx4 v[190:193], v152, s[100:101] offset:256
	global_load_dwordx4 v[194:197], v153, s[80:81] offset:256
	v_add_u32_e32 v152, 0x522000, v150
	v_add_u32_e32 v153, 0x90000, v151
	global_load_dwordx4 v[198:201], v152, s[100:101] offset:0
	global_load_dwordx4 v[202:205], v153, s[80:81] offset:0
	global_load_dwordx4 v[206:209], v152, s[100:101] offset:256
	global_load_dwordx4 v[210:213], v153, s[80:81] offset:256
	v_add_u32_e32 v153, 0x80000, v151
	s_waitcnt vmcnt(6)
	v_lshlrev_b32_e32 v154, 16, v182
	v_and_b32_e32 v155, 0xffff0000, v182
	v_lshlrev_b32_e32 v156, 16, v183
	v_and_b32_e32 v157, 0xffff0000, v183
	v_lshlrev_b32_e32 v158, 16, v184
	v_and_b32_e32 v159, 0xffff0000, v184
	v_lshlrev_b32_e32 v160, 16, v185
	v_and_b32_e32 v161, 0xffff0000, v185
	v_lshlrev_b32_e32 v162, 16, v186
	v_and_b32_e32 v163, 0xffff0000, v186
	v_lshlrev_b32_e32 v164, 16, v187
	v_and_b32_e32 v165, 0xffff0000, v187
	v_lshlrev_b32_e32 v166, 16, v188
	v_and_b32_e32 v167, 0xffff0000, v188
	v_lshlrev_b32_e32 v168, 16, v189
	v_and_b32_e32 v169, 0xffff0000, v189
	v_pk_fma_f32 v[62:63], v[62:63], v[154:155], v[162:163]
	v_pk_fma_f32 v[64:65], v[64:65], v[156:157], v[164:165]
	v_pk_fma_f32 v[58:59], v[58:59], v[158:159], v[166:167]
	v_pk_fma_f32 v[60:61], v[60:61], v[160:161], v[168:169]
	v_cvt_pk_bf16_f32 v182, v62, v63
	v_cvt_pk_bf16_f32 v183, v64, v65
	v_cvt_pk_bf16_f32 v184, v58, v59
	v_cvt_pk_bf16_f32 v185, v60, v61
	global_store_dwordx4 v153, v[182:185], s[80:81] offset:0
	s_waitcnt vmcnt(5)
;     __device__ __forceinline__ void operator()(const f32x4 (&acc)[2][2][4][2], const pg8::Unit& u, int wr, int wc, int fr, int fq) const {
;         const int z = u.z;
;         EPI_LOOP_BEGIN
;             float g[8]; unpack8(*(const u32x4*)(PROJ + (size_t)row * NP + C_G + z * 2048 + col), g);
;             bf16_t* mp = MERGED + (size_t)row * D + col;
;             if (z == 0) {
; #pragma unroll
;                 for (int i = 0; i < 8; ++i) v[i] *= g[i];
;             } else {
;                 float mm[8]; unpack8(*(const u32x4*)mp, mm);
; #pragma unroll
;                 for (int i = 0; i < 8; ++i) v[i] = mm[i] + v[i] * g[i];
;             }
;             *(u32x4*)mp = pack8(v);
;         EPI_LOOP_END
	v_lshlrev_b32_e32 v154, 16, v190
	v_and_b32_e32 v155, 0xffff0000, v190
	v_lshlrev_b32_e32 v156, 16, v191
	v_and_b32_e32 v157, 0xffff0000, v191
	v_lshlrev_b32_e32 v158, 16, v192
	v_and_b32_e32 v159, 0xffff0000, v192
	v_lshlrev_b32_e32 v160, 16, v193
	v_and_b32_e32 v161, 0xffff0000, v193
	v_lshlrev_b32_e32 v162, 16, v194
	v_and_b32_e32 v163, 0xffff0000, v194
	v_lshlrev_b32_e32 v164, 16, v195
	v_and_b32_e32 v165, 0xffff0000, v195
	v_lshlrev_b32_e32 v166, 16, v196
	v_and_b32_e32 v167, 0xffff0000, v196
	v_lshlrev_b32_e32 v168, 16, v197
	v_and_b32_e32 v169, 0xffff0000, v197
	v_pk_fma_f32 v[54:55], v[54:55], v[154:155], v[162:163]
	v_pk_fma_f32 v[56:57], v[56:57], v[156:157], v[164:165]
	v_pk_fma_f32 v[50:51], v[50:51], v[158:159], v[166:167]
	v_pk_fma_f32 v[52:53], v[52:53], v[160:161], v[168:169]
	v_cvt_pk_bf16_f32 v190, v54, v55
	v_cvt_pk_bf16_f32 v191, v56, v57
	v_cvt_pk_bf16_f32 v192, v50, v51
	v_cvt_pk_bf16_f32 v193, v52, v53
	global_store_dwordx4 v153, v[190:193], s[80:81] offset:256
	v_add_u32_e32 v153, 0x90000, v151
	s_waitcnt vmcnt(4)
	v_lshlrev_b32_e32 v154, 16, v198
	v_and_b32_e32 v155, 0xffff0000, v198
	v_lshlrev_b32_e32 v156, 16, v199
	v_and_b32_e32 v157, 0xffff0000, v199
	v_lshlrev_b32_e32 v158, 16, v200
	v_and_b32_e32 v159, 0xffff0000, v200
	v_lshlrev_b32_e32 v160, 16, v201
	v_and_b32_e32 v161, 0xffff0000, v201
	v_lshlrev_b32_e32 v162, 16, v202
	v_and_b32_e32 v163, 0xffff0000, v202
	v_lshlrev_b32_e32 v164, 16, v203
	v_and_b32_e32 v165, 0xffff0000, v203
	v_lshlrev_b32_e32 v166, 16, v204
	v_and_b32_e32 v167, 0xffff0000, v204
	v_lshlrev_b32_e32 v168, 16, v205
	v_and_b32_e32 v169, 0xffff0000, v205
	v_pk_fma_f32 v[46:47], v[46:47], v[154:155], v[162:163]
	v_pk_fma_f32 v[48:49], v[48:49], v[156:157], v[164:165]
	v_pk_fma_f32 v[42:43], v[42:43], v[158:159], v[166:167]
	v_pk_fma_f32 v[44:45], v[44:45], v[160:161], v[168:169]
	v_cvt_pk_bf16_f32 v198, v46, v47
	v_cvt_pk_bf16_f32 v199, v48, v49
	v_cvt_pk_bf16_f32 v200, v42, v43
	v_cvt_pk_bf16_f32 v201, v44, v45
	global_store_dwordx4 v153, v[198:201], s[80:81] offset:0
	s_waitcnt vmcnt(3)
	v_lshlrev_b32_e32 v154, 16, v206
	v_and_b32_e32 v155, 0xffff0000, v206
	v_lshlrev_b32_e32 v156, 16, v207
	v_and_b32_e32 v157, 0xffff0000, v207
	v_lshlrev_b32_e32 v158, 16, v208
	v_and_b32_e32 v159, 0xffff0000, v208
	v_lshlrev_b32_e32 v160, 16, v209
	v_and_b32_e32 v161, 0xffff0000, v209
	v_lshlrev_b32_e32 v162, 16, v210
	v_and_b32_e32 v163, 0xffff0000, v210
	v_lshlrev_b32_e32 v164, 16, v211
	v_and_b32_e32 v165, 0xffff0000, v211
	v_lshlrev_b32_e32 v166, 16, v212
	v_and_b32_e32 v167, 0xffff0000, v212
	v_lshlrev_b32_e32 v168, 16, v213
	v_and_b32_e32 v169, 0xffff0000, v213
	v_pk_fma_f32 v[38:39], v[38:39], v[154:155], v[162:163]
	v_pk_fma_f32 v[40:41], v[40:41], v[156:157], v[164:165]
	v_pk_fma_f32 v[34:35], v[34:35], v[158:159], v[166:167]
	v_pk_fma_f32 v[36:37], v[36:37], v[160:161], v[168:169]
	v_cvt_pk_bf16_f32 v206, v38, v39
	v_cvt_pk_bf16_f32 v207, v40, v41
	v_cvt_pk_bf16_f32 v208, v34, v35
	v_cvt_pk_bf16_f32 v209, v36, v37
	global_store_dwordx4 v153, v[206:209], s[80:81] offset:256
	v_add_u32_e32 v152, 0x5b4000, v150
	v_add_u32_e32 v153, 0xa0000, v151
	global_load_dwordx4 v[182:185], v152, s[100:101] offset:0
	global_load_dwordx4 v[186:189], v153, s[80:81] offset:0
	global_load_dwordx4 v[190:193], v152, s[100:101] offset:256
	global_load_dwordx4 v[194:197], v153, s[80:81] offset:256
	v_add_u32_e32 v152, 0x646000, v150
	v_add_u32_e32 v153, 0xb0000, v151
	global_load_dwordx4 v[198:201], v152, s[100:101] offset:0
	global_load_dwordx4 v[202:205], v153, s[80:81] offset:0
	global_load_dwordx4 v[206:209], v152, s[100:101] offset:256
	global_load_dwordx4 v[210:213], v153, s[80:81] offset:256
	v_add_u32_e32 v153, 0xa0000, v151
	s_waitcnt vmcnt(6)
	v_lshlrev_b32_e32 v154, 16, v182
	v_and_b32_e32 v155, 0xffff0000, v182
	v_lshlrev_b32_e32 v156, 16, v183
	v_and_b32_e32 v157, 0xffff0000, v183
	v_lshlrev_b32_e32 v158, 16, v184
	v_and_b32_e32 v159, 0xffff0000, v184
	v_lshlrev_b32_e32 v160, 16, v185
	v_and_b32_e32 v161, 0xffff0000, v185
	v_lshlrev_b32_e32 v162, 16, v186
	v_and_b32_e32 v163, 0xffff0000, v186
	v_lshlrev_b32_e32 v164, 16, v187
	v_and_b32_e32 v165, 0xffff0000, v187
	v_lshlrev_b32_e32 v166, 16, v188
	v_and_b32_e32 v167, 0xffff0000, v188
	v_lshlrev_b32_e32 v168, 16, v189
	v_and_b32_e32 v169, 0xffff0000, v189
	v_pk_fma_f32 v[30:31], v[30:31], v[154:155], v[162:163]
	v_pk_fma_f32 v[32:33], v[32:33], v[156:157], v[164:165]
	v_pk_fma_f32 v[26:27], v[26:27], v[158:159], v[166:167]
	v_pk_fma_f32 v[28:29], v[28:29], v[160:161], v[168:169]
	v_cvt_pk_bf16_f32 v182, v30, v31
	v_cvt_pk_bf16_f32 v183, v32, v33
	v_cvt_pk_bf16_f32 v184, v26, v27
	v_cvt_pk_bf16_f32 v185, v28, v29
	global_store_dwordx4 v153, v[182:185], s[80:81] offset:0
	s_waitcnt vmcnt(5)
	v_lshlrev_b32_e32 v154, 16, v190
	v_and_b32_e32 v155, 0xffff0000, v190
	v_lshlrev_b32_e32 v156, 16, v191
	v_and_b32_e32 v157, 0xffff0000, v191
	v_lshlrev_b32_e32 v158, 16, v192
	v_and_b32_e32 v159, 0xffff0000, v192
	v_lshlrev_b32_e32 v160, 16, v193
	v_and_b32_e32 v161, 0xffff0000, v193
	v_lshlrev_b32_e32 v162, 16, v194
	v_and_b32_e32 v163, 0xffff0000, v194
	v_lshlrev_b32_e32 v164, 16, v195
	v_and_b32_e32 v165, 0xffff0000, v195
	v_lshlrev_b32_e32 v166, 16, v196
	v_and_b32_e32 v167, 0xffff0000, v196
	v_lshlrev_b32_e32 v168, 16, v197
	v_and_b32_e32 v169, 0xffff0000, v197
	v_pk_fma_f32 v[22:23], v[22:23], v[154:155], v[162:163]
	v_pk_fma_f32 v[24:25], v[24:25], v[156:157], v[164:165]
	v_pk_fma_f32 v[18:19], v[18:19], v[158:159], v[166:167]
	v_pk_fma_f32 v[20:21], v[20:21], v[160:161], v[168:169]
	v_cvt_pk_bf16_f32 v190, v22, v23
	v_cvt_pk_bf16_f32 v191, v24, v25
	v_cvt_pk_bf16_f32 v192, v18, v19
	v_cvt_pk_bf16_f32 v193, v20, v21
	global_store_dwordx4 v153, v[190:193], s[80:81] offset:256
	v_add_u32_e32 v153, 0xb0000, v151
	s_waitcnt vmcnt(4)
;     __device__ __forceinline__ void operator()(const f32x4 (&acc)[2][2][4][2], const pg8::Unit& u, int wr, int wc, int fr, int fq) const {
;         const int z = u.z;
;         EPI_LOOP_BEGIN
;             float g[8]; unpack8(*(const u32x4*)(PROJ + (size_t)row * NP + C_G + z * 2048 + col), g);
;             bf16_t* mp = MERGED + (size_t)row * D + col;
;             if (z == 0) {
; #pragma unroll
;                 for (int i = 0; i < 8; ++i) v[i] *= g[i];
;             } else {
;                 float mm[8]; unpack8(*(const u32x4*)mp, mm);
; #pragma unroll
;                 for (int i = 0; i < 8; ++i) v[i] = mm[i] + v[i] * g[i];
;             }
;             *(u32x4*)mp = pack8(v);
;         EPI_LOOP_END
	v_lshlrev_b32_e32 v154, 16, v198
	v_and_b32_e32 v155, 0xffff0000, v198
	v_lshlrev_b32_e32 v156, 16, v199
	v_and_b32_e32 v157, 0xffff0000, v199
	v_lshlrev_b32_e32 v158, 16, v200
	v_and_b32_e32 v159, 0xffff0000, v200
	v_lshlrev_b32_e32 v160, 16, v201
	v_and_b32_e32 v161, 0xffff0000, v201
	v_lshlrev_b32_e32 v162, 16, v202
	v_and_b32_e32 v163, 0xffff0000, v202
	v_lshlrev_b32_e32 v164, 16, v203
	v_and_b32_e32 v165, 0xffff0000, v203
	v_lshlrev_b32_e32 v166, 16, v204
	v_and_b32_e32 v167, 0xffff0000, v204
	v_lshlrev_b32_e32 v168, 16, v205
	v_and_b32_e32 v169, 0xffff0000, v205
	v_pk_fma_f32 v[14:15], v[14:15], v[154:155], v[162:163]
	v_pk_fma_f32 v[16:17], v[16:17], v[156:157], v[164:165]
	v_pk_fma_f32 v[10:11], v[10:11], v[158:159], v[166:167]
	v_pk_fma_f32 v[12:13], v[12:13], v[160:161], v[168:169]
	v_cvt_pk_bf16_f32 v198, v14, v15
	v_cvt_pk_bf16_f32 v199, v16, v17
	v_cvt_pk_bf16_f32 v200, v10, v11
	v_cvt_pk_bf16_f32 v201, v12, v13
	global_store_dwordx4 v153, v[198:201], s[80:81] offset:0
	s_waitcnt vmcnt(3)
	v_lshlrev_b32_e32 v154, 16, v206
	v_and_b32_e32 v155, 0xffff0000, v206
	v_lshlrev_b32_e32 v156, 16, v207
	v_and_b32_e32 v157, 0xffff0000, v207
	v_lshlrev_b32_e32 v158, 16, v208
	v_and_b32_e32 v159, 0xffff0000, v208
	v_lshlrev_b32_e32 v160, 16, v209
	v_and_b32_e32 v161, 0xffff0000, v209
	v_lshlrev_b32_e32 v162, 16, v210
	v_and_b32_e32 v163, 0xffff0000, v210
	v_lshlrev_b32_e32 v164, 16, v211
	v_and_b32_e32 v165, 0xffff0000, v211
	v_lshlrev_b32_e32 v166, 16, v212
	v_and_b32_e32 v167, 0xffff0000, v212
	v_lshlrev_b32_e32 v168, 16, v213
	v_and_b32_e32 v169, 0xffff0000, v213
	v_pk_fma_f32 v[4:5], v[4:5], v[154:155], v[162:163]
	v_pk_fma_f32 v[6:7], v[6:7], v[156:157], v[164:165]
	v_pk_fma_f32 v[0:1], v[0:1], v[158:159], v[166:167]
	v_pk_fma_f32 v[2:3], v[2:3], v[160:161], v[168:169]
	v_cvt_pk_bf16_f32 v206, v4, v5
	v_cvt_pk_bf16_f32 v207, v6, v7
	v_cvt_pk_bf16_f32 v208, v0, v1
	v_cvt_pk_bf16_f32 v209, v2, v3
	global_store_dwordx4 v153, v[206:209], s[80:81] offset:256
	s_branch .Lg2epi_done
.Lg2epi_z0:
	v_add_u32_e32 v152, 0x0, v150
	global_load_dwordx4 v[182:185], v152, s[100:101] offset:0
	global_load_dwordx4 v[186:189], v152, s[100:101] offset:256
	v_add_u32_e32 v152, 0x92000, v150
	global_load_dwordx4 v[190:193], v152, s[100:101] offset:0
	global_load_dwordx4 v[194:197], v152, s[100:101] offset:256
	v_add_u32_e32 v152, 0x124000, v150
	global_load_dwordx4 v[198:201], v152, s[100:101] offset:0
	global_load_dwordx4 v[202:205], v152, s[100:101] offset:256
	v_add_u32_e32 v152, 0x1b6000, v150
	global_load_dwordx4 v[206:209], v152, s[100:101] offset:0
	global_load_dwordx4 v[210:213], v152, s[100:101] offset:256
	v_add_u32_e32 v153, 0x0, v151
	s_waitcnt vmcnt(7)
	v_lshlrev_b32_e32 v154, 16, v182
	v_and_b32_e32 v155, 0xffff0000, v182
	v_lshlrev_b32_e32 v156, 16, v183
	v_and_b32_e32 v157, 0xffff0000, v183
	v_lshlrev_b32_e32 v158, 16, v184
	v_and_b32_e32 v159, 0xffff0000, v184
	v_lshlrev_b32_e32 v160, 16, v185
	v_and_b32_e32 v161, 0xffff0000, v185
	v_pk_mul_f32 v[126:127], v[126:127], v[154:155]
	v_pk_mul_f32 v[128:129], v[128:129], v[156:157]
	v_pk_mul_f32 v[122:123], v[122:123], v[158:159]
	v_pk_mul_f32 v[124:125], v[124:125], v[160:161]
	v_cvt_pk_bf16_f32 v182, v126, v127
	v_cvt_pk_bf16_f32 v183, v128, v129
	v_cvt_pk_bf16_f32 v184, v122, v123
	v_cvt_pk_bf16_f32 v185, v124, v125
	global_store_dwordx4 v153, v[182:185], s[80:81] offset:0
	s_waitcnt vmcnt(7)
	v_lshlrev_b32_e32 v154, 16, v186
	v_and_b32_e32 v155, 0xffff0000, v186
	v_lshlrev_b32_e32 v156, 16, v187
	v_and_b32_e32 v157, 0xffff0000, v187
	v_lshlrev_b32_e32 v158, 16, v188
	v_and_b32_e32 v159, 0xffff0000, v188
	v_lshlrev_b32_e32 v160, 16, v189
	v_and_b32_e32 v161, 0xffff0000, v189
	v_pk_mul_f32 v[118:119], v[118:119], v[154:155]
	v_pk_mul_f32 v[120:121], v[120:121], v[156:157]
	v_pk_mul_f32 v[114:115], v[114:115], v[158:159]
	v_pk_mul_f32 v[116:117], v[116:117], v[160:161]
	v_cvt_pk_bf16_f32 v186, v118, v119
	v_cvt_pk_bf16_f32 v187, v120, v121
	v_cvt_pk_bf16_f32 v188, v114, v115
	v_cvt_pk_bf16_f32 v189, v116, v117
	global_store_dwordx4 v153, v[186:189], s[80:81] offset:256
	v_add_u32_e32 v153, 0x10000, v151
	s_waitcnt vmcnt(7)
	v_lshlrev_b32_e32 v154, 16, v190
	v_and_b32_e32 v155, 0xffff0000, v190
	v_lshlrev_b32_e32 v156, 16, v191
	v_and_b32_e32 v157, 0xffff0000, v191
	v_lshlrev_b32_e32 v158, 16, v192
	v_and_b32_e32 v159, 0xffff0000, v192
	v_lshlrev_b32_e32 v160, 16, v193
	v_and_b32_e32 v161, 0xffff0000, v193
	v_pk_mul_f32 v[110:111], v[110:111], v[154:155]
	v_pk_mul_f32 v[112:113], v[112:113], v[156:157]
	v_pk_mul_f32 v[106:107], v[106:107], v[158:159]
	v_pk_mul_f32 v[108:109], v[108:109], v[160:161]
	v_cvt_pk_bf16_f32 v190, v110, v111
	v_cvt_pk_bf16_f32 v191, v112, v113
	v_cvt_pk_bf16_f32 v192, v106, v107
	v_cvt_pk_bf16_f32 v193, v108, v109
	global_store_dwordx4 v153, v[190:193], s[80:81] offset:0
	s_waitcnt vmcnt(7)
	v_lshlrev_b32_e32 v154, 16, v194
	v_and_b32_e32 v155, 0xffff0000, v194
	v_lshlrev_b32_e32 v156, 16, v195
	v_and_b32_e32 v157, 0xffff0000, v195
	v_lshlrev_b32_e32 v158, 16, v196
	v_and_b32_e32 v159, 0xffff0000, v196
	v_lshlrev_b32_e32 v160, 16, v197
	v_and_b32_e32 v161, 0xffff0000, v197
	v_pk_mul_f32 v[102:103], v[102:103], v[154:155]
	v_pk_mul_f32 v[104:105], v[104:105], v[156:157]
	v_pk_mul_f32 v[98:99], v[98:99], v[158:159]
	v_pk_mul_f32 v[100:101], v[100:101], v[160:161]
	v_cvt_pk_bf16_f32 v194, v102, v103
	v_cvt_pk_bf16_f32 v195, v104, v105
	v_cvt_pk_bf16_f32 v196, v98, v99
	v_cvt_pk_bf16_f32 v197, v100, v101
	global_store_dwordx4 v153, v[194:197], s[80:81] offset:256
	v_add_u32_e32 v153, 0x20000, v151
	s_waitcnt vmcnt(7)
;     __device__ __forceinline__ void operator()(const f32x4 (&acc)[2][2][4][2], const pg8::Unit& u, int wr, int wc, int fr, int fq) const {
;     ...
;             if (z == 0) {
; #pragma unroll
;                 for (int i = 0; i < 8; ++i) v[i] *= g[i];
;             } else {
;                 float mm[8]; unpack8(*(const u32x4*)mp, mm);
; #pragma unroll
;                 for (int i = 0; i < 8; ++i) v[i] = mm[i] + v[i] * g[i];
;             }
;             *(u32x4*)mp = pack8(v);
	v_lshlrev_b32_e32 v154, 16, v198
	v_and_b32_e32 v155, 0xffff0000, v198
	v_lshlrev_b32_e32 v156, 16, v199
	v_and_b32_e32 v157, 0xffff0000, v199
	v_lshlrev_b32_e32 v158, 16, v200
	v_and_b32_e32 v159, 0xffff0000, v200
	v_lshlrev_b32_e32 v160, 16, v201
	v_and_b32_e32 v161, 0xffff0000, v201
	v_pk_mul_f32 v[94:95], v[94:95], v[154:155]
	v_pk_mul_f32 v[96:97], v[96:97], v[156:157]
	v_pk_mul_f32 v[90:91], v[90:91], v[158:159]
	v_pk_mul_f32 v[92:93], v[92:93], v[160:161]
	v_cvt_pk_bf16_f32 v198, v94, v95
	v_cvt_pk_bf16_f32 v199, v96, v97
	v_cvt_pk_bf16_f32 v200, v90, v91
	v_cvt_pk_bf16_f32 v201, v92, v93
	global_store_dwordx4 v153, v[198:201], s[80:81] offset:0
	s_waitcnt vmcnt(7)
	v_lshlrev_b32_e32 v154, 16, v202
	v_and_b32_e32 v155, 0xffff0000, v202
	v_lshlrev_b32_e32 v156, 16, v203
	v_and_b32_e32 v157, 0xffff0000, v203
	v_lshlrev_b32_e32 v158, 16, v204
	v_and_b32_e32 v159, 0xffff0000, v204
	v_lshlrev_b32_e32 v160, 16, v205
	v_and_b32_e32 v161, 0xffff0000, v205
	v_pk_mul_f32 v[86:87], v[86:87], v[154:155]
	v_pk_mul_f32 v[88:89], v[88:89], v[156:157]
	v_pk_mul_f32 v[82:83], v[82:83], v[158:159]
	v_pk_mul_f32 v[84:85], v[84:85], v[160:161]
	v_cvt_pk_bf16_f32 v202, v86, v87
	v_cvt_pk_bf16_f32 v203, v88, v89
	v_cvt_pk_bf16_f32 v204, v82, v83
	v_cvt_pk_bf16_f32 v205, v84, v85
	global_store_dwordx4 v153, v[202:205], s[80:81] offset:256
	v_add_u32_e32 v153, 0x30000, v151
	s_waitcnt vmcnt(7)
	v_lshlrev_b32_e32 v154, 16, v206
	v_and_b32_e32 v155, 0xffff0000, v206
	v_lshlrev_b32_e32 v156, 16, v207
	v_and_b32_e32 v157, 0xffff0000, v207
	v_lshlrev_b32_e32 v158, 16, v208
	v_and_b32_e32 v159, 0xffff0000, v208
	v_lshlrev_b32_e32 v160, 16, v209
	v_and_b32_e32 v161, 0xffff0000, v209
	v_pk_mul_f32 v[78:79], v[78:79], v[154:155]
	v_pk_mul_f32 v[80:81], v[80:81], v[156:157]
	v_pk_mul_f32 v[74:75], v[74:75], v[158:159]
	v_pk_mul_f32 v[76:77], v[76:77], v[160:161]
	v_cvt_pk_bf16_f32 v206, v78, v79
	v_cvt_pk_bf16_f32 v207, v80, v81
	v_cvt_pk_bf16_f32 v208, v74, v75
	v_cvt_pk_bf16_f32 v209, v76, v77
	global_store_dwordx4 v153, v[206:209], s[80:81] offset:0
	s_waitcnt vmcnt(7)
	v_lshlrev_b32_e32 v154, 16, v210
	v_and_b32_e32 v155, 0xffff0000, v210
	v_lshlrev_b32_e32 v156, 16, v211
	v_and_b32_e32 v157, 0xffff0000, v211
	v_lshlrev_b32_e32 v158, 16, v212
	v_and_b32_e32 v159, 0xffff0000, v212
	v_lshlrev_b32_e32 v160, 16, v213
	v_and_b32_e32 v161, 0xffff0000, v213
	v_pk_mul_f32 v[70:71], v[70:71], v[154:155]
	v_pk_mul_f32 v[72:73], v[72:73], v[156:157]
	v_pk_mul_f32 v[66:67], v[66:67], v[158:159]
	v_pk_mul_f32 v[68:69], v[68:69], v[160:161]
	v_cvt_pk_bf16_f32 v210, v70, v71
	v_cvt_pk_bf16_f32 v211, v72, v73
	v_cvt_pk_bf16_f32 v212, v66, v67
	v_cvt_pk_bf16_f32 v213, v68, v69
	global_store_dwordx4 v153, v[210:213], s[80:81] offset:256
	v_add_u32_e32 v152, 0x490000, v150
	global_load_dwordx4 v[182:185], v152, s[100:101] offset:0
	global_load_dwordx4 v[186:189], v152, s[100:101] offset:256
	v_add_u32_e32 v152, 0x522000, v150
	global_load_dwordx4 v[190:193], v152, s[100:101] offset:0
	global_load_dwordx4 v[194:197], v152, s[100:101] offset:256
	v_add_u32_e32 v152, 0x5b4000, v150
	global_load_dwordx4 v[198:201], v152, s[100:101] offset:0
	global_load_dwordx4 v[202:205], v152, s[100:101] offset:256
	v_add_u32_e32 v152, 0x646000, v150
	global_load_dwordx4 v[206:209], v152, s[100:101] offset:0
	global_load_dwordx4 v[210:213], v152, s[100:101] offset:256
	v_add_u32_e32 v153, 0x80000, v151
	s_waitcnt vmcnt(7)
	v_lshlrev_b32_e32 v154, 16, v182
	v_and_b32_e32 v155, 0xffff0000, v182
	v_lshlrev_b32_e32 v156, 16, v183
	v_and_b32_e32 v157, 0xffff0000, v183
	v_lshlrev_b32_e32 v158, 16, v184
	v_and_b32_e32 v159, 0xffff0000, v184
	v_lshlrev_b32_e32 v160, 16, v185
	v_and_b32_e32 v161, 0xffff0000, v185
	v_pk_mul_f32 v[62:63], v[62:63], v[154:155]
	v_pk_mul_f32 v[64:65], v[64:65], v[156:157]
	v_pk_mul_f32 v[58:59], v[58:59], v[158:159]
	v_pk_mul_f32 v[60:61], v[60:61], v[160:161]
	v_cvt_pk_bf16_f32 v182, v62, v63
	v_cvt_pk_bf16_f32 v183, v64, v65
	v_cvt_pk_bf16_f32 v184, v58, v59
	v_cvt_pk_bf16_f32 v185, v60, v61
	global_store_dwordx4 v153, v[182:185], s[80:81] offset:0
	s_waitcnt vmcnt(7)
	v_lshlrev_b32_e32 v154, 16, v186
	v_and_b32_e32 v155, 0xffff0000, v186
	v_lshlrev_b32_e32 v156, 16, v187
	v_and_b32_e32 v157, 0xffff0000, v187
	v_lshlrev_b32_e32 v158, 16, v188
	v_and_b32_e32 v159, 0xffff0000, v188
	v_lshlrev_b32_e32 v160, 16, v189
	v_and_b32_e32 v161, 0xffff0000, v189
	v_pk_mul_f32 v[54:55], v[54:55], v[154:155]
	v_pk_mul_f32 v[56:57], v[56:57], v[156:157]
	v_pk_mul_f32 v[50:51], v[50:51], v[158:159]
	v_pk_mul_f32 v[52:53], v[52:53], v[160:161]
	v_cvt_pk_bf16_f32 v186, v54, v55
	v_cvt_pk_bf16_f32 v187, v56, v57
	v_cvt_pk_bf16_f32 v188, v50, v51
	v_cvt_pk_bf16_f32 v189, v52, v53
	global_store_dwordx4 v153, v[186:189], s[80:81] offset:256
	v_add_u32_e32 v153, 0x90000, v151
	s_waitcnt vmcnt(7)
; #define PG8_BAR __builtin_amdgcn_s_barrier()
; template <class Epi>
; __device__ __forceinline__ void gemm_phase(LAS unsigned char* lds, const Gemm g, const Order& S, const Epi& E) {
;     ...
;         if (wr == 0) PG8_BAR;
;         E(acc, cur, wr, wc, fr, fq);
;         if (!has_next) break;
;     __device__ __forceinline__ void operator()(const f32x4 (&acc)[2][2][4][2], const pg8::Unit& u, int wr, int wc, int fr, int fq) const {
;     ...
;             if (z == 0) {
; #pragma unroll
;                 for (int i = 0; i < 8; ++i) v[i] *= g[i];
;             } else {
;                 float mm[8]; unpack8(*(const u32x4*)mp, mm);
; #pragma unroll
;                 for (int i = 0; i < 8; ++i) v[i] = mm[i] + v[i] * g[i];
;             }
;             *(u32x4*)mp = pack8(v);
	v_lshlrev_b32_e32 v154, 16, v190
	v_and_b32_e32 v155, 0xffff0000, v190
	v_lshlrev_b32_e32 v156, 16, v191
	v_and_b32_e32 v157, 0xffff0000, v191
	v_lshlrev_b32_e32 v158, 16, v192
	v_and_b32_e32 v159, 0xffff0000, v192
	v_lshlrev_b32_e32 v160, 16, v193
	v_and_b32_e32 v161, 0xffff0000, v193
	v_pk_mul_f32 v[46:47], v[46:47], v[154:155]
	v_pk_mul_f32 v[48:49], v[48:49], v[156:157]
	v_pk_mul_f32 v[42:43], v[42:43], v[158:159]
	v_pk_mul_f32 v[44:45], v[44:45], v[160:161]
	v_cvt_pk_bf16_f32 v190, v46, v47
	v_cvt_pk_bf16_f32 v191, v48, v49
	v_cvt_pk_bf16_f32 v192, v42, v43
	v_cvt_pk_bf16_f32 v193, v44, v45
	global_store_dwordx4 v153, v[190:193], s[80:81] offset:0
	s_waitcnt vmcnt(7)
	v_lshlrev_b32_e32 v154, 16, v194
	v_and_b32_e32 v155, 0xffff0000, v194
	v_lshlrev_b32_e32 v156, 16, v195
	v_and_b32_e32 v157, 0xffff0000, v195
	v_lshlrev_b32_e32 v158, 16, v196
	v_and_b32_e32 v159, 0xffff0000, v196
	v_lshlrev_b32_e32 v160, 16, v197
	v_and_b32_e32 v161, 0xffff0000, v197
	v_pk_mul_f32 v[38:39], v[38:39], v[154:155]
	v_pk_mul_f32 v[40:41], v[40:41], v[156:157]
	v_pk_mul_f32 v[34:35], v[34:35], v[158:159]
	v_pk_mul_f32 v[36:37], v[36:37], v[160:161]
	v_cvt_pk_bf16_f32 v194, v38, v39
	v_cvt_pk_bf16_f32 v195, v40, v41
	v_cvt_pk_bf16_f32 v196, v34, v35
	v_cvt_pk_bf16_f32 v197, v36, v37
	global_store_dwordx4 v153, v[194:197], s[80:81] offset:256
	v_add_u32_e32 v153, 0xa0000, v151
	s_waitcnt vmcnt(7)
	v_lshlrev_b32_e32 v154, 16, v198
	v_and_b32_e32 v155, 0xffff0000, v198
	v_lshlrev_b32_e32 v156, 16, v199
	v_and_b32_e32 v157, 0xffff0000, v199
	v_lshlrev_b32_e32 v158, 16, v200
	v_and_b32_e32 v159, 0xffff0000, v200
	v_lshlrev_b32_e32 v160, 16, v201
	v_and_b32_e32 v161, 0xffff0000, v201
	v_pk_mul_f32 v[30:31], v[30:31], v[154:155]
	v_pk_mul_f32 v[32:33], v[32:33], v[156:157]
	v_pk_mul_f32 v[26:27], v[26:27], v[158:159]
	v_pk_mul_f32 v[28:29], v[28:29], v[160:161]
	v_cvt_pk_bf16_f32 v198, v30, v31
	v_cvt_pk_bf16_f32 v199, v32, v33
	v_cvt_pk_bf16_f32 v200, v26, v27
	v_cvt_pk_bf16_f32 v201, v28, v29
	global_store_dwordx4 v153, v[198:201], s[80:81] offset:0
	s_waitcnt vmcnt(7)
	v_lshlrev_b32_e32 v154, 16, v202
	v_and_b32_e32 v155, 0xffff0000, v202
	v_lshlrev_b32_e32 v156, 16, v203
	v_and_b32_e32 v157, 0xffff0000, v203
	v_lshlrev_b32_e32 v158, 16, v204
	v_and_b32_e32 v159, 0xffff0000, v204
	v_lshlrev_b32_e32 v160, 16, v205
	v_and_b32_e32 v161, 0xffff0000, v205
	v_pk_mul_f32 v[22:23], v[22:23], v[154:155]
	v_pk_mul_f32 v[24:25], v[24:25], v[156:157]
	v_pk_mul_f32 v[18:19], v[18:19], v[158:159]
	v_pk_mul_f32 v[20:21], v[20:21], v[160:161]
	v_cvt_pk_bf16_f32 v202, v22, v23
	v_cvt_pk_bf16_f32 v203, v24, v25
	v_cvt_pk_bf16_f32 v204, v18, v19
	v_cvt_pk_bf16_f32 v205, v20, v21
	global_store_dwordx4 v153, v[202:205], s[80:81] offset:256
	v_add_u32_e32 v153, 0xb0000, v151
	s_waitcnt vmcnt(7)
	v_lshlrev_b32_e32 v154, 16, v206
	v_and_b32_e32 v155, 0xffff0000, v206
	v_lshlrev_b32_e32 v156, 16, v207
	v_and_b32_e32 v157, 0xffff0000, v207
	v_lshlrev_b32_e32 v158, 16, v208
	v_and_b32_e32 v159, 0xffff0000, v208
	v_lshlrev_b32_e32 v160, 16, v209
	v_and_b32_e32 v161, 0xffff0000, v209
	v_pk_mul_f32 v[14:15], v[14:15], v[154:155]
	v_pk_mul_f32 v[16:17], v[16:17], v[156:157]
	v_pk_mul_f32 v[10:11], v[10:11], v[158:159]
	v_pk_mul_f32 v[12:13], v[12:13], v[160:161]
	v_cvt_pk_bf16_f32 v206, v14, v15
	v_cvt_pk_bf16_f32 v207, v16, v17
	v_cvt_pk_bf16_f32 v208, v10, v11
	v_cvt_pk_bf16_f32 v209, v12, v13
	global_store_dwordx4 v153, v[206:209], s[80:81] offset:0
	s_waitcnt vmcnt(7)
	v_lshlrev_b32_e32 v154, 16, v210
	v_and_b32_e32 v155, 0xffff0000, v210
	v_lshlrev_b32_e32 v156, 16, v211
	v_and_b32_e32 v157, 0xffff0000, v211
	v_lshlrev_b32_e32 v158, 16, v212
	v_and_b32_e32 v159, 0xffff0000, v212
	v_lshlrev_b32_e32 v160, 16, v213
	v_and_b32_e32 v161, 0xffff0000, v213
	v_pk_mul_f32 v[4:5], v[4:5], v[154:155]
	v_pk_mul_f32 v[6:7], v[6:7], v[156:157]
	v_pk_mul_f32 v[0:1], v[0:1], v[158:159]
	v_pk_mul_f32 v[2:3], v[2:3], v[160:161]
	v_cvt_pk_bf16_f32 v210, v4, v5
	v_cvt_pk_bf16_f32 v211, v6, v7
	v_cvt_pk_bf16_f32 v212, v0, v1
	v_cvt_pk_bf16_f32 v213, v2, v3
	global_store_dwordx4 v153, v[210:213], s[80:81] offset:256
.Lg2epi_done:
	s_andn2_b64 s[44:45], exec, s[56:57]
	s_and_b64 vcc, exec, s[42:43]
	s_mov_b64 s[42:43], -1
	s_cbranch_vccnz .LBB0_1577
	s_andn2_b64 vcc, exec, s[38:39]
	s_cbranch_vccnz .LBB0_1576
	s_barrier
	s_branch .LBB0_1576
